# v6 + MFMAs inside each 8-MFMA group of the GEMM K-loops reordered so consecutive MFMAs always share one operand register (less operand switching; independent accumulators, bit-exact)
# speedup vs baseline: 1.0012x; 1.0012x over previous
; #define PG8_STAGE(bufoff, gbase, voff) do { _Pragma("unroll") for (int _i = 0; _i < 2; ++_i) \
;         __builtin_amdgcn_global_load_lds((const unsigned*)((const char*)(gbase) + (voff)[_i]), (PG8_LAS unsigned*)(lds + (bufoff) + ldsw + _i * 8192), 16, 0, 0); } while (0)
; #define PG8_LDA(dst, b, h) do { _Pragma("unroll") for (int m = 0; m < 4; ++m) _Pragma("unroll") for (int k = 0; k < 2; ++k) dst[m][k] = *(const PG8_LAS bf16x8*)(lds + PG8_SA(b, h) + aoff + m * 2048 + k * 1024); } while (0)
; #define PG8_LDB(dst, b, h) do { _Pragma("unroll") for (int n = 0; n < 2; ++n) _Pragma("unroll") for (int k = 0; k < 2; ++k) dst[n][k] = *(const PG8_LAS bf16x8*)(lds + PG8_SB(b, h) + boff + n * 2048 + k * 1024); } while (0)
; #define PG8_MMA(ai, bj, At, Bt) do { __builtin_amdgcn_s_setprio(1); _Pragma("unroll") for (int m = 0; m < 4; ++m) _Pragma("unroll") for (int n = 0; n < 2; ++n) _Pragma("unroll") for (int k = 0; k < 2; ++k) \
;         acc[ai][bj][m][n] = __builtin_amdgcn_mfma_f32_16x16x32_bf16(Bt[n][k], At[m][k], acc[ai][bj][m][n], 0, 0, 0); __builtin_amdgcn_s_setprio(0); } while (0)
; #define PG8_WAIT_V(n) asm volatile("s_waitcnt vmcnt(" #n ")" ::: "memory")
; #define PG8_BAR __builtin_amdgcn_s_barrier()
; template <class Epi, class Sched, bool ALIGN_EPI = false, bool SP2 = false>
; __device__ __forceinline__ void gemm_phase(PG8_LAS unsigned char* lds, const Gemm g, const Sched& S, const Epi& E) {
;     ...
;         for (int t = 0; t < nt; t += 2) {
;             const bool last = (t == nt - 2);
;             const char* a1 = cA + (size_t)(t + 1) * kstep;
;             const char* a2 = last ? nA : cA + (size_t)(t + 2) * kstep; const char* b2 = last ? nB : cB + (size_t)(t + 2) * kstep;
;             const char* a3 = a2 + kstep; const char* b3 = b2 + kstep;
;             if (last && has_next) S.a_ready(nxt);
;             if constexpr (SP2) {
;             PG8_LDB(B0, 0, 0); PG8_LDB(B1, 0, 1); PG8_SCHED; PG8_LDA(At, 0, 0); PG8_STAGE(PG8_SA(1, 1), a1 + hstepA, voffA);
;             PG8_WAIT_V(8); PG8_WAIT_L(0); PG8_BAR; PG8_MMA(0, 0, At, B0); PG8_MMA(0, 1, At, B1); PG8_BAR; PG8_SCHED;
;             PG8_LDA(At, 0, 1); PG8_STAGE(PG8_SB(0, 0), b2, voffB); PG8_STAGE(PG8_SB(0, 1), b2 + hstepB, voffB); PG8_STAGE(PG8_SA(0, 0), a2, voffA);
;             PG8_WAIT_V(8); PG8_WAIT_L(0); PG8_BAR; PG8_MMA(1, 0, At, B0); PG8_MMA(1, 1, At, B1); PG8_BAR; PG8_SCHED;
.LBB0_196:
	s_ashr_i32 s21, s20, 31
	s_lshl_b64 s[22:23], s[20:21], 19
	s_add_u32 s22, s3, s22
	s_addc_u32 s23, s34, s23
	s_and_b64 s[24:25], s[6:7], exec
	s_cselect_b32 s1, s23, s27
	s_cselect_b32 s2, s22, s26
	s_ashr_i32 s19, s18, 31
	s_lshl_b64 s[24:25], s[18:19], 19
	s_add_u32 s24, s35, s24
	s_addc_u32 s25, s36, s25
	s_and_b64 s[30:31], s[6:7], exec
	s_cselect_b32 s5, s25, s29
	s_cselect_b32 s19, s24, s28
	s_add_u32 s26, s26, 0x40080
	s_addc_u32 s27, s27, 0
	s_add_u32 s21, s28, 0x100
	s_addc_u32 s33, s29, 0
	s_mov_b32 s60, -2
	s_waitcnt lgkmcnt(0)
	ds_read_b128 v[168:171], v163
	ds_read_b128 v[176:179], v163 offset:1024
	ds_read_b128 v[184:187], v163 offset:2048
	ds_read_b128 v[188:191], v163 offset:3072
	ds_read_b128 v[192:195], v165
	ds_read_b128 v[196:199], v165 offset:1024
	ds_read_b128 v[200:203], v165 offset:2048
	ds_read_b128 v[204:207], v165 offset:3072
	s_add_u32 s28, s26, 0xfffc0080
	s_addc_u32 s29, s27, -1
	s_cmp_eq_u32 s60, 12
	s_cselect_b32 s31, s1, s29
	s_cselect_b32 s30, s2, s28
	s_cselect_b32 s29, s5, s33
	s_cselect_b32 s28, s19, s21
	v_lshl_add_u64 v[158:159], s[26:27], 0, v[146:147]
	s_add_i32 m0, s40, 0xc000
	ds_read_b128 v[208:211], v167
	ds_read_b128 v[212:215], v167 offset:1024
	ds_read_b128 v[216:219], v167 offset:2048
	ds_read_b128 v[220:223], v167 offset:3072
	ds_read_b128 v[224:227], v167 offset:4096
	ds_read_b128 v[228:231], v167 offset:5120
	ds_read_b128 v[232:235], v167 offset:6144
	ds_read_b128 v[236:239], v167 offset:7168
	global_load_lds_dwordx4 v[158:159], off
	v_lshl_add_u64 v[158:159], s[26:27], 0, v[148:149]
	s_add_i32 m0, s40, 0xe000
	s_nop 0
	global_load_lds_dwordx4 v[158:159], off
	s_waitcnt vmcnt(8)
	s_waitcnt lgkmcnt(0)
	s_barrier
	s_setprio 1
	s_waitcnt lgkmcnt(0)
	v_mfma_f32_16x16x32_bf16 v[126:129], v[168:171], v[208:211], 0
	v_mfma_f32_16x16x32_bf16 v[122:125], v[184:187], v[208:211], 0
	v_mfma_f32_16x16x32_bf16 v[106:109], v[184:187], v[216:219], 0
	v_mfma_f32_16x16x32_bf16 v[110:113], v[168:171], v[216:219], 0
	v_mfma_f32_16x16x32_bf16 v[94:97], v[168:171], v[224:227], 0
	v_mfma_f32_16x16x32_bf16 v[90:93], v[184:187], v[224:227], 0
	v_mfma_f32_16x16x32_bf16 v[74:77], v[184:187], v[232:235], 0
	v_mfma_f32_16x16x32_bf16 v[78:81], v[168:171], v[232:235], 0
	v_mfma_f32_16x16x32_bf16 v[126:129], v[176:179], v[212:215], v[126:129]
	v_mfma_f32_16x16x32_bf16 v[122:125], v[188:191], v[212:215], v[122:125]
	v_mfma_f32_16x16x32_bf16 v[106:109], v[188:191], v[220:223], v[106:109]
	v_mfma_f32_16x16x32_bf16 v[110:113], v[176:179], v[220:223], v[110:113]
	v_mfma_f32_16x16x32_bf16 v[94:97], v[176:179], v[228:231], v[94:97]
	v_mfma_f32_16x16x32_bf16 v[90:93], v[188:191], v[228:231], v[90:93]
	v_mfma_f32_16x16x32_bf16 v[74:77], v[188:191], v[236:239], v[74:77]
	v_mfma_f32_16x16x32_bf16 v[78:81], v[176:179], v[236:239], v[78:81]
	s_setprio 0
	s_setprio 1
	v_mfma_f32_16x16x32_bf16 v[118:121], v[192:195], v[208:211], 0
	v_mfma_f32_16x16x32_bf16 v[114:117], v[200:203], v[208:211], 0
	v_mfma_f32_16x16x32_bf16 v[98:101], v[200:203], v[216:219], 0
	v_mfma_f32_16x16x32_bf16 v[102:105], v[192:195], v[216:219], 0
	v_mfma_f32_16x16x32_bf16 v[86:89], v[192:195], v[224:227], 0
	v_mfma_f32_16x16x32_bf16 v[82:85], v[200:203], v[224:227], 0
	v_mfma_f32_16x16x32_bf16 v[66:69], v[200:203], v[232:235], 0
	v_mfma_f32_16x16x32_bf16 v[70:73], v[192:195], v[232:235], 0
	v_mfma_f32_16x16x32_bf16 v[118:121], v[196:199], v[212:215], v[118:121]
	v_mfma_f32_16x16x32_bf16 v[114:117], v[204:207], v[212:215], v[114:117]
	v_mfma_f32_16x16x32_bf16 v[98:101], v[204:207], v[220:223], v[98:101]
	v_mfma_f32_16x16x32_bf16 v[102:105], v[196:199], v[220:223], v[102:105]
	v_mfma_f32_16x16x32_bf16 v[86:89], v[196:199], v[228:231], v[86:89]
	v_mfma_f32_16x16x32_bf16 v[82:85], v[204:207], v[228:231], v[82:85]
	v_mfma_f32_16x16x32_bf16 v[66:69], v[204:207], v[236:239], v[66:69]
	v_mfma_f32_16x16x32_bf16 v[70:73], v[196:199], v[236:239], v[70:73]
	s_setprio 0
	s_barrier
	s_add_i32 s61, s53, s37
	v_lshl_add_u64 v[158:159], s[28:29], 0, v[134:135]
	s_mov_b32 m0, s61
	ds_read_b128 v[208:211], v167 offset:16384
	ds_read_b128 v[212:215], v167 offset:17408
	ds_read_b128 v[216:219], v167 offset:18432
	ds_read_b128 v[220:223], v167 offset:19456
	ds_read_b128 v[224:227], v167 offset:20480
	ds_read_b128 v[228:231], v167 offset:21504
	ds_read_b128 v[232:235], v167 offset:22528
	ds_read_b128 v[236:239], v167 offset:23552
	global_load_lds_dwordx4 v[158:159], off
	s_add_i32 m0, s61, 0x2000
	s_add_u32 s62, s28, 0x40000
	v_lshl_add_u64 v[180:181], s[28:29], 0, v[130:131]
	s_addc_u32 s63, s29, 0
	s_add_i32 s61, s54, s37
	global_load_lds_dwordx4 v[180:181], off
	v_lshl_add_u64 v[240:241], s[62:63], 0, v[134:135]
	s_mov_b32 m0, s61
	v_lshl_add_u64 v[242:243], s[30:31], 0, v[132:133]
	global_load_lds_dwordx4 v[240:241], off
	v_lshl_add_u64 v[240:241], s[62:63], 0, v[130:131]
	s_add_i32 m0, s61, 0x2000
	s_nop 0
	global_load_lds_dwordx4 v[240:241], off
	v_lshl_add_u64 v[240:241], s[30:31], 0, v[136:137]
	s_mov_b32 m0, s40
	s_nop 0
	global_load_lds_dwordx4 v[240:241], off
	s_mov_b32 m0, s41
	s_nop 0
	global_load_lds_dwordx4 v[242:243], off
	s_waitcnt vmcnt(8)
	s_waitcnt lgkmcnt(0)
	s_barrier
; #define PG8_STAGE(bufoff, gbase, voff) do { _Pragma("unroll") for (int _i = 0; _i < 2; ++_i) \
;         __builtin_amdgcn_global_load_lds((const unsigned*)((const char*)(gbase) + (voff)[_i]), (PG8_LAS unsigned*)(lds + (bufoff) + ldsw + _i * 8192), 16, 0, 0); } while (0)
; #define PG8_LDA(dst, b, h) do { _Pragma("unroll") for (int m = 0; m < 4; ++m) _Pragma("unroll") for (int k = 0; k < 2; ++k) dst[m][k] = *(const PG8_LAS bf16x8*)(lds + PG8_SA(b, h) + aoff + m * 2048 + k * 1024); } while (0)
; #define PG8_LDB(dst, b, h) do { _Pragma("unroll") for (int n = 0; n < 2; ++n) _Pragma("unroll") for (int k = 0; k < 2; ++k) dst[n][k] = *(const PG8_LAS bf16x8*)(lds + PG8_SB(b, h) + boff + n * 2048 + k * 1024); } while (0)
; #define PG8_MMA(ai, bj, At, Bt) do { __builtin_amdgcn_s_setprio(1); _Pragma("unroll") for (int m = 0; m < 4; ++m) _Pragma("unroll") for (int n = 0; n < 2; ++n) _Pragma("unroll") for (int k = 0; k < 2; ++k) \
;         acc[ai][bj][m][n] = __builtin_amdgcn_mfma_f32_16x16x32_bf16(Bt[n][k], At[m][k], acc[ai][bj][m][n], 0, 0, 0); __builtin_amdgcn_s_setprio(0); } while (0)
; #define PG8_WAIT_V(n) asm volatile("s_waitcnt vmcnt(" #n ")" ::: "memory")
; #define PG8_WAIT_L(n) asm volatile("s_waitcnt lgkmcnt(" #n ")" ::: "memory")
; #define PG8_BAR __builtin_amdgcn_s_barrier()
; template <class Epi, class Sched, bool ALIGN_EPI = false, bool SP2 = false>
; __device__ __forceinline__ void gemm_phase(PG8_LAS unsigned char* lds, const Gemm g, const Sched& S, const Epi& E) {
;     ...
;             PG8_WAIT_V(8); PG8_WAIT_L(0); PG8_BAR; PG8_MMA(0, 0, At, B0); PG8_MMA(0, 1, At, B1); PG8_BAR; PG8_SCHED;
;             PG8_LDA(At, 0, 1); PG8_STAGE(PG8_SB(0, 0), b2, voffB); PG8_STAGE(PG8_SB(0, 1), b2 + hstepB, voffB); PG8_STAGE(PG8_SA(0, 0), a2, voffA);
;             PG8_WAIT_V(8); PG8_WAIT_L(0); PG8_BAR; PG8_MMA(1, 0, At, B0); PG8_MMA(1, 1, At, B1); PG8_BAR; PG8_SCHED;
;             PG8_LDB(B0, 1, 0); PG8_LDB(B1, 1, 1); PG8_SCHED; PG8_LDA(At, 1, 0); PG8_STAGE(PG8_SA(0, 1), a2 + hstepA, voffA);
;             PG8_WAIT_V(8); PG8_WAIT_L(0); PG8_BAR; PG8_MMA(0, 0, At, B0); PG8_MMA(0, 1, At, B1); PG8_BAR; PG8_SCHED;
;             PG8_LDA(At, 1, 1); PG8_STAGE(PG8_SB(1, 0), b3, voffB); PG8_STAGE(PG8_SB(1, 1), b3 + hstepB, voffB); PG8_STAGE(PG8_SA(1, 0), a3, voffA);
;             PG8_WAIT_V(8); PG8_WAIT_L(0); PG8_BAR; PG8_MMA(1, 0, At, B0); PG8_MMA(1, 1, At, B1); PG8_BAR; PG8_SCHED;
	s_setprio 1
	s_waitcnt lgkmcnt(0)
	v_mfma_f32_16x16x32_bf16 v[62:65], v[168:171], v[208:211], 0
	v_mfma_f32_16x16x32_bf16 v[58:61], v[184:187], v[208:211], 0
	v_mfma_f32_16x16x32_bf16 v[42:45], v[184:187], v[216:219], 0
	v_mfma_f32_16x16x32_bf16 v[46:49], v[168:171], v[216:219], 0
	v_mfma_f32_16x16x32_bf16 v[30:33], v[168:171], v[224:227], 0
	v_mfma_f32_16x16x32_bf16 v[26:29], v[184:187], v[224:227], 0
	v_mfma_f32_16x16x32_bf16 v[10:13], v[184:187], v[232:235], 0
	v_mfma_f32_16x16x32_bf16 v[14:17], v[168:171], v[232:235], 0
	v_mfma_f32_16x16x32_bf16 v[62:65], v[176:179], v[212:215], v[62:65]
	v_mfma_f32_16x16x32_bf16 v[58:61], v[188:191], v[212:215], v[58:61]
	v_mfma_f32_16x16x32_bf16 v[42:45], v[188:191], v[220:223], v[42:45]
	v_mfma_f32_16x16x32_bf16 v[46:49], v[176:179], v[220:223], v[46:49]
	v_mfma_f32_16x16x32_bf16 v[30:33], v[176:179], v[228:231], v[30:33]
	v_mfma_f32_16x16x32_bf16 v[26:29], v[188:191], v[228:231], v[26:29]
	v_mfma_f32_16x16x32_bf16 v[10:13], v[188:191], v[236:239], v[10:13]
	v_mfma_f32_16x16x32_bf16 v[14:17], v[176:179], v[236:239], v[14:17]
	s_setprio 0
	s_setprio 1
	v_mfma_f32_16x16x32_bf16 v[54:57], v[192:195], v[208:211], 0
	v_mfma_f32_16x16x32_bf16 v[50:53], v[200:203], v[208:211], 0
	v_mfma_f32_16x16x32_bf16 v[34:37], v[200:203], v[216:219], 0
	v_mfma_f32_16x16x32_bf16 v[38:41], v[192:195], v[216:219], 0
	v_mfma_f32_16x16x32_bf16 v[22:25], v[192:195], v[224:227], 0
	v_mfma_f32_16x16x32_bf16 v[18:21], v[200:203], v[224:227], 0
	v_mfma_f32_16x16x32_bf16 v[2:5], v[200:203], v[232:235], 0
	v_mfma_f32_16x16x32_bf16 v[6:9], v[192:195], v[232:235], 0
	v_mfma_f32_16x16x32_bf16 v[54:57], v[196:199], v[212:215], v[54:57]
	v_mfma_f32_16x16x32_bf16 v[50:53], v[204:207], v[212:215], v[50:53]
	v_mfma_f32_16x16x32_bf16 v[34:37], v[204:207], v[220:223], v[34:37]
	v_mfma_f32_16x16x32_bf16 v[38:41], v[196:199], v[220:223], v[38:41]
	v_mfma_f32_16x16x32_bf16 v[22:25], v[196:199], v[228:231], v[22:25]
	v_mfma_f32_16x16x32_bf16 v[18:21], v[204:207], v[228:231], v[18:21]
	v_mfma_f32_16x16x32_bf16 v[2:5], v[204:207], v[236:239], v[2:5]
	v_mfma_f32_16x16x32_bf16 v[6:9], v[196:199], v[236:239], v[6:9]
	s_setprio 0
	s_barrier
	s_add_i32 s61, 0, 0x18000
	v_add_u32_e32 v138, s61, v141
	s_add_i32 s62, 0, 0x1c000
	ds_read_b128 v[168:171], v138
	ds_read_b128 v[176:179], v138 offset:1024
	ds_read_b128 v[184:187], v138 offset:2048
	ds_read_b128 v[188:191], v138 offset:3072
	v_add_u32_e32 v138, s62, v141
	ds_read_b128 v[192:195], v138
	ds_read_b128 v[196:199], v138 offset:1024
	ds_read_b128 v[200:203], v138 offset:2048
	ds_read_b128 v[204:207], v138 offset:3072
	s_add_u32 s30, s30, 0x40000
	s_addc_u32 s31, s31, 0
	s_mov_b32 m0, s42
	v_lshl_add_u64 v[244:245], s[30:31], 0, v[136:137]
	ds_read_b128 v[208:211], v167 offset:32768
	ds_read_b128 v[212:215], v167 offset:33792
	ds_read_b128 v[216:219], v167 offset:34816
	ds_read_b128 v[220:223], v167 offset:35840
	ds_read_b128 v[224:227], v167 offset:36864
	ds_read_b128 v[228:231], v167 offset:37888
	ds_read_b128 v[232:235], v167 offset:38912
	ds_read_b128 v[236:239], v167 offset:39936
	global_load_lds_dwordx4 v[244:245], off
	v_lshl_add_u64 v[244:245], s[30:31], 0, v[132:133]
	s_mov_b32 m0, s43
	s_nop 0
	global_load_lds_dwordx4 v[244:245], off
	s_waitcnt vmcnt(8)
	s_waitcnt lgkmcnt(0)
	s_barrier
	s_setprio 1
	s_waitcnt lgkmcnt(0)
	v_mfma_f32_16x16x32_bf16 v[126:129], v[168:171], v[208:211], v[126:129]
	v_mfma_f32_16x16x32_bf16 v[122:125], v[184:187], v[208:211], v[122:125]
	v_mfma_f32_16x16x32_bf16 v[106:109], v[184:187], v[216:219], v[106:109]
	v_mfma_f32_16x16x32_bf16 v[110:113], v[168:171], v[216:219], v[110:113]
	v_mfma_f32_16x16x32_bf16 v[94:97], v[168:171], v[224:227], v[94:97]
	v_mfma_f32_16x16x32_bf16 v[90:93], v[184:187], v[224:227], v[90:93]
	v_mfma_f32_16x16x32_bf16 v[74:77], v[184:187], v[232:235], v[74:77]
	v_mfma_f32_16x16x32_bf16 v[78:81], v[168:171], v[232:235], v[78:81]
	v_mfma_f32_16x16x32_bf16 v[126:129], v[176:179], v[212:215], v[126:129]
	v_mfma_f32_16x16x32_bf16 v[122:125], v[188:191], v[212:215], v[122:125]
	v_mfma_f32_16x16x32_bf16 v[106:109], v[188:191], v[220:223], v[106:109]
	v_mfma_f32_16x16x32_bf16 v[110:113], v[176:179], v[220:223], v[110:113]
	v_mfma_f32_16x16x32_bf16 v[94:97], v[176:179], v[228:231], v[94:97]
	v_mfma_f32_16x16x32_bf16 v[90:93], v[188:191], v[228:231], v[90:93]
	v_mfma_f32_16x16x32_bf16 v[74:77], v[188:191], v[236:239], v[74:77]
	v_mfma_f32_16x16x32_bf16 v[78:81], v[176:179], v[236:239], v[78:81]
	s_setprio 0
	s_setprio 1
	v_mfma_f32_16x16x32_bf16 v[118:121], v[192:195], v[208:211], v[118:121]
	v_mfma_f32_16x16x32_bf16 v[114:117], v[200:203], v[208:211], v[114:117]
	v_mfma_f32_16x16x32_bf16 v[98:101], v[200:203], v[216:219], v[98:101]
	v_mfma_f32_16x16x32_bf16 v[102:105], v[192:195], v[216:219], v[102:105]
	v_mfma_f32_16x16x32_bf16 v[86:89], v[192:195], v[224:227], v[86:89]
	v_mfma_f32_16x16x32_bf16 v[82:85], v[200:203], v[224:227], v[82:85]
	v_mfma_f32_16x16x32_bf16 v[66:69], v[200:203], v[232:235], v[66:69]
	v_mfma_f32_16x16x32_bf16 v[70:73], v[192:195], v[232:235], v[70:73]
	v_mfma_f32_16x16x32_bf16 v[118:121], v[196:199], v[212:215], v[118:121]
	v_mfma_f32_16x16x32_bf16 v[114:117], v[204:207], v[212:215], v[114:117]
	v_mfma_f32_16x16x32_bf16 v[98:101], v[204:207], v[220:223], v[98:101]
	v_mfma_f32_16x16x32_bf16 v[102:105], v[196:199], v[220:223], v[102:105]
	v_mfma_f32_16x16x32_bf16 v[86:89], v[196:199], v[228:231], v[86:89]
	v_mfma_f32_16x16x32_bf16 v[82:85], v[204:207], v[228:231], v[82:85]
	v_mfma_f32_16x16x32_bf16 v[66:69], v[204:207], v[236:239], v[66:69]
	v_mfma_f32_16x16x32_bf16 v[70:73], v[196:199], v[236:239], v[70:73]
	s_setprio 0
	s_barrier
; #define PG8_STAGE(bufoff, gbase, voff) do { _Pragma("unroll") for (int _i = 0; _i < 2; ++_i) \
;         __builtin_amdgcn_global_load_lds((const unsigned*)((const char*)(gbase) + (voff)[_i]), (PG8_LAS unsigned*)(lds + (bufoff) + ldsw + _i * 8192), 16, 0, 0); } while (0)
; #define PG8_LDA(dst, b, h) do { _Pragma("unroll") for (int m = 0; m < 4; ++m) _Pragma("unroll") for (int k = 0; k < 2; ++k) dst[m][k] = *(const PG8_LAS bf16x8*)(lds + PG8_SA(b, h) + aoff + m * 2048 + k * 1024); } while (0)
; #define PG8_LDB(dst, b, h) do { _Pragma("unroll") for (int n = 0; n < 2; ++n) _Pragma("unroll") for (int k = 0; k < 2; ++k) dst[n][k] = *(const PG8_LAS bf16x8*)(lds + PG8_SB(b, h) + boff + n * 2048 + k * 1024); } while (0)
; #define PG8_MMA(ai, bj, At, Bt) do { __builtin_amdgcn_s_setprio(1); _Pragma("unroll") for (int m = 0; m < 4; ++m) _Pragma("unroll") for (int n = 0; n < 2; ++n) _Pragma("unroll") for (int k = 0; k < 2; ++k) \
;         acc[ai][bj][m][n] = __builtin_amdgcn_mfma_f32_16x16x32_bf16(Bt[n][k], At[m][k], acc[ai][bj][m][n], 0, 0, 0); __builtin_amdgcn_s_setprio(0); } while (0)
; #define PG8_WAIT_V(n) asm volatile("s_waitcnt vmcnt(" #n ")" ::: "memory")
; #define PG8_WAIT_L(n) asm volatile("s_waitcnt lgkmcnt(" #n ")" ::: "memory")
; #define PG8_BAR __builtin_amdgcn_s_barrier()
; #define PG8_SCHED __builtin_amdgcn_sched_barrier(0)
; template <class Epi, class Sched, bool ALIGN_EPI = false, bool SP2 = false>
; __device__ __forceinline__ void gemm_phase(PG8_LAS unsigned char* lds, const Gemm g, const Sched& S, const Epi& E) {
;     ...
;         for (int t = 0; t < nt; t += 2) {
;             const bool last = (t == nt - 2);
;             const char* a1 = cA + (size_t)(t + 1) * kstep;
;             const char* a2 = last ? nA : cA + (size_t)(t + 2) * kstep; const char* b2 = last ? nB : cB + (size_t)(t + 2) * kstep;
;             const char* a3 = a2 + kstep; const char* b3 = b2 + kstep;
;             if (last && has_next) S.a_ready(nxt);
;             if constexpr (SP2) {
;             PG8_LDB(B0, 0, 0); PG8_LDB(B1, 0, 1); PG8_SCHED; PG8_LDA(At, 0, 0); PG8_STAGE(PG8_SA(1, 1), a1 + hstepA, voffA);
;     ...
;             PG8_LDA(At, 1, 1); PG8_STAGE(PG8_SB(1, 0), b3, voffB); PG8_STAGE(PG8_SB(1, 1), b3 + hstepB, voffB); PG8_STAGE(PG8_SA(1, 0), a3, voffA);
;             PG8_WAIT_V(8); PG8_WAIT_L(0); PG8_BAR; PG8_MMA(1, 0, At, B0); PG8_MMA(1, 1, At, B1); PG8_BAR; PG8_SCHED;
	s_add_i32 s30, s61, s37
	v_lshl_add_u64 v[158:159], v[158:159], 0, s[14:15]
	s_mov_b32 m0, s30
	ds_read_b128 v[208:211], v167 offset:49152
	ds_read_b128 v[212:215], v167 offset:50176
	ds_read_b128 v[216:219], v167 offset:51200
	ds_read_b128 v[220:223], v167 offset:52224
	ds_read_b128 v[224:227], v167 offset:53248
	ds_read_b128 v[228:231], v167 offset:54272
	ds_read_b128 v[232:235], v167 offset:55296
	ds_read_b128 v[236:239], v167 offset:56320
	global_load_lds_dwordx4 v[158:159], off
	s_add_i32 m0, s30, 0x2000
	s_add_u32 s28, s28, 0x40080
	v_lshl_add_u64 v[158:159], v[180:181], 0, s[14:15]
	s_addc_u32 s29, s29, 0
	s_add_i32 s30, s62, s37
	global_load_lds_dwordx4 v[158:159], off
	v_lshl_add_u64 v[158:159], s[28:29], 0, v[134:135]
	s_mov_b32 m0, s30
	s_nop 0
	global_load_lds_dwordx4 v[158:159], off
	v_lshl_add_u64 v[158:159], s[28:29], 0, v[130:131]
	s_add_i32 m0, s30, 0x2000
	s_nop 0
	global_load_lds_dwordx4 v[158:159], off
	v_lshl_add_u64 v[158:159], v[240:241], 0, s[14:15]
	s_mov_b32 m0, s49
	s_nop 0
	global_load_lds_dwordx4 v[158:159], off
	v_lshl_add_u64 v[158:159], v[242:243], 0, s[14:15]
	s_mov_b32 m0, s50
	s_nop 0
	global_load_lds_dwordx4 v[158:159], off
	s_waitcnt vmcnt(8)
	s_waitcnt lgkmcnt(0)
	s_barrier
	s_setprio 1
	s_waitcnt lgkmcnt(0)
	v_mfma_f32_16x16x32_bf16 v[62:65], v[168:171], v[208:211], v[62:65]
	v_mfma_f32_16x16x32_bf16 v[58:61], v[184:187], v[208:211], v[58:61]
	v_mfma_f32_16x16x32_bf16 v[42:45], v[184:187], v[216:219], v[42:45]
	v_mfma_f32_16x16x32_bf16 v[46:49], v[168:171], v[216:219], v[46:49]
	v_mfma_f32_16x16x32_bf16 v[30:33], v[168:171], v[224:227], v[30:33]
	v_mfma_f32_16x16x32_bf16 v[26:29], v[184:187], v[224:227], v[26:29]
	v_mfma_f32_16x16x32_bf16 v[10:13], v[184:187], v[232:235], v[10:13]
	v_mfma_f32_16x16x32_bf16 v[14:17], v[168:171], v[232:235], v[14:17]
	v_mfma_f32_16x16x32_bf16 v[62:65], v[176:179], v[212:215], v[62:65]
	v_mfma_f32_16x16x32_bf16 v[58:61], v[188:191], v[212:215], v[58:61]
	v_mfma_f32_16x16x32_bf16 v[42:45], v[188:191], v[220:223], v[42:45]
	v_mfma_f32_16x16x32_bf16 v[46:49], v[176:179], v[220:223], v[46:49]
	v_mfma_f32_16x16x32_bf16 v[30:33], v[176:179], v[228:231], v[30:33]
	v_mfma_f32_16x16x32_bf16 v[26:29], v[188:191], v[228:231], v[26:29]
	v_mfma_f32_16x16x32_bf16 v[10:13], v[188:191], v[236:239], v[10:13]
	v_mfma_f32_16x16x32_bf16 v[14:17], v[176:179], v[236:239], v[14:17]
	s_setprio 0
	s_setprio 1
	v_mfma_f32_16x16x32_bf16 v[54:57], v[192:195], v[208:211], v[54:57]
	v_mfma_f32_16x16x32_bf16 v[50:53], v[200:203], v[208:211], v[50:53]
	v_mfma_f32_16x16x32_bf16 v[34:37], v[200:203], v[216:219], v[34:37]
	v_mfma_f32_16x16x32_bf16 v[38:41], v[192:195], v[216:219], v[38:41]
	v_mfma_f32_16x16x32_bf16 v[22:25], v[192:195], v[224:227], v[22:25]
	v_mfma_f32_16x16x32_bf16 v[18:21], v[200:203], v[224:227], v[18:21]
	v_mfma_f32_16x16x32_bf16 v[2:5], v[200:203], v[232:235], v[2:5]
	v_mfma_f32_16x16x32_bf16 v[6:9], v[192:195], v[232:235], v[6:9]
	v_mfma_f32_16x16x32_bf16 v[54:57], v[196:199], v[212:215], v[54:57]
	v_mfma_f32_16x16x32_bf16 v[50:53], v[204:207], v[212:215], v[50:53]
	v_mfma_f32_16x16x32_bf16 v[34:37], v[204:207], v[220:223], v[34:37]
	v_mfma_f32_16x16x32_bf16 v[38:41], v[196:199], v[220:223], v[38:41]
	v_mfma_f32_16x16x32_bf16 v[22:25], v[196:199], v[228:231], v[22:25]
	v_mfma_f32_16x16x32_bf16 v[18:21], v[204:207], v[228:231], v[18:21]
	v_mfma_f32_16x16x32_bf16 v[2:5], v[204:207], v[236:239], v[2:5]
	v_mfma_f32_16x16x32_bf16 v[6:9], v[196:199], v[236:239], v[6:9]
	s_setprio 0
	s_barrier
	s_add_i32 s60, s60, 2
	s_add_u32 s26, s26, 0x100
	s_addc_u32 s27, s27, 0
	s_add_u32 s21, s21, 0x100
	s_addc_u32 s33, s33, 0
	s_cmp_gt_u32 s60, 13
.LBB0_197:
	ds_read_b128 v[168:171], v163
	ds_read_b128 v[176:179], v163 offset:1024
	ds_read_b128 v[184:187], v163 offset:2048
	ds_read_b128 v[188:191], v163 offset:3072
	ds_read_b128 v[192:195], v165
	ds_read_b128 v[196:199], v165 offset:1024
	ds_read_b128 v[200:203], v165 offset:2048
	ds_read_b128 v[204:207], v165 offset:3072
	s_add_u32 s28, s26, 0xfffc0080
	s_addc_u32 s29, s27, -1
	s_cmp_eq_u32 s60, 12
	s_cselect_b32 s31, s1, s29
	s_cselect_b32 s30, s2, s28
	s_cselect_b32 s29, s5, s33
	s_cselect_b32 s28, s19, s21
	v_lshl_add_u64 v[158:159], s[26:27], 0, v[146:147]
	s_add_i32 m0, s40, 0xc000
	ds_read_b128 v[208:211], v167
	ds_read_b128 v[212:215], v167 offset:1024
	ds_read_b128 v[216:219], v167 offset:2048
	ds_read_b128 v[220:223], v167 offset:3072
	ds_read_b128 v[224:227], v167 offset:4096
	ds_read_b128 v[228:231], v167 offset:5120
	ds_read_b128 v[232:235], v167 offset:6144
	ds_read_b128 v[236:239], v167 offset:7168
	global_load_lds_dwordx4 v[158:159], off
	v_lshl_add_u64 v[158:159], s[26:27], 0, v[148:149]
	s_add_i32 m0, s40, 0xe000
	s_nop 0
	global_load_lds_dwordx4 v[158:159], off
	s_waitcnt vmcnt(8)
	s_waitcnt lgkmcnt(0)
	s_barrier
; #define PG8_STAGE(bufoff, gbase, voff) do { _Pragma("unroll") for (int _i = 0; _i < 2; ++_i) \
;         __builtin_amdgcn_global_load_lds((const unsigned*)((const char*)(gbase) + (voff)[_i]), (PG8_LAS unsigned*)(lds + (bufoff) + ldsw + _i * 8192), 16, 0, 0); } while (0)
; #define PG8_LDA(dst, b, h) do { _Pragma("unroll") for (int m = 0; m < 4; ++m) _Pragma("unroll") for (int k = 0; k < 2; ++k) dst[m][k] = *(const PG8_LAS bf16x8*)(lds + PG8_SA(b, h) + aoff + m * 2048 + k * 1024); } while (0)
; #define PG8_LDB(dst, b, h) do { _Pragma("unroll") for (int n = 0; n < 2; ++n) _Pragma("unroll") for (int k = 0; k < 2; ++k) dst[n][k] = *(const PG8_LAS bf16x8*)(lds + PG8_SB(b, h) + boff + n * 2048 + k * 1024); } while (0)
; #define PG8_MMA(ai, bj, At, Bt) do { __builtin_amdgcn_s_setprio(1); _Pragma("unroll") for (int m = 0; m < 4; ++m) _Pragma("unroll") for (int n = 0; n < 2; ++n) _Pragma("unroll") for (int k = 0; k < 2; ++k) \
;         acc[ai][bj][m][n] = __builtin_amdgcn_mfma_f32_16x16x32_bf16(Bt[n][k], At[m][k], acc[ai][bj][m][n], 0, 0, 0); __builtin_amdgcn_s_setprio(0); } while (0)
; #define PG8_WAIT_V(n) asm volatile("s_waitcnt vmcnt(" #n ")" ::: "memory")
; #define PG8_WAIT_L(n) asm volatile("s_waitcnt lgkmcnt(" #n ")" ::: "memory")
; #define PG8_BAR __builtin_amdgcn_s_barrier()
; #define PG8_SCHED __builtin_amdgcn_sched_barrier(0)
; template <class Epi, class Sched, bool ALIGN_EPI = false, bool SP2 = false>
; __device__ __forceinline__ void gemm_phase(PG8_LAS unsigned char* lds, const Gemm g, const Sched& S, const Epi& E) {
;     ...
;             PG8_LDB(B0, 0, 0); PG8_LDB(B1, 0, 1); PG8_SCHED; PG8_LDA(At, 0, 0); PG8_STAGE(PG8_SA(1, 1), a1 + hstepA, voffA);
;             PG8_WAIT_V(8); PG8_WAIT_L(0); PG8_BAR; PG8_MMA(0, 0, At, B0); PG8_MMA(0, 1, At, B1); PG8_BAR; PG8_SCHED;
;             PG8_LDA(At, 0, 1); PG8_STAGE(PG8_SB(0, 0), b2, voffB); PG8_STAGE(PG8_SB(0, 1), b2 + hstepB, voffB); PG8_STAGE(PG8_SA(0, 0), a2, voffA);
;             PG8_WAIT_V(8); PG8_WAIT_L(0); PG8_BAR; PG8_MMA(1, 0, At, B0); PG8_MMA(1, 1, At, B1); PG8_BAR; PG8_SCHED;
	s_setprio 1
	s_waitcnt lgkmcnt(0)
	v_mfma_f32_16x16x32_bf16 v[126:129], v[168:171], v[208:211], v[126:129]
	v_mfma_f32_16x16x32_bf16 v[122:125], v[184:187], v[208:211], v[122:125]
	v_mfma_f32_16x16x32_bf16 v[106:109], v[184:187], v[216:219], v[106:109]
	v_mfma_f32_16x16x32_bf16 v[110:113], v[168:171], v[216:219], v[110:113]
	v_mfma_f32_16x16x32_bf16 v[94:97], v[168:171], v[224:227], v[94:97]
	v_mfma_f32_16x16x32_bf16 v[90:93], v[184:187], v[224:227], v[90:93]
	v_mfma_f32_16x16x32_bf16 v[74:77], v[184:187], v[232:235], v[74:77]
	v_mfma_f32_16x16x32_bf16 v[78:81], v[168:171], v[232:235], v[78:81]
	v_mfma_f32_16x16x32_bf16 v[126:129], v[176:179], v[212:215], v[126:129]
	v_mfma_f32_16x16x32_bf16 v[122:125], v[188:191], v[212:215], v[122:125]
	v_mfma_f32_16x16x32_bf16 v[106:109], v[188:191], v[220:223], v[106:109]
	v_mfma_f32_16x16x32_bf16 v[110:113], v[176:179], v[220:223], v[110:113]
	v_mfma_f32_16x16x32_bf16 v[94:97], v[176:179], v[228:231], v[94:97]
	v_mfma_f32_16x16x32_bf16 v[90:93], v[188:191], v[228:231], v[90:93]
	v_mfma_f32_16x16x32_bf16 v[74:77], v[188:191], v[236:239], v[74:77]
	v_mfma_f32_16x16x32_bf16 v[78:81], v[176:179], v[236:239], v[78:81]
	s_setprio 0
	s_setprio 1
	v_mfma_f32_16x16x32_bf16 v[118:121], v[192:195], v[208:211], v[118:121]
	v_mfma_f32_16x16x32_bf16 v[114:117], v[200:203], v[208:211], v[114:117]
	v_mfma_f32_16x16x32_bf16 v[98:101], v[200:203], v[216:219], v[98:101]
	v_mfma_f32_16x16x32_bf16 v[102:105], v[192:195], v[216:219], v[102:105]
	v_mfma_f32_16x16x32_bf16 v[86:89], v[192:195], v[224:227], v[86:89]
	v_mfma_f32_16x16x32_bf16 v[82:85], v[200:203], v[224:227], v[82:85]
	v_mfma_f32_16x16x32_bf16 v[66:69], v[200:203], v[232:235], v[66:69]
	v_mfma_f32_16x16x32_bf16 v[70:73], v[192:195], v[232:235], v[70:73]
	v_mfma_f32_16x16x32_bf16 v[118:121], v[196:199], v[212:215], v[118:121]
	v_mfma_f32_16x16x32_bf16 v[114:117], v[204:207], v[212:215], v[114:117]
	v_mfma_f32_16x16x32_bf16 v[98:101], v[204:207], v[220:223], v[98:101]
	v_mfma_f32_16x16x32_bf16 v[102:105], v[196:199], v[220:223], v[102:105]
	v_mfma_f32_16x16x32_bf16 v[86:89], v[196:199], v[228:231], v[86:89]
	v_mfma_f32_16x16x32_bf16 v[82:85], v[204:207], v[228:231], v[82:85]
	v_mfma_f32_16x16x32_bf16 v[66:69], v[204:207], v[236:239], v[66:69]
	v_mfma_f32_16x16x32_bf16 v[70:73], v[196:199], v[236:239], v[70:73]
	s_setprio 0
	s_barrier
	s_add_i32 s61, s53, s37
	v_lshl_add_u64 v[158:159], s[28:29], 0, v[134:135]
	s_mov_b32 m0, s61
	ds_read_b128 v[208:211], v167 offset:16384
	ds_read_b128 v[212:215], v167 offset:17408
	ds_read_b128 v[216:219], v167 offset:18432
	ds_read_b128 v[220:223], v167 offset:19456
	ds_read_b128 v[224:227], v167 offset:20480
	ds_read_b128 v[228:231], v167 offset:21504
	ds_read_b128 v[232:235], v167 offset:22528
	ds_read_b128 v[236:239], v167 offset:23552
	global_load_lds_dwordx4 v[158:159], off
	s_add_i32 m0, s61, 0x2000
	s_add_u32 s62, s28, 0x40000
	v_lshl_add_u64 v[180:181], s[28:29], 0, v[130:131]
	s_addc_u32 s63, s29, 0
	s_add_i32 s61, s54, s37
	global_load_lds_dwordx4 v[180:181], off
	v_lshl_add_u64 v[240:241], s[62:63], 0, v[134:135]
	s_mov_b32 m0, s61
	v_lshl_add_u64 v[242:243], s[30:31], 0, v[132:133]
	global_load_lds_dwordx4 v[240:241], off
	v_lshl_add_u64 v[240:241], s[62:63], 0, v[130:131]
	s_add_i32 m0, s61, 0x2000
	s_nop 0
	global_load_lds_dwordx4 v[240:241], off
	v_lshl_add_u64 v[240:241], s[30:31], 0, v[136:137]
	s_mov_b32 m0, s40
	s_nop 0
	global_load_lds_dwordx4 v[240:241], off
	s_mov_b32 m0, s41
	s_nop 0
	global_load_lds_dwordx4 v[242:243], off
	s_waitcnt vmcnt(8)
	s_waitcnt lgkmcnt(0)
	s_barrier
	s_setprio 1
	s_waitcnt lgkmcnt(0)
	v_mfma_f32_16x16x32_bf16 v[62:65], v[168:171], v[208:211], v[62:65]
	v_mfma_f32_16x16x32_bf16 v[58:61], v[184:187], v[208:211], v[58:61]
	v_mfma_f32_16x16x32_bf16 v[42:45], v[184:187], v[216:219], v[42:45]
	v_mfma_f32_16x16x32_bf16 v[46:49], v[168:171], v[216:219], v[46:49]
	v_mfma_f32_16x16x32_bf16 v[30:33], v[168:171], v[224:227], v[30:33]
	v_mfma_f32_16x16x32_bf16 v[26:29], v[184:187], v[224:227], v[26:29]
	v_mfma_f32_16x16x32_bf16 v[10:13], v[184:187], v[232:235], v[10:13]
	v_mfma_f32_16x16x32_bf16 v[14:17], v[168:171], v[232:235], v[14:17]
	v_mfma_f32_16x16x32_bf16 v[62:65], v[176:179], v[212:215], v[62:65]
	v_mfma_f32_16x16x32_bf16 v[58:61], v[188:191], v[212:215], v[58:61]
	v_mfma_f32_16x16x32_bf16 v[42:45], v[188:191], v[220:223], v[42:45]
	v_mfma_f32_16x16x32_bf16 v[46:49], v[176:179], v[220:223], v[46:49]
	v_mfma_f32_16x16x32_bf16 v[30:33], v[176:179], v[228:231], v[30:33]
	v_mfma_f32_16x16x32_bf16 v[26:29], v[188:191], v[228:231], v[26:29]
	v_mfma_f32_16x16x32_bf16 v[10:13], v[188:191], v[236:239], v[10:13]
	v_mfma_f32_16x16x32_bf16 v[14:17], v[176:179], v[236:239], v[14:17]
	s_setprio 0
	s_setprio 1
	v_mfma_f32_16x16x32_bf16 v[54:57], v[192:195], v[208:211], v[54:57]
	v_mfma_f32_16x16x32_bf16 v[50:53], v[200:203], v[208:211], v[50:53]
	v_mfma_f32_16x16x32_bf16 v[34:37], v[200:203], v[216:219], v[34:37]
	v_mfma_f32_16x16x32_bf16 v[38:41], v[192:195], v[216:219], v[38:41]
	v_mfma_f32_16x16x32_bf16 v[22:25], v[192:195], v[224:227], v[22:25]
	v_mfma_f32_16x16x32_bf16 v[18:21], v[200:203], v[224:227], v[18:21]
	v_mfma_f32_16x16x32_bf16 v[2:5], v[200:203], v[232:235], v[2:5]
	v_mfma_f32_16x16x32_bf16 v[6:9], v[192:195], v[232:235], v[6:9]
	v_mfma_f32_16x16x32_bf16 v[54:57], v[196:199], v[212:215], v[54:57]
	v_mfma_f32_16x16x32_bf16 v[50:53], v[204:207], v[212:215], v[50:53]
	v_mfma_f32_16x16x32_bf16 v[34:37], v[204:207], v[220:223], v[34:37]
	v_mfma_f32_16x16x32_bf16 v[38:41], v[196:199], v[220:223], v[38:41]
	v_mfma_f32_16x16x32_bf16 v[22:25], v[196:199], v[228:231], v[22:25]
	v_mfma_f32_16x16x32_bf16 v[18:21], v[204:207], v[228:231], v[18:21]
	v_mfma_f32_16x16x32_bf16 v[2:5], v[204:207], v[236:239], v[2:5]
	v_mfma_f32_16x16x32_bf16 v[6:9], v[196:199], v[236:239], v[6:9]
	s_setprio 0
	s_barrier
; #define PG8_STAGE(bufoff, gbase, voff) do { _Pragma("unroll") for (int _i = 0; _i < 2; ++_i) \
;         __builtin_amdgcn_global_load_lds((const unsigned*)((const char*)(gbase) + (voff)[_i]), (PG8_LAS unsigned*)(lds + (bufoff) + ldsw + _i * 8192), 16, 0, 0); } while (0)
; #define PG8_LDA(dst, b, h) do { _Pragma("unroll") for (int m = 0; m < 4; ++m) _Pragma("unroll") for (int k = 0; k < 2; ++k) dst[m][k] = *(const PG8_LAS bf16x8*)(lds + PG8_SA(b, h) + aoff + m * 2048 + k * 1024); } while (0)
; #define PG8_LDB(dst, b, h) do { _Pragma("unroll") for (int n = 0; n < 2; ++n) _Pragma("unroll") for (int k = 0; k < 2; ++k) dst[n][k] = *(const PG8_LAS bf16x8*)(lds + PG8_SB(b, h) + boff + n * 2048 + k * 1024); } while (0)
; #define PG8_MMA(ai, bj, At, Bt) do { __builtin_amdgcn_s_setprio(1); _Pragma("unroll") for (int m = 0; m < 4; ++m) _Pragma("unroll") for (int n = 0; n < 2; ++n) _Pragma("unroll") for (int k = 0; k < 2; ++k) \
;         acc[ai][bj][m][n] = __builtin_amdgcn_mfma_f32_16x16x32_bf16(Bt[n][k], At[m][k], acc[ai][bj][m][n], 0, 0, 0); __builtin_amdgcn_s_setprio(0); } while (0)
; #define PG8_WAIT_V(n) asm volatile("s_waitcnt vmcnt(" #n ")" ::: "memory")
; #define PG8_WAIT_L(n) asm volatile("s_waitcnt lgkmcnt(" #n ")" ::: "memory")
; #define PG8_BAR __builtin_amdgcn_s_barrier()
; #define PG8_SCHED __builtin_amdgcn_sched_barrier(0)
; template <class Epi, class Sched, bool ALIGN_EPI = false, bool SP2 = false>
; __device__ __forceinline__ void gemm_phase(PG8_LAS unsigned char* lds, const Gemm g, const Sched& S, const Epi& E) {
;     ...
;             PG8_LDB(B0, 1, 0); PG8_LDB(B1, 1, 1); PG8_SCHED; PG8_LDA(At, 1, 0); PG8_STAGE(PG8_SA(0, 1), a2 + hstepA, voffA);
;             PG8_WAIT_V(8); PG8_WAIT_L(0); PG8_BAR; PG8_MMA(0, 0, At, B0); PG8_MMA(0, 1, At, B1); PG8_BAR; PG8_SCHED;
	s_add_i32 s61, 0, 0x18000
	v_add_u32_e32 v138, s61, v141
	s_add_i32 s62, 0, 0x1c000
	ds_read_b128 v[168:171], v138
	ds_read_b128 v[176:179], v138 offset:1024
	ds_read_b128 v[184:187], v138 offset:2048
	ds_read_b128 v[188:191], v138 offset:3072
	v_add_u32_e32 v138, s62, v141
	ds_read_b128 v[192:195], v138
	ds_read_b128 v[196:199], v138 offset:1024
	ds_read_b128 v[200:203], v138 offset:2048
	ds_read_b128 v[204:207], v138 offset:3072
	s_add_u32 s30, s30, 0x40000
	s_addc_u32 s31, s31, 0
	s_mov_b32 m0, s42
	v_lshl_add_u64 v[244:245], s[30:31], 0, v[136:137]
	ds_read_b128 v[208:211], v167 offset:32768
	ds_read_b128 v[212:215], v167 offset:33792
	ds_read_b128 v[216:219], v167 offset:34816
	ds_read_b128 v[220:223], v167 offset:35840
	ds_read_b128 v[224:227], v167 offset:36864
	ds_read_b128 v[228:231], v167 offset:37888
	ds_read_b128 v[232:235], v167 offset:38912
	ds_read_b128 v[236:239], v167 offset:39936
	global_load_lds_dwordx4 v[244:245], off
	v_lshl_add_u64 v[244:245], s[30:31], 0, v[132:133]
	s_mov_b32 m0, s43
	s_nop 0
	global_load_lds_dwordx4 v[244:245], off
	s_waitcnt vmcnt(8)
	s_waitcnt lgkmcnt(0)
	s_barrier
	s_setprio 1
	s_waitcnt lgkmcnt(0)
	v_mfma_f32_16x16x32_bf16 v[126:129], v[168:171], v[208:211], v[126:129]
	v_mfma_f32_16x16x32_bf16 v[122:125], v[184:187], v[208:211], v[122:125]
	v_mfma_f32_16x16x32_bf16 v[106:109], v[184:187], v[216:219], v[106:109]
	v_mfma_f32_16x16x32_bf16 v[110:113], v[168:171], v[216:219], v[110:113]
	v_mfma_f32_16x16x32_bf16 v[94:97], v[168:171], v[224:227], v[94:97]
	v_mfma_f32_16x16x32_bf16 v[90:93], v[184:187], v[224:227], v[90:93]
	v_mfma_f32_16x16x32_bf16 v[74:77], v[184:187], v[232:235], v[74:77]
	v_mfma_f32_16x16x32_bf16 v[78:81], v[168:171], v[232:235], v[78:81]
	v_mfma_f32_16x16x32_bf16 v[126:129], v[176:179], v[212:215], v[126:129]
	v_mfma_f32_16x16x32_bf16 v[122:125], v[188:191], v[212:215], v[122:125]
	v_mfma_f32_16x16x32_bf16 v[106:109], v[188:191], v[220:223], v[106:109]
	v_mfma_f32_16x16x32_bf16 v[110:113], v[176:179], v[220:223], v[110:113]
	v_mfma_f32_16x16x32_bf16 v[94:97], v[176:179], v[228:231], v[94:97]
	v_mfma_f32_16x16x32_bf16 v[90:93], v[188:191], v[228:231], v[90:93]
	v_mfma_f32_16x16x32_bf16 v[74:77], v[188:191], v[236:239], v[74:77]
	v_mfma_f32_16x16x32_bf16 v[78:81], v[176:179], v[236:239], v[78:81]
	s_setprio 0
	s_setprio 1
	v_mfma_f32_16x16x32_bf16 v[118:121], v[192:195], v[208:211], v[118:121]
	v_mfma_f32_16x16x32_bf16 v[114:117], v[200:203], v[208:211], v[114:117]
	v_mfma_f32_16x16x32_bf16 v[98:101], v[200:203], v[216:219], v[98:101]
	v_mfma_f32_16x16x32_bf16 v[102:105], v[192:195], v[216:219], v[102:105]
	v_mfma_f32_16x16x32_bf16 v[86:89], v[192:195], v[224:227], v[86:89]
	v_mfma_f32_16x16x32_bf16 v[82:85], v[200:203], v[224:227], v[82:85]
	v_mfma_f32_16x16x32_bf16 v[66:69], v[200:203], v[232:235], v[66:69]
	v_mfma_f32_16x16x32_bf16 v[70:73], v[192:195], v[232:235], v[70:73]
	v_mfma_f32_16x16x32_bf16 v[118:121], v[196:199], v[212:215], v[118:121]
	v_mfma_f32_16x16x32_bf16 v[114:117], v[204:207], v[212:215], v[114:117]
	v_mfma_f32_16x16x32_bf16 v[98:101], v[204:207], v[220:223], v[98:101]
	v_mfma_f32_16x16x32_bf16 v[102:105], v[196:199], v[220:223], v[102:105]
	v_mfma_f32_16x16x32_bf16 v[86:89], v[196:199], v[228:231], v[86:89]
	v_mfma_f32_16x16x32_bf16 v[82:85], v[204:207], v[228:231], v[82:85]
	v_mfma_f32_16x16x32_bf16 v[66:69], v[204:207], v[236:239], v[66:69]
	v_mfma_f32_16x16x32_bf16 v[70:73], v[196:199], v[236:239], v[70:73]
	s_setprio 0
	s_barrier
; #define PG8_STAGE(bufoff, gbase, voff) do { _Pragma("unroll") for (int _i = 0; _i < 2; ++_i) \
;         __builtin_amdgcn_global_load_lds((const unsigned*)((const char*)(gbase) + (voff)[_i]), (PG8_LAS unsigned*)(lds + (bufoff) + ldsw + _i * 8192), 16, 0, 0); } while (0)
; #define PG8_LDA(dst, b, h) do { _Pragma("unroll") for (int m = 0; m < 4; ++m) _Pragma("unroll") for (int k = 0; k < 2; ++k) dst[m][k] = *(const PG8_LAS bf16x8*)(lds + PG8_SA(b, h) + aoff + m * 2048 + k * 1024); } while (0)
; #define PG8_MMA(ai, bj, At, Bt) do { __builtin_amdgcn_s_setprio(1); _Pragma("unroll") for (int m = 0; m < 4; ++m) _Pragma("unroll") for (int n = 0; n < 2; ++n) _Pragma("unroll") for (int k = 0; k < 2; ++k) \
;         acc[ai][bj][m][n] = __builtin_amdgcn_mfma_f32_16x16x32_bf16(Bt[n][k], At[m][k], acc[ai][bj][m][n], 0, 0, 0); __builtin_amdgcn_s_setprio(0); } while (0)
; #define PG8_WAIT_V(n) asm volatile("s_waitcnt vmcnt(" #n ")" ::: "memory")
; #define PG8_WAIT_L(n) asm volatile("s_waitcnt lgkmcnt(" #n ")" ::: "memory")
; #define PG8_BAR __builtin_amdgcn_s_barrier()
; #define PG8_SCHED __builtin_amdgcn_sched_barrier(0)
; template <class Epi, class Sched, bool ALIGN_EPI = false, bool SP2 = false>
; __device__ __forceinline__ void gemm_phase(PG8_LAS unsigned char* lds, const Gemm g, const Sched& S, const Epi& E) {
;     ...
;         for (int t = 0; t < nt; t += 2) {
;     ...
;             PG8_LDA(At, 1, 1); PG8_STAGE(PG8_SB(1, 0), b3, voffB); PG8_STAGE(PG8_SB(1, 1), b3 + hstepB, voffB); PG8_STAGE(PG8_SA(1, 0), a3, voffA);
;             PG8_WAIT_V(8); PG8_WAIT_L(0); PG8_BAR; PG8_MMA(1, 0, At, B0); PG8_MMA(1, 1, At, B1); PG8_BAR; PG8_SCHED;
;     ...
;         if constexpr (ALIGN_EPI) { if (wr == 0) PG8_BAR; }
	s_add_i32 s30, s61, s37
	v_lshl_add_u64 v[158:159], v[158:159], 0, s[14:15]
	s_mov_b32 m0, s30
	ds_read_b128 v[208:211], v167 offset:49152
	ds_read_b128 v[212:215], v167 offset:50176
	ds_read_b128 v[216:219], v167 offset:51200
	ds_read_b128 v[220:223], v167 offset:52224
	ds_read_b128 v[224:227], v167 offset:53248
	ds_read_b128 v[228:231], v167 offset:54272
	ds_read_b128 v[232:235], v167 offset:55296
	ds_read_b128 v[236:239], v167 offset:56320
	global_load_lds_dwordx4 v[158:159], off
	s_add_i32 m0, s30, 0x2000
	s_add_u32 s28, s28, 0x40080
	v_lshl_add_u64 v[158:159], v[180:181], 0, s[14:15]
	s_addc_u32 s29, s29, 0
	s_add_i32 s30, s62, s37
	global_load_lds_dwordx4 v[158:159], off
	v_lshl_add_u64 v[158:159], s[28:29], 0, v[134:135]
	s_mov_b32 m0, s30
	s_nop 0
	global_load_lds_dwordx4 v[158:159], off
	v_lshl_add_u64 v[158:159], s[28:29], 0, v[130:131]
	s_add_i32 m0, s30, 0x2000
	s_nop 0
	global_load_lds_dwordx4 v[158:159], off
	v_lshl_add_u64 v[158:159], v[240:241], 0, s[14:15]
	s_mov_b32 m0, s49
	s_nop 0
	global_load_lds_dwordx4 v[158:159], off
	v_lshl_add_u64 v[158:159], v[242:243], 0, s[14:15]
	s_mov_b32 m0, s50
	s_nop 0
	global_load_lds_dwordx4 v[158:159], off
	s_waitcnt vmcnt(8)
	s_waitcnt lgkmcnt(0)
	s_barrier
	s_setprio 1
	s_waitcnt lgkmcnt(0)
	v_mfma_f32_16x16x32_bf16 v[62:65], v[168:171], v[208:211], v[62:65]
	v_mfma_f32_16x16x32_bf16 v[58:61], v[184:187], v[208:211], v[58:61]
	v_mfma_f32_16x16x32_bf16 v[42:45], v[184:187], v[216:219], v[42:45]
	v_mfma_f32_16x16x32_bf16 v[46:49], v[168:171], v[216:219], v[46:49]
	v_mfma_f32_16x16x32_bf16 v[30:33], v[168:171], v[224:227], v[30:33]
	v_mfma_f32_16x16x32_bf16 v[26:29], v[184:187], v[224:227], v[26:29]
	v_mfma_f32_16x16x32_bf16 v[10:13], v[184:187], v[232:235], v[10:13]
	v_mfma_f32_16x16x32_bf16 v[14:17], v[168:171], v[232:235], v[14:17]
	v_mfma_f32_16x16x32_bf16 v[62:65], v[176:179], v[212:215], v[62:65]
	v_mfma_f32_16x16x32_bf16 v[58:61], v[188:191], v[212:215], v[58:61]
	v_mfma_f32_16x16x32_bf16 v[42:45], v[188:191], v[220:223], v[42:45]
	v_mfma_f32_16x16x32_bf16 v[46:49], v[176:179], v[220:223], v[46:49]
	v_mfma_f32_16x16x32_bf16 v[30:33], v[176:179], v[228:231], v[30:33]
	v_mfma_f32_16x16x32_bf16 v[26:29], v[188:191], v[228:231], v[26:29]
	v_mfma_f32_16x16x32_bf16 v[10:13], v[188:191], v[236:239], v[10:13]
	v_mfma_f32_16x16x32_bf16 v[14:17], v[176:179], v[236:239], v[14:17]
	s_setprio 0
	s_setprio 1
	v_mfma_f32_16x16x32_bf16 v[54:57], v[192:195], v[208:211], v[54:57]
	v_mfma_f32_16x16x32_bf16 v[50:53], v[200:203], v[208:211], v[50:53]
	v_mfma_f32_16x16x32_bf16 v[34:37], v[200:203], v[216:219], v[34:37]
	v_mfma_f32_16x16x32_bf16 v[38:41], v[192:195], v[216:219], v[38:41]
	v_mfma_f32_16x16x32_bf16 v[22:25], v[192:195], v[224:227], v[22:25]
	v_mfma_f32_16x16x32_bf16 v[18:21], v[200:203], v[224:227], v[18:21]
	v_mfma_f32_16x16x32_bf16 v[2:5], v[200:203], v[232:235], v[2:5]
	v_mfma_f32_16x16x32_bf16 v[6:9], v[192:195], v[232:235], v[6:9]
	v_mfma_f32_16x16x32_bf16 v[54:57], v[196:199], v[212:215], v[54:57]
	v_mfma_f32_16x16x32_bf16 v[50:53], v[204:207], v[212:215], v[50:53]
	v_mfma_f32_16x16x32_bf16 v[34:37], v[204:207], v[220:223], v[34:37]
	v_mfma_f32_16x16x32_bf16 v[38:41], v[196:199], v[220:223], v[38:41]
	v_mfma_f32_16x16x32_bf16 v[22:25], v[196:199], v[228:231], v[22:25]
	v_mfma_f32_16x16x32_bf16 v[18:21], v[204:207], v[228:231], v[18:21]
	v_mfma_f32_16x16x32_bf16 v[2:5], v[204:207], v[236:239], v[2:5]
	v_mfma_f32_16x16x32_bf16 v[6:9], v[196:199], v[236:239], v[6:9]
	s_setprio 0
	s_barrier
	s_add_i32 s60, s60, 2
	s_add_u32 s26, s26, 0x100
	s_addc_u32 s27, s27, 0
	s_add_u32 s21, s21, 0x100
	s_addc_u32 s33, s33, 0
	s_cmp_gt_u32 s60, 13
	s_cbranch_scc0 .LBB0_197
	s_and_b64 vcc, exec, s[16:17]
	s_cbranch_vccz .LBB0_200
	s_barrier

; #define PG8_STAGE(bufoff, gbase, voff) do { _Pragma("unroll") for (int _i = 0; _i < 2; ++_i) \
;         __builtin_amdgcn_global_load_lds((const unsigned*)((const char*)(gbase) + (voff)[_i]), (PG8_LAS unsigned*)(lds + (bufoff) + ldsw + _i * 8192), 16, 0, 0); } while (0)
; #define PG8_LDA(dst, b, h) do { _Pragma("unroll") for (int m = 0; m < 4; ++m) _Pragma("unroll") for (int k = 0; k < 2; ++k) dst[m][k] = *(const PG8_LAS bf16x8*)(lds + PG8_SA(b, h) + aoff + m * 2048 + k * 1024); } while (0)
; #define PG8_LDB(dst, b, h) do { _Pragma("unroll") for (int n = 0; n < 2; ++n) _Pragma("unroll") for (int k = 0; k < 2; ++k) dst[n][k] = *(const PG8_LAS bf16x8*)(lds + PG8_SB(b, h) + boff + n * 2048 + k * 1024); } while (0)
; #define PG8_MMA(ai, bj, At, Bt) do { __builtin_amdgcn_s_setprio(1); _Pragma("unroll") for (int m = 0; m < 4; ++m) _Pragma("unroll") for (int n = 0; n < 2; ++n) _Pragma("unroll") for (int k = 0; k < 2; ++k) \
;         acc[ai][bj][m][n] = __builtin_amdgcn_mfma_f32_16x16x32_bf16(Bt[n][k], At[m][k], acc[ai][bj][m][n], 0, 0, 0); __builtin_amdgcn_s_setprio(0); } while (0)
; #define PG8_WAIT_V(n) asm volatile("s_waitcnt vmcnt(" #n ")" ::: "memory")
; #define PG8_WAIT_L(n) asm volatile("s_waitcnt lgkmcnt(" #n ")" ::: "memory")
; #define PG8_BAR __builtin_amdgcn_s_barrier()
; #define PG8_SCHED __builtin_amdgcn_sched_barrier(0)
; template <class Epi, class Sched, bool ALIGN_EPI = false, bool SP2 = false>
; __device__ __forceinline__ void gemm_phase(PG8_LAS unsigned char* lds, const Gemm g, const Sched& S, const Epi& E) {
;     ...
;             PG8_LDB(B0, 0, 0); PG8_LDB(B1, 0, 1); PG8_SCHED; PG8_LDA(At, 0, 0); PG8_STAGE(PG8_SA(1, 1), a1 + hstepA, voffA);
;             PG8_WAIT_V(8); PG8_WAIT_L(0); PG8_BAR; PG8_MMA(0, 0, At, B0); PG8_MMA(0, 1, At, B1); PG8_BAR; PG8_SCHED;
;             PG8_LDA(At, 0, 1); PG8_STAGE(PG8_SB(0, 0), b2, voffB); PG8_STAGE(PG8_SB(0, 1), b2 + hstepB, voffB); PG8_STAGE(PG8_SA(0, 0), a2, voffA);
;             PG8_WAIT_V(8); PG8_WAIT_L(0); PG8_BAR; PG8_MMA(1, 0, At, B0); PG8_MMA(1, 1, At, B1); PG8_BAR; PG8_SCHED;
.LBB0_280:
	ds_read_b128 v[84:87], v81
	ds_read_b128 v[88:91], v81 offset:1024
	ds_read_b128 v[92:95], v81 offset:2048
	ds_read_b128 v[96:99], v81 offset:3072
	s_add_u32 s38, s36, 0x100
	s_addc_u32 s39, s37, 0
	s_cmp_eq_u32 s68, 4
	s_cselect_b32 s43, s31, s39
	s_cselect_b32 s42, s30, s38
	s_cselect_b32 s41, s9, s67
	s_cselect_b32 s40, s29, s66
	v_lshl_add_u64 v[132:133], s[36:37], 0, v[76:77]
	s_add_i32 m0, s45, 0xc000
	ds_read_b128 v[100:103], v82
	ds_read_b128 v[104:107], v82 offset:1024
	ds_read_b128 v[108:111], v82 offset:2048
	ds_read_b128 v[112:115], v82 offset:3072
	ds_read_b128 v[116:119], v82 offset:4096
	ds_read_b128 v[120:123], v82 offset:5120
	ds_read_b128 v[124:127], v82 offset:6144
	ds_read_b128 v[128:131], v82 offset:7168
	global_load_lds_dwordx4 v[132:133], off
	v_lshl_add_u64 v[132:133], s[36:37], 0, v[78:79]
	s_add_i32 m0, s45, 0xe000
	s_nop 0
	global_load_lds_dwordx4 v[132:133], off
	s_waitcnt vmcnt(8)
	s_waitcnt lgkmcnt(0)
	s_barrier
	s_setprio 1
	s_waitcnt lgkmcnt(0)
	v_mfma_f32_16x16x32_bf16 v[62:65], v[84:87], v[100:103], v[62:65]
	v_mfma_f32_16x16x32_bf16 v[58:61], v[92:95], v[100:103], v[58:61]
	v_mfma_f32_16x16x32_bf16 v[50:53], v[92:95], v[108:111], v[50:53]
	v_mfma_f32_16x16x32_bf16 v[54:57], v[84:87], v[108:111], v[54:57]
	v_mfma_f32_16x16x32_bf16 v[46:49], v[84:87], v[116:119], v[46:49]
	v_mfma_f32_16x16x32_bf16 v[42:45], v[92:95], v[116:119], v[42:45]
	v_mfma_f32_16x16x32_bf16 v[34:37], v[92:95], v[124:127], v[34:37]
	v_mfma_f32_16x16x32_bf16 v[38:41], v[84:87], v[124:127], v[38:41]
	v_mfma_f32_16x16x32_bf16 v[62:65], v[88:91], v[104:107], v[62:65]
	v_mfma_f32_16x16x32_bf16 v[58:61], v[96:99], v[104:107], v[58:61]
	v_mfma_f32_16x16x32_bf16 v[50:53], v[96:99], v[112:115], v[50:53]
	v_mfma_f32_16x16x32_bf16 v[54:57], v[88:91], v[112:115], v[54:57]
	v_mfma_f32_16x16x32_bf16 v[46:49], v[88:91], v[120:123], v[46:49]
	v_mfma_f32_16x16x32_bf16 v[42:45], v[96:99], v[120:123], v[42:45]
	v_mfma_f32_16x16x32_bf16 v[34:37], v[96:99], v[128:131], v[34:37]
	v_mfma_f32_16x16x32_bf16 v[38:41], v[88:91], v[128:131], v[38:41]
	s_setprio 0
	s_setprio 1
	s_setprio 0
	s_barrier
	s_add_i32 s36, s64, s1
	v_lshl_add_u64 v[132:133], s[40:41], 0, v[70:71]
	s_mov_b32 m0, s36
	ds_read_b128 v[100:103], v82 offset:16384
	ds_read_b128 v[104:107], v82 offset:17408
	ds_read_b128 v[108:111], v82 offset:18432
	ds_read_b128 v[112:115], v82 offset:19456
	ds_read_b128 v[116:119], v82 offset:20480
	ds_read_b128 v[120:123], v82 offset:21504
	ds_read_b128 v[124:127], v82 offset:22528
	ds_read_b128 v[128:131], v82 offset:23552
	global_load_lds_dwordx4 v[132:133], off
	s_add_i32 m0, s36, 0x2000
	s_add_u32 s36, s40, 0x20000
	v_lshl_add_u64 v[134:135], s[40:41], 0, v[66:67]
	s_addc_u32 s37, s41, 0
	global_load_lds_dwordx4 v[134:135], off
	v_lshl_add_u64 v[136:137], s[36:37], 0, v[70:71]
	s_mov_b32 m0, s46
	v_lshl_add_u64 v[138:139], s[42:43], 0, v[68:69]
	global_load_lds_dwordx4 v[136:137], off
	v_lshl_add_u64 v[136:137], s[36:37], 0, v[66:67]
	s_mov_b32 m0, s47
	s_nop 0
	global_load_lds_dwordx4 v[136:137], off
	v_lshl_add_u64 v[136:137], s[42:43], 0, v[72:73]
	s_mov_b32 m0, s45
	s_nop 0
	global_load_lds_dwordx4 v[136:137], off
	s_mov_b32 m0, s48
	s_nop 0
	global_load_lds_dwordx4 v[138:139], off
	s_waitcnt vmcnt(8)
	s_waitcnt lgkmcnt(0)
	s_barrier
	s_setprio 1
	s_waitcnt lgkmcnt(0)
	v_mfma_f32_16x16x32_bf16 v[30:33], v[84:87], v[100:103], v[30:33]
	v_mfma_f32_16x16x32_bf16 v[26:29], v[92:95], v[100:103], v[26:29]
	v_mfma_f32_16x16x32_bf16 v[18:21], v[92:95], v[108:111], v[18:21]
	v_mfma_f32_16x16x32_bf16 v[22:25], v[84:87], v[108:111], v[22:25]
	v_mfma_f32_16x16x32_bf16 v[14:17], v[84:87], v[116:119], v[14:17]
	v_mfma_f32_16x16x32_bf16 v[10:13], v[92:95], v[116:119], v[10:13]
	v_mfma_f32_16x16x32_bf16 v[2:5], v[92:95], v[124:127], v[2:5]
	v_mfma_f32_16x16x32_bf16 v[6:9], v[84:87], v[124:127], v[6:9]
	v_mfma_f32_16x16x32_bf16 v[30:33], v[88:91], v[104:107], v[30:33]
	v_mfma_f32_16x16x32_bf16 v[26:29], v[96:99], v[104:107], v[26:29]
	v_mfma_f32_16x16x32_bf16 v[18:21], v[96:99], v[112:115], v[18:21]
	v_mfma_f32_16x16x32_bf16 v[22:25], v[88:91], v[112:115], v[22:25]
	v_mfma_f32_16x16x32_bf16 v[14:17], v[88:91], v[120:123], v[14:17]
	v_mfma_f32_16x16x32_bf16 v[10:13], v[96:99], v[120:123], v[10:13]
	v_mfma_f32_16x16x32_bf16 v[2:5], v[96:99], v[128:131], v[2:5]
	v_mfma_f32_16x16x32_bf16 v[6:9], v[88:91], v[128:131], v[6:9]
	s_setprio 0
	s_setprio 1
	s_setprio 0
	s_barrier
; #define PG8_STAGE(bufoff, gbase, voff) do { _Pragma("unroll") for (int _i = 0; _i < 2; ++_i) \
;         __builtin_amdgcn_global_load_lds((const unsigned*)((const char*)(gbase) + (voff)[_i]), (PG8_LAS unsigned*)(lds + (bufoff) + ldsw + _i * 8192), 16, 0, 0); } while (0)
; #define PG8_LDA(dst, b, h) do { _Pragma("unroll") for (int m = 0; m < 4; ++m) _Pragma("unroll") for (int k = 0; k < 2; ++k) dst[m][k] = *(const PG8_LAS bf16x8*)(lds + PG8_SA(b, h) + aoff + m * 2048 + k * 1024); } while (0)
; #define PG8_LDB(dst, b, h) do { _Pragma("unroll") for (int n = 0; n < 2; ++n) _Pragma("unroll") for (int k = 0; k < 2; ++k) dst[n][k] = *(const PG8_LAS bf16x8*)(lds + PG8_SB(b, h) + boff + n * 2048 + k * 1024); } while (0)
; #define PG8_MMA(ai, bj, At, Bt) do { __builtin_amdgcn_s_setprio(1); _Pragma("unroll") for (int m = 0; m < 4; ++m) _Pragma("unroll") for (int n = 0; n < 2; ++n) _Pragma("unroll") for (int k = 0; k < 2; ++k) \
;         acc[ai][bj][m][n] = __builtin_amdgcn_mfma_f32_16x16x32_bf16(Bt[n][k], At[m][k], acc[ai][bj][m][n], 0, 0, 0); __builtin_amdgcn_s_setprio(0); } while (0)
; #define PG8_WAIT_V(n) asm volatile("s_waitcnt vmcnt(" #n ")" ::: "memory")
; #define PG8_WAIT_L(n) asm volatile("s_waitcnt lgkmcnt(" #n ")" ::: "memory")
; #define PG8_BAR __builtin_amdgcn_s_barrier()
; #define PG8_SCHED __builtin_amdgcn_sched_barrier(0)
; template <class Epi, class Sched, bool ALIGN_EPI = false, bool SP2 = false>
; __device__ __forceinline__ void gemm_phase(PG8_LAS unsigned char* lds, const Gemm g, const Sched& S, const Epi& E) {
;     ...
;         for (int t = 0; t < nt; t += 2) {
;     ...
;             PG8_LDB(B0, 1, 0); PG8_LDB(B1, 1, 1); PG8_SCHED; PG8_LDA(At, 1, 0); PG8_STAGE(PG8_SA(0, 1), a2 + hstepA, voffA);
;             PG8_WAIT_V(8); PG8_WAIT_L(0); PG8_BAR; PG8_MMA(0, 0, At, B0); PG8_MMA(0, 1, At, B1); PG8_BAR; PG8_SCHED;
;             PG8_LDA(At, 1, 1); PG8_STAGE(PG8_SB(1, 0), b3, voffB); PG8_STAGE(PG8_SB(1, 1), b3 + hstepB, voffB); PG8_STAGE(PG8_SA(1, 0), a3, voffA);
;             PG8_WAIT_V(8); PG8_WAIT_L(0); PG8_BAR; PG8_MMA(1, 0, At, B0); PG8_MMA(1, 1, At, B1); PG8_BAR; PG8_SCHED;
	s_add_i32 s69, 0, 0x18000
	v_add_u32_e32 v83, s69, v80
	ds_read_b128 v[84:87], v83
	ds_read_b128 v[88:91], v83 offset:1024
	ds_read_b128 v[92:95], v83 offset:2048
	ds_read_b128 v[96:99], v83 offset:3072
	s_add_u32 s36, s42, 0x28000
	s_addc_u32 s37, s43, 0
	s_mov_b32 m0, s49
	v_lshl_add_u64 v[140:141], s[36:37], 0, v[72:73]
	ds_read_b128 v[100:103], v82 offset:32768
	ds_read_b128 v[104:107], v82 offset:33792
	ds_read_b128 v[108:111], v82 offset:34816
	ds_read_b128 v[112:115], v82 offset:35840
	ds_read_b128 v[116:119], v82 offset:36864
	ds_read_b128 v[120:123], v82 offset:37888
	ds_read_b128 v[124:127], v82 offset:38912
	ds_read_b128 v[128:131], v82 offset:39936
	global_load_lds_dwordx4 v[140:141], off
	v_lshl_add_u64 v[140:141], s[36:37], 0, v[68:69]
	s_mov_b32 m0, s50
	s_nop 0
	global_load_lds_dwordx4 v[140:141], off
	s_waitcnt vmcnt(8)
	s_waitcnt lgkmcnt(0)
	s_barrier
	s_setprio 1
	s_waitcnt lgkmcnt(0)
	v_mfma_f32_16x16x32_bf16 v[62:65], v[84:87], v[100:103], v[62:65]
	v_mfma_f32_16x16x32_bf16 v[58:61], v[92:95], v[100:103], v[58:61]
	v_mfma_f32_16x16x32_bf16 v[50:53], v[92:95], v[108:111], v[50:53]
	v_mfma_f32_16x16x32_bf16 v[54:57], v[84:87], v[108:111], v[54:57]
	v_mfma_f32_16x16x32_bf16 v[46:49], v[84:87], v[116:119], v[46:49]
	v_mfma_f32_16x16x32_bf16 v[42:45], v[92:95], v[116:119], v[42:45]
	v_mfma_f32_16x16x32_bf16 v[34:37], v[92:95], v[124:127], v[34:37]
	v_mfma_f32_16x16x32_bf16 v[38:41], v[84:87], v[124:127], v[38:41]
	v_mfma_f32_16x16x32_bf16 v[62:65], v[88:91], v[104:107], v[62:65]
	v_mfma_f32_16x16x32_bf16 v[58:61], v[96:99], v[104:107], v[58:61]
	v_mfma_f32_16x16x32_bf16 v[50:53], v[96:99], v[112:115], v[50:53]
	v_mfma_f32_16x16x32_bf16 v[54:57], v[88:91], v[112:115], v[54:57]
	v_mfma_f32_16x16x32_bf16 v[46:49], v[88:91], v[120:123], v[46:49]
	v_mfma_f32_16x16x32_bf16 v[42:45], v[96:99], v[120:123], v[42:45]
	v_mfma_f32_16x16x32_bf16 v[34:37], v[96:99], v[128:131], v[34:37]
	v_mfma_f32_16x16x32_bf16 v[38:41], v[88:91], v[128:131], v[38:41]
	s_setprio 0
	s_setprio 1
	s_setprio 0
	s_barrier
	s_add_i32 s36, s69, s1
	v_lshl_add_u64 v[132:133], v[132:133], 0, s[10:11]
	s_mov_b32 m0, s36
	ds_read_b128 v[100:103], v82 offset:49152
	ds_read_b128 v[104:107], v82 offset:50176
	ds_read_b128 v[108:111], v82 offset:51200
	ds_read_b128 v[112:115], v82 offset:52224
	ds_read_b128 v[116:119], v82 offset:53248
	ds_read_b128 v[120:123], v82 offset:54272
	ds_read_b128 v[124:127], v82 offset:55296
	ds_read_b128 v[128:131], v82 offset:56320
	global_load_lds_dwordx4 v[132:133], off
	s_add_i32 m0, s36, 0x2000
	s_add_u32 s36, s40, 0x20080
	v_lshl_add_u64 v[132:133], v[134:135], 0, s[10:11]
	s_addc_u32 s37, s41, 0
	global_load_lds_dwordx4 v[132:133], off
	v_lshl_add_u64 v[132:133], s[36:37], 0, v[70:71]
	s_mov_b32 m0, s62
	s_nop 0
	global_load_lds_dwordx4 v[132:133], off
	v_lshl_add_u64 v[132:133], s[36:37], 0, v[66:67]
	s_mov_b32 m0, s63
	s_nop 0
	global_load_lds_dwordx4 v[132:133], off
	v_lshl_add_u64 v[132:133], v[136:137], 0, s[10:11]
	s_mov_b32 m0, s60
	s_nop 0
	global_load_lds_dwordx4 v[132:133], off
	v_lshl_add_u64 v[132:133], v[138:139], 0, s[10:11]
	s_mov_b32 m0, s61
	s_nop 0
	global_load_lds_dwordx4 v[132:133], off
	s_waitcnt vmcnt(8)
	s_waitcnt lgkmcnt(0)
	s_barrier
	s_setprio 1
	s_waitcnt lgkmcnt(0)
	v_mfma_f32_16x16x32_bf16 v[30:33], v[84:87], v[100:103], v[30:33]
	v_mfma_f32_16x16x32_bf16 v[26:29], v[92:95], v[100:103], v[26:29]
	v_mfma_f32_16x16x32_bf16 v[18:21], v[92:95], v[108:111], v[18:21]
	v_mfma_f32_16x16x32_bf16 v[22:25], v[84:87], v[108:111], v[22:25]
	v_mfma_f32_16x16x32_bf16 v[14:17], v[84:87], v[116:119], v[14:17]
	v_mfma_f32_16x16x32_bf16 v[10:13], v[92:95], v[116:119], v[10:13]
	v_mfma_f32_16x16x32_bf16 v[2:5], v[92:95], v[124:127], v[2:5]
	v_mfma_f32_16x16x32_bf16 v[6:9], v[84:87], v[124:127], v[6:9]
	v_mfma_f32_16x16x32_bf16 v[30:33], v[88:91], v[104:107], v[30:33]
	v_mfma_f32_16x16x32_bf16 v[26:29], v[96:99], v[104:107], v[26:29]
	v_mfma_f32_16x16x32_bf16 v[18:21], v[96:99], v[112:115], v[18:21]
	v_mfma_f32_16x16x32_bf16 v[22:25], v[88:91], v[112:115], v[22:25]
	v_mfma_f32_16x16x32_bf16 v[14:17], v[88:91], v[120:123], v[14:17]
	v_mfma_f32_16x16x32_bf16 v[10:13], v[96:99], v[120:123], v[10:13]
	v_mfma_f32_16x16x32_bf16 v[2:5], v[96:99], v[128:131], v[2:5]
	v_mfma_f32_16x16x32_bf16 v[6:9], v[88:91], v[128:131], v[6:9]
	s_setprio 0
	s_setprio 1
	s_setprio 0
	s_barrier
	s_add_i32 s68, s68, 2
	s_add_u32 s66, s66, 0x100
	s_addc_u32 s67, s67, 0
	s_cmp_gt_u32 s68, 5
	s_mov_b64 s[36:37], s[38:39]
	s_cbranch_scc0 .LBB0_280
	s_and_b64 vcc, exec, s[12:13]
	s_cbranch_vccz .LBB0_283
	s_barrier

; #define PG8_STAGE(bufoff, gbase, voff) do { _Pragma("unroll") for (int _i = 0; _i < 2; ++_i) \
;         __builtin_amdgcn_global_load_lds((const unsigned*)((const char*)(gbase) + (voff)[_i]), (PG8_LAS unsigned*)(lds + (bufoff) + ldsw + _i * 8192), 16, 0, 0); } while (0)
; #define PG8_LDA(dst, b, h) do { _Pragma("unroll") for (int m = 0; m < 4; ++m) _Pragma("unroll") for (int k = 0; k < 2; ++k) dst[m][k] = *(const PG8_LAS bf16x8*)(lds + PG8_SA(b, h) + aoff + m * 2048 + k * 1024); } while (0)
; #define PG8_LDB(dst, b, h) do { _Pragma("unroll") for (int n = 0; n < 2; ++n) _Pragma("unroll") for (int k = 0; k < 2; ++k) dst[n][k] = *(const PG8_LAS bf16x8*)(lds + PG8_SB(b, h) + boff + n * 2048 + k * 1024); } while (0)
; #define PG8_WAIT_V(n) asm volatile("s_waitcnt vmcnt(" #n ")" ::: "memory")
; #define PG8_WAIT_L(n) asm volatile("s_waitcnt lgkmcnt(" #n ")" ::: "memory")
; #define PG8_BAR __builtin_amdgcn_s_barrier()
; template <class Epi, class Sched, bool ALIGN_EPI = false, bool SP2 = false>
; __device__ __forceinline__ void gemm_phase(PG8_LAS unsigned char* lds, const Gemm g, const Sched& S, const Epi& E) {
;     ...
;         const bool has_next = S.next(ui + 1, nxt);
;         const char* nA = has_next ? (const char*)g.A + (size_t)nxt.g * g.gsA * 2 + (size_t)nxt.pm * tstepA : cA; const char* nB = has_next ? (const char*)g.Bt + (size_t)nxt.g * g.gsB * 2 + (size_t)nxt.pn * tstepB : cB;
;         for (int t = 0; t < nt; t += 2) {
;             const bool last = (t == nt - 2);
;             const char* a1 = cA + (size_t)(t + 1) * kstep;
;             const char* a2 = last ? nA : cA + (size_t)(t + 2) * kstep; const char* b2 = last ? nB : cB + (size_t)(t + 2) * kstep;
;             const char* a3 = a2 + kstep; const char* b3 = b2 + kstep;
;             if (last && has_next) S.a_ready(nxt);
;             if constexpr (SP2) {
;             PG8_LDB(B0, 0, 0); PG8_LDB(B1, 0, 1); PG8_SCHED; PG8_LDA(At, 0, 0); PG8_STAGE(PG8_SA(1, 1), a1 + hstepA, voffA);
;             PG8_WAIT_V(8); PG8_WAIT_L(0); PG8_BAR; PG8_MMA(0, 0, At, B0); PG8_MMA(0, 1, At, B1); PG8_BAR; PG8_SCHED;
;             PG8_LDA(At, 0, 1); PG8_STAGE(PG8_SB(0, 0), b2, voffB); PG8_STAGE(PG8_SB(0, 1), b2 + hstepB, voffB); PG8_STAGE(PG8_SA(0, 0), a2, voffA);
;             PG8_WAIT_V(8); PG8_WAIT_L(0); PG8_BAR; PG8_MMA(1, 0, At, B0); PG8_MMA(1, 1, At, B1); PG8_BAR; PG8_SCHED;
.LBB0_429:
	s_add_u32 s2, s42, 0x100
	s_addc_u32 s5, s43, 0
	s_mov_b32 s33, -2
	ds_read_b128 v[62:65], v168
	ds_read_b128 v[66:69], v168 offset:1024
	ds_read_b128 v[138:141], v168 offset:2048
	ds_read_b128 v[142:145], v168 offset:3072
	ds_read_b128 v[162:165], v169
	ds_read_b128 v[172:175], v169 offset:1024
	ds_read_b128 v[176:179], v169 offset:2048
	ds_read_b128 v[180:183], v169 offset:3072
	s_add_u32 s42, s40, 0x100
	s_addc_u32 s43, s41, 0
	s_cmp_eq_u32 s33, 6
	s_cselect_b32 s47, s37, s43
	s_cselect_b32 s46, s36, s42
	s_cselect_b32 s45, s39, s5
	s_cselect_b32 s44, s38, s2
	v_lshl_add_u64 v[216:217], s[40:41], 0, v[158:159]
	s_add_i32 m0, s51, 0xc000
	ds_read_b128 v[184:187], v170
	ds_read_b128 v[188:191], v170 offset:1024
	ds_read_b128 v[192:195], v170 offset:2048
	ds_read_b128 v[196:199], v170 offset:3072
	ds_read_b128 v[200:203], v170 offset:4096
	ds_read_b128 v[204:207], v170 offset:5120
	ds_read_b128 v[208:211], v170 offset:6144
	ds_read_b128 v[212:215], v170 offset:7168
	global_load_lds_dwordx4 v[216:217], off
	v_lshl_add_u64 v[216:217], s[40:41], 0, v[160:161]
	s_add_i32 m0, s51, 0xe000
	s_nop 0
	global_load_lds_dwordx4 v[216:217], off
	s_waitcnt vmcnt(8)
	s_waitcnt lgkmcnt(0)
	s_barrier
	s_setprio 1
	s_waitcnt lgkmcnt(0)
	v_mfma_f32_16x16x32_bf16 v[134:137], v[62:65], v[184:187], 0
	v_mfma_f32_16x16x32_bf16 v[130:133], v[138:141], v[184:187], 0
	v_mfma_f32_16x16x32_bf16 v[114:117], v[138:141], v[192:195], 0
	v_mfma_f32_16x16x32_bf16 v[118:121], v[62:65], v[192:195], 0
	v_mfma_f32_16x16x32_bf16 v[102:105], v[62:65], v[200:203], 0
	v_mfma_f32_16x16x32_bf16 v[98:101], v[138:141], v[200:203], 0
	v_mfma_f32_16x16x32_bf16 v[82:85], v[138:141], v[208:211], 0
	v_mfma_f32_16x16x32_bf16 v[86:89], v[62:65], v[208:211], 0
	v_mfma_f32_16x16x32_bf16 v[134:137], v[66:69], v[188:191], v[134:137]
	v_mfma_f32_16x16x32_bf16 v[130:133], v[142:145], v[188:191], v[130:133]
	v_mfma_f32_16x16x32_bf16 v[114:117], v[142:145], v[196:199], v[114:117]
	v_mfma_f32_16x16x32_bf16 v[118:121], v[66:69], v[196:199], v[118:121]
	v_mfma_f32_16x16x32_bf16 v[102:105], v[66:69], v[204:207], v[102:105]
	v_mfma_f32_16x16x32_bf16 v[98:101], v[142:145], v[204:207], v[98:101]
	v_mfma_f32_16x16x32_bf16 v[82:85], v[142:145], v[212:215], v[82:85]
	v_mfma_f32_16x16x32_bf16 v[86:89], v[66:69], v[212:215], v[86:89]
	s_setprio 0
	s_setprio 1
	v_mfma_f32_16x16x32_bf16 v[126:129], v[162:165], v[184:187], 0
	v_mfma_f32_16x16x32_bf16 v[122:125], v[176:179], v[184:187], 0
	v_mfma_f32_16x16x32_bf16 v[106:109], v[176:179], v[192:195], 0
	v_mfma_f32_16x16x32_bf16 v[110:113], v[162:165], v[192:195], 0
	v_mfma_f32_16x16x32_bf16 v[94:97], v[162:165], v[200:203], 0
	v_mfma_f32_16x16x32_bf16 v[90:93], v[176:179], v[200:203], 0
	v_mfma_f32_16x16x32_bf16 v[74:77], v[176:179], v[208:211], 0
	v_mfma_f32_16x16x32_bf16 v[78:81], v[162:165], v[208:211], 0
	v_mfma_f32_16x16x32_bf16 v[126:129], v[172:175], v[188:191], v[126:129]
	v_mfma_f32_16x16x32_bf16 v[122:125], v[180:183], v[188:191], v[122:125]
	v_mfma_f32_16x16x32_bf16 v[106:109], v[180:183], v[196:199], v[106:109]
	v_mfma_f32_16x16x32_bf16 v[110:113], v[172:175], v[196:199], v[110:113]
	v_mfma_f32_16x16x32_bf16 v[94:97], v[172:175], v[204:207], v[94:97]
	v_mfma_f32_16x16x32_bf16 v[90:93], v[180:183], v[204:207], v[90:93]
	v_mfma_f32_16x16x32_bf16 v[74:77], v[180:183], v[212:215], v[74:77]
	v_mfma_f32_16x16x32_bf16 v[78:81], v[172:175], v[212:215], v[78:81]
	s_setprio 0
	s_barrier
	s_add_i32 s40, s59, s48
	v_lshl_add_u64 v[216:217], s[44:45], 0, v[150:151]
	s_mov_b32 m0, s40
	ds_read_b128 v[184:187], v170 offset:16384
	ds_read_b128 v[188:191], v170 offset:17408
	ds_read_b128 v[192:195], v170 offset:18432
	ds_read_b128 v[196:199], v170 offset:19456
	ds_read_b128 v[200:203], v170 offset:20480
	ds_read_b128 v[204:207], v170 offset:21504
	ds_read_b128 v[208:211], v170 offset:22528
	ds_read_b128 v[212:215], v170 offset:23552
	global_load_lds_dwordx4 v[216:217], off
	s_add_i32 m0, s40, 0x2000
	s_add_u32 s40, s44, 0x28000
	v_lshl_add_u64 v[218:219], s[44:45], 0, v[146:147]
	s_addc_u32 s41, s45, 0
	s_add_i32 s71, s60, s48
	global_load_lds_dwordx4 v[218:219], off
	v_lshl_add_u64 v[220:221], s[40:41], 0, v[150:151]
	s_mov_b32 m0, s71
	v_lshl_add_u64 v[222:223], s[46:47], 0, v[148:149]
	global_load_lds_dwordx4 v[220:221], off
	v_lshl_add_u64 v[220:221], s[40:41], 0, v[146:147]
	s_add_i32 m0, s71, 0x2000
	s_nop 0
	global_load_lds_dwordx4 v[220:221], off
	v_lshl_add_u64 v[220:221], s[46:47], 0, v[152:153]
	s_mov_b32 m0, s51
	s_nop 0
	global_load_lds_dwordx4 v[220:221], off
	s_mov_b32 m0, s52
	s_nop 0
	global_load_lds_dwordx4 v[222:223], off
	s_waitcnt vmcnt(8)
	s_waitcnt lgkmcnt(0)
	s_barrier
; #define PG8_STAGE(bufoff, gbase, voff) do { _Pragma("unroll") for (int _i = 0; _i < 2; ++_i) \
;         __builtin_amdgcn_global_load_lds((const unsigned*)((const char*)(gbase) + (voff)[_i]), (PG8_LAS unsigned*)(lds + (bufoff) + ldsw + _i * 8192), 16, 0, 0); } while (0)
; #define PG8_LDA(dst, b, h) do { _Pragma("unroll") for (int m = 0; m < 4; ++m) _Pragma("unroll") for (int k = 0; k < 2; ++k) dst[m][k] = *(const PG8_LAS bf16x8*)(lds + PG8_SA(b, h) + aoff + m * 2048 + k * 1024); } while (0)
; #define PG8_LDB(dst, b, h) do { _Pragma("unroll") for (int n = 0; n < 2; ++n) _Pragma("unroll") for (int k = 0; k < 2; ++k) dst[n][k] = *(const PG8_LAS bf16x8*)(lds + PG8_SB(b, h) + boff + n * 2048 + k * 1024); } while (0)
; #define PG8_MMA(ai, bj, At, Bt) do { __builtin_amdgcn_s_setprio(1); _Pragma("unroll") for (int m = 0; m < 4; ++m) _Pragma("unroll") for (int n = 0; n < 2; ++n) _Pragma("unroll") for (int k = 0; k < 2; ++k) \
;         acc[ai][bj][m][n] = __builtin_amdgcn_mfma_f32_16x16x32_bf16(Bt[n][k], At[m][k], acc[ai][bj][m][n], 0, 0, 0); __builtin_amdgcn_s_setprio(0); } while (0)
; #define PG8_WAIT_V(n) asm volatile("s_waitcnt vmcnt(" #n ")" ::: "memory")
; #define PG8_WAIT_L(n) asm volatile("s_waitcnt lgkmcnt(" #n ")" ::: "memory")
; #define PG8_BAR __builtin_amdgcn_s_barrier()
; #define PG8_SCHED __builtin_amdgcn_sched_barrier(0)
; template <class Epi, class Sched, bool ALIGN_EPI = false, bool SP2 = false>
; __device__ __forceinline__ void gemm_phase(PG8_LAS unsigned char* lds, const Gemm g, const Sched& S, const Epi& E) {
;     ...
;             PG8_WAIT_V(8); PG8_WAIT_L(0); PG8_BAR; PG8_MMA(0, 0, At, B0); PG8_MMA(0, 1, At, B1); PG8_BAR; PG8_SCHED;
;             PG8_LDA(At, 0, 1); PG8_STAGE(PG8_SB(0, 0), b2, voffB); PG8_STAGE(PG8_SB(0, 1), b2 + hstepB, voffB); PG8_STAGE(PG8_SA(0, 0), a2, voffA);
;             PG8_WAIT_V(8); PG8_WAIT_L(0); PG8_BAR; PG8_MMA(1, 0, At, B0); PG8_MMA(1, 1, At, B1); PG8_BAR; PG8_SCHED;
;             PG8_LDB(B0, 1, 0); PG8_LDB(B1, 1, 1); PG8_SCHED; PG8_LDA(At, 1, 0); PG8_STAGE(PG8_SA(0, 1), a2 + hstepA, voffA);
;             PG8_WAIT_V(8); PG8_WAIT_L(0); PG8_BAR; PG8_MMA(0, 0, At, B0); PG8_MMA(0, 1, At, B1); PG8_BAR; PG8_SCHED;
	s_setprio 1
	s_waitcnt lgkmcnt(0)
	v_mfma_f32_16x16x32_bf16 v[70:73], v[62:65], v[184:187], 0
	v_mfma_f32_16x16x32_bf16 v[58:61], v[138:141], v[184:187], 0
	v_mfma_f32_16x16x32_bf16 v[42:45], v[138:141], v[192:195], 0
	v_mfma_f32_16x16x32_bf16 v[46:49], v[62:65], v[192:195], 0
	v_mfma_f32_16x16x32_bf16 v[30:33], v[62:65], v[200:203], 0
	v_mfma_f32_16x16x32_bf16 v[26:29], v[138:141], v[200:203], 0
	v_mfma_f32_16x16x32_bf16 v[10:13], v[138:141], v[208:211], 0
	v_mfma_f32_16x16x32_bf16 v[14:17], v[62:65], v[208:211], 0
	v_mfma_f32_16x16x32_bf16 v[70:73], v[66:69], v[188:191], v[70:73]
	v_mfma_f32_16x16x32_bf16 v[58:61], v[142:145], v[188:191], v[58:61]
	v_mfma_f32_16x16x32_bf16 v[42:45], v[142:145], v[196:199], v[42:45]
	v_mfma_f32_16x16x32_bf16 v[46:49], v[66:69], v[196:199], v[46:49]
	v_mfma_f32_16x16x32_bf16 v[30:33], v[66:69], v[204:207], v[30:33]
	v_mfma_f32_16x16x32_bf16 v[26:29], v[142:145], v[204:207], v[26:29]
	v_mfma_f32_16x16x32_bf16 v[10:13], v[142:145], v[212:215], v[10:13]
	v_mfma_f32_16x16x32_bf16 v[14:17], v[66:69], v[212:215], v[14:17]
	s_setprio 0
	s_setprio 1
	v_mfma_f32_16x16x32_bf16 v[54:57], v[162:165], v[184:187], 0
	v_mfma_f32_16x16x32_bf16 v[50:53], v[176:179], v[184:187], 0
	v_mfma_f32_16x16x32_bf16 v[34:37], v[176:179], v[192:195], 0
	v_mfma_f32_16x16x32_bf16 v[38:41], v[162:165], v[192:195], 0
	v_mfma_f32_16x16x32_bf16 v[22:25], v[162:165], v[200:203], 0
	v_mfma_f32_16x16x32_bf16 v[18:21], v[176:179], v[200:203], 0
	v_mfma_f32_16x16x32_bf16 v[2:5], v[176:179], v[208:211], 0
	v_mfma_f32_16x16x32_bf16 v[6:9], v[162:165], v[208:211], 0
	v_mfma_f32_16x16x32_bf16 v[54:57], v[172:175], v[188:191], v[54:57]
	v_mfma_f32_16x16x32_bf16 v[50:53], v[180:183], v[188:191], v[50:53]
	v_mfma_f32_16x16x32_bf16 v[34:37], v[180:183], v[196:199], v[34:37]
	v_mfma_f32_16x16x32_bf16 v[38:41], v[172:175], v[196:199], v[38:41]
	v_mfma_f32_16x16x32_bf16 v[22:25], v[172:175], v[204:207], v[22:25]
	v_mfma_f32_16x16x32_bf16 v[18:21], v[180:183], v[204:207], v[18:21]
	v_mfma_f32_16x16x32_bf16 v[2:5], v[180:183], v[212:215], v[2:5]
	v_mfma_f32_16x16x32_bf16 v[6:9], v[172:175], v[212:215], v[6:9]
	s_setprio 0
	s_barrier
	s_add_i32 s71, 0, 0x18000
	s_add_i32 s72, 0, 0x1c000
	v_add_u32_e32 v142, s71, v166
	v_add_u32_e32 v180, s72, v166
	ds_read_b128 v[62:65], v142
	ds_read_b128 v[66:69], v142 offset:1024
	ds_read_b128 v[138:141], v142 offset:2048
	ds_read_b128 v[142:145], v142 offset:3072
	ds_read_b128 v[162:165], v180
	ds_read_b128 v[172:175], v180 offset:1024
	ds_read_b128 v[176:179], v180 offset:2048
	ds_read_b128 v[180:183], v180 offset:3072
	s_add_u32 s40, s46, 0x28000
	s_addc_u32 s41, s47, 0
	s_mov_b32 m0, s53
	v_lshl_add_u64 v[224:225], s[40:41], 0, v[152:153]
	ds_read_b128 v[184:187], v170 offset:32768
	ds_read_b128 v[188:191], v170 offset:33792
	ds_read_b128 v[192:195], v170 offset:34816
	ds_read_b128 v[196:199], v170 offset:35840
	ds_read_b128 v[200:203], v170 offset:36864
	ds_read_b128 v[204:207], v170 offset:37888
	ds_read_b128 v[208:211], v170 offset:38912
	ds_read_b128 v[212:215], v170 offset:39936
	global_load_lds_dwordx4 v[224:225], off
	v_lshl_add_u64 v[224:225], s[40:41], 0, v[148:149]
	s_mov_b32 m0, s54
	s_nop 0
	global_load_lds_dwordx4 v[224:225], off
	s_waitcnt vmcnt(8)
	s_waitcnt lgkmcnt(0)
	s_barrier
	s_setprio 1
	s_waitcnt lgkmcnt(0)
	v_mfma_f32_16x16x32_bf16 v[134:137], v[62:65], v[184:187], v[134:137]
	v_mfma_f32_16x16x32_bf16 v[130:133], v[138:141], v[184:187], v[130:133]
	v_mfma_f32_16x16x32_bf16 v[114:117], v[138:141], v[192:195], v[114:117]
	v_mfma_f32_16x16x32_bf16 v[118:121], v[62:65], v[192:195], v[118:121]
	v_mfma_f32_16x16x32_bf16 v[102:105], v[62:65], v[200:203], v[102:105]
	v_mfma_f32_16x16x32_bf16 v[98:101], v[138:141], v[200:203], v[98:101]
	v_mfma_f32_16x16x32_bf16 v[82:85], v[138:141], v[208:211], v[82:85]
	v_mfma_f32_16x16x32_bf16 v[86:89], v[62:65], v[208:211], v[86:89]
	v_mfma_f32_16x16x32_bf16 v[134:137], v[66:69], v[188:191], v[134:137]
	v_mfma_f32_16x16x32_bf16 v[130:133], v[142:145], v[188:191], v[130:133]
	v_mfma_f32_16x16x32_bf16 v[114:117], v[142:145], v[196:199], v[114:117]
	v_mfma_f32_16x16x32_bf16 v[118:121], v[66:69], v[196:199], v[118:121]
	v_mfma_f32_16x16x32_bf16 v[102:105], v[66:69], v[204:207], v[102:105]
	v_mfma_f32_16x16x32_bf16 v[98:101], v[142:145], v[204:207], v[98:101]
	v_mfma_f32_16x16x32_bf16 v[82:85], v[142:145], v[212:215], v[82:85]
	v_mfma_f32_16x16x32_bf16 v[86:89], v[66:69], v[212:215], v[86:89]
	s_setprio 0
	s_setprio 1
	v_mfma_f32_16x16x32_bf16 v[126:129], v[162:165], v[184:187], v[126:129]
	v_mfma_f32_16x16x32_bf16 v[122:125], v[176:179], v[184:187], v[122:125]
	v_mfma_f32_16x16x32_bf16 v[106:109], v[176:179], v[192:195], v[106:109]
	v_mfma_f32_16x16x32_bf16 v[110:113], v[162:165], v[192:195], v[110:113]
	v_mfma_f32_16x16x32_bf16 v[94:97], v[162:165], v[200:203], v[94:97]
	v_mfma_f32_16x16x32_bf16 v[90:93], v[176:179], v[200:203], v[90:93]
	v_mfma_f32_16x16x32_bf16 v[74:77], v[176:179], v[208:211], v[74:77]
	v_mfma_f32_16x16x32_bf16 v[78:81], v[162:165], v[208:211], v[78:81]
	v_mfma_f32_16x16x32_bf16 v[126:129], v[172:175], v[188:191], v[126:129]
	v_mfma_f32_16x16x32_bf16 v[122:125], v[180:183], v[188:191], v[122:125]
	v_mfma_f32_16x16x32_bf16 v[106:109], v[180:183], v[196:199], v[106:109]
	v_mfma_f32_16x16x32_bf16 v[110:113], v[172:175], v[196:199], v[110:113]
	v_mfma_f32_16x16x32_bf16 v[94:97], v[172:175], v[204:207], v[94:97]
	v_mfma_f32_16x16x32_bf16 v[90:93], v[180:183], v[204:207], v[90:93]
	v_mfma_f32_16x16x32_bf16 v[74:77], v[180:183], v[212:215], v[74:77]
	v_mfma_f32_16x16x32_bf16 v[78:81], v[172:175], v[212:215], v[78:81]
	s_setprio 0
	s_barrier
; #define PG8_STAGE(bufoff, gbase, voff) do { _Pragma("unroll") for (int _i = 0; _i < 2; ++_i) \
;         __builtin_amdgcn_global_load_lds((const unsigned*)((const char*)(gbase) + (voff)[_i]), (PG8_LAS unsigned*)(lds + (bufoff) + ldsw + _i * 8192), 16, 0, 0); } while (0)
; #define PG8_LDA(dst, b, h) do { _Pragma("unroll") for (int m = 0; m < 4; ++m) _Pragma("unroll") for (int k = 0; k < 2; ++k) dst[m][k] = *(const PG8_LAS bf16x8*)(lds + PG8_SA(b, h) + aoff + m * 2048 + k * 1024); } while (0)
; #define PG8_LDB(dst, b, h) do { _Pragma("unroll") for (int n = 0; n < 2; ++n) _Pragma("unroll") for (int k = 0; k < 2; ++k) dst[n][k] = *(const PG8_LAS bf16x8*)(lds + PG8_SB(b, h) + boff + n * 2048 + k * 1024); } while (0)
; #define PG8_WAIT_V(n) asm volatile("s_waitcnt vmcnt(" #n ")" ::: "memory")
; #define PG8_WAIT_L(n) asm volatile("s_waitcnt lgkmcnt(" #n ")" ::: "memory")
; #define PG8_BAR __builtin_amdgcn_s_barrier()
; template <class Epi, class Sched, bool ALIGN_EPI = false, bool SP2 = false>
; __device__ __forceinline__ void gemm_phase(PG8_LAS unsigned char* lds, const Gemm g, const Sched& S, const Epi& E) {
;     ...
;         for (int t = 0; t < nt; t += 2) {
;             const bool last = (t == nt - 2);
;             const char* a1 = cA + (size_t)(t + 1) * kstep;
;             const char* a2 = last ? nA : cA + (size_t)(t + 2) * kstep; const char* b2 = last ? nB : cB + (size_t)(t + 2) * kstep;
;             const char* a3 = a2 + kstep; const char* b3 = b2 + kstep;
;             if (last && has_next) S.a_ready(nxt);
;             if constexpr (SP2) {
;             PG8_LDB(B0, 0, 0); PG8_LDB(B1, 0, 1); PG8_SCHED; PG8_LDA(At, 0, 0); PG8_STAGE(PG8_SA(1, 1), a1 + hstepA, voffA);
;             PG8_WAIT_V(8); PG8_WAIT_L(0); PG8_BAR; PG8_MMA(0, 0, At, B0); PG8_MMA(0, 1, At, B1); PG8_BAR; PG8_SCHED;
;             PG8_LDA(At, 0, 1); PG8_STAGE(PG8_SB(0, 0), b2, voffB); PG8_STAGE(PG8_SB(0, 1), b2 + hstepB, voffB); PG8_STAGE(PG8_SA(0, 0), a2, voffA);
;             PG8_WAIT_V(8); PG8_WAIT_L(0); PG8_BAR; PG8_MMA(1, 0, At, B0); PG8_MMA(1, 1, At, B1); PG8_BAR; PG8_SCHED;
;     ...
;             PG8_LDA(At, 1, 1); PG8_STAGE(PG8_SB(1, 0), b3, voffB); PG8_STAGE(PG8_SB(1, 1), b3 + hstepB, voffB); PG8_STAGE(PG8_SA(1, 0), a3, voffA);
;             PG8_WAIT_V(8); PG8_WAIT_L(0); PG8_BAR; PG8_MMA(1, 0, At, B0); PG8_MMA(1, 1, At, B1); PG8_BAR; PG8_SCHED;
	s_add_i32 s40, s71, s48
	v_lshl_add_u64 v[216:217], v[216:217], 0, s[16:17]
	s_mov_b32 m0, s40
	ds_read_b128 v[184:187], v170 offset:49152
	ds_read_b128 v[188:191], v170 offset:50176
	ds_read_b128 v[192:195], v170 offset:51200
	ds_read_b128 v[196:199], v170 offset:52224
	ds_read_b128 v[200:203], v170 offset:53248
	ds_read_b128 v[204:207], v170 offset:54272
	ds_read_b128 v[208:211], v170 offset:55296
	ds_read_b128 v[212:215], v170 offset:56320
	global_load_lds_dwordx4 v[216:217], off
	s_add_i32 m0, s40, 0x2000
	s_add_u32 s40, s44, 0x28080
	v_lshl_add_u64 v[216:217], v[218:219], 0, s[16:17]
	s_addc_u32 s41, s45, 0
	s_add_i32 s44, s72, s48
	global_load_lds_dwordx4 v[216:217], off
	v_lshl_add_u64 v[216:217], s[40:41], 0, v[150:151]
	s_mov_b32 m0, s44
	s_nop 0
	global_load_lds_dwordx4 v[216:217], off
	v_lshl_add_u64 v[216:217], s[40:41], 0, v[146:147]
	s_add_i32 m0, s44, 0x2000
	s_nop 0
	global_load_lds_dwordx4 v[216:217], off
	v_lshl_add_u64 v[216:217], v[220:221], 0, s[16:17]
	s_mov_b32 m0, s56
	s_nop 0
	global_load_lds_dwordx4 v[216:217], off
	v_lshl_add_u64 v[216:217], v[222:223], 0, s[16:17]
	s_mov_b32 m0, s57
	s_nop 0
	global_load_lds_dwordx4 v[216:217], off
	s_waitcnt vmcnt(8)
	s_waitcnt lgkmcnt(0)
	s_barrier
	s_setprio 1
	s_waitcnt lgkmcnt(0)
	v_mfma_f32_16x16x32_bf16 v[70:73], v[62:65], v[184:187], v[70:73]
	v_mfma_f32_16x16x32_bf16 v[58:61], v[138:141], v[184:187], v[58:61]
	v_mfma_f32_16x16x32_bf16 v[42:45], v[138:141], v[192:195], v[42:45]
	v_mfma_f32_16x16x32_bf16 v[46:49], v[62:65], v[192:195], v[46:49]
	v_mfma_f32_16x16x32_bf16 v[30:33], v[62:65], v[200:203], v[30:33]
	v_mfma_f32_16x16x32_bf16 v[26:29], v[138:141], v[200:203], v[26:29]
	v_mfma_f32_16x16x32_bf16 v[10:13], v[138:141], v[208:211], v[10:13]
	v_mfma_f32_16x16x32_bf16 v[14:17], v[62:65], v[208:211], v[14:17]
	v_mfma_f32_16x16x32_bf16 v[70:73], v[66:69], v[188:191], v[70:73]
	v_mfma_f32_16x16x32_bf16 v[58:61], v[142:145], v[188:191], v[58:61]
	v_mfma_f32_16x16x32_bf16 v[42:45], v[142:145], v[196:199], v[42:45]
	v_mfma_f32_16x16x32_bf16 v[46:49], v[66:69], v[196:199], v[46:49]
	v_mfma_f32_16x16x32_bf16 v[30:33], v[66:69], v[204:207], v[30:33]
	v_mfma_f32_16x16x32_bf16 v[26:29], v[142:145], v[204:207], v[26:29]
	v_mfma_f32_16x16x32_bf16 v[10:13], v[142:145], v[212:215], v[10:13]
	v_mfma_f32_16x16x32_bf16 v[14:17], v[66:69], v[212:215], v[14:17]
	s_setprio 0
	s_setprio 1
	v_mfma_f32_16x16x32_bf16 v[54:57], v[162:165], v[184:187], v[54:57]
	v_mfma_f32_16x16x32_bf16 v[50:53], v[176:179], v[184:187], v[50:53]
	v_mfma_f32_16x16x32_bf16 v[34:37], v[176:179], v[192:195], v[34:37]
	v_mfma_f32_16x16x32_bf16 v[38:41], v[162:165], v[192:195], v[38:41]
	v_mfma_f32_16x16x32_bf16 v[22:25], v[162:165], v[200:203], v[22:25]
	v_mfma_f32_16x16x32_bf16 v[18:21], v[176:179], v[200:203], v[18:21]
	v_mfma_f32_16x16x32_bf16 v[2:5], v[176:179], v[208:211], v[2:5]
	v_mfma_f32_16x16x32_bf16 v[6:9], v[162:165], v[208:211], v[6:9]
	v_mfma_f32_16x16x32_bf16 v[54:57], v[172:175], v[188:191], v[54:57]
	v_mfma_f32_16x16x32_bf16 v[50:53], v[180:183], v[188:191], v[50:53]
	v_mfma_f32_16x16x32_bf16 v[34:37], v[180:183], v[196:199], v[34:37]
	v_mfma_f32_16x16x32_bf16 v[38:41], v[172:175], v[196:199], v[38:41]
	v_mfma_f32_16x16x32_bf16 v[22:25], v[172:175], v[204:207], v[22:25]
	v_mfma_f32_16x16x32_bf16 v[18:21], v[180:183], v[204:207], v[18:21]
	v_mfma_f32_16x16x32_bf16 v[2:5], v[180:183], v[212:215], v[2:5]
	v_mfma_f32_16x16x32_bf16 v[6:9], v[172:175], v[212:215], v[6:9]
	s_setprio 0
	s_barrier
	s_add_i32 s33, s33, 2
	s_add_u32 s2, s2, 0x100
	s_addc_u32 s5, s5, 0
	s_cmp_gt_u32 s33, 7
	s_mov_b64 s[40:41], s[42:43]
.LBB0_430:
	ds_read_b128 v[62:65], v168
	ds_read_b128 v[66:69], v168 offset:1024
	ds_read_b128 v[138:141], v168 offset:2048
	ds_read_b128 v[142:145], v168 offset:3072
	ds_read_b128 v[162:165], v169
	ds_read_b128 v[172:175], v169 offset:1024
	ds_read_b128 v[176:179], v169 offset:2048
	ds_read_b128 v[180:183], v169 offset:3072
	s_add_u32 s42, s40, 0x100
	s_addc_u32 s43, s41, 0
	s_cmp_eq_u32 s33, 6
	s_cselect_b32 s47, s37, s43
	s_cselect_b32 s46, s36, s42
	s_cselect_b32 s45, s39, s5
	s_cselect_b32 s44, s38, s2
	v_lshl_add_u64 v[216:217], s[40:41], 0, v[158:159]
	s_add_i32 m0, s51, 0xc000
	ds_read_b128 v[184:187], v170
	ds_read_b128 v[188:191], v170 offset:1024
	ds_read_b128 v[192:195], v170 offset:2048
	ds_read_b128 v[196:199], v170 offset:3072
	ds_read_b128 v[200:203], v170 offset:4096
	ds_read_b128 v[204:207], v170 offset:5120
	ds_read_b128 v[208:211], v170 offset:6144
	ds_read_b128 v[212:215], v170 offset:7168
	global_load_lds_dwordx4 v[216:217], off
	v_lshl_add_u64 v[216:217], s[40:41], 0, v[160:161]
	s_add_i32 m0, s51, 0xe000
	s_nop 0
	global_load_lds_dwordx4 v[216:217], off
	s_waitcnt vmcnt(8)
	s_waitcnt lgkmcnt(0)
	s_barrier
; #define PG8_STAGE(bufoff, gbase, voff) do { _Pragma("unroll") for (int _i = 0; _i < 2; ++_i) \
;         __builtin_amdgcn_global_load_lds((const unsigned*)((const char*)(gbase) + (voff)[_i]), (PG8_LAS unsigned*)(lds + (bufoff) + ldsw + _i * 8192), 16, 0, 0); } while (0)
; #define PG8_LDA(dst, b, h) do { _Pragma("unroll") for (int m = 0; m < 4; ++m) _Pragma("unroll") for (int k = 0; k < 2; ++k) dst[m][k] = *(const PG8_LAS bf16x8*)(lds + PG8_SA(b, h) + aoff + m * 2048 + k * 1024); } while (0)
; #define PG8_LDB(dst, b, h) do { _Pragma("unroll") for (int n = 0; n < 2; ++n) _Pragma("unroll") for (int k = 0; k < 2; ++k) dst[n][k] = *(const PG8_LAS bf16x8*)(lds + PG8_SB(b, h) + boff + n * 2048 + k * 1024); } while (0)
; #define PG8_MMA(ai, bj, At, Bt) do { __builtin_amdgcn_s_setprio(1); _Pragma("unroll") for (int m = 0; m < 4; ++m) _Pragma("unroll") for (int n = 0; n < 2; ++n) _Pragma("unroll") for (int k = 0; k < 2; ++k) \
;         acc[ai][bj][m][n] = __builtin_amdgcn_mfma_f32_16x16x32_bf16(Bt[n][k], At[m][k], acc[ai][bj][m][n], 0, 0, 0); __builtin_amdgcn_s_setprio(0); } while (0)
; #define PG8_WAIT_V(n) asm volatile("s_waitcnt vmcnt(" #n ")" ::: "memory")
; #define PG8_WAIT_L(n) asm volatile("s_waitcnt lgkmcnt(" #n ")" ::: "memory")
; #define PG8_BAR __builtin_amdgcn_s_barrier()
; #define PG8_SCHED __builtin_amdgcn_sched_barrier(0)
; template <class Epi, class Sched, bool ALIGN_EPI = false, bool SP2 = false>
; __device__ __forceinline__ void gemm_phase(PG8_LAS unsigned char* lds, const Gemm g, const Sched& S, const Epi& E) {
;     ...
;             PG8_LDB(B0, 0, 0); PG8_LDB(B1, 0, 1); PG8_SCHED; PG8_LDA(At, 0, 0); PG8_STAGE(PG8_SA(1, 1), a1 + hstepA, voffA);
;             PG8_WAIT_V(8); PG8_WAIT_L(0); PG8_BAR; PG8_MMA(0, 0, At, B0); PG8_MMA(0, 1, At, B1); PG8_BAR; PG8_SCHED;
;             PG8_LDA(At, 0, 1); PG8_STAGE(PG8_SB(0, 0), b2, voffB); PG8_STAGE(PG8_SB(0, 1), b2 + hstepB, voffB); PG8_STAGE(PG8_SA(0, 0), a2, voffA);
;             PG8_WAIT_V(8); PG8_WAIT_L(0); PG8_BAR; PG8_MMA(1, 0, At, B0); PG8_MMA(1, 1, At, B1); PG8_BAR; PG8_SCHED;
	s_setprio 1
	s_waitcnt lgkmcnt(0)
	v_mfma_f32_16x16x32_bf16 v[134:137], v[62:65], v[184:187], v[134:137]
	v_mfma_f32_16x16x32_bf16 v[130:133], v[138:141], v[184:187], v[130:133]
	v_mfma_f32_16x16x32_bf16 v[114:117], v[138:141], v[192:195], v[114:117]
	v_mfma_f32_16x16x32_bf16 v[118:121], v[62:65], v[192:195], v[118:121]
	v_mfma_f32_16x16x32_bf16 v[102:105], v[62:65], v[200:203], v[102:105]
	v_mfma_f32_16x16x32_bf16 v[98:101], v[138:141], v[200:203], v[98:101]
	v_mfma_f32_16x16x32_bf16 v[82:85], v[138:141], v[208:211], v[82:85]
	v_mfma_f32_16x16x32_bf16 v[86:89], v[62:65], v[208:211], v[86:89]
	v_mfma_f32_16x16x32_bf16 v[134:137], v[66:69], v[188:191], v[134:137]
	v_mfma_f32_16x16x32_bf16 v[130:133], v[142:145], v[188:191], v[130:133]
	v_mfma_f32_16x16x32_bf16 v[114:117], v[142:145], v[196:199], v[114:117]
	v_mfma_f32_16x16x32_bf16 v[118:121], v[66:69], v[196:199], v[118:121]
	v_mfma_f32_16x16x32_bf16 v[102:105], v[66:69], v[204:207], v[102:105]
	v_mfma_f32_16x16x32_bf16 v[98:101], v[142:145], v[204:207], v[98:101]
	v_mfma_f32_16x16x32_bf16 v[82:85], v[142:145], v[212:215], v[82:85]
	v_mfma_f32_16x16x32_bf16 v[86:89], v[66:69], v[212:215], v[86:89]
	s_setprio 0
	s_setprio 1
	v_mfma_f32_16x16x32_bf16 v[126:129], v[162:165], v[184:187], v[126:129]
	v_mfma_f32_16x16x32_bf16 v[122:125], v[176:179], v[184:187], v[122:125]
	v_mfma_f32_16x16x32_bf16 v[106:109], v[176:179], v[192:195], v[106:109]
	v_mfma_f32_16x16x32_bf16 v[110:113], v[162:165], v[192:195], v[110:113]
	v_mfma_f32_16x16x32_bf16 v[94:97], v[162:165], v[200:203], v[94:97]
	v_mfma_f32_16x16x32_bf16 v[90:93], v[176:179], v[200:203], v[90:93]
	v_mfma_f32_16x16x32_bf16 v[74:77], v[176:179], v[208:211], v[74:77]
	v_mfma_f32_16x16x32_bf16 v[78:81], v[162:165], v[208:211], v[78:81]
	v_mfma_f32_16x16x32_bf16 v[126:129], v[172:175], v[188:191], v[126:129]
	v_mfma_f32_16x16x32_bf16 v[122:125], v[180:183], v[188:191], v[122:125]
	v_mfma_f32_16x16x32_bf16 v[106:109], v[180:183], v[196:199], v[106:109]
	v_mfma_f32_16x16x32_bf16 v[110:113], v[172:175], v[196:199], v[110:113]
	v_mfma_f32_16x16x32_bf16 v[94:97], v[172:175], v[204:207], v[94:97]
	v_mfma_f32_16x16x32_bf16 v[90:93], v[180:183], v[204:207], v[90:93]
	v_mfma_f32_16x16x32_bf16 v[74:77], v[180:183], v[212:215], v[74:77]
	v_mfma_f32_16x16x32_bf16 v[78:81], v[172:175], v[212:215], v[78:81]
	s_setprio 0
	s_barrier
	s_add_i32 s40, s59, s48
	v_lshl_add_u64 v[216:217], s[44:45], 0, v[150:151]
	s_mov_b32 m0, s40
	ds_read_b128 v[184:187], v170 offset:16384
	ds_read_b128 v[188:191], v170 offset:17408
	ds_read_b128 v[192:195], v170 offset:18432
	ds_read_b128 v[196:199], v170 offset:19456
	ds_read_b128 v[200:203], v170 offset:20480
	ds_read_b128 v[204:207], v170 offset:21504
	ds_read_b128 v[208:211], v170 offset:22528
	ds_read_b128 v[212:215], v170 offset:23552
	global_load_lds_dwordx4 v[216:217], off
	s_add_i32 m0, s40, 0x2000
	s_add_u32 s40, s44, 0x28000
	v_lshl_add_u64 v[218:219], s[44:45], 0, v[146:147]
	s_addc_u32 s41, s45, 0
	s_add_i32 s71, s60, s48
	global_load_lds_dwordx4 v[218:219], off
	v_lshl_add_u64 v[220:221], s[40:41], 0, v[150:151]
	s_mov_b32 m0, s71
	v_lshl_add_u64 v[222:223], s[46:47], 0, v[148:149]
	global_load_lds_dwordx4 v[220:221], off
	v_lshl_add_u64 v[220:221], s[40:41], 0, v[146:147]
	s_add_i32 m0, s71, 0x2000
	s_nop 0
	global_load_lds_dwordx4 v[220:221], off
	v_lshl_add_u64 v[220:221], s[46:47], 0, v[152:153]
	s_mov_b32 m0, s51
	s_nop 0
	global_load_lds_dwordx4 v[220:221], off
	s_mov_b32 m0, s52
	s_nop 0
	global_load_lds_dwordx4 v[222:223], off
	s_waitcnt vmcnt(8)
	s_waitcnt lgkmcnt(0)
	s_barrier
	s_setprio 1
	s_waitcnt lgkmcnt(0)
	v_mfma_f32_16x16x32_bf16 v[70:73], v[62:65], v[184:187], v[70:73]
	v_mfma_f32_16x16x32_bf16 v[58:61], v[138:141], v[184:187], v[58:61]
	v_mfma_f32_16x16x32_bf16 v[42:45], v[138:141], v[192:195], v[42:45]
	v_mfma_f32_16x16x32_bf16 v[46:49], v[62:65], v[192:195], v[46:49]
	v_mfma_f32_16x16x32_bf16 v[30:33], v[62:65], v[200:203], v[30:33]
	v_mfma_f32_16x16x32_bf16 v[26:29], v[138:141], v[200:203], v[26:29]
	v_mfma_f32_16x16x32_bf16 v[10:13], v[138:141], v[208:211], v[10:13]
	v_mfma_f32_16x16x32_bf16 v[14:17], v[62:65], v[208:211], v[14:17]
	v_mfma_f32_16x16x32_bf16 v[70:73], v[66:69], v[188:191], v[70:73]
	v_mfma_f32_16x16x32_bf16 v[58:61], v[142:145], v[188:191], v[58:61]
	v_mfma_f32_16x16x32_bf16 v[42:45], v[142:145], v[196:199], v[42:45]
	v_mfma_f32_16x16x32_bf16 v[46:49], v[66:69], v[196:199], v[46:49]
	v_mfma_f32_16x16x32_bf16 v[30:33], v[66:69], v[204:207], v[30:33]
	v_mfma_f32_16x16x32_bf16 v[26:29], v[142:145], v[204:207], v[26:29]
	v_mfma_f32_16x16x32_bf16 v[10:13], v[142:145], v[212:215], v[10:13]
	v_mfma_f32_16x16x32_bf16 v[14:17], v[66:69], v[212:215], v[14:17]
	s_setprio 0
	s_setprio 1
	v_mfma_f32_16x16x32_bf16 v[54:57], v[162:165], v[184:187], v[54:57]
	v_mfma_f32_16x16x32_bf16 v[50:53], v[176:179], v[184:187], v[50:53]
	v_mfma_f32_16x16x32_bf16 v[34:37], v[176:179], v[192:195], v[34:37]
	v_mfma_f32_16x16x32_bf16 v[38:41], v[162:165], v[192:195], v[38:41]
	v_mfma_f32_16x16x32_bf16 v[22:25], v[162:165], v[200:203], v[22:25]
	v_mfma_f32_16x16x32_bf16 v[18:21], v[176:179], v[200:203], v[18:21]
	v_mfma_f32_16x16x32_bf16 v[2:5], v[176:179], v[208:211], v[2:5]
	v_mfma_f32_16x16x32_bf16 v[6:9], v[162:165], v[208:211], v[6:9]
	v_mfma_f32_16x16x32_bf16 v[54:57], v[172:175], v[188:191], v[54:57]
	v_mfma_f32_16x16x32_bf16 v[50:53], v[180:183], v[188:191], v[50:53]
	v_mfma_f32_16x16x32_bf16 v[34:37], v[180:183], v[196:199], v[34:37]
	v_mfma_f32_16x16x32_bf16 v[38:41], v[172:175], v[196:199], v[38:41]
	v_mfma_f32_16x16x32_bf16 v[22:25], v[172:175], v[204:207], v[22:25]
	v_mfma_f32_16x16x32_bf16 v[18:21], v[180:183], v[204:207], v[18:21]
	v_mfma_f32_16x16x32_bf16 v[2:5], v[180:183], v[212:215], v[2:5]
	v_mfma_f32_16x16x32_bf16 v[6:9], v[172:175], v[212:215], v[6:9]
	s_setprio 0
	s_barrier
; #define PG8_STAGE(bufoff, gbase, voff) do { _Pragma("unroll") for (int _i = 0; _i < 2; ++_i) \
;         __builtin_amdgcn_global_load_lds((const unsigned*)((const char*)(gbase) + (voff)[_i]), (PG8_LAS unsigned*)(lds + (bufoff) + ldsw + _i * 8192), 16, 0, 0); } while (0)
; #define PG8_LDA(dst, b, h) do { _Pragma("unroll") for (int m = 0; m < 4; ++m) _Pragma("unroll") for (int k = 0; k < 2; ++k) dst[m][k] = *(const PG8_LAS bf16x8*)(lds + PG8_SA(b, h) + aoff + m * 2048 + k * 1024); } while (0)
; #define PG8_LDB(dst, b, h) do { _Pragma("unroll") for (int n = 0; n < 2; ++n) _Pragma("unroll") for (int k = 0; k < 2; ++k) dst[n][k] = *(const PG8_LAS bf16x8*)(lds + PG8_SB(b, h) + boff + n * 2048 + k * 1024); } while (0)
; #define PG8_MMA(ai, bj, At, Bt) do { __builtin_amdgcn_s_setprio(1); _Pragma("unroll") for (int m = 0; m < 4; ++m) _Pragma("unroll") for (int n = 0; n < 2; ++n) _Pragma("unroll") for (int k = 0; k < 2; ++k) \
;         acc[ai][bj][m][n] = __builtin_amdgcn_mfma_f32_16x16x32_bf16(Bt[n][k], At[m][k], acc[ai][bj][m][n], 0, 0, 0); __builtin_amdgcn_s_setprio(0); } while (0)
; #define PG8_WAIT_V(n) asm volatile("s_waitcnt vmcnt(" #n ")" ::: "memory")
; #define PG8_WAIT_L(n) asm volatile("s_waitcnt lgkmcnt(" #n ")" ::: "memory")
; #define PG8_BAR __builtin_amdgcn_s_barrier()
; #define PG8_SCHED __builtin_amdgcn_sched_barrier(0)
; template <class Epi, class Sched, bool ALIGN_EPI = false, bool SP2 = false>
; __device__ __forceinline__ void gemm_phase(PG8_LAS unsigned char* lds, const Gemm g, const Sched& S, const Epi& E) {
;     ...
;             PG8_LDB(B0, 1, 0); PG8_LDB(B1, 1, 1); PG8_SCHED; PG8_LDA(At, 1, 0); PG8_STAGE(PG8_SA(0, 1), a2 + hstepA, voffA);
;             PG8_WAIT_V(8); PG8_WAIT_L(0); PG8_BAR; PG8_MMA(0, 0, At, B0); PG8_MMA(0, 1, At, B1); PG8_BAR; PG8_SCHED;
	s_add_i32 s71, 0, 0x18000
	s_add_i32 s72, 0, 0x1c000
	v_add_u32_e32 v142, s71, v166
	v_add_u32_e32 v180, s72, v166
	ds_read_b128 v[62:65], v142
	ds_read_b128 v[66:69], v142 offset:1024
	ds_read_b128 v[138:141], v142 offset:2048
	ds_read_b128 v[142:145], v142 offset:3072
	ds_read_b128 v[162:165], v180
	ds_read_b128 v[172:175], v180 offset:1024
	ds_read_b128 v[176:179], v180 offset:2048
	ds_read_b128 v[180:183], v180 offset:3072
	s_add_u32 s40, s46, 0x28000
	s_addc_u32 s41, s47, 0
	s_mov_b32 m0, s53
	v_lshl_add_u64 v[224:225], s[40:41], 0, v[152:153]
	ds_read_b128 v[184:187], v170 offset:32768
	ds_read_b128 v[188:191], v170 offset:33792
	ds_read_b128 v[192:195], v170 offset:34816
	ds_read_b128 v[196:199], v170 offset:35840
	ds_read_b128 v[200:203], v170 offset:36864
	ds_read_b128 v[204:207], v170 offset:37888
	ds_read_b128 v[208:211], v170 offset:38912
	ds_read_b128 v[212:215], v170 offset:39936
	global_load_lds_dwordx4 v[224:225], off
	v_lshl_add_u64 v[224:225], s[40:41], 0, v[148:149]
	s_mov_b32 m0, s54
	s_nop 0
	global_load_lds_dwordx4 v[224:225], off
	s_waitcnt vmcnt(8)
	s_waitcnt lgkmcnt(0)
	s_barrier
	s_setprio 1
	s_waitcnt lgkmcnt(0)
	v_mfma_f32_16x16x32_bf16 v[134:137], v[62:65], v[184:187], v[134:137]
	v_mfma_f32_16x16x32_bf16 v[130:133], v[138:141], v[184:187], v[130:133]
	v_mfma_f32_16x16x32_bf16 v[114:117], v[138:141], v[192:195], v[114:117]
	v_mfma_f32_16x16x32_bf16 v[118:121], v[62:65], v[192:195], v[118:121]
	v_mfma_f32_16x16x32_bf16 v[102:105], v[62:65], v[200:203], v[102:105]
	v_mfma_f32_16x16x32_bf16 v[98:101], v[138:141], v[200:203], v[98:101]
	v_mfma_f32_16x16x32_bf16 v[82:85], v[138:141], v[208:211], v[82:85]
	v_mfma_f32_16x16x32_bf16 v[86:89], v[62:65], v[208:211], v[86:89]
	v_mfma_f32_16x16x32_bf16 v[134:137], v[66:69], v[188:191], v[134:137]
	v_mfma_f32_16x16x32_bf16 v[130:133], v[142:145], v[188:191], v[130:133]
	v_mfma_f32_16x16x32_bf16 v[114:117], v[142:145], v[196:199], v[114:117]
	v_mfma_f32_16x16x32_bf16 v[118:121], v[66:69], v[196:199], v[118:121]
	v_mfma_f32_16x16x32_bf16 v[102:105], v[66:69], v[204:207], v[102:105]
	v_mfma_f32_16x16x32_bf16 v[98:101], v[142:145], v[204:207], v[98:101]
	v_mfma_f32_16x16x32_bf16 v[82:85], v[142:145], v[212:215], v[82:85]
	v_mfma_f32_16x16x32_bf16 v[86:89], v[66:69], v[212:215], v[86:89]
	s_setprio 0
	s_setprio 1
	v_mfma_f32_16x16x32_bf16 v[126:129], v[162:165], v[184:187], v[126:129]
	v_mfma_f32_16x16x32_bf16 v[122:125], v[176:179], v[184:187], v[122:125]
	v_mfma_f32_16x16x32_bf16 v[106:109], v[176:179], v[192:195], v[106:109]
	v_mfma_f32_16x16x32_bf16 v[110:113], v[162:165], v[192:195], v[110:113]
	v_mfma_f32_16x16x32_bf16 v[94:97], v[162:165], v[200:203], v[94:97]
	v_mfma_f32_16x16x32_bf16 v[90:93], v[176:179], v[200:203], v[90:93]
	v_mfma_f32_16x16x32_bf16 v[74:77], v[176:179], v[208:211], v[74:77]
	v_mfma_f32_16x16x32_bf16 v[78:81], v[162:165], v[208:211], v[78:81]
	v_mfma_f32_16x16x32_bf16 v[126:129], v[172:175], v[188:191], v[126:129]
	v_mfma_f32_16x16x32_bf16 v[122:125], v[180:183], v[188:191], v[122:125]
	v_mfma_f32_16x16x32_bf16 v[106:109], v[180:183], v[196:199], v[106:109]
	v_mfma_f32_16x16x32_bf16 v[110:113], v[172:175], v[196:199], v[110:113]
	v_mfma_f32_16x16x32_bf16 v[94:97], v[172:175], v[204:207], v[94:97]
	v_mfma_f32_16x16x32_bf16 v[90:93], v[180:183], v[204:207], v[90:93]
	v_mfma_f32_16x16x32_bf16 v[74:77], v[180:183], v[212:215], v[74:77]
	v_mfma_f32_16x16x32_bf16 v[78:81], v[172:175], v[212:215], v[78:81]
	s_setprio 0
	s_barrier
; #define PG8_STAGE(bufoff, gbase, voff) do { _Pragma("unroll") for (int _i = 0; _i < 2; ++_i) \
;         __builtin_amdgcn_global_load_lds((const unsigned*)((const char*)(gbase) + (voff)[_i]), (PG8_LAS unsigned*)(lds + (bufoff) + ldsw + _i * 8192), 16, 0, 0); } while (0)
; #define PG8_LDA(dst, b, h) do { _Pragma("unroll") for (int m = 0; m < 4; ++m) _Pragma("unroll") for (int k = 0; k < 2; ++k) dst[m][k] = *(const PG8_LAS bf16x8*)(lds + PG8_SA(b, h) + aoff + m * 2048 + k * 1024); } while (0)
; #define PG8_MMA(ai, bj, At, Bt) do { __builtin_amdgcn_s_setprio(1); _Pragma("unroll") for (int m = 0; m < 4; ++m) _Pragma("unroll") for (int n = 0; n < 2; ++n) _Pragma("unroll") for (int k = 0; k < 2; ++k) \
;         acc[ai][bj][m][n] = __builtin_amdgcn_mfma_f32_16x16x32_bf16(Bt[n][k], At[m][k], acc[ai][bj][m][n], 0, 0, 0); __builtin_amdgcn_s_setprio(0); } while (0)
; #define PG8_WAIT_V(n) asm volatile("s_waitcnt vmcnt(" #n ")" ::: "memory")
; #define PG8_WAIT_L(n) asm volatile("s_waitcnt lgkmcnt(" #n ")" ::: "memory")
; #define PG8_BAR __builtin_amdgcn_s_barrier()
; #define PG8_SCHED __builtin_amdgcn_sched_barrier(0)
; template <class Epi, class Sched, bool ALIGN_EPI = false, bool SP2 = false>
; __device__ __forceinline__ void gemm_phase(PG8_LAS unsigned char* lds, const Gemm g, const Sched& S, const Epi& E) {
;     ...
;         for (int t = 0; t < nt; t += 2) {
;     ...
;             PG8_LDA(At, 1, 1); PG8_STAGE(PG8_SB(1, 0), b3, voffB); PG8_STAGE(PG8_SB(1, 1), b3 + hstepB, voffB); PG8_STAGE(PG8_SA(1, 0), a3, voffA);
;             PG8_WAIT_V(8); PG8_WAIT_L(0); PG8_BAR; PG8_MMA(1, 0, At, B0); PG8_MMA(1, 1, At, B1); PG8_BAR; PG8_SCHED;
	s_add_i32 s40, s71, s48
	v_lshl_add_u64 v[216:217], v[216:217], 0, s[16:17]
	s_mov_b32 m0, s40
	ds_read_b128 v[184:187], v170 offset:49152
	ds_read_b128 v[188:191], v170 offset:50176
	ds_read_b128 v[192:195], v170 offset:51200
	ds_read_b128 v[196:199], v170 offset:52224
	ds_read_b128 v[200:203], v170 offset:53248
	ds_read_b128 v[204:207], v170 offset:54272
	ds_read_b128 v[208:211], v170 offset:55296
	ds_read_b128 v[212:215], v170 offset:56320
	global_load_lds_dwordx4 v[216:217], off
	s_add_i32 m0, s40, 0x2000
	s_add_u32 s40, s44, 0x28080
	v_lshl_add_u64 v[216:217], v[218:219], 0, s[16:17]
	s_addc_u32 s41, s45, 0
	s_add_i32 s44, s72, s48
	global_load_lds_dwordx4 v[216:217], off
	v_lshl_add_u64 v[216:217], s[40:41], 0, v[150:151]
	s_mov_b32 m0, s44
	s_nop 0
	global_load_lds_dwordx4 v[216:217], off
	v_lshl_add_u64 v[216:217], s[40:41], 0, v[146:147]
	s_add_i32 m0, s44, 0x2000
	s_nop 0
	global_load_lds_dwordx4 v[216:217], off
	v_lshl_add_u64 v[216:217], v[220:221], 0, s[16:17]
	s_mov_b32 m0, s56
	s_nop 0
	global_load_lds_dwordx4 v[216:217], off
	v_lshl_add_u64 v[216:217], v[222:223], 0, s[16:17]
	s_mov_b32 m0, s57
	s_nop 0
	global_load_lds_dwordx4 v[216:217], off
	s_waitcnt vmcnt(8)
	s_waitcnt lgkmcnt(0)
	s_barrier
	s_setprio 1
	s_waitcnt lgkmcnt(0)
	v_mfma_f32_16x16x32_bf16 v[70:73], v[62:65], v[184:187], v[70:73]
	v_mfma_f32_16x16x32_bf16 v[58:61], v[138:141], v[184:187], v[58:61]
	v_mfma_f32_16x16x32_bf16 v[42:45], v[138:141], v[192:195], v[42:45]
	v_mfma_f32_16x16x32_bf16 v[46:49], v[62:65], v[192:195], v[46:49]
	v_mfma_f32_16x16x32_bf16 v[30:33], v[62:65], v[200:203], v[30:33]
	v_mfma_f32_16x16x32_bf16 v[26:29], v[138:141], v[200:203], v[26:29]
	v_mfma_f32_16x16x32_bf16 v[10:13], v[138:141], v[208:211], v[10:13]
	v_mfma_f32_16x16x32_bf16 v[14:17], v[62:65], v[208:211], v[14:17]
	v_mfma_f32_16x16x32_bf16 v[70:73], v[66:69], v[188:191], v[70:73]
	v_mfma_f32_16x16x32_bf16 v[58:61], v[142:145], v[188:191], v[58:61]
	v_mfma_f32_16x16x32_bf16 v[42:45], v[142:145], v[196:199], v[42:45]
	v_mfma_f32_16x16x32_bf16 v[46:49], v[66:69], v[196:199], v[46:49]
	v_mfma_f32_16x16x32_bf16 v[30:33], v[66:69], v[204:207], v[30:33]
	v_mfma_f32_16x16x32_bf16 v[26:29], v[142:145], v[204:207], v[26:29]
	v_mfma_f32_16x16x32_bf16 v[10:13], v[142:145], v[212:215], v[10:13]
	v_mfma_f32_16x16x32_bf16 v[14:17], v[66:69], v[212:215], v[14:17]
	s_setprio 0
	s_setprio 1
	v_mfma_f32_16x16x32_bf16 v[54:57], v[162:165], v[184:187], v[54:57]
	v_mfma_f32_16x16x32_bf16 v[50:53], v[176:179], v[184:187], v[50:53]
	v_mfma_f32_16x16x32_bf16 v[34:37], v[176:179], v[192:195], v[34:37]
	v_mfma_f32_16x16x32_bf16 v[38:41], v[162:165], v[192:195], v[38:41]
	v_mfma_f32_16x16x32_bf16 v[22:25], v[162:165], v[200:203], v[22:25]
	v_mfma_f32_16x16x32_bf16 v[18:21], v[176:179], v[200:203], v[18:21]
	v_mfma_f32_16x16x32_bf16 v[2:5], v[176:179], v[208:211], v[2:5]
	v_mfma_f32_16x16x32_bf16 v[6:9], v[162:165], v[208:211], v[6:9]
	v_mfma_f32_16x16x32_bf16 v[54:57], v[172:175], v[188:191], v[54:57]
	v_mfma_f32_16x16x32_bf16 v[50:53], v[180:183], v[188:191], v[50:53]
	v_mfma_f32_16x16x32_bf16 v[34:37], v[180:183], v[196:199], v[34:37]
	v_mfma_f32_16x16x32_bf16 v[38:41], v[172:175], v[196:199], v[38:41]
	v_mfma_f32_16x16x32_bf16 v[22:25], v[172:175], v[204:207], v[22:25]
	v_mfma_f32_16x16x32_bf16 v[18:21], v[180:183], v[204:207], v[18:21]
	v_mfma_f32_16x16x32_bf16 v[2:5], v[180:183], v[212:215], v[2:5]
	v_mfma_f32_16x16x32_bf16 v[6:9], v[172:175], v[212:215], v[6:9]
	s_setprio 0
	s_barrier
	s_add_i32 s33, s33, 2
	s_add_u32 s2, s2, 0x100
	s_addc_u32 s5, s5, 0
	s_cmp_gt_u32 s33, 7
	s_mov_b64 s[40:41], s[42:43]
	s_cbranch_scc0 .LBB0_430
	s_and_b64 vcc, exec, s[18:19]
	s_cbranch_vccz .LBB0_433
	s_barrier

; #define PG8_STAGE(bufoff, gbase, voff) do { _Pragma("unroll") for (int _i = 0; _i < 2; ++_i) \
;         __builtin_amdgcn_global_load_lds((const unsigned*)((const char*)(gbase) + (voff)[_i]), (PG8_LAS unsigned*)(lds + (bufoff) + ldsw + _i * 8192), 16, 0, 0); } while (0)
; #define PG8_LDA(dst, b, h) do { _Pragma("unroll") for (int m = 0; m < 4; ++m) _Pragma("unroll") for (int k = 0; k < 2; ++k) dst[m][k] = *(const PG8_LAS bf16x8*)(lds + PG8_SA(b, h) + aoff + m * 2048 + k * 1024); } while (0)
; #define PG8_LDB(dst, b, h) do { _Pragma("unroll") for (int n = 0; n < 2; ++n) _Pragma("unroll") for (int k = 0; k < 2; ++k) dst[n][k] = *(const PG8_LAS bf16x8*)(lds + PG8_SB(b, h) + boff + n * 2048 + k * 1024); } while (0)
; #define PG8_WAIT_V(n) asm volatile("s_waitcnt vmcnt(" #n ")" ::: "memory")
; #define PG8_WAIT_L(n) asm volatile("s_waitcnt lgkmcnt(" #n ")" ::: "memory")
; #define PG8_BAR __builtin_amdgcn_s_barrier()
; template <class Epi, class Sched, bool ALIGN_EPI = false, bool SP2 = false>
; __device__ __forceinline__ void gemm_phase(PG8_LAS unsigned char* lds, const Gemm g, const Sched& S, const Epi& E) {
;     ...
;         const bool has_next = S.next(ui + 1, nxt);
;         const char* nA = has_next ? (const char*)g.A + (size_t)nxt.g * g.gsA * 2 + (size_t)nxt.pm * tstepA : cA; const char* nB = has_next ? (const char*)g.Bt + (size_t)nxt.g * g.gsB * 2 + (size_t)nxt.pn * tstepB : cB;
;         for (int t = 0; t < nt; t += 2) {
;             const bool last = (t == nt - 2);
;             const char* a1 = cA + (size_t)(t + 1) * kstep;
;             const char* a2 = last ? nA : cA + (size_t)(t + 2) * kstep; const char* b2 = last ? nB : cB + (size_t)(t + 2) * kstep;
;             const char* a3 = a2 + kstep; const char* b3 = b2 + kstep;
;             if (last && has_next) S.a_ready(nxt);
;             if constexpr (SP2) {
;             PG8_LDB(B0, 0, 0); PG8_LDB(B1, 0, 1); PG8_SCHED; PG8_LDA(At, 0, 0); PG8_STAGE(PG8_SA(1, 1), a1 + hstepA, voffA);
;             PG8_WAIT_V(8); PG8_WAIT_L(0); PG8_BAR; PG8_MMA(0, 0, At, B0); PG8_MMA(0, 1, At, B1); PG8_BAR; PG8_SCHED;
;             PG8_LDA(At, 0, 1); PG8_STAGE(PG8_SB(0, 0), b2, voffB); PG8_STAGE(PG8_SB(0, 1), b2 + hstepB, voffB); PG8_STAGE(PG8_SA(0, 0), a2, voffA);
;             PG8_WAIT_V(8); PG8_WAIT_L(0); PG8_BAR; PG8_MMA(1, 0, At, B0); PG8_MMA(1, 1, At, B1); PG8_BAR; PG8_SCHED;
.LBB0_522:
	s_ashr_i32 s19, s18, 31
	s_lshl_b64 s[20:21], s[18:19], 18
	s_add_u32 s20, s8, s20
	s_addc_u32 s21, s9, s21
	s_and_b64 s[22:23], s[6:7], exec
	s_cselect_b32 s19, s21, s27
	s_cselect_b32 s44, s20, s26
	s_ashr_i32 s17, s16, 31
	s_lshl_b64 s[22:23], s[16:17], 18
	s_add_u32 s22, s33, s22
	s_addc_u32 s23, s34, s23
	s_and_b64 s[30:31], s[6:7], exec
	s_cselect_b32 s17, s23, s29
	s_cselect_b32 s45, s22, s28
	s_add_u32 s26, s26, 0x20080
	s_addc_u32 s27, s27, 0
	s_add_u32 s46, s28, 0x100
	s_addc_u32 s47, s29, 0
	s_mov_b32 s48, -2
	s_waitcnt lgkmcnt(0)
	ds_read_b128 v[146:149], v152
	ds_read_b128 v[156:159], v152 offset:1024
	ds_read_b128 v[160:163], v152 offset:2048
	ds_read_b128 v[164:167], v152 offset:3072
	ds_read_b128 v[168:171], v153
	ds_read_b128 v[172:175], v153 offset:1024
	ds_read_b128 v[176:179], v153 offset:2048
	ds_read_b128 v[180:183], v153 offset:3072
	s_add_u32 s28, s26, 0xfffe0080
	s_addc_u32 s29, s27, -1
	s_cmp_eq_u32 s48, 4
	s_cselect_b32 s31, s19, s29
	s_cselect_b32 s30, s44, s28
	s_cselect_b32 s29, s17, s47
	s_cselect_b32 s28, s45, s46
	v_lshl_add_u64 v[216:217], s[26:27], 0, v[138:139]
	s_add_i32 m0, s25, 0xc000
	ds_read_b128 v[184:187], v154
	ds_read_b128 v[188:191], v154 offset:1024
	ds_read_b128 v[192:195], v154 offset:2048
	ds_read_b128 v[196:199], v154 offset:3072
	ds_read_b128 v[200:203], v154 offset:4096
	ds_read_b128 v[204:207], v154 offset:5120
	ds_read_b128 v[208:211], v154 offset:6144
	ds_read_b128 v[212:215], v154 offset:7168
	global_load_lds_dwordx4 v[216:217], off
	v_lshl_add_u64 v[216:217], s[26:27], 0, v[140:141]
	s_add_i32 m0, s25, 0xe000
	s_nop 0
	global_load_lds_dwordx4 v[216:217], off
	s_waitcnt vmcnt(8)
	s_waitcnt lgkmcnt(0)
	s_barrier
	s_setprio 1
	s_waitcnt lgkmcnt(0)
	v_mfma_f32_16x16x32_bf16 v[126:129], v[146:149], v[184:187], 0
	v_mfma_f32_16x16x32_bf16 v[122:125], v[160:163], v[184:187], 0
	v_mfma_f32_16x16x32_bf16 v[106:109], v[160:163], v[192:195], 0
	v_mfma_f32_16x16x32_bf16 v[110:113], v[146:149], v[192:195], 0
	v_mfma_f32_16x16x32_bf16 v[94:97], v[146:149], v[200:203], 0
	v_mfma_f32_16x16x32_bf16 v[90:93], v[160:163], v[200:203], 0
	v_mfma_f32_16x16x32_bf16 v[74:77], v[160:163], v[208:211], 0
	v_mfma_f32_16x16x32_bf16 v[78:81], v[146:149], v[208:211], 0
	v_mfma_f32_16x16x32_bf16 v[126:129], v[156:159], v[188:191], v[126:129]
	v_mfma_f32_16x16x32_bf16 v[122:125], v[164:167], v[188:191], v[122:125]
	v_mfma_f32_16x16x32_bf16 v[106:109], v[164:167], v[196:199], v[106:109]
	v_mfma_f32_16x16x32_bf16 v[110:113], v[156:159], v[196:199], v[110:113]
	v_mfma_f32_16x16x32_bf16 v[94:97], v[156:159], v[204:207], v[94:97]
	v_mfma_f32_16x16x32_bf16 v[90:93], v[164:167], v[204:207], v[90:93]
	v_mfma_f32_16x16x32_bf16 v[74:77], v[164:167], v[212:215], v[74:77]
	v_mfma_f32_16x16x32_bf16 v[78:81], v[156:159], v[212:215], v[78:81]
	s_setprio 0
	s_setprio 1
	v_mfma_f32_16x16x32_bf16 v[118:121], v[168:171], v[184:187], 0
	v_mfma_f32_16x16x32_bf16 v[114:117], v[176:179], v[184:187], 0
	v_mfma_f32_16x16x32_bf16 v[98:101], v[176:179], v[192:195], 0
	v_mfma_f32_16x16x32_bf16 v[102:105], v[168:171], v[192:195], 0
	v_mfma_f32_16x16x32_bf16 v[86:89], v[168:171], v[200:203], 0
	v_mfma_f32_16x16x32_bf16 v[82:85], v[176:179], v[200:203], 0
	v_mfma_f32_16x16x32_bf16 v[66:69], v[176:179], v[208:211], 0
	v_mfma_f32_16x16x32_bf16 v[70:73], v[168:171], v[208:211], 0
	v_mfma_f32_16x16x32_bf16 v[118:121], v[172:175], v[188:191], v[118:121]
	v_mfma_f32_16x16x32_bf16 v[114:117], v[180:183], v[188:191], v[114:117]
	v_mfma_f32_16x16x32_bf16 v[98:101], v[180:183], v[196:199], v[98:101]
	v_mfma_f32_16x16x32_bf16 v[102:105], v[172:175], v[196:199], v[102:105]
	v_mfma_f32_16x16x32_bf16 v[86:89], v[172:175], v[204:207], v[86:89]
	v_mfma_f32_16x16x32_bf16 v[82:85], v[180:183], v[204:207], v[82:85]
	v_mfma_f32_16x16x32_bf16 v[66:69], v[180:183], v[212:215], v[66:69]
	v_mfma_f32_16x16x32_bf16 v[70:73], v[172:175], v[212:215], v[70:73]
	s_setprio 0
	s_barrier
	s_add_i32 s49, s41, s2
	v_lshl_add_u64 v[216:217], s[28:29], 0, v[132:133]
	s_mov_b32 m0, s49
	ds_read_b128 v[184:187], v154 offset:16384
	ds_read_b128 v[188:191], v154 offset:17408
	ds_read_b128 v[192:195], v154 offset:18432
	ds_read_b128 v[196:199], v154 offset:19456
	ds_read_b128 v[200:203], v154 offset:20480
	ds_read_b128 v[204:207], v154 offset:21504
	ds_read_b128 v[208:211], v154 offset:22528
	ds_read_b128 v[212:215], v154 offset:23552
	global_load_lds_dwordx4 v[216:217], off
	s_add_i32 m0, s49, 0x2000
	s_add_u32 s50, s28, 0x20000
	v_lshl_add_u64 v[218:219], s[28:29], 0, v[136:137]
	s_addc_u32 s51, s29, 0
	s_add_i32 s49, s42, s2
	global_load_lds_dwordx4 v[218:219], off
	v_lshl_add_u64 v[220:221], s[50:51], 0, v[132:133]
	s_mov_b32 m0, s49
	v_lshl_add_u64 v[222:223], s[30:31], 0, v[134:135]
	global_load_lds_dwordx4 v[220:221], off
	v_lshl_add_u64 v[220:221], s[50:51], 0, v[136:137]
	s_add_i32 m0, s49, 0x2000
	s_nop 0
	global_load_lds_dwordx4 v[220:221], off
	v_lshl_add_u64 v[220:221], s[30:31], 0, v[130:131]
	s_mov_b32 m0, s25
	s_nop 0
	global_load_lds_dwordx4 v[220:221], off
	s_mov_b32 m0, s35
	s_nop 0
	global_load_lds_dwordx4 v[222:223], off
	s_waitcnt vmcnt(8)
	s_waitcnt lgkmcnt(0)
	s_barrier
; #define PG8_STAGE(bufoff, gbase, voff) do { _Pragma("unroll") for (int _i = 0; _i < 2; ++_i) \
;         __builtin_amdgcn_global_load_lds((const unsigned*)((const char*)(gbase) + (voff)[_i]), (PG8_LAS unsigned*)(lds + (bufoff) + ldsw + _i * 8192), 16, 0, 0); } while (0)
; #define PG8_LDA(dst, b, h) do { _Pragma("unroll") for (int m = 0; m < 4; ++m) _Pragma("unroll") for (int k = 0; k < 2; ++k) dst[m][k] = *(const PG8_LAS bf16x8*)(lds + PG8_SA(b, h) + aoff + m * 2048 + k * 1024); } while (0)
; #define PG8_LDB(dst, b, h) do { _Pragma("unroll") for (int n = 0; n < 2; ++n) _Pragma("unroll") for (int k = 0; k < 2; ++k) dst[n][k] = *(const PG8_LAS bf16x8*)(lds + PG8_SB(b, h) + boff + n * 2048 + k * 1024); } while (0)
; #define PG8_MMA(ai, bj, At, Bt) do { __builtin_amdgcn_s_setprio(1); _Pragma("unroll") for (int m = 0; m < 4; ++m) _Pragma("unroll") for (int n = 0; n < 2; ++n) _Pragma("unroll") for (int k = 0; k < 2; ++k) \
;         acc[ai][bj][m][n] = __builtin_amdgcn_mfma_f32_16x16x32_bf16(Bt[n][k], At[m][k], acc[ai][bj][m][n], 0, 0, 0); __builtin_amdgcn_s_setprio(0); } while (0)
; #define PG8_WAIT_V(n) asm volatile("s_waitcnt vmcnt(" #n ")" ::: "memory")
; #define PG8_WAIT_L(n) asm volatile("s_waitcnt lgkmcnt(" #n ")" ::: "memory")
; #define PG8_BAR __builtin_amdgcn_s_barrier()
; #define PG8_SCHED __builtin_amdgcn_sched_barrier(0)
; template <class Epi, class Sched, bool ALIGN_EPI = false, bool SP2 = false>
; __device__ __forceinline__ void gemm_phase(PG8_LAS unsigned char* lds, const Gemm g, const Sched& S, const Epi& E) {
;     ...
;             PG8_WAIT_V(8); PG8_WAIT_L(0); PG8_BAR; PG8_MMA(0, 0, At, B0); PG8_MMA(0, 1, At, B1); PG8_BAR; PG8_SCHED;
;             PG8_LDA(At, 0, 1); PG8_STAGE(PG8_SB(0, 0), b2, voffB); PG8_STAGE(PG8_SB(0, 1), b2 + hstepB, voffB); PG8_STAGE(PG8_SA(0, 0), a2, voffA);
;             PG8_WAIT_V(8); PG8_WAIT_L(0); PG8_BAR; PG8_MMA(1, 0, At, B0); PG8_MMA(1, 1, At, B1); PG8_BAR; PG8_SCHED;
;             PG8_LDB(B0, 1, 0); PG8_LDB(B1, 1, 1); PG8_SCHED; PG8_LDA(At, 1, 0); PG8_STAGE(PG8_SA(0, 1), a2 + hstepA, voffA);
;             PG8_WAIT_V(8); PG8_WAIT_L(0); PG8_BAR; PG8_MMA(0, 0, At, B0); PG8_MMA(0, 1, At, B1); PG8_BAR; PG8_SCHED;
	s_setprio 1
	s_waitcnt lgkmcnt(0)
	v_mfma_f32_16x16x32_bf16 v[62:65], v[146:149], v[184:187], 0
	v_mfma_f32_16x16x32_bf16 v[58:61], v[160:163], v[184:187], 0
	v_mfma_f32_16x16x32_bf16 v[42:45], v[160:163], v[192:195], 0
	v_mfma_f32_16x16x32_bf16 v[46:49], v[146:149], v[192:195], 0
	v_mfma_f32_16x16x32_bf16 v[30:33], v[146:149], v[200:203], 0
	v_mfma_f32_16x16x32_bf16 v[26:29], v[160:163], v[200:203], 0
	v_mfma_f32_16x16x32_bf16 v[10:13], v[160:163], v[208:211], 0
	v_mfma_f32_16x16x32_bf16 v[14:17], v[146:149], v[208:211], 0
	v_mfma_f32_16x16x32_bf16 v[62:65], v[156:159], v[188:191], v[62:65]
	v_mfma_f32_16x16x32_bf16 v[58:61], v[164:167], v[188:191], v[58:61]
	v_mfma_f32_16x16x32_bf16 v[42:45], v[164:167], v[196:199], v[42:45]
	v_mfma_f32_16x16x32_bf16 v[46:49], v[156:159], v[196:199], v[46:49]
	v_mfma_f32_16x16x32_bf16 v[30:33], v[156:159], v[204:207], v[30:33]
	v_mfma_f32_16x16x32_bf16 v[26:29], v[164:167], v[204:207], v[26:29]
	v_mfma_f32_16x16x32_bf16 v[10:13], v[164:167], v[212:215], v[10:13]
	v_mfma_f32_16x16x32_bf16 v[14:17], v[156:159], v[212:215], v[14:17]
	s_setprio 0
	s_setprio 1
	v_mfma_f32_16x16x32_bf16 v[54:57], v[168:171], v[184:187], 0
	v_mfma_f32_16x16x32_bf16 v[50:53], v[176:179], v[184:187], 0
	v_mfma_f32_16x16x32_bf16 v[34:37], v[176:179], v[192:195], 0
	v_mfma_f32_16x16x32_bf16 v[38:41], v[168:171], v[192:195], 0
	v_mfma_f32_16x16x32_bf16 v[22:25], v[168:171], v[200:203], 0
	v_mfma_f32_16x16x32_bf16 v[18:21], v[176:179], v[200:203], 0
	v_mfma_f32_16x16x32_bf16 v[2:5], v[176:179], v[208:211], 0
	v_mfma_f32_16x16x32_bf16 v[6:9], v[168:171], v[208:211], 0
	v_mfma_f32_16x16x32_bf16 v[54:57], v[172:175], v[188:191], v[54:57]
	v_mfma_f32_16x16x32_bf16 v[50:53], v[180:183], v[188:191], v[50:53]
	v_mfma_f32_16x16x32_bf16 v[34:37], v[180:183], v[196:199], v[34:37]
	v_mfma_f32_16x16x32_bf16 v[38:41], v[172:175], v[196:199], v[38:41]
	v_mfma_f32_16x16x32_bf16 v[22:25], v[172:175], v[204:207], v[22:25]
	v_mfma_f32_16x16x32_bf16 v[18:21], v[180:183], v[204:207], v[18:21]
	v_mfma_f32_16x16x32_bf16 v[2:5], v[180:183], v[212:215], v[2:5]
	v_mfma_f32_16x16x32_bf16 v[6:9], v[172:175], v[212:215], v[6:9]
	s_setprio 0
	s_barrier
	s_add_i32 s49, 0, 0x18000
	v_add_u32_e32 v155, s49, v150
	s_add_i32 s50, 0, 0x1c000
	ds_read_b128 v[146:149], v155
	ds_read_b128 v[156:159], v155 offset:1024
	ds_read_b128 v[160:163], v155 offset:2048
	ds_read_b128 v[164:167], v155 offset:3072
	v_add_u32_e32 v155, s50, v150
	ds_read_b128 v[168:171], v155
	ds_read_b128 v[172:175], v155 offset:1024
	ds_read_b128 v[176:179], v155 offset:2048
	ds_read_b128 v[180:183], v155 offset:3072
	s_add_u32 s30, s30, 0x20000
	s_addc_u32 s31, s31, 0
	s_mov_b32 m0, s36
	v_lshl_add_u64 v[224:225], s[30:31], 0, v[130:131]
	ds_read_b128 v[184:187], v154 offset:32768
	ds_read_b128 v[188:191], v154 offset:33792
	ds_read_b128 v[192:195], v154 offset:34816
	ds_read_b128 v[196:199], v154 offset:35840
	ds_read_b128 v[200:203], v154 offset:36864
	ds_read_b128 v[204:207], v154 offset:37888
	ds_read_b128 v[208:211], v154 offset:38912
	ds_read_b128 v[212:215], v154 offset:39936
	global_load_lds_dwordx4 v[224:225], off
	v_lshl_add_u64 v[224:225], s[30:31], 0, v[134:135]
	s_mov_b32 m0, s37
	s_nop 0
	global_load_lds_dwordx4 v[224:225], off
	s_waitcnt vmcnt(8)
	s_waitcnt lgkmcnt(0)
	s_barrier
	s_setprio 1
	s_waitcnt lgkmcnt(0)
	v_mfma_f32_16x16x32_bf16 v[126:129], v[146:149], v[184:187], v[126:129]
	v_mfma_f32_16x16x32_bf16 v[122:125], v[160:163], v[184:187], v[122:125]
	v_mfma_f32_16x16x32_bf16 v[106:109], v[160:163], v[192:195], v[106:109]
	v_mfma_f32_16x16x32_bf16 v[110:113], v[146:149], v[192:195], v[110:113]
	v_mfma_f32_16x16x32_bf16 v[94:97], v[146:149], v[200:203], v[94:97]
	v_mfma_f32_16x16x32_bf16 v[90:93], v[160:163], v[200:203], v[90:93]
	v_mfma_f32_16x16x32_bf16 v[74:77], v[160:163], v[208:211], v[74:77]
	v_mfma_f32_16x16x32_bf16 v[78:81], v[146:149], v[208:211], v[78:81]
	v_mfma_f32_16x16x32_bf16 v[126:129], v[156:159], v[188:191], v[126:129]
	v_mfma_f32_16x16x32_bf16 v[122:125], v[164:167], v[188:191], v[122:125]
	v_mfma_f32_16x16x32_bf16 v[106:109], v[164:167], v[196:199], v[106:109]
	v_mfma_f32_16x16x32_bf16 v[110:113], v[156:159], v[196:199], v[110:113]
	v_mfma_f32_16x16x32_bf16 v[94:97], v[156:159], v[204:207], v[94:97]
	v_mfma_f32_16x16x32_bf16 v[90:93], v[164:167], v[204:207], v[90:93]
	v_mfma_f32_16x16x32_bf16 v[74:77], v[164:167], v[212:215], v[74:77]
	v_mfma_f32_16x16x32_bf16 v[78:81], v[156:159], v[212:215], v[78:81]
	s_setprio 0
	s_setprio 1
	v_mfma_f32_16x16x32_bf16 v[118:121], v[168:171], v[184:187], v[118:121]
	v_mfma_f32_16x16x32_bf16 v[114:117], v[176:179], v[184:187], v[114:117]
	v_mfma_f32_16x16x32_bf16 v[98:101], v[176:179], v[192:195], v[98:101]
	v_mfma_f32_16x16x32_bf16 v[102:105], v[168:171], v[192:195], v[102:105]
	v_mfma_f32_16x16x32_bf16 v[86:89], v[168:171], v[200:203], v[86:89]
	v_mfma_f32_16x16x32_bf16 v[82:85], v[176:179], v[200:203], v[82:85]
	v_mfma_f32_16x16x32_bf16 v[66:69], v[176:179], v[208:211], v[66:69]
	v_mfma_f32_16x16x32_bf16 v[70:73], v[168:171], v[208:211], v[70:73]
	v_mfma_f32_16x16x32_bf16 v[118:121], v[172:175], v[188:191], v[118:121]
	v_mfma_f32_16x16x32_bf16 v[114:117], v[180:183], v[188:191], v[114:117]
	v_mfma_f32_16x16x32_bf16 v[98:101], v[180:183], v[196:199], v[98:101]
	v_mfma_f32_16x16x32_bf16 v[102:105], v[172:175], v[196:199], v[102:105]
	v_mfma_f32_16x16x32_bf16 v[86:89], v[172:175], v[204:207], v[86:89]
	v_mfma_f32_16x16x32_bf16 v[82:85], v[180:183], v[204:207], v[82:85]
	v_mfma_f32_16x16x32_bf16 v[66:69], v[180:183], v[212:215], v[66:69]
	v_mfma_f32_16x16x32_bf16 v[70:73], v[172:175], v[212:215], v[70:73]
	s_setprio 0
	s_barrier
; #define PG8_STAGE(bufoff, gbase, voff) do { _Pragma("unroll") for (int _i = 0; _i < 2; ++_i) \
;         __builtin_amdgcn_global_load_lds((const unsigned*)((const char*)(gbase) + (voff)[_i]), (PG8_LAS unsigned*)(lds + (bufoff) + ldsw + _i * 8192), 16, 0, 0); } while (0)
; #define PG8_LDA(dst, b, h) do { _Pragma("unroll") for (int m = 0; m < 4; ++m) _Pragma("unroll") for (int k = 0; k < 2; ++k) dst[m][k] = *(const PG8_LAS bf16x8*)(lds + PG8_SA(b, h) + aoff + m * 2048 + k * 1024); } while (0)
; #define PG8_LDB(dst, b, h) do { _Pragma("unroll") for (int n = 0; n < 2; ++n) _Pragma("unroll") for (int k = 0; k < 2; ++k) dst[n][k] = *(const PG8_LAS bf16x8*)(lds + PG8_SB(b, h) + boff + n * 2048 + k * 1024); } while (0)
; #define PG8_WAIT_V(n) asm volatile("s_waitcnt vmcnt(" #n ")" ::: "memory")
; #define PG8_WAIT_L(n) asm volatile("s_waitcnt lgkmcnt(" #n ")" ::: "memory")
; #define PG8_BAR __builtin_amdgcn_s_barrier()
; template <class Epi, class Sched, bool ALIGN_EPI = false, bool SP2 = false>
; __device__ __forceinline__ void gemm_phase(PG8_LAS unsigned char* lds, const Gemm g, const Sched& S, const Epi& E) {
;     ...
;         for (int t = 0; t < nt; t += 2) {
;             const bool last = (t == nt - 2);
;             const char* a1 = cA + (size_t)(t + 1) * kstep;
;             const char* a2 = last ? nA : cA + (size_t)(t + 2) * kstep; const char* b2 = last ? nB : cB + (size_t)(t + 2) * kstep;
;             const char* a3 = a2 + kstep; const char* b3 = b2 + kstep;
;             if (last && has_next) S.a_ready(nxt);
;             if constexpr (SP2) {
;             PG8_LDB(B0, 0, 0); PG8_LDB(B1, 0, 1); PG8_SCHED; PG8_LDA(At, 0, 0); PG8_STAGE(PG8_SA(1, 1), a1 + hstepA, voffA);
;             PG8_WAIT_V(8); PG8_WAIT_L(0); PG8_BAR; PG8_MMA(0, 0, At, B0); PG8_MMA(0, 1, At, B1); PG8_BAR; PG8_SCHED;
;             PG8_LDA(At, 0, 1); PG8_STAGE(PG8_SB(0, 0), b2, voffB); PG8_STAGE(PG8_SB(0, 1), b2 + hstepB, voffB); PG8_STAGE(PG8_SA(0, 0), a2, voffA);
;             PG8_WAIT_V(8); PG8_WAIT_L(0); PG8_BAR; PG8_MMA(1, 0, At, B0); PG8_MMA(1, 1, At, B1); PG8_BAR; PG8_SCHED;
;     ...
;             PG8_LDA(At, 1, 1); PG8_STAGE(PG8_SB(1, 0), b3, voffB); PG8_STAGE(PG8_SB(1, 1), b3 + hstepB, voffB); PG8_STAGE(PG8_SA(1, 0), a3, voffA);
;             PG8_WAIT_V(8); PG8_WAIT_L(0); PG8_BAR; PG8_MMA(1, 0, At, B0); PG8_MMA(1, 1, At, B1); PG8_BAR; PG8_SCHED;
	s_add_i32 s30, s49, s2
	v_lshl_add_u64 v[216:217], v[216:217], 0, s[14:15]
	s_mov_b32 m0, s30
	ds_read_b128 v[184:187], v154 offset:49152
	ds_read_b128 v[188:191], v154 offset:50176
	ds_read_b128 v[192:195], v154 offset:51200
	ds_read_b128 v[196:199], v154 offset:52224
	ds_read_b128 v[200:203], v154 offset:53248
	ds_read_b128 v[204:207], v154 offset:54272
	ds_read_b128 v[208:211], v154 offset:55296
	ds_read_b128 v[212:215], v154 offset:56320
	global_load_lds_dwordx4 v[216:217], off
	s_add_i32 m0, s30, 0x2000
	s_add_u32 s28, s28, 0x20080
	v_lshl_add_u64 v[216:217], v[218:219], 0, s[14:15]
	s_addc_u32 s29, s29, 0
	s_add_i32 s30, s50, s2
	global_load_lds_dwordx4 v[216:217], off
	v_lshl_add_u64 v[216:217], s[28:29], 0, v[132:133]
	s_mov_b32 m0, s30
	s_nop 0
	global_load_lds_dwordx4 v[216:217], off
	v_lshl_add_u64 v[216:217], s[28:29], 0, v[136:137]
	s_add_i32 m0, s30, 0x2000
	s_nop 0
	global_load_lds_dwordx4 v[216:217], off
	v_lshl_add_u64 v[216:217], v[220:221], 0, s[14:15]
	s_mov_b32 m0, s39
	s_nop 0
	global_load_lds_dwordx4 v[216:217], off
	v_lshl_add_u64 v[216:217], v[222:223], 0, s[14:15]
	s_mov_b32 m0, s40
	s_nop 0
	global_load_lds_dwordx4 v[216:217], off
	s_waitcnt vmcnt(8)
	s_waitcnt lgkmcnt(0)
	s_barrier
	s_setprio 1
	s_waitcnt lgkmcnt(0)
	v_mfma_f32_16x16x32_bf16 v[62:65], v[146:149], v[184:187], v[62:65]
	v_mfma_f32_16x16x32_bf16 v[58:61], v[160:163], v[184:187], v[58:61]
	v_mfma_f32_16x16x32_bf16 v[42:45], v[160:163], v[192:195], v[42:45]
	v_mfma_f32_16x16x32_bf16 v[46:49], v[146:149], v[192:195], v[46:49]
	v_mfma_f32_16x16x32_bf16 v[30:33], v[146:149], v[200:203], v[30:33]
	v_mfma_f32_16x16x32_bf16 v[26:29], v[160:163], v[200:203], v[26:29]
	v_mfma_f32_16x16x32_bf16 v[10:13], v[160:163], v[208:211], v[10:13]
	v_mfma_f32_16x16x32_bf16 v[14:17], v[146:149], v[208:211], v[14:17]
	v_mfma_f32_16x16x32_bf16 v[62:65], v[156:159], v[188:191], v[62:65]
	v_mfma_f32_16x16x32_bf16 v[58:61], v[164:167], v[188:191], v[58:61]
	v_mfma_f32_16x16x32_bf16 v[42:45], v[164:167], v[196:199], v[42:45]
	v_mfma_f32_16x16x32_bf16 v[46:49], v[156:159], v[196:199], v[46:49]
	v_mfma_f32_16x16x32_bf16 v[30:33], v[156:159], v[204:207], v[30:33]
	v_mfma_f32_16x16x32_bf16 v[26:29], v[164:167], v[204:207], v[26:29]
	v_mfma_f32_16x16x32_bf16 v[10:13], v[164:167], v[212:215], v[10:13]
	v_mfma_f32_16x16x32_bf16 v[14:17], v[156:159], v[212:215], v[14:17]
	s_setprio 0
	s_setprio 1
	v_mfma_f32_16x16x32_bf16 v[54:57], v[168:171], v[184:187], v[54:57]
	v_mfma_f32_16x16x32_bf16 v[50:53], v[176:179], v[184:187], v[50:53]
	v_mfma_f32_16x16x32_bf16 v[34:37], v[176:179], v[192:195], v[34:37]
	v_mfma_f32_16x16x32_bf16 v[38:41], v[168:171], v[192:195], v[38:41]
	v_mfma_f32_16x16x32_bf16 v[22:25], v[168:171], v[200:203], v[22:25]
	v_mfma_f32_16x16x32_bf16 v[18:21], v[176:179], v[200:203], v[18:21]
	v_mfma_f32_16x16x32_bf16 v[2:5], v[176:179], v[208:211], v[2:5]
	v_mfma_f32_16x16x32_bf16 v[6:9], v[168:171], v[208:211], v[6:9]
	v_mfma_f32_16x16x32_bf16 v[54:57], v[172:175], v[188:191], v[54:57]
	v_mfma_f32_16x16x32_bf16 v[50:53], v[180:183], v[188:191], v[50:53]
	v_mfma_f32_16x16x32_bf16 v[34:37], v[180:183], v[196:199], v[34:37]
	v_mfma_f32_16x16x32_bf16 v[38:41], v[172:175], v[196:199], v[38:41]
	v_mfma_f32_16x16x32_bf16 v[22:25], v[172:175], v[204:207], v[22:25]
	v_mfma_f32_16x16x32_bf16 v[18:21], v[180:183], v[204:207], v[18:21]
	v_mfma_f32_16x16x32_bf16 v[2:5], v[180:183], v[212:215], v[2:5]
	v_mfma_f32_16x16x32_bf16 v[6:9], v[172:175], v[212:215], v[6:9]
	s_setprio 0
	s_barrier
	s_add_i32 s48, s48, 2
	s_add_u32 s26, s26, 0x100
	s_addc_u32 s27, s27, 0
	s_add_u32 s46, s46, 0x100
	s_addc_u32 s47, s47, 0
	s_cmp_gt_u32 s48, 5
.LBB0_523:
	ds_read_b128 v[146:149], v152
	ds_read_b128 v[156:159], v152 offset:1024
	ds_read_b128 v[160:163], v152 offset:2048
	ds_read_b128 v[164:167], v152 offset:3072
	ds_read_b128 v[168:171], v153
	ds_read_b128 v[172:175], v153 offset:1024
	ds_read_b128 v[176:179], v153 offset:2048
	ds_read_b128 v[180:183], v153 offset:3072
	s_add_u32 s28, s26, 0xfffe0080
	s_addc_u32 s29, s27, -1
	s_cmp_eq_u32 s48, 4
	s_cselect_b32 s31, s19, s29
	s_cselect_b32 s30, s44, s28
	s_cselect_b32 s29, s17, s47
	s_cselect_b32 s28, s45, s46
	v_lshl_add_u64 v[216:217], s[26:27], 0, v[138:139]
	s_add_i32 m0, s25, 0xc000
	ds_read_b128 v[184:187], v154
	ds_read_b128 v[188:191], v154 offset:1024
	ds_read_b128 v[192:195], v154 offset:2048
	ds_read_b128 v[196:199], v154 offset:3072
	ds_read_b128 v[200:203], v154 offset:4096
	ds_read_b128 v[204:207], v154 offset:5120
	ds_read_b128 v[208:211], v154 offset:6144
	ds_read_b128 v[212:215], v154 offset:7168
	global_load_lds_dwordx4 v[216:217], off
	v_lshl_add_u64 v[216:217], s[26:27], 0, v[140:141]
	s_add_i32 m0, s25, 0xe000
	s_nop 0
	global_load_lds_dwordx4 v[216:217], off
	s_waitcnt vmcnt(8)
	s_waitcnt lgkmcnt(0)
	s_barrier
; #define PG8_STAGE(bufoff, gbase, voff) do { _Pragma("unroll") for (int _i = 0; _i < 2; ++_i) \
;         __builtin_amdgcn_global_load_lds((const unsigned*)((const char*)(gbase) + (voff)[_i]), (PG8_LAS unsigned*)(lds + (bufoff) + ldsw + _i * 8192), 16, 0, 0); } while (0)
; #define PG8_LDA(dst, b, h) do { _Pragma("unroll") for (int m = 0; m < 4; ++m) _Pragma("unroll") for (int k = 0; k < 2; ++k) dst[m][k] = *(const PG8_LAS bf16x8*)(lds + PG8_SA(b, h) + aoff + m * 2048 + k * 1024); } while (0)
; #define PG8_LDB(dst, b, h) do { _Pragma("unroll") for (int n = 0; n < 2; ++n) _Pragma("unroll") for (int k = 0; k < 2; ++k) dst[n][k] = *(const PG8_LAS bf16x8*)(lds + PG8_SB(b, h) + boff + n * 2048 + k * 1024); } while (0)
; #define PG8_MMA(ai, bj, At, Bt) do { __builtin_amdgcn_s_setprio(1); _Pragma("unroll") for (int m = 0; m < 4; ++m) _Pragma("unroll") for (int n = 0; n < 2; ++n) _Pragma("unroll") for (int k = 0; k < 2; ++k) \
;         acc[ai][bj][m][n] = __builtin_amdgcn_mfma_f32_16x16x32_bf16(Bt[n][k], At[m][k], acc[ai][bj][m][n], 0, 0, 0); __builtin_amdgcn_s_setprio(0); } while (0)
; #define PG8_WAIT_V(n) asm volatile("s_waitcnt vmcnt(" #n ")" ::: "memory")
; #define PG8_WAIT_L(n) asm volatile("s_waitcnt lgkmcnt(" #n ")" ::: "memory")
; #define PG8_BAR __builtin_amdgcn_s_barrier()
; #define PG8_SCHED __builtin_amdgcn_sched_barrier(0)
; template <class Epi, class Sched, bool ALIGN_EPI = false, bool SP2 = false>
; __device__ __forceinline__ void gemm_phase(PG8_LAS unsigned char* lds, const Gemm g, const Sched& S, const Epi& E) {
;     ...
;             PG8_LDB(B0, 0, 0); PG8_LDB(B1, 0, 1); PG8_SCHED; PG8_LDA(At, 0, 0); PG8_STAGE(PG8_SA(1, 1), a1 + hstepA, voffA);
;             PG8_WAIT_V(8); PG8_WAIT_L(0); PG8_BAR; PG8_MMA(0, 0, At, B0); PG8_MMA(0, 1, At, B1); PG8_BAR; PG8_SCHED;
;             PG8_LDA(At, 0, 1); PG8_STAGE(PG8_SB(0, 0), b2, voffB); PG8_STAGE(PG8_SB(0, 1), b2 + hstepB, voffB); PG8_STAGE(PG8_SA(0, 0), a2, voffA);
;             PG8_WAIT_V(8); PG8_WAIT_L(0); PG8_BAR; PG8_MMA(1, 0, At, B0); PG8_MMA(1, 1, At, B1); PG8_BAR; PG8_SCHED;
	s_setprio 1
	s_waitcnt lgkmcnt(0)
	v_mfma_f32_16x16x32_bf16 v[126:129], v[146:149], v[184:187], v[126:129]
	v_mfma_f32_16x16x32_bf16 v[122:125], v[160:163], v[184:187], v[122:125]
	v_mfma_f32_16x16x32_bf16 v[106:109], v[160:163], v[192:195], v[106:109]
	v_mfma_f32_16x16x32_bf16 v[110:113], v[146:149], v[192:195], v[110:113]
	v_mfma_f32_16x16x32_bf16 v[94:97], v[146:149], v[200:203], v[94:97]
	v_mfma_f32_16x16x32_bf16 v[90:93], v[160:163], v[200:203], v[90:93]
	v_mfma_f32_16x16x32_bf16 v[74:77], v[160:163], v[208:211], v[74:77]
	v_mfma_f32_16x16x32_bf16 v[78:81], v[146:149], v[208:211], v[78:81]
	v_mfma_f32_16x16x32_bf16 v[126:129], v[156:159], v[188:191], v[126:129]
	v_mfma_f32_16x16x32_bf16 v[122:125], v[164:167], v[188:191], v[122:125]
	v_mfma_f32_16x16x32_bf16 v[106:109], v[164:167], v[196:199], v[106:109]
	v_mfma_f32_16x16x32_bf16 v[110:113], v[156:159], v[196:199], v[110:113]
	v_mfma_f32_16x16x32_bf16 v[94:97], v[156:159], v[204:207], v[94:97]
	v_mfma_f32_16x16x32_bf16 v[90:93], v[164:167], v[204:207], v[90:93]
	v_mfma_f32_16x16x32_bf16 v[74:77], v[164:167], v[212:215], v[74:77]
	v_mfma_f32_16x16x32_bf16 v[78:81], v[156:159], v[212:215], v[78:81]
	s_setprio 0
	s_setprio 1
	v_mfma_f32_16x16x32_bf16 v[118:121], v[168:171], v[184:187], v[118:121]
	v_mfma_f32_16x16x32_bf16 v[114:117], v[176:179], v[184:187], v[114:117]
	v_mfma_f32_16x16x32_bf16 v[98:101], v[176:179], v[192:195], v[98:101]
	v_mfma_f32_16x16x32_bf16 v[102:105], v[168:171], v[192:195], v[102:105]
	v_mfma_f32_16x16x32_bf16 v[86:89], v[168:171], v[200:203], v[86:89]
	v_mfma_f32_16x16x32_bf16 v[82:85], v[176:179], v[200:203], v[82:85]
	v_mfma_f32_16x16x32_bf16 v[66:69], v[176:179], v[208:211], v[66:69]
	v_mfma_f32_16x16x32_bf16 v[70:73], v[168:171], v[208:211], v[70:73]
	v_mfma_f32_16x16x32_bf16 v[118:121], v[172:175], v[188:191], v[118:121]
	v_mfma_f32_16x16x32_bf16 v[114:117], v[180:183], v[188:191], v[114:117]
	v_mfma_f32_16x16x32_bf16 v[98:101], v[180:183], v[196:199], v[98:101]
	v_mfma_f32_16x16x32_bf16 v[102:105], v[172:175], v[196:199], v[102:105]
	v_mfma_f32_16x16x32_bf16 v[86:89], v[172:175], v[204:207], v[86:89]
	v_mfma_f32_16x16x32_bf16 v[82:85], v[180:183], v[204:207], v[82:85]
	v_mfma_f32_16x16x32_bf16 v[66:69], v[180:183], v[212:215], v[66:69]
	v_mfma_f32_16x16x32_bf16 v[70:73], v[172:175], v[212:215], v[70:73]
	s_setprio 0
	s_barrier
	s_add_i32 s49, s41, s2
	v_lshl_add_u64 v[216:217], s[28:29], 0, v[132:133]
	s_mov_b32 m0, s49
	ds_read_b128 v[184:187], v154 offset:16384
	ds_read_b128 v[188:191], v154 offset:17408
	ds_read_b128 v[192:195], v154 offset:18432
	ds_read_b128 v[196:199], v154 offset:19456
	ds_read_b128 v[200:203], v154 offset:20480
	ds_read_b128 v[204:207], v154 offset:21504
	ds_read_b128 v[208:211], v154 offset:22528
	ds_read_b128 v[212:215], v154 offset:23552
	global_load_lds_dwordx4 v[216:217], off
	s_add_i32 m0, s49, 0x2000
	s_add_u32 s50, s28, 0x20000
	v_lshl_add_u64 v[218:219], s[28:29], 0, v[136:137]
	s_addc_u32 s51, s29, 0
	s_add_i32 s49, s42, s2
	global_load_lds_dwordx4 v[218:219], off
	v_lshl_add_u64 v[220:221], s[50:51], 0, v[132:133]
	s_mov_b32 m0, s49
	v_lshl_add_u64 v[222:223], s[30:31], 0, v[134:135]
	global_load_lds_dwordx4 v[220:221], off
	v_lshl_add_u64 v[220:221], s[50:51], 0, v[136:137]
	s_add_i32 m0, s49, 0x2000
	s_nop 0
	global_load_lds_dwordx4 v[220:221], off
	v_lshl_add_u64 v[220:221], s[30:31], 0, v[130:131]
	s_mov_b32 m0, s25
	s_nop 0
	global_load_lds_dwordx4 v[220:221], off
	s_mov_b32 m0, s35
	s_nop 0
	global_load_lds_dwordx4 v[222:223], off
	s_waitcnt vmcnt(8)
	s_waitcnt lgkmcnt(0)
	s_barrier
	s_setprio 1
	s_waitcnt lgkmcnt(0)
	v_mfma_f32_16x16x32_bf16 v[62:65], v[146:149], v[184:187], v[62:65]
	v_mfma_f32_16x16x32_bf16 v[58:61], v[160:163], v[184:187], v[58:61]
	v_mfma_f32_16x16x32_bf16 v[42:45], v[160:163], v[192:195], v[42:45]
	v_mfma_f32_16x16x32_bf16 v[46:49], v[146:149], v[192:195], v[46:49]
	v_mfma_f32_16x16x32_bf16 v[30:33], v[146:149], v[200:203], v[30:33]
	v_mfma_f32_16x16x32_bf16 v[26:29], v[160:163], v[200:203], v[26:29]
	v_mfma_f32_16x16x32_bf16 v[10:13], v[160:163], v[208:211], v[10:13]
	v_mfma_f32_16x16x32_bf16 v[14:17], v[146:149], v[208:211], v[14:17]
	v_mfma_f32_16x16x32_bf16 v[62:65], v[156:159], v[188:191], v[62:65]
	v_mfma_f32_16x16x32_bf16 v[58:61], v[164:167], v[188:191], v[58:61]
	v_mfma_f32_16x16x32_bf16 v[42:45], v[164:167], v[196:199], v[42:45]
	v_mfma_f32_16x16x32_bf16 v[46:49], v[156:159], v[196:199], v[46:49]
	v_mfma_f32_16x16x32_bf16 v[30:33], v[156:159], v[204:207], v[30:33]
	v_mfma_f32_16x16x32_bf16 v[26:29], v[164:167], v[204:207], v[26:29]
	v_mfma_f32_16x16x32_bf16 v[10:13], v[164:167], v[212:215], v[10:13]
	v_mfma_f32_16x16x32_bf16 v[14:17], v[156:159], v[212:215], v[14:17]
	s_setprio 0
	s_setprio 1
	v_mfma_f32_16x16x32_bf16 v[54:57], v[168:171], v[184:187], v[54:57]
	v_mfma_f32_16x16x32_bf16 v[50:53], v[176:179], v[184:187], v[50:53]
	v_mfma_f32_16x16x32_bf16 v[34:37], v[176:179], v[192:195], v[34:37]
	v_mfma_f32_16x16x32_bf16 v[38:41], v[168:171], v[192:195], v[38:41]
	v_mfma_f32_16x16x32_bf16 v[22:25], v[168:171], v[200:203], v[22:25]
	v_mfma_f32_16x16x32_bf16 v[18:21], v[176:179], v[200:203], v[18:21]
	v_mfma_f32_16x16x32_bf16 v[2:5], v[176:179], v[208:211], v[2:5]
	v_mfma_f32_16x16x32_bf16 v[6:9], v[168:171], v[208:211], v[6:9]
	v_mfma_f32_16x16x32_bf16 v[54:57], v[172:175], v[188:191], v[54:57]
	v_mfma_f32_16x16x32_bf16 v[50:53], v[180:183], v[188:191], v[50:53]
	v_mfma_f32_16x16x32_bf16 v[34:37], v[180:183], v[196:199], v[34:37]
	v_mfma_f32_16x16x32_bf16 v[38:41], v[172:175], v[196:199], v[38:41]
	v_mfma_f32_16x16x32_bf16 v[22:25], v[172:175], v[204:207], v[22:25]
	v_mfma_f32_16x16x32_bf16 v[18:21], v[180:183], v[204:207], v[18:21]
	v_mfma_f32_16x16x32_bf16 v[2:5], v[180:183], v[212:215], v[2:5]
	v_mfma_f32_16x16x32_bf16 v[6:9], v[172:175], v[212:215], v[6:9]
	s_setprio 0
	s_barrier
; #define PG8_STAGE(bufoff, gbase, voff) do { _Pragma("unroll") for (int _i = 0; _i < 2; ++_i) \
;         __builtin_amdgcn_global_load_lds((const unsigned*)((const char*)(gbase) + (voff)[_i]), (PG8_LAS unsigned*)(lds + (bufoff) + ldsw + _i * 8192), 16, 0, 0); } while (0)
; #define PG8_LDA(dst, b, h) do { _Pragma("unroll") for (int m = 0; m < 4; ++m) _Pragma("unroll") for (int k = 0; k < 2; ++k) dst[m][k] = *(const PG8_LAS bf16x8*)(lds + PG8_SA(b, h) + aoff + m * 2048 + k * 1024); } while (0)
; #define PG8_LDB(dst, b, h) do { _Pragma("unroll") for (int n = 0; n < 2; ++n) _Pragma("unroll") for (int k = 0; k < 2; ++k) dst[n][k] = *(const PG8_LAS bf16x8*)(lds + PG8_SB(b, h) + boff + n * 2048 + k * 1024); } while (0)
; #define PG8_MMA(ai, bj, At, Bt) do { __builtin_amdgcn_s_setprio(1); _Pragma("unroll") for (int m = 0; m < 4; ++m) _Pragma("unroll") for (int n = 0; n < 2; ++n) _Pragma("unroll") for (int k = 0; k < 2; ++k) \
;         acc[ai][bj][m][n] = __builtin_amdgcn_mfma_f32_16x16x32_bf16(Bt[n][k], At[m][k], acc[ai][bj][m][n], 0, 0, 0); __builtin_amdgcn_s_setprio(0); } while (0)
; #define PG8_WAIT_V(n) asm volatile("s_waitcnt vmcnt(" #n ")" ::: "memory")
; #define PG8_WAIT_L(n) asm volatile("s_waitcnt lgkmcnt(" #n ")" ::: "memory")
; #define PG8_BAR __builtin_amdgcn_s_barrier()
; #define PG8_SCHED __builtin_amdgcn_sched_barrier(0)
; template <class Epi, class Sched, bool ALIGN_EPI = false, bool SP2 = false>
; __device__ __forceinline__ void gemm_phase(PG8_LAS unsigned char* lds, const Gemm g, const Sched& S, const Epi& E) {
;     ...
;             PG8_LDB(B0, 1, 0); PG8_LDB(B1, 1, 1); PG8_SCHED; PG8_LDA(At, 1, 0); PG8_STAGE(PG8_SA(0, 1), a2 + hstepA, voffA);
;             PG8_WAIT_V(8); PG8_WAIT_L(0); PG8_BAR; PG8_MMA(0, 0, At, B0); PG8_MMA(0, 1, At, B1); PG8_BAR; PG8_SCHED;
	s_add_i32 s49, 0, 0x18000
	v_add_u32_e32 v155, s49, v150
	s_add_i32 s50, 0, 0x1c000
	ds_read_b128 v[146:149], v155
	ds_read_b128 v[156:159], v155 offset:1024
	ds_read_b128 v[160:163], v155 offset:2048
	ds_read_b128 v[164:167], v155 offset:3072
	v_add_u32_e32 v155, s50, v150
	ds_read_b128 v[168:171], v155
	ds_read_b128 v[172:175], v155 offset:1024
	ds_read_b128 v[176:179], v155 offset:2048
	ds_read_b128 v[180:183], v155 offset:3072
	s_add_u32 s30, s30, 0x20000
	s_addc_u32 s31, s31, 0
	s_mov_b32 m0, s36
	v_lshl_add_u64 v[224:225], s[30:31], 0, v[130:131]
	ds_read_b128 v[184:187], v154 offset:32768
	ds_read_b128 v[188:191], v154 offset:33792
	ds_read_b128 v[192:195], v154 offset:34816
	ds_read_b128 v[196:199], v154 offset:35840
	ds_read_b128 v[200:203], v154 offset:36864
	ds_read_b128 v[204:207], v154 offset:37888
	ds_read_b128 v[208:211], v154 offset:38912
	ds_read_b128 v[212:215], v154 offset:39936
	global_load_lds_dwordx4 v[224:225], off
	v_lshl_add_u64 v[224:225], s[30:31], 0, v[134:135]
	s_mov_b32 m0, s37
	s_nop 0
	global_load_lds_dwordx4 v[224:225], off
	s_waitcnt vmcnt(8)
	s_waitcnt lgkmcnt(0)
	s_barrier
	s_setprio 1
	s_waitcnt lgkmcnt(0)
	v_mfma_f32_16x16x32_bf16 v[126:129], v[146:149], v[184:187], v[126:129]
	v_mfma_f32_16x16x32_bf16 v[122:125], v[160:163], v[184:187], v[122:125]
	v_mfma_f32_16x16x32_bf16 v[106:109], v[160:163], v[192:195], v[106:109]
	v_mfma_f32_16x16x32_bf16 v[110:113], v[146:149], v[192:195], v[110:113]
	v_mfma_f32_16x16x32_bf16 v[94:97], v[146:149], v[200:203], v[94:97]
	v_mfma_f32_16x16x32_bf16 v[90:93], v[160:163], v[200:203], v[90:93]
	v_mfma_f32_16x16x32_bf16 v[74:77], v[160:163], v[208:211], v[74:77]
	v_mfma_f32_16x16x32_bf16 v[78:81], v[146:149], v[208:211], v[78:81]
	v_mfma_f32_16x16x32_bf16 v[126:129], v[156:159], v[188:191], v[126:129]
	v_mfma_f32_16x16x32_bf16 v[122:125], v[164:167], v[188:191], v[122:125]
	v_mfma_f32_16x16x32_bf16 v[106:109], v[164:167], v[196:199], v[106:109]
	v_mfma_f32_16x16x32_bf16 v[110:113], v[156:159], v[196:199], v[110:113]
	v_mfma_f32_16x16x32_bf16 v[94:97], v[156:159], v[204:207], v[94:97]
	v_mfma_f32_16x16x32_bf16 v[90:93], v[164:167], v[204:207], v[90:93]
	v_mfma_f32_16x16x32_bf16 v[74:77], v[164:167], v[212:215], v[74:77]
	v_mfma_f32_16x16x32_bf16 v[78:81], v[156:159], v[212:215], v[78:81]
	s_setprio 0
	s_setprio 1
	v_mfma_f32_16x16x32_bf16 v[118:121], v[168:171], v[184:187], v[118:121]
	v_mfma_f32_16x16x32_bf16 v[114:117], v[176:179], v[184:187], v[114:117]
	v_mfma_f32_16x16x32_bf16 v[98:101], v[176:179], v[192:195], v[98:101]
	v_mfma_f32_16x16x32_bf16 v[102:105], v[168:171], v[192:195], v[102:105]
	v_mfma_f32_16x16x32_bf16 v[86:89], v[168:171], v[200:203], v[86:89]
	v_mfma_f32_16x16x32_bf16 v[82:85], v[176:179], v[200:203], v[82:85]
	v_mfma_f32_16x16x32_bf16 v[66:69], v[176:179], v[208:211], v[66:69]
	v_mfma_f32_16x16x32_bf16 v[70:73], v[168:171], v[208:211], v[70:73]
	v_mfma_f32_16x16x32_bf16 v[118:121], v[172:175], v[188:191], v[118:121]
	v_mfma_f32_16x16x32_bf16 v[114:117], v[180:183], v[188:191], v[114:117]
	v_mfma_f32_16x16x32_bf16 v[98:101], v[180:183], v[196:199], v[98:101]
	v_mfma_f32_16x16x32_bf16 v[102:105], v[172:175], v[196:199], v[102:105]
	v_mfma_f32_16x16x32_bf16 v[86:89], v[172:175], v[204:207], v[86:89]
	v_mfma_f32_16x16x32_bf16 v[82:85], v[180:183], v[204:207], v[82:85]
	v_mfma_f32_16x16x32_bf16 v[66:69], v[180:183], v[212:215], v[66:69]
	v_mfma_f32_16x16x32_bf16 v[70:73], v[172:175], v[212:215], v[70:73]
	s_setprio 0
	s_barrier
; #define PG8_STAGE(bufoff, gbase, voff) do { _Pragma("unroll") for (int _i = 0; _i < 2; ++_i) \
;         __builtin_amdgcn_global_load_lds((const unsigned*)((const char*)(gbase) + (voff)[_i]), (PG8_LAS unsigned*)(lds + (bufoff) + ldsw + _i * 8192), 16, 0, 0); } while (0)
; #define PG8_LDA(dst, b, h) do { _Pragma("unroll") for (int m = 0; m < 4; ++m) _Pragma("unroll") for (int k = 0; k < 2; ++k) dst[m][k] = *(const PG8_LAS bf16x8*)(lds + PG8_SA(b, h) + aoff + m * 2048 + k * 1024); } while (0)
; #define PG8_MMA(ai, bj, At, Bt) do { __builtin_amdgcn_s_setprio(1); _Pragma("unroll") for (int m = 0; m < 4; ++m) _Pragma("unroll") for (int n = 0; n < 2; ++n) _Pragma("unroll") for (int k = 0; k < 2; ++k) \
;         acc[ai][bj][m][n] = __builtin_amdgcn_mfma_f32_16x16x32_bf16(Bt[n][k], At[m][k], acc[ai][bj][m][n], 0, 0, 0); __builtin_amdgcn_s_setprio(0); } while (0)
; #define PG8_WAIT_V(n) asm volatile("s_waitcnt vmcnt(" #n ")" ::: "memory")
; #define PG8_WAIT_L(n) asm volatile("s_waitcnt lgkmcnt(" #n ")" ::: "memory")
; #define PG8_BAR __builtin_amdgcn_s_barrier()
; #define PG8_SCHED __builtin_amdgcn_sched_barrier(0)
; template <class Epi, class Sched, bool ALIGN_EPI = false, bool SP2 = false>
; __device__ __forceinline__ void gemm_phase(PG8_LAS unsigned char* lds, const Gemm g, const Sched& S, const Epi& E) {
;     ...
;         for (int t = 0; t < nt; t += 2) {
;     ...
;             PG8_LDA(At, 1, 1); PG8_STAGE(PG8_SB(1, 0), b3, voffB); PG8_STAGE(PG8_SB(1, 1), b3 + hstepB, voffB); PG8_STAGE(PG8_SA(1, 0), a3, voffA);
;             PG8_WAIT_V(8); PG8_WAIT_L(0); PG8_BAR; PG8_MMA(1, 0, At, B0); PG8_MMA(1, 1, At, B1); PG8_BAR; PG8_SCHED;
	s_add_i32 s30, s49, s2
	v_lshl_add_u64 v[216:217], v[216:217], 0, s[14:15]
	s_mov_b32 m0, s30
	ds_read_b128 v[184:187], v154 offset:49152
	ds_read_b128 v[188:191], v154 offset:50176
	ds_read_b128 v[192:195], v154 offset:51200
	ds_read_b128 v[196:199], v154 offset:52224
	ds_read_b128 v[200:203], v154 offset:53248
	ds_read_b128 v[204:207], v154 offset:54272
	ds_read_b128 v[208:211], v154 offset:55296
	ds_read_b128 v[212:215], v154 offset:56320
	global_load_lds_dwordx4 v[216:217], off
	s_add_i32 m0, s30, 0x2000
	s_add_u32 s28, s28, 0x20080
	v_lshl_add_u64 v[216:217], v[218:219], 0, s[14:15]
	s_addc_u32 s29, s29, 0
	s_add_i32 s30, s50, s2
	global_load_lds_dwordx4 v[216:217], off
	v_lshl_add_u64 v[216:217], s[28:29], 0, v[132:133]
	s_mov_b32 m0, s30
	s_nop 0
	global_load_lds_dwordx4 v[216:217], off
	v_lshl_add_u64 v[216:217], s[28:29], 0, v[136:137]
	s_add_i32 m0, s30, 0x2000
	s_nop 0
	global_load_lds_dwordx4 v[216:217], off
	v_lshl_add_u64 v[216:217], v[220:221], 0, s[14:15]
	s_mov_b32 m0, s39
	s_nop 0
	global_load_lds_dwordx4 v[216:217], off
	v_lshl_add_u64 v[216:217], v[222:223], 0, s[14:15]
	s_mov_b32 m0, s40
	s_nop 0
	global_load_lds_dwordx4 v[216:217], off
	s_waitcnt vmcnt(8)
	s_waitcnt lgkmcnt(0)
	s_barrier
	s_setprio 1
	s_waitcnt lgkmcnt(0)
	v_mfma_f32_16x16x32_bf16 v[62:65], v[146:149], v[184:187], v[62:65]
	v_mfma_f32_16x16x32_bf16 v[58:61], v[160:163], v[184:187], v[58:61]
	v_mfma_f32_16x16x32_bf16 v[42:45], v[160:163], v[192:195], v[42:45]
	v_mfma_f32_16x16x32_bf16 v[46:49], v[146:149], v[192:195], v[46:49]
	v_mfma_f32_16x16x32_bf16 v[30:33], v[146:149], v[200:203], v[30:33]
	v_mfma_f32_16x16x32_bf16 v[26:29], v[160:163], v[200:203], v[26:29]
	v_mfma_f32_16x16x32_bf16 v[10:13], v[160:163], v[208:211], v[10:13]
	v_mfma_f32_16x16x32_bf16 v[14:17], v[146:149], v[208:211], v[14:17]
	v_mfma_f32_16x16x32_bf16 v[62:65], v[156:159], v[188:191], v[62:65]
	v_mfma_f32_16x16x32_bf16 v[58:61], v[164:167], v[188:191], v[58:61]
	v_mfma_f32_16x16x32_bf16 v[42:45], v[164:167], v[196:199], v[42:45]
	v_mfma_f32_16x16x32_bf16 v[46:49], v[156:159], v[196:199], v[46:49]
	v_mfma_f32_16x16x32_bf16 v[30:33], v[156:159], v[204:207], v[30:33]
	v_mfma_f32_16x16x32_bf16 v[26:29], v[164:167], v[204:207], v[26:29]
	v_mfma_f32_16x16x32_bf16 v[10:13], v[164:167], v[212:215], v[10:13]
	v_mfma_f32_16x16x32_bf16 v[14:17], v[156:159], v[212:215], v[14:17]
	s_setprio 0
	s_setprio 1
	v_mfma_f32_16x16x32_bf16 v[54:57], v[168:171], v[184:187], v[54:57]
	v_mfma_f32_16x16x32_bf16 v[50:53], v[176:179], v[184:187], v[50:53]
	v_mfma_f32_16x16x32_bf16 v[34:37], v[176:179], v[192:195], v[34:37]
	v_mfma_f32_16x16x32_bf16 v[38:41], v[168:171], v[192:195], v[38:41]
	v_mfma_f32_16x16x32_bf16 v[22:25], v[168:171], v[200:203], v[22:25]
	v_mfma_f32_16x16x32_bf16 v[18:21], v[176:179], v[200:203], v[18:21]
	v_mfma_f32_16x16x32_bf16 v[2:5], v[176:179], v[208:211], v[2:5]
	v_mfma_f32_16x16x32_bf16 v[6:9], v[168:171], v[208:211], v[6:9]
	v_mfma_f32_16x16x32_bf16 v[54:57], v[172:175], v[188:191], v[54:57]
	v_mfma_f32_16x16x32_bf16 v[50:53], v[180:183], v[188:191], v[50:53]
	v_mfma_f32_16x16x32_bf16 v[34:37], v[180:183], v[196:199], v[34:37]
	v_mfma_f32_16x16x32_bf16 v[38:41], v[172:175], v[196:199], v[38:41]
	v_mfma_f32_16x16x32_bf16 v[22:25], v[172:175], v[204:207], v[22:25]
	v_mfma_f32_16x16x32_bf16 v[18:21], v[180:183], v[204:207], v[18:21]
	v_mfma_f32_16x16x32_bf16 v[2:5], v[180:183], v[212:215], v[2:5]
	v_mfma_f32_16x16x32_bf16 v[6:9], v[172:175], v[212:215], v[6:9]
	s_setprio 0
	s_barrier
	s_add_i32 s48, s48, 2
	s_add_u32 s26, s26, 0x100
	s_addc_u32 s27, s27, 0
	s_add_u32 s46, s46, 0x100
	s_addc_u32 s47, s47, 0
	s_cmp_gt_u32 s48, 5
	s_cbranch_scc0 .LBB0_523
	s_and_b64 vcc, exec, s[4:5]
	s_cbranch_vccz .LBB0_526
	s_barrier

; #define PG8_STAGE(bufoff, gbase, voff) do { _Pragma("unroll") for (int _i = 0; _i < 2; ++_i) \
;         __builtin_amdgcn_global_load_lds((const unsigned*)((const char*)(gbase) + (voff)[_i]), (PG8_LAS unsigned*)(lds + (bufoff) + ldsw + _i * 8192), 16, 0, 0); } while (0)
; #define PG8_LDA(dst, b, h) do { _Pragma("unroll") for (int m = 0; m < 4; ++m) _Pragma("unroll") for (int k = 0; k < 2; ++k) dst[m][k] = *(const PG8_LAS bf16x8*)(lds + PG8_SA(b, h) + aoff + m * 2048 + k * 1024); } while (0)
; #define PG8_LDB(dst, b, h) do { _Pragma("unroll") for (int n = 0; n < 2; ++n) _Pragma("unroll") for (int k = 0; k < 2; ++k) dst[n][k] = *(const PG8_LAS bf16x8*)(lds + PG8_SB(b, h) + boff + n * 2048 + k * 1024); } while (0)
; #define PG8_WAIT_V(n) asm volatile("s_waitcnt vmcnt(" #n ")" ::: "memory")
; #define PG8_WAIT_L(n) asm volatile("s_waitcnt lgkmcnt(" #n ")" ::: "memory")
; #define PG8_BAR __builtin_amdgcn_s_barrier()
; template <class Epi, class Sched, bool ALIGN_EPI = false, bool SP2 = false>
; __device__ __forceinline__ void gemm_phase(PG8_LAS unsigned char* lds, const Gemm g, const Sched& S, const Epi& E) {
;     ...
;         const bool has_next = S.next(ui + 1, nxt);
;         const char* nA = has_next ? (const char*)g.A + (size_t)nxt.g * g.gsA * 2 + (size_t)nxt.pm * tstepA : cA; const char* nB = has_next ? (const char*)g.Bt + (size_t)nxt.g * g.gsB * 2 + (size_t)nxt.pn * tstepB : cB;
;         for (int t = 0; t < nt; t += 2) {
;             const bool last = (t == nt - 2);
;             const char* a1 = cA + (size_t)(t + 1) * kstep;
;             const char* a2 = last ? nA : cA + (size_t)(t + 2) * kstep; const char* b2 = last ? nB : cB + (size_t)(t + 2) * kstep;
;             const char* a3 = a2 + kstep; const char* b3 = b2 + kstep;
;             if (last && has_next) S.a_ready(nxt);
;             if constexpr (SP2) {
;             PG8_LDB(B0, 0, 0); PG8_LDB(B1, 0, 1); PG8_SCHED; PG8_LDA(At, 0, 0); PG8_STAGE(PG8_SA(1, 1), a1 + hstepA, voffA);
;             PG8_WAIT_V(8); PG8_WAIT_L(0); PG8_BAR; PG8_MMA(0, 0, At, B0); PG8_MMA(0, 1, At, B1); PG8_BAR; PG8_SCHED;
;             PG8_LDA(At, 0, 1); PG8_STAGE(PG8_SB(0, 0), b2, voffB); PG8_STAGE(PG8_SB(0, 1), b2 + hstepB, voffB); PG8_STAGE(PG8_SA(0, 0), a2, voffA);
;             PG8_WAIT_V(8); PG8_WAIT_L(0); PG8_BAR; PG8_MMA(1, 0, At, B0); PG8_MMA(1, 1, At, B1); PG8_BAR; PG8_SCHED;
.LBB0_604:
	s_ashr_i32 s25, s24, 31
	s_lshl_b64 s[26:27], s[24:25], 19
	s_add_u32 s26, s0, s26
	s_addc_u32 s27, s1, s27
	s_and_b64 s[28:29], s[8:9], exec
	s_cselect_b32 s25, s27, s35
	s_cselect_b32 s31, s26, s34
	s_ashr_i32 s23, s22, 31
	s_lshl_b64 s[28:29], s[22:23], 19
	s_add_u32 s28, s2, s28
	s_addc_u32 s29, s3, s29
	s_and_b64 s[38:39], s[8:9], exec
	s_cselect_b32 s23, s29, s37
	s_cselect_b32 s53, s28, s36
	s_add_u32 s34, s34, 0x40080
	s_addc_u32 s35, s35, 0
	s_add_u32 s54, s36, 0x100
	s_addc_u32 s55, s37, 0
	s_mov_b32 s56, -2
	s_waitcnt lgkmcnt(0)
	s_waitcnt lgkmcnt(0)
	ds_read_b128 v[130:133], v172
	ds_read_b128 v[134:137], v172 offset:1024
	ds_read_b128 v[138:141], v172 offset:2048
	ds_read_b128 v[142:145], v172 offset:3072
	ds_read_b128 v[162:165], v173
	ds_read_b128 v[166:169], v173 offset:1024
	ds_read_b128 v[176:179], v173 offset:2048
	ds_read_b128 v[180:183], v173 offset:3072
	s_add_u32 s36, s34, 0xfffc0080
	s_addc_u32 s37, s35, -1
	s_cmp_eq_u32 s56, 12
	s_cselect_b32 s39, s25, s37
	s_cselect_b32 s38, s31, s36
	s_cselect_b32 s37, s23, s55
	s_cselect_b32 s36, s53, s54
	v_lshl_add_u64 v[216:217], s[34:35], 0, v[154:155]
	s_add_i32 m0, s40, 0xc000
	ds_read_b128 v[184:187], v174
	ds_read_b128 v[188:191], v174 offset:1024
	ds_read_b128 v[192:195], v174 offset:2048
	ds_read_b128 v[196:199], v174 offset:3072
	ds_read_b128 v[200:203], v174 offset:4096
	ds_read_b128 v[204:207], v174 offset:5120
	ds_read_b128 v[208:211], v174 offset:6144
	ds_read_b128 v[212:215], v174 offset:7168
	global_load_lds_dwordx4 v[216:217], off
	v_lshl_add_u64 v[216:217], s[34:35], 0, v[156:157]
	s_add_i32 m0, s40, 0xe000
	s_nop 0
	global_load_lds_dwordx4 v[216:217], off
	s_waitcnt vmcnt(8)
	s_waitcnt lgkmcnt(0)
	s_barrier
	s_setprio 1
	s_waitcnt lgkmcnt(0)
	v_mfma_f32_16x16x32_bf16 v[126:129], v[130:133], v[184:187], 0
	v_mfma_f32_16x16x32_bf16 v[122:125], v[138:141], v[184:187], 0
	v_mfma_f32_16x16x32_bf16 v[106:109], v[138:141], v[192:195], 0
	v_mfma_f32_16x16x32_bf16 v[110:113], v[130:133], v[192:195], 0
	v_mfma_f32_16x16x32_bf16 v[94:97], v[130:133], v[200:203], 0
	v_mfma_f32_16x16x32_bf16 v[90:93], v[138:141], v[200:203], 0
	v_mfma_f32_16x16x32_bf16 v[74:77], v[138:141], v[208:211], 0
	v_mfma_f32_16x16x32_bf16 v[78:81], v[130:133], v[208:211], 0
	v_mfma_f32_16x16x32_bf16 v[126:129], v[134:137], v[188:191], v[126:129]
	v_mfma_f32_16x16x32_bf16 v[122:125], v[142:145], v[188:191], v[122:125]
	v_mfma_f32_16x16x32_bf16 v[106:109], v[142:145], v[196:199], v[106:109]
	v_mfma_f32_16x16x32_bf16 v[110:113], v[134:137], v[196:199], v[110:113]
	v_mfma_f32_16x16x32_bf16 v[94:97], v[134:137], v[204:207], v[94:97]
	v_mfma_f32_16x16x32_bf16 v[90:93], v[142:145], v[204:207], v[90:93]
	v_mfma_f32_16x16x32_bf16 v[74:77], v[142:145], v[212:215], v[74:77]
	v_mfma_f32_16x16x32_bf16 v[78:81], v[134:137], v[212:215], v[78:81]
	s_setprio 0
	s_setprio 1
	v_mfma_f32_16x16x32_bf16 v[118:121], v[162:165], v[184:187], 0
	v_mfma_f32_16x16x32_bf16 v[114:117], v[176:179], v[184:187], 0
	v_mfma_f32_16x16x32_bf16 v[98:101], v[176:179], v[192:195], 0
	v_mfma_f32_16x16x32_bf16 v[102:105], v[162:165], v[192:195], 0
	v_mfma_f32_16x16x32_bf16 v[86:89], v[162:165], v[200:203], 0
	v_mfma_f32_16x16x32_bf16 v[82:85], v[176:179], v[200:203], 0
	v_mfma_f32_16x16x32_bf16 v[66:69], v[176:179], v[208:211], 0
	v_mfma_f32_16x16x32_bf16 v[70:73], v[162:165], v[208:211], 0
	v_mfma_f32_16x16x32_bf16 v[118:121], v[166:169], v[188:191], v[118:121]
	v_mfma_f32_16x16x32_bf16 v[114:117], v[180:183], v[188:191], v[114:117]
	v_mfma_f32_16x16x32_bf16 v[98:101], v[180:183], v[196:199], v[98:101]
	v_mfma_f32_16x16x32_bf16 v[102:105], v[166:169], v[196:199], v[102:105]
	v_mfma_f32_16x16x32_bf16 v[86:89], v[166:169], v[204:207], v[86:89]
	v_mfma_f32_16x16x32_bf16 v[82:85], v[180:183], v[204:207], v[82:85]
	v_mfma_f32_16x16x32_bf16 v[66:69], v[180:183], v[212:215], v[66:69]
	v_mfma_f32_16x16x32_bf16 v[70:73], v[166:169], v[212:215], v[70:73]
	s_setprio 0
	s_barrier
	s_add_i32 s57, s50, s33
	v_lshl_add_u64 v[216:217], s[36:37], 0, v[148:149]
	s_mov_b32 m0, s57
	ds_read_b128 v[184:187], v174 offset:16384
	ds_read_b128 v[188:191], v174 offset:17408
	ds_read_b128 v[192:195], v174 offset:18432
	ds_read_b128 v[196:199], v174 offset:19456
	ds_read_b128 v[200:203], v174 offset:20480
	ds_read_b128 v[204:207], v174 offset:21504
	ds_read_b128 v[208:211], v174 offset:22528
	ds_read_b128 v[212:215], v174 offset:23552
	global_load_lds_dwordx4 v[216:217], off
	s_add_i32 m0, s57, 0x2000
	s_add_u32 s58, s36, 0x40000
	v_lshl_add_u64 v[218:219], s[36:37], 0, v[152:153]
	s_addc_u32 s59, s37, 0
	s_add_i32 s57, s51, s33
	global_load_lds_dwordx4 v[218:219], off
	v_lshl_add_u64 v[220:221], s[58:59], 0, v[148:149]
	s_mov_b32 m0, s57
	v_lshl_add_u64 v[222:223], s[38:39], 0, v[150:151]
	global_load_lds_dwordx4 v[220:221], off
	v_lshl_add_u64 v[220:221], s[58:59], 0, v[152:153]
	s_add_i32 m0, s57, 0x2000
	s_nop 0
	global_load_lds_dwordx4 v[220:221], off
	v_lshl_add_u64 v[220:221], s[38:39], 0, v[146:147]
	s_mov_b32 m0, s40
	s_nop 0
	global_load_lds_dwordx4 v[220:221], off
	s_mov_b32 m0, s41
	s_nop 0
	global_load_lds_dwordx4 v[222:223], off
	s_waitcnt vmcnt(8)
	s_waitcnt lgkmcnt(0)
	s_barrier
; #define PG8_STAGE(bufoff, gbase, voff) do { _Pragma("unroll") for (int _i = 0; _i < 2; ++_i) \
;         __builtin_amdgcn_global_load_lds((const unsigned*)((const char*)(gbase) + (voff)[_i]), (PG8_LAS unsigned*)(lds + (bufoff) + ldsw + _i * 8192), 16, 0, 0); } while (0)
; #define PG8_LDA(dst, b, h) do { _Pragma("unroll") for (int m = 0; m < 4; ++m) _Pragma("unroll") for (int k = 0; k < 2; ++k) dst[m][k] = *(const PG8_LAS bf16x8*)(lds + PG8_SA(b, h) + aoff + m * 2048 + k * 1024); } while (0)
; #define PG8_LDB(dst, b, h) do { _Pragma("unroll") for (int n = 0; n < 2; ++n) _Pragma("unroll") for (int k = 0; k < 2; ++k) dst[n][k] = *(const PG8_LAS bf16x8*)(lds + PG8_SB(b, h) + boff + n * 2048 + k * 1024); } while (0)
; #define PG8_MMA(ai, bj, At, Bt) do { __builtin_amdgcn_s_setprio(1); _Pragma("unroll") for (int m = 0; m < 4; ++m) _Pragma("unroll") for (int n = 0; n < 2; ++n) _Pragma("unroll") for (int k = 0; k < 2; ++k) \
;         acc[ai][bj][m][n] = __builtin_amdgcn_mfma_f32_16x16x32_bf16(Bt[n][k], At[m][k], acc[ai][bj][m][n], 0, 0, 0); __builtin_amdgcn_s_setprio(0); } while (0)
; #define PG8_WAIT_V(n) asm volatile("s_waitcnt vmcnt(" #n ")" ::: "memory")
; #define PG8_WAIT_L(n) asm volatile("s_waitcnt lgkmcnt(" #n ")" ::: "memory")
; #define PG8_BAR __builtin_amdgcn_s_barrier()
; #define PG8_SCHED __builtin_amdgcn_sched_barrier(0)
; template <class Epi, class Sched, bool ALIGN_EPI = false, bool SP2 = false>
; __device__ __forceinline__ void gemm_phase(PG8_LAS unsigned char* lds, const Gemm g, const Sched& S, const Epi& E) {
;     ...
;             PG8_WAIT_V(8); PG8_WAIT_L(0); PG8_BAR; PG8_MMA(0, 0, At, B0); PG8_MMA(0, 1, At, B1); PG8_BAR; PG8_SCHED;
;             PG8_LDA(At, 0, 1); PG8_STAGE(PG8_SB(0, 0), b2, voffB); PG8_STAGE(PG8_SB(0, 1), b2 + hstepB, voffB); PG8_STAGE(PG8_SA(0, 0), a2, voffA);
;             PG8_WAIT_V(8); PG8_WAIT_L(0); PG8_BAR; PG8_MMA(1, 0, At, B0); PG8_MMA(1, 1, At, B1); PG8_BAR; PG8_SCHED;
;             PG8_LDB(B0, 1, 0); PG8_LDB(B1, 1, 1); PG8_SCHED; PG8_LDA(At, 1, 0); PG8_STAGE(PG8_SA(0, 1), a2 + hstepA, voffA);
;             PG8_WAIT_V(8); PG8_WAIT_L(0); PG8_BAR; PG8_MMA(0, 0, At, B0); PG8_MMA(0, 1, At, B1); PG8_BAR; PG8_SCHED;
	s_setprio 1
	s_waitcnt lgkmcnt(0)
	v_mfma_f32_16x16x32_bf16 v[62:65], v[130:133], v[184:187], 0
	v_mfma_f32_16x16x32_bf16 v[58:61], v[138:141], v[184:187], 0
	v_mfma_f32_16x16x32_bf16 v[42:45], v[138:141], v[192:195], 0
	v_mfma_f32_16x16x32_bf16 v[46:49], v[130:133], v[192:195], 0
	v_mfma_f32_16x16x32_bf16 v[30:33], v[130:133], v[200:203], 0
	v_mfma_f32_16x16x32_bf16 v[26:29], v[138:141], v[200:203], 0
	v_mfma_f32_16x16x32_bf16 v[10:13], v[138:141], v[208:211], 0
	v_mfma_f32_16x16x32_bf16 v[14:17], v[130:133], v[208:211], 0
	v_mfma_f32_16x16x32_bf16 v[62:65], v[134:137], v[188:191], v[62:65]
	v_mfma_f32_16x16x32_bf16 v[58:61], v[142:145], v[188:191], v[58:61]
	v_mfma_f32_16x16x32_bf16 v[42:45], v[142:145], v[196:199], v[42:45]
	v_mfma_f32_16x16x32_bf16 v[46:49], v[134:137], v[196:199], v[46:49]
	v_mfma_f32_16x16x32_bf16 v[30:33], v[134:137], v[204:207], v[30:33]
	v_mfma_f32_16x16x32_bf16 v[26:29], v[142:145], v[204:207], v[26:29]
	v_mfma_f32_16x16x32_bf16 v[10:13], v[142:145], v[212:215], v[10:13]
	v_mfma_f32_16x16x32_bf16 v[14:17], v[134:137], v[212:215], v[14:17]
	s_setprio 0
	s_setprio 1
	v_mfma_f32_16x16x32_bf16 v[54:57], v[162:165], v[184:187], 0
	v_mfma_f32_16x16x32_bf16 v[50:53], v[176:179], v[184:187], 0
	v_mfma_f32_16x16x32_bf16 v[34:37], v[176:179], v[192:195], 0
	v_mfma_f32_16x16x32_bf16 v[38:41], v[162:165], v[192:195], 0
	v_mfma_f32_16x16x32_bf16 v[22:25], v[162:165], v[200:203], 0
	v_mfma_f32_16x16x32_bf16 v[18:21], v[176:179], v[200:203], 0
	v_mfma_f32_16x16x32_bf16 v[2:5], v[176:179], v[208:211], 0
	v_mfma_f32_16x16x32_bf16 v[6:9], v[162:165], v[208:211], 0
	v_mfma_f32_16x16x32_bf16 v[54:57], v[166:169], v[188:191], v[54:57]
	v_mfma_f32_16x16x32_bf16 v[50:53], v[180:183], v[188:191], v[50:53]
	v_mfma_f32_16x16x32_bf16 v[34:37], v[180:183], v[196:199], v[34:37]
	v_mfma_f32_16x16x32_bf16 v[38:41], v[166:169], v[196:199], v[38:41]
	v_mfma_f32_16x16x32_bf16 v[22:25], v[166:169], v[204:207], v[22:25]
	v_mfma_f32_16x16x32_bf16 v[18:21], v[180:183], v[204:207], v[18:21]
	v_mfma_f32_16x16x32_bf16 v[2:5], v[180:183], v[212:215], v[2:5]
	v_mfma_f32_16x16x32_bf16 v[6:9], v[166:169], v[212:215], v[6:9]
	s_setprio 0
	s_barrier
	s_add_i32 s57, 0, 0x18000
	s_add_i32 s58, 0, 0x1c000
	v_add_u32_e32 v142, s57, v170
	v_add_u32_e32 v180, s58, v170
	ds_read_b128 v[130:133], v142
	ds_read_b128 v[134:137], v142 offset:1024
	ds_read_b128 v[138:141], v142 offset:2048
	ds_read_b128 v[142:145], v142 offset:3072
	ds_read_b128 v[162:165], v180
	ds_read_b128 v[166:169], v180 offset:1024
	ds_read_b128 v[176:179], v180 offset:2048
	ds_read_b128 v[180:183], v180 offset:3072
	s_add_u32 s38, s38, 0x40000
	s_addc_u32 s39, s39, 0
	s_mov_b32 m0, s42
	v_lshl_add_u64 v[224:225], s[38:39], 0, v[146:147]
	ds_read_b128 v[184:187], v174 offset:32768
	ds_read_b128 v[188:191], v174 offset:33792
	ds_read_b128 v[192:195], v174 offset:34816
	ds_read_b128 v[196:199], v174 offset:35840
	ds_read_b128 v[200:203], v174 offset:36864
	ds_read_b128 v[204:207], v174 offset:37888
	ds_read_b128 v[208:211], v174 offset:38912
	ds_read_b128 v[212:215], v174 offset:39936
	global_load_lds_dwordx4 v[224:225], off
	v_lshl_add_u64 v[224:225], s[38:39], 0, v[150:151]
	s_mov_b32 m0, s43
	s_nop 0
	global_load_lds_dwordx4 v[224:225], off
	s_waitcnt vmcnt(8)
	s_waitcnt lgkmcnt(0)
	s_barrier
	s_setprio 1
	s_waitcnt lgkmcnt(0)
	v_mfma_f32_16x16x32_bf16 v[126:129], v[130:133], v[184:187], v[126:129]
	v_mfma_f32_16x16x32_bf16 v[122:125], v[138:141], v[184:187], v[122:125]
	v_mfma_f32_16x16x32_bf16 v[106:109], v[138:141], v[192:195], v[106:109]
	v_mfma_f32_16x16x32_bf16 v[110:113], v[130:133], v[192:195], v[110:113]
	v_mfma_f32_16x16x32_bf16 v[94:97], v[130:133], v[200:203], v[94:97]
	v_mfma_f32_16x16x32_bf16 v[90:93], v[138:141], v[200:203], v[90:93]
	v_mfma_f32_16x16x32_bf16 v[74:77], v[138:141], v[208:211], v[74:77]
	v_mfma_f32_16x16x32_bf16 v[78:81], v[130:133], v[208:211], v[78:81]
	v_mfma_f32_16x16x32_bf16 v[126:129], v[134:137], v[188:191], v[126:129]
	v_mfma_f32_16x16x32_bf16 v[122:125], v[142:145], v[188:191], v[122:125]
	v_mfma_f32_16x16x32_bf16 v[106:109], v[142:145], v[196:199], v[106:109]
	v_mfma_f32_16x16x32_bf16 v[110:113], v[134:137], v[196:199], v[110:113]
	v_mfma_f32_16x16x32_bf16 v[94:97], v[134:137], v[204:207], v[94:97]
	v_mfma_f32_16x16x32_bf16 v[90:93], v[142:145], v[204:207], v[90:93]
	v_mfma_f32_16x16x32_bf16 v[74:77], v[142:145], v[212:215], v[74:77]
	v_mfma_f32_16x16x32_bf16 v[78:81], v[134:137], v[212:215], v[78:81]
	s_setprio 0
	s_setprio 1
	v_mfma_f32_16x16x32_bf16 v[118:121], v[162:165], v[184:187], v[118:121]
	v_mfma_f32_16x16x32_bf16 v[114:117], v[176:179], v[184:187], v[114:117]
	v_mfma_f32_16x16x32_bf16 v[98:101], v[176:179], v[192:195], v[98:101]
	v_mfma_f32_16x16x32_bf16 v[102:105], v[162:165], v[192:195], v[102:105]
	v_mfma_f32_16x16x32_bf16 v[86:89], v[162:165], v[200:203], v[86:89]
	v_mfma_f32_16x16x32_bf16 v[82:85], v[176:179], v[200:203], v[82:85]
	v_mfma_f32_16x16x32_bf16 v[66:69], v[176:179], v[208:211], v[66:69]
	v_mfma_f32_16x16x32_bf16 v[70:73], v[162:165], v[208:211], v[70:73]
	v_mfma_f32_16x16x32_bf16 v[118:121], v[166:169], v[188:191], v[118:121]
	v_mfma_f32_16x16x32_bf16 v[114:117], v[180:183], v[188:191], v[114:117]
	v_mfma_f32_16x16x32_bf16 v[98:101], v[180:183], v[196:199], v[98:101]
	v_mfma_f32_16x16x32_bf16 v[102:105], v[166:169], v[196:199], v[102:105]
	v_mfma_f32_16x16x32_bf16 v[86:89], v[166:169], v[204:207], v[86:89]
	v_mfma_f32_16x16x32_bf16 v[82:85], v[180:183], v[204:207], v[82:85]
	v_mfma_f32_16x16x32_bf16 v[66:69], v[180:183], v[212:215], v[66:69]
	v_mfma_f32_16x16x32_bf16 v[70:73], v[166:169], v[212:215], v[70:73]
	s_setprio 0
	s_barrier
; #define PG8_STAGE(bufoff, gbase, voff) do { _Pragma("unroll") for (int _i = 0; _i < 2; ++_i) \
;         __builtin_amdgcn_global_load_lds((const unsigned*)((const char*)(gbase) + (voff)[_i]), (PG8_LAS unsigned*)(lds + (bufoff) + ldsw + _i * 8192), 16, 0, 0); } while (0)
; #define PG8_LDA(dst, b, h) do { _Pragma("unroll") for (int m = 0; m < 4; ++m) _Pragma("unroll") for (int k = 0; k < 2; ++k) dst[m][k] = *(const PG8_LAS bf16x8*)(lds + PG8_SA(b, h) + aoff + m * 2048 + k * 1024); } while (0)
; #define PG8_LDB(dst, b, h) do { _Pragma("unroll") for (int n = 0; n < 2; ++n) _Pragma("unroll") for (int k = 0; k < 2; ++k) dst[n][k] = *(const PG8_LAS bf16x8*)(lds + PG8_SB(b, h) + boff + n * 2048 + k * 1024); } while (0)
; #define PG8_WAIT_V(n) asm volatile("s_waitcnt vmcnt(" #n ")" ::: "memory")
; #define PG8_WAIT_L(n) asm volatile("s_waitcnt lgkmcnt(" #n ")" ::: "memory")
; #define PG8_BAR __builtin_amdgcn_s_barrier()
; template <class Epi, class Sched, bool ALIGN_EPI = false, bool SP2 = false>
; __device__ __forceinline__ void gemm_phase(PG8_LAS unsigned char* lds, const Gemm g, const Sched& S, const Epi& E) {
;     ...
;         for (int t = 0; t < nt; t += 2) {
;             const bool last = (t == nt - 2);
;             const char* a1 = cA + (size_t)(t + 1) * kstep;
;             const char* a2 = last ? nA : cA + (size_t)(t + 2) * kstep; const char* b2 = last ? nB : cB + (size_t)(t + 2) * kstep;
;             const char* a3 = a2 + kstep; const char* b3 = b2 + kstep;
;             if (last && has_next) S.a_ready(nxt);
;             if constexpr (SP2) {
;             PG8_LDB(B0, 0, 0); PG8_LDB(B1, 0, 1); PG8_SCHED; PG8_LDA(At, 0, 0); PG8_STAGE(PG8_SA(1, 1), a1 + hstepA, voffA);
;             PG8_WAIT_V(8); PG8_WAIT_L(0); PG8_BAR; PG8_MMA(0, 0, At, B0); PG8_MMA(0, 1, At, B1); PG8_BAR; PG8_SCHED;
;             PG8_LDA(At, 0, 1); PG8_STAGE(PG8_SB(0, 0), b2, voffB); PG8_STAGE(PG8_SB(0, 1), b2 + hstepB, voffB); PG8_STAGE(PG8_SA(0, 0), a2, voffA);
;             PG8_WAIT_V(8); PG8_WAIT_L(0); PG8_BAR; PG8_MMA(1, 0, At, B0); PG8_MMA(1, 1, At, B1); PG8_BAR; PG8_SCHED;
;     ...
;             PG8_LDA(At, 1, 1); PG8_STAGE(PG8_SB(1, 0), b3, voffB); PG8_STAGE(PG8_SB(1, 1), b3 + hstepB, voffB); PG8_STAGE(PG8_SA(1, 0), a3, voffA);
;             PG8_WAIT_V(8); PG8_WAIT_L(0); PG8_BAR; PG8_MMA(1, 0, At, B0); PG8_MMA(1, 1, At, B1); PG8_BAR; PG8_SCHED;
	s_add_i32 s38, s57, s33
	v_lshl_add_u64 v[216:217], v[216:217], 0, s[18:19]
	s_mov_b32 m0, s38
	ds_read_b128 v[184:187], v174 offset:49152
	ds_read_b128 v[188:191], v174 offset:50176
	ds_read_b128 v[192:195], v174 offset:51200
	ds_read_b128 v[196:199], v174 offset:52224
	ds_read_b128 v[200:203], v174 offset:53248
	ds_read_b128 v[204:207], v174 offset:54272
	ds_read_b128 v[208:211], v174 offset:55296
	ds_read_b128 v[212:215], v174 offset:56320
	global_load_lds_dwordx4 v[216:217], off
	s_add_i32 m0, s38, 0x2000
	s_add_u32 s36, s36, 0x40080
	v_lshl_add_u64 v[216:217], v[218:219], 0, s[18:19]
	s_addc_u32 s37, s37, 0
	s_add_i32 s38, s58, s33
	global_load_lds_dwordx4 v[216:217], off
	v_lshl_add_u64 v[216:217], s[36:37], 0, v[148:149]
	s_mov_b32 m0, s38
	s_nop 0
	global_load_lds_dwordx4 v[216:217], off
	v_lshl_add_u64 v[216:217], s[36:37], 0, v[152:153]
	s_add_i32 m0, s38, 0x2000
	s_nop 0
	global_load_lds_dwordx4 v[216:217], off
	v_lshl_add_u64 v[216:217], v[220:221], 0, s[18:19]
	s_mov_b32 m0, s45
	s_nop 0
	global_load_lds_dwordx4 v[216:217], off
	v_lshl_add_u64 v[216:217], v[222:223], 0, s[18:19]
	s_mov_b32 m0, s46
	s_nop 0
	global_load_lds_dwordx4 v[216:217], off
	s_waitcnt vmcnt(8)
	s_waitcnt lgkmcnt(0)
	s_barrier
	s_setprio 1
	s_waitcnt lgkmcnt(0)
	v_mfma_f32_16x16x32_bf16 v[62:65], v[130:133], v[184:187], v[62:65]
	v_mfma_f32_16x16x32_bf16 v[58:61], v[138:141], v[184:187], v[58:61]
	v_mfma_f32_16x16x32_bf16 v[42:45], v[138:141], v[192:195], v[42:45]
	v_mfma_f32_16x16x32_bf16 v[46:49], v[130:133], v[192:195], v[46:49]
	v_mfma_f32_16x16x32_bf16 v[30:33], v[130:133], v[200:203], v[30:33]
	v_mfma_f32_16x16x32_bf16 v[26:29], v[138:141], v[200:203], v[26:29]
	v_mfma_f32_16x16x32_bf16 v[10:13], v[138:141], v[208:211], v[10:13]
	v_mfma_f32_16x16x32_bf16 v[14:17], v[130:133], v[208:211], v[14:17]
	v_mfma_f32_16x16x32_bf16 v[62:65], v[134:137], v[188:191], v[62:65]
	v_mfma_f32_16x16x32_bf16 v[58:61], v[142:145], v[188:191], v[58:61]
	v_mfma_f32_16x16x32_bf16 v[42:45], v[142:145], v[196:199], v[42:45]
	v_mfma_f32_16x16x32_bf16 v[46:49], v[134:137], v[196:199], v[46:49]
	v_mfma_f32_16x16x32_bf16 v[30:33], v[134:137], v[204:207], v[30:33]
	v_mfma_f32_16x16x32_bf16 v[26:29], v[142:145], v[204:207], v[26:29]
	v_mfma_f32_16x16x32_bf16 v[10:13], v[142:145], v[212:215], v[10:13]
	v_mfma_f32_16x16x32_bf16 v[14:17], v[134:137], v[212:215], v[14:17]
	s_setprio 0
	s_setprio 1
	v_mfma_f32_16x16x32_bf16 v[54:57], v[162:165], v[184:187], v[54:57]
	v_mfma_f32_16x16x32_bf16 v[50:53], v[176:179], v[184:187], v[50:53]
	v_mfma_f32_16x16x32_bf16 v[34:37], v[176:179], v[192:195], v[34:37]
	v_mfma_f32_16x16x32_bf16 v[38:41], v[162:165], v[192:195], v[38:41]
	v_mfma_f32_16x16x32_bf16 v[22:25], v[162:165], v[200:203], v[22:25]
	v_mfma_f32_16x16x32_bf16 v[18:21], v[176:179], v[200:203], v[18:21]
	v_mfma_f32_16x16x32_bf16 v[2:5], v[176:179], v[208:211], v[2:5]
	v_mfma_f32_16x16x32_bf16 v[6:9], v[162:165], v[208:211], v[6:9]
	v_mfma_f32_16x16x32_bf16 v[54:57], v[166:169], v[188:191], v[54:57]
	v_mfma_f32_16x16x32_bf16 v[50:53], v[180:183], v[188:191], v[50:53]
	v_mfma_f32_16x16x32_bf16 v[34:37], v[180:183], v[196:199], v[34:37]
	v_mfma_f32_16x16x32_bf16 v[38:41], v[166:169], v[196:199], v[38:41]
	v_mfma_f32_16x16x32_bf16 v[22:25], v[166:169], v[204:207], v[22:25]
	v_mfma_f32_16x16x32_bf16 v[18:21], v[180:183], v[204:207], v[18:21]
	v_mfma_f32_16x16x32_bf16 v[2:5], v[180:183], v[212:215], v[2:5]
	v_mfma_f32_16x16x32_bf16 v[6:9], v[166:169], v[212:215], v[6:9]
	s_setprio 0
	s_barrier
	s_add_i32 s56, s56, 2
	s_add_u32 s34, s34, 0x100
	s_addc_u32 s35, s35, 0
	s_add_u32 s54, s54, 0x100
	s_addc_u32 s55, s55, 0
	s_cmp_gt_u32 s56, 13
.LBB0_605:
	ds_read_b128 v[130:133], v172
	ds_read_b128 v[134:137], v172 offset:1024
	ds_read_b128 v[138:141], v172 offset:2048
	ds_read_b128 v[142:145], v172 offset:3072
	ds_read_b128 v[162:165], v173
	ds_read_b128 v[166:169], v173 offset:1024
	ds_read_b128 v[176:179], v173 offset:2048
	ds_read_b128 v[180:183], v173 offset:3072
	s_add_u32 s36, s34, 0xfffc0080
	s_addc_u32 s37, s35, -1
	s_cmp_eq_u32 s56, 12
	s_cselect_b32 s39, s25, s37
	s_cselect_b32 s38, s31, s36
	s_cselect_b32 s37, s23, s55
	s_cselect_b32 s36, s53, s54
	v_lshl_add_u64 v[216:217], s[34:35], 0, v[154:155]
	s_add_i32 m0, s40, 0xc000
	ds_read_b128 v[184:187], v174
	ds_read_b128 v[188:191], v174 offset:1024
	ds_read_b128 v[192:195], v174 offset:2048
	ds_read_b128 v[196:199], v174 offset:3072
	ds_read_b128 v[200:203], v174 offset:4096
	ds_read_b128 v[204:207], v174 offset:5120
	ds_read_b128 v[208:211], v174 offset:6144
	ds_read_b128 v[212:215], v174 offset:7168
	global_load_lds_dwordx4 v[216:217], off
	v_lshl_add_u64 v[216:217], s[34:35], 0, v[156:157]
	s_add_i32 m0, s40, 0xe000
	s_nop 0
	global_load_lds_dwordx4 v[216:217], off
	s_waitcnt vmcnt(8)
	s_waitcnt lgkmcnt(0)
	s_barrier
; #define PG8_STAGE(bufoff, gbase, voff) do { _Pragma("unroll") for (int _i = 0; _i < 2; ++_i) \
;         __builtin_amdgcn_global_load_lds((const unsigned*)((const char*)(gbase) + (voff)[_i]), (PG8_LAS unsigned*)(lds + (bufoff) + ldsw + _i * 8192), 16, 0, 0); } while (0)
; #define PG8_LDA(dst, b, h) do { _Pragma("unroll") for (int m = 0; m < 4; ++m) _Pragma("unroll") for (int k = 0; k < 2; ++k) dst[m][k] = *(const PG8_LAS bf16x8*)(lds + PG8_SA(b, h) + aoff + m * 2048 + k * 1024); } while (0)
; #define PG8_LDB(dst, b, h) do { _Pragma("unroll") for (int n = 0; n < 2; ++n) _Pragma("unroll") for (int k = 0; k < 2; ++k) dst[n][k] = *(const PG8_LAS bf16x8*)(lds + PG8_SB(b, h) + boff + n * 2048 + k * 1024); } while (0)
; #define PG8_MMA(ai, bj, At, Bt) do { __builtin_amdgcn_s_setprio(1); _Pragma("unroll") for (int m = 0; m < 4; ++m) _Pragma("unroll") for (int n = 0; n < 2; ++n) _Pragma("unroll") for (int k = 0; k < 2; ++k) \
;         acc[ai][bj][m][n] = __builtin_amdgcn_mfma_f32_16x16x32_bf16(Bt[n][k], At[m][k], acc[ai][bj][m][n], 0, 0, 0); __builtin_amdgcn_s_setprio(0); } while (0)
; #define PG8_WAIT_V(n) asm volatile("s_waitcnt vmcnt(" #n ")" ::: "memory")
; #define PG8_WAIT_L(n) asm volatile("s_waitcnt lgkmcnt(" #n ")" ::: "memory")
; #define PG8_BAR __builtin_amdgcn_s_barrier()
; #define PG8_SCHED __builtin_amdgcn_sched_barrier(0)
; template <class Epi, class Sched, bool ALIGN_EPI = false, bool SP2 = false>
; __device__ __forceinline__ void gemm_phase(PG8_LAS unsigned char* lds, const Gemm g, const Sched& S, const Epi& E) {
;     ...
;             PG8_LDB(B0, 0, 0); PG8_LDB(B1, 0, 1); PG8_SCHED; PG8_LDA(At, 0, 0); PG8_STAGE(PG8_SA(1, 1), a1 + hstepA, voffA);
;             PG8_WAIT_V(8); PG8_WAIT_L(0); PG8_BAR; PG8_MMA(0, 0, At, B0); PG8_MMA(0, 1, At, B1); PG8_BAR; PG8_SCHED;
;             PG8_LDA(At, 0, 1); PG8_STAGE(PG8_SB(0, 0), b2, voffB); PG8_STAGE(PG8_SB(0, 1), b2 + hstepB, voffB); PG8_STAGE(PG8_SA(0, 0), a2, voffA);
;             PG8_WAIT_V(8); PG8_WAIT_L(0); PG8_BAR; PG8_MMA(1, 0, At, B0); PG8_MMA(1, 1, At, B1); PG8_BAR; PG8_SCHED;
	s_setprio 1
	s_waitcnt lgkmcnt(0)
	v_mfma_f32_16x16x32_bf16 v[126:129], v[130:133], v[184:187], v[126:129]
	v_mfma_f32_16x16x32_bf16 v[122:125], v[138:141], v[184:187], v[122:125]
	v_mfma_f32_16x16x32_bf16 v[106:109], v[138:141], v[192:195], v[106:109]
	v_mfma_f32_16x16x32_bf16 v[110:113], v[130:133], v[192:195], v[110:113]
	v_mfma_f32_16x16x32_bf16 v[94:97], v[130:133], v[200:203], v[94:97]
	v_mfma_f32_16x16x32_bf16 v[90:93], v[138:141], v[200:203], v[90:93]
	v_mfma_f32_16x16x32_bf16 v[74:77], v[138:141], v[208:211], v[74:77]
	v_mfma_f32_16x16x32_bf16 v[78:81], v[130:133], v[208:211], v[78:81]
	v_mfma_f32_16x16x32_bf16 v[126:129], v[134:137], v[188:191], v[126:129]
	v_mfma_f32_16x16x32_bf16 v[122:125], v[142:145], v[188:191], v[122:125]
	v_mfma_f32_16x16x32_bf16 v[106:109], v[142:145], v[196:199], v[106:109]
	v_mfma_f32_16x16x32_bf16 v[110:113], v[134:137], v[196:199], v[110:113]
	v_mfma_f32_16x16x32_bf16 v[94:97], v[134:137], v[204:207], v[94:97]
	v_mfma_f32_16x16x32_bf16 v[90:93], v[142:145], v[204:207], v[90:93]
	v_mfma_f32_16x16x32_bf16 v[74:77], v[142:145], v[212:215], v[74:77]
	v_mfma_f32_16x16x32_bf16 v[78:81], v[134:137], v[212:215], v[78:81]
	s_setprio 0
	s_setprio 1
	v_mfma_f32_16x16x32_bf16 v[118:121], v[162:165], v[184:187], v[118:121]
	v_mfma_f32_16x16x32_bf16 v[114:117], v[176:179], v[184:187], v[114:117]
	v_mfma_f32_16x16x32_bf16 v[98:101], v[176:179], v[192:195], v[98:101]
	v_mfma_f32_16x16x32_bf16 v[102:105], v[162:165], v[192:195], v[102:105]
	v_mfma_f32_16x16x32_bf16 v[86:89], v[162:165], v[200:203], v[86:89]
	v_mfma_f32_16x16x32_bf16 v[82:85], v[176:179], v[200:203], v[82:85]
	v_mfma_f32_16x16x32_bf16 v[66:69], v[176:179], v[208:211], v[66:69]
	v_mfma_f32_16x16x32_bf16 v[70:73], v[162:165], v[208:211], v[70:73]
	v_mfma_f32_16x16x32_bf16 v[118:121], v[166:169], v[188:191], v[118:121]
	v_mfma_f32_16x16x32_bf16 v[114:117], v[180:183], v[188:191], v[114:117]
	v_mfma_f32_16x16x32_bf16 v[98:101], v[180:183], v[196:199], v[98:101]
	v_mfma_f32_16x16x32_bf16 v[102:105], v[166:169], v[196:199], v[102:105]
	v_mfma_f32_16x16x32_bf16 v[86:89], v[166:169], v[204:207], v[86:89]
	v_mfma_f32_16x16x32_bf16 v[82:85], v[180:183], v[204:207], v[82:85]
	v_mfma_f32_16x16x32_bf16 v[66:69], v[180:183], v[212:215], v[66:69]
	v_mfma_f32_16x16x32_bf16 v[70:73], v[166:169], v[212:215], v[70:73]
	s_setprio 0
	s_barrier
	s_add_i32 s57, s50, s33
	v_lshl_add_u64 v[216:217], s[36:37], 0, v[148:149]
	s_mov_b32 m0, s57
	ds_read_b128 v[184:187], v174 offset:16384
	ds_read_b128 v[188:191], v174 offset:17408
	ds_read_b128 v[192:195], v174 offset:18432
	ds_read_b128 v[196:199], v174 offset:19456
	ds_read_b128 v[200:203], v174 offset:20480
	ds_read_b128 v[204:207], v174 offset:21504
	ds_read_b128 v[208:211], v174 offset:22528
	ds_read_b128 v[212:215], v174 offset:23552
	global_load_lds_dwordx4 v[216:217], off
	s_add_i32 m0, s57, 0x2000
	s_add_u32 s58, s36, 0x40000
	v_lshl_add_u64 v[218:219], s[36:37], 0, v[152:153]
	s_addc_u32 s59, s37, 0
	s_add_i32 s57, s51, s33
	global_load_lds_dwordx4 v[218:219], off
	v_lshl_add_u64 v[220:221], s[58:59], 0, v[148:149]
	s_mov_b32 m0, s57
	v_lshl_add_u64 v[222:223], s[38:39], 0, v[150:151]
	global_load_lds_dwordx4 v[220:221], off
	v_lshl_add_u64 v[220:221], s[58:59], 0, v[152:153]
	s_add_i32 m0, s57, 0x2000
	s_nop 0
	global_load_lds_dwordx4 v[220:221], off
	v_lshl_add_u64 v[220:221], s[38:39], 0, v[146:147]
	s_mov_b32 m0, s40
	s_nop 0
	global_load_lds_dwordx4 v[220:221], off
	s_mov_b32 m0, s41
	s_nop 0
	global_load_lds_dwordx4 v[222:223], off
	s_waitcnt vmcnt(8)
	s_waitcnt lgkmcnt(0)
	s_barrier
	s_setprio 1
	s_waitcnt lgkmcnt(0)
	v_mfma_f32_16x16x32_bf16 v[62:65], v[130:133], v[184:187], v[62:65]
	v_mfma_f32_16x16x32_bf16 v[58:61], v[138:141], v[184:187], v[58:61]
	v_mfma_f32_16x16x32_bf16 v[42:45], v[138:141], v[192:195], v[42:45]
	v_mfma_f32_16x16x32_bf16 v[46:49], v[130:133], v[192:195], v[46:49]
	v_mfma_f32_16x16x32_bf16 v[30:33], v[130:133], v[200:203], v[30:33]
	v_mfma_f32_16x16x32_bf16 v[26:29], v[138:141], v[200:203], v[26:29]
	v_mfma_f32_16x16x32_bf16 v[10:13], v[138:141], v[208:211], v[10:13]
	v_mfma_f32_16x16x32_bf16 v[14:17], v[130:133], v[208:211], v[14:17]
	v_mfma_f32_16x16x32_bf16 v[62:65], v[134:137], v[188:191], v[62:65]
	v_mfma_f32_16x16x32_bf16 v[58:61], v[142:145], v[188:191], v[58:61]
	v_mfma_f32_16x16x32_bf16 v[42:45], v[142:145], v[196:199], v[42:45]
	v_mfma_f32_16x16x32_bf16 v[46:49], v[134:137], v[196:199], v[46:49]
	v_mfma_f32_16x16x32_bf16 v[30:33], v[134:137], v[204:207], v[30:33]
	v_mfma_f32_16x16x32_bf16 v[26:29], v[142:145], v[204:207], v[26:29]
	v_mfma_f32_16x16x32_bf16 v[10:13], v[142:145], v[212:215], v[10:13]
	v_mfma_f32_16x16x32_bf16 v[14:17], v[134:137], v[212:215], v[14:17]
	s_setprio 0
	s_setprio 1
	v_mfma_f32_16x16x32_bf16 v[54:57], v[162:165], v[184:187], v[54:57]
	v_mfma_f32_16x16x32_bf16 v[50:53], v[176:179], v[184:187], v[50:53]
	v_mfma_f32_16x16x32_bf16 v[34:37], v[176:179], v[192:195], v[34:37]
	v_mfma_f32_16x16x32_bf16 v[38:41], v[162:165], v[192:195], v[38:41]
	v_mfma_f32_16x16x32_bf16 v[22:25], v[162:165], v[200:203], v[22:25]
	v_mfma_f32_16x16x32_bf16 v[18:21], v[176:179], v[200:203], v[18:21]
	v_mfma_f32_16x16x32_bf16 v[2:5], v[176:179], v[208:211], v[2:5]
	v_mfma_f32_16x16x32_bf16 v[6:9], v[162:165], v[208:211], v[6:9]
	v_mfma_f32_16x16x32_bf16 v[54:57], v[166:169], v[188:191], v[54:57]
	v_mfma_f32_16x16x32_bf16 v[50:53], v[180:183], v[188:191], v[50:53]
	v_mfma_f32_16x16x32_bf16 v[34:37], v[180:183], v[196:199], v[34:37]
	v_mfma_f32_16x16x32_bf16 v[38:41], v[166:169], v[196:199], v[38:41]
	v_mfma_f32_16x16x32_bf16 v[22:25], v[166:169], v[204:207], v[22:25]
	v_mfma_f32_16x16x32_bf16 v[18:21], v[180:183], v[204:207], v[18:21]
	v_mfma_f32_16x16x32_bf16 v[2:5], v[180:183], v[212:215], v[2:5]
	v_mfma_f32_16x16x32_bf16 v[6:9], v[166:169], v[212:215], v[6:9]
	s_setprio 0
	s_barrier
; #define PG8_STAGE(bufoff, gbase, voff) do { _Pragma("unroll") for (int _i = 0; _i < 2; ++_i) \
;         __builtin_amdgcn_global_load_lds((const unsigned*)((const char*)(gbase) + (voff)[_i]), (PG8_LAS unsigned*)(lds + (bufoff) + ldsw + _i * 8192), 16, 0, 0); } while (0)
; #define PG8_LDA(dst, b, h) do { _Pragma("unroll") for (int m = 0; m < 4; ++m) _Pragma("unroll") for (int k = 0; k < 2; ++k) dst[m][k] = *(const PG8_LAS bf16x8*)(lds + PG8_SA(b, h) + aoff + m * 2048 + k * 1024); } while (0)
; #define PG8_LDB(dst, b, h) do { _Pragma("unroll") for (int n = 0; n < 2; ++n) _Pragma("unroll") for (int k = 0; k < 2; ++k) dst[n][k] = *(const PG8_LAS bf16x8*)(lds + PG8_SB(b, h) + boff + n * 2048 + k * 1024); } while (0)
; #define PG8_MMA(ai, bj, At, Bt) do { __builtin_amdgcn_s_setprio(1); _Pragma("unroll") for (int m = 0; m < 4; ++m) _Pragma("unroll") for (int n = 0; n < 2; ++n) _Pragma("unroll") for (int k = 0; k < 2; ++k) \
;         acc[ai][bj][m][n] = __builtin_amdgcn_mfma_f32_16x16x32_bf16(Bt[n][k], At[m][k], acc[ai][bj][m][n], 0, 0, 0); __builtin_amdgcn_s_setprio(0); } while (0)
; #define PG8_WAIT_V(n) asm volatile("s_waitcnt vmcnt(" #n ")" ::: "memory")
; #define PG8_WAIT_L(n) asm volatile("s_waitcnt lgkmcnt(" #n ")" ::: "memory")
; #define PG8_BAR __builtin_amdgcn_s_barrier()
; #define PG8_SCHED __builtin_amdgcn_sched_barrier(0)
; template <class Epi, class Sched, bool ALIGN_EPI = false, bool SP2 = false>
; __device__ __forceinline__ void gemm_phase(PG8_LAS unsigned char* lds, const Gemm g, const Sched& S, const Epi& E) {
;     ...
;             PG8_LDB(B0, 1, 0); PG8_LDB(B1, 1, 1); PG8_SCHED; PG8_LDA(At, 1, 0); PG8_STAGE(PG8_SA(0, 1), a2 + hstepA, voffA);
;             PG8_WAIT_V(8); PG8_WAIT_L(0); PG8_BAR; PG8_MMA(0, 0, At, B0); PG8_MMA(0, 1, At, B1); PG8_BAR; PG8_SCHED;
	s_add_i32 s57, 0, 0x18000
	s_add_i32 s58, 0, 0x1c000
	v_add_u32_e32 v142, s57, v170
	v_add_u32_e32 v180, s58, v170
	ds_read_b128 v[130:133], v142
	ds_read_b128 v[134:137], v142 offset:1024
	ds_read_b128 v[138:141], v142 offset:2048
	ds_read_b128 v[142:145], v142 offset:3072
	ds_read_b128 v[162:165], v180
	ds_read_b128 v[166:169], v180 offset:1024
	ds_read_b128 v[176:179], v180 offset:2048
	ds_read_b128 v[180:183], v180 offset:3072
	s_add_u32 s38, s38, 0x40000
	s_addc_u32 s39, s39, 0
	s_mov_b32 m0, s42
	v_lshl_add_u64 v[224:225], s[38:39], 0, v[146:147]
	ds_read_b128 v[184:187], v174 offset:32768
	ds_read_b128 v[188:191], v174 offset:33792
	ds_read_b128 v[192:195], v174 offset:34816
	ds_read_b128 v[196:199], v174 offset:35840
	ds_read_b128 v[200:203], v174 offset:36864
	ds_read_b128 v[204:207], v174 offset:37888
	ds_read_b128 v[208:211], v174 offset:38912
	ds_read_b128 v[212:215], v174 offset:39936
	global_load_lds_dwordx4 v[224:225], off
	v_lshl_add_u64 v[224:225], s[38:39], 0, v[150:151]
	s_mov_b32 m0, s43
	s_nop 0
	global_load_lds_dwordx4 v[224:225], off
	s_waitcnt vmcnt(8)
	s_waitcnt lgkmcnt(0)
	s_barrier
	s_setprio 1
	s_waitcnt lgkmcnt(0)
	v_mfma_f32_16x16x32_bf16 v[126:129], v[130:133], v[184:187], v[126:129]
	v_mfma_f32_16x16x32_bf16 v[122:125], v[138:141], v[184:187], v[122:125]
	v_mfma_f32_16x16x32_bf16 v[106:109], v[138:141], v[192:195], v[106:109]
	v_mfma_f32_16x16x32_bf16 v[110:113], v[130:133], v[192:195], v[110:113]
	v_mfma_f32_16x16x32_bf16 v[94:97], v[130:133], v[200:203], v[94:97]
	v_mfma_f32_16x16x32_bf16 v[90:93], v[138:141], v[200:203], v[90:93]
	v_mfma_f32_16x16x32_bf16 v[74:77], v[138:141], v[208:211], v[74:77]
	v_mfma_f32_16x16x32_bf16 v[78:81], v[130:133], v[208:211], v[78:81]
	v_mfma_f32_16x16x32_bf16 v[126:129], v[134:137], v[188:191], v[126:129]
	v_mfma_f32_16x16x32_bf16 v[122:125], v[142:145], v[188:191], v[122:125]
	v_mfma_f32_16x16x32_bf16 v[106:109], v[142:145], v[196:199], v[106:109]
	v_mfma_f32_16x16x32_bf16 v[110:113], v[134:137], v[196:199], v[110:113]
	v_mfma_f32_16x16x32_bf16 v[94:97], v[134:137], v[204:207], v[94:97]
	v_mfma_f32_16x16x32_bf16 v[90:93], v[142:145], v[204:207], v[90:93]
	v_mfma_f32_16x16x32_bf16 v[74:77], v[142:145], v[212:215], v[74:77]
	v_mfma_f32_16x16x32_bf16 v[78:81], v[134:137], v[212:215], v[78:81]
	s_setprio 0
	s_setprio 1
	v_mfma_f32_16x16x32_bf16 v[118:121], v[162:165], v[184:187], v[118:121]
	v_mfma_f32_16x16x32_bf16 v[114:117], v[176:179], v[184:187], v[114:117]
	v_mfma_f32_16x16x32_bf16 v[98:101], v[176:179], v[192:195], v[98:101]
	v_mfma_f32_16x16x32_bf16 v[102:105], v[162:165], v[192:195], v[102:105]
	v_mfma_f32_16x16x32_bf16 v[86:89], v[162:165], v[200:203], v[86:89]
	v_mfma_f32_16x16x32_bf16 v[82:85], v[176:179], v[200:203], v[82:85]
	v_mfma_f32_16x16x32_bf16 v[66:69], v[176:179], v[208:211], v[66:69]
	v_mfma_f32_16x16x32_bf16 v[70:73], v[162:165], v[208:211], v[70:73]
	v_mfma_f32_16x16x32_bf16 v[118:121], v[166:169], v[188:191], v[118:121]
	v_mfma_f32_16x16x32_bf16 v[114:117], v[180:183], v[188:191], v[114:117]
	v_mfma_f32_16x16x32_bf16 v[98:101], v[180:183], v[196:199], v[98:101]
	v_mfma_f32_16x16x32_bf16 v[102:105], v[166:169], v[196:199], v[102:105]
	v_mfma_f32_16x16x32_bf16 v[86:89], v[166:169], v[204:207], v[86:89]
	v_mfma_f32_16x16x32_bf16 v[82:85], v[180:183], v[204:207], v[82:85]
	v_mfma_f32_16x16x32_bf16 v[66:69], v[180:183], v[212:215], v[66:69]
	v_mfma_f32_16x16x32_bf16 v[70:73], v[166:169], v[212:215], v[70:73]
	s_setprio 0
	s_barrier
; #define PG8_STAGE(bufoff, gbase, voff) do { _Pragma("unroll") for (int _i = 0; _i < 2; ++_i) \
;         __builtin_amdgcn_global_load_lds((const unsigned*)((const char*)(gbase) + (voff)[_i]), (PG8_LAS unsigned*)(lds + (bufoff) + ldsw + _i * 8192), 16, 0, 0); } while (0)
; #define PG8_LDA(dst, b, h) do { _Pragma("unroll") for (int m = 0; m < 4; ++m) _Pragma("unroll") for (int k = 0; k < 2; ++k) dst[m][k] = *(const PG8_LAS bf16x8*)(lds + PG8_SA(b, h) + aoff + m * 2048 + k * 1024); } while (0)
; #define PG8_MMA(ai, bj, At, Bt) do { __builtin_amdgcn_s_setprio(1); _Pragma("unroll") for (int m = 0; m < 4; ++m) _Pragma("unroll") for (int n = 0; n < 2; ++n) _Pragma("unroll") for (int k = 0; k < 2; ++k) \
;         acc[ai][bj][m][n] = __builtin_amdgcn_mfma_f32_16x16x32_bf16(Bt[n][k], At[m][k], acc[ai][bj][m][n], 0, 0, 0); __builtin_amdgcn_s_setprio(0); } while (0)
; #define PG8_WAIT_V(n) asm volatile("s_waitcnt vmcnt(" #n ")" ::: "memory")
; #define PG8_WAIT_L(n) asm volatile("s_waitcnt lgkmcnt(" #n ")" ::: "memory")
; #define PG8_BAR __builtin_amdgcn_s_barrier()
; #define PG8_SCHED __builtin_amdgcn_sched_barrier(0)
; template <class Epi, class Sched, bool ALIGN_EPI = false, bool SP2 = false>
; __device__ __forceinline__ void gemm_phase(PG8_LAS unsigned char* lds, const Gemm g, const Sched& S, const Epi& E) {
;     ...
;             PG8_LDA(At, 1, 1); PG8_STAGE(PG8_SB(1, 0), b3, voffB); PG8_STAGE(PG8_SB(1, 1), b3 + hstepB, voffB); PG8_STAGE(PG8_SA(1, 0), a3, voffA);
;             PG8_WAIT_V(8); PG8_WAIT_L(0); PG8_BAR; PG8_MMA(1, 0, At, B0); PG8_MMA(1, 1, At, B1); PG8_BAR; PG8_SCHED;
	s_add_i32 s38, s57, s33
	v_lshl_add_u64 v[216:217], v[216:217], 0, s[18:19]
	s_mov_b32 m0, s38
	ds_read_b128 v[184:187], v174 offset:49152
	ds_read_b128 v[188:191], v174 offset:50176
	ds_read_b128 v[192:195], v174 offset:51200
	ds_read_b128 v[196:199], v174 offset:52224
	ds_read_b128 v[200:203], v174 offset:53248
	ds_read_b128 v[204:207], v174 offset:54272
	ds_read_b128 v[208:211], v174 offset:55296
	ds_read_b128 v[212:215], v174 offset:56320
	global_load_lds_dwordx4 v[216:217], off
	s_add_i32 m0, s38, 0x2000
	s_add_u32 s36, s36, 0x40080
	v_lshl_add_u64 v[216:217], v[218:219], 0, s[18:19]
	s_addc_u32 s37, s37, 0
	s_add_i32 s38, s58, s33
	global_load_lds_dwordx4 v[216:217], off
	v_lshl_add_u64 v[216:217], s[36:37], 0, v[148:149]
	s_mov_b32 m0, s38
	s_nop 0
	global_load_lds_dwordx4 v[216:217], off
	v_lshl_add_u64 v[216:217], s[36:37], 0, v[152:153]
	s_add_i32 m0, s38, 0x2000
	s_nop 0
	global_load_lds_dwordx4 v[216:217], off
	v_lshl_add_u64 v[216:217], v[220:221], 0, s[18:19]
	s_mov_b32 m0, s45
	s_nop 0
	global_load_lds_dwordx4 v[216:217], off
	v_lshl_add_u64 v[216:217], v[222:223], 0, s[18:19]
	s_mov_b32 m0, s46
	s_nop 0
	global_load_lds_dwordx4 v[216:217], off
	s_waitcnt vmcnt(8)
	s_waitcnt lgkmcnt(0)
	s_barrier
	s_setprio 1
	s_waitcnt lgkmcnt(0)
	v_mfma_f32_16x16x32_bf16 v[62:65], v[130:133], v[184:187], v[62:65]
	v_mfma_f32_16x16x32_bf16 v[58:61], v[138:141], v[184:187], v[58:61]
	v_mfma_f32_16x16x32_bf16 v[42:45], v[138:141], v[192:195], v[42:45]
	v_mfma_f32_16x16x32_bf16 v[46:49], v[130:133], v[192:195], v[46:49]
	v_mfma_f32_16x16x32_bf16 v[30:33], v[130:133], v[200:203], v[30:33]
	v_mfma_f32_16x16x32_bf16 v[26:29], v[138:141], v[200:203], v[26:29]
	v_mfma_f32_16x16x32_bf16 v[10:13], v[138:141], v[208:211], v[10:13]
	v_mfma_f32_16x16x32_bf16 v[14:17], v[130:133], v[208:211], v[14:17]
	v_mfma_f32_16x16x32_bf16 v[62:65], v[134:137], v[188:191], v[62:65]
	v_mfma_f32_16x16x32_bf16 v[58:61], v[142:145], v[188:191], v[58:61]
	v_mfma_f32_16x16x32_bf16 v[42:45], v[142:145], v[196:199], v[42:45]
	v_mfma_f32_16x16x32_bf16 v[46:49], v[134:137], v[196:199], v[46:49]
	v_mfma_f32_16x16x32_bf16 v[30:33], v[134:137], v[204:207], v[30:33]
	v_mfma_f32_16x16x32_bf16 v[26:29], v[142:145], v[204:207], v[26:29]
	v_mfma_f32_16x16x32_bf16 v[10:13], v[142:145], v[212:215], v[10:13]
	v_mfma_f32_16x16x32_bf16 v[14:17], v[134:137], v[212:215], v[14:17]
	s_setprio 0
	s_setprio 1
	v_mfma_f32_16x16x32_bf16 v[54:57], v[162:165], v[184:187], v[54:57]
	v_mfma_f32_16x16x32_bf16 v[50:53], v[176:179], v[184:187], v[50:53]
	v_mfma_f32_16x16x32_bf16 v[34:37], v[176:179], v[192:195], v[34:37]
	v_mfma_f32_16x16x32_bf16 v[38:41], v[162:165], v[192:195], v[38:41]
	v_mfma_f32_16x16x32_bf16 v[22:25], v[162:165], v[200:203], v[22:25]
	v_mfma_f32_16x16x32_bf16 v[18:21], v[176:179], v[200:203], v[18:21]
	v_mfma_f32_16x16x32_bf16 v[2:5], v[176:179], v[208:211], v[2:5]
	v_mfma_f32_16x16x32_bf16 v[6:9], v[162:165], v[208:211], v[6:9]
	v_mfma_f32_16x16x32_bf16 v[54:57], v[166:169], v[188:191], v[54:57]
	v_mfma_f32_16x16x32_bf16 v[50:53], v[180:183], v[188:191], v[50:53]
	v_mfma_f32_16x16x32_bf16 v[34:37], v[180:183], v[196:199], v[34:37]
	v_mfma_f32_16x16x32_bf16 v[38:41], v[166:169], v[196:199], v[38:41]
	v_mfma_f32_16x16x32_bf16 v[22:25], v[166:169], v[204:207], v[22:25]
	v_mfma_f32_16x16x32_bf16 v[18:21], v[180:183], v[204:207], v[18:21]
	v_mfma_f32_16x16x32_bf16 v[2:5], v[180:183], v[212:215], v[2:5]
	v_mfma_f32_16x16x32_bf16 v[6:9], v[166:169], v[212:215], v[6:9]
	s_setprio 0
	s_barrier
	s_add_i32 s56, s56, 2
	s_add_u32 s34, s34, 0x100
	s_addc_u32 s35, s35, 0
	s_add_u32 s54, s54, 0x100
	s_addc_u32 s55, s55, 0
	s_cmp_gt_u32 s56, 13
	s_cbranch_scc0 .LBB0_605
	s_and_b64 vcc, exec, s[20:21]
	s_cbranch_vccz .LBB0_608
	s_barrier

; #define PG8_STAGE(bufoff, gbase, voff) do { _Pragma("unroll") for (int _i = 0; _i < 2; ++_i) \
;         __builtin_amdgcn_global_load_lds((const unsigned*)((const char*)(gbase) + (voff)[_i]), (PG8_LAS unsigned*)(lds + (bufoff) + ldsw + _i * 8192), 16, 0, 0); } while (0)
; #define PG8_LDA(dst, b, h) do { _Pragma("unroll") for (int m = 0; m < 4; ++m) _Pragma("unroll") for (int k = 0; k < 2; ++k) dst[m][k] = *(const PG8_LAS bf16x8*)(lds + PG8_SA(b, h) + aoff + m * 2048 + k * 1024); } while (0)
; #define PG8_LDB(dst, b, h) do { _Pragma("unroll") for (int n = 0; n < 2; ++n) _Pragma("unroll") for (int k = 0; k < 2; ++k) dst[n][k] = *(const PG8_LAS bf16x8*)(lds + PG8_SB(b, h) + boff + n * 2048 + k * 1024); } while (0)
; #define PG8_WAIT_V(n) asm volatile("s_waitcnt vmcnt(" #n ")" ::: "memory")
; #define PG8_WAIT_L(n) asm volatile("s_waitcnt lgkmcnt(" #n ")" ::: "memory")
; #define PG8_BAR __builtin_amdgcn_s_barrier()
; #define PG8_SCHED __builtin_amdgcn_sched_barrier(0)
; template <class Epi, class Sched, bool ALIGN_EPI = false, bool SP2 = false>
; __device__ __forceinline__ void gemm_phase(PG8_LAS unsigned char* lds, const Gemm g, const Sched& S, const Epi& E) {
;     ...
;         const char* nA = has_next ? (const char*)g.A + (size_t)nxt.g * g.gsA * 2 + (size_t)nxt.pm * tstepA : cA; const char* nB = has_next ? (const char*)g.Bt + (size_t)nxt.g * g.gsB * 2 + (size_t)nxt.pn * tstepB : cB;
;         for (int t = 0; t < nt; t += 2) {
;             const bool last = (t == nt - 2);
;             const char* a1 = cA + (size_t)(t + 1) * kstep;
;             const char* a2 = last ? nA : cA + (size_t)(t + 2) * kstep; const char* b2 = last ? nB : cB + (size_t)(t + 2) * kstep;
;             const char* a3 = a2 + kstep; const char* b3 = b2 + kstep;
;             if (last && has_next) S.a_ready(nxt);
;             if constexpr (SP2) {
;             PG8_LDB(B0, 0, 0); PG8_LDB(B1, 0, 1); PG8_SCHED; PG8_LDA(At, 0, 0); PG8_STAGE(PG8_SA(1, 1), a1 + hstepA, voffA);
;             PG8_WAIT_V(8); PG8_WAIT_L(0); PG8_BAR; PG8_MMA(0, 0, At, B0); PG8_MMA(0, 1, At, B1); PG8_BAR; PG8_SCHED;
;             PG8_LDA(At, 0, 1); PG8_STAGE(PG8_SB(0, 0), b2, voffB); PG8_STAGE(PG8_SB(0, 1), b2 + hstepB, voffB); PG8_STAGE(PG8_SA(0, 0), a2, voffA);
;             PG8_WAIT_V(8); PG8_WAIT_L(0); PG8_BAR; PG8_MMA(1, 0, At, B0); PG8_MMA(1, 1, At, B1); PG8_BAR; PG8_SCHED;
.LBB0_690:
	s_ashr_i32 s17, s16, 31
	s_lshl_b64 s[18:19], s[16:17], 19
	s_add_u32 s18, s0, s18
	s_addc_u32 s19, s1, s19
	s_and_b64 s[20:21], s[6:7], exec
	s_cselect_b32 s17, s19, s25
	s_cselect_b32 s46, s18, s24
	s_ashr_i32 s15, s14, 31
	s_lshl_b64 s[20:21], s[14:15], 19
	s_add_u32 s20, s2, s20
	s_addc_u32 s21, s3, s21
	s_and_b64 s[28:29], s[6:7], exec
	s_cselect_b32 s15, s21, s27
	s_cselect_b32 s47, s20, s26
	s_add_u32 s24, s24, 0x40080
	s_addc_u32 s25, s25, 0
	s_add_u32 s48, s26, 0x100
	s_addc_u32 s49, s27, 0
	s_mov_b32 s50, -2
	ds_read_b128 v[148:151], v168
	ds_read_b128 v[152:155], v168 offset:1024
	ds_read_b128 v[156:159], v168 offset:2048
	ds_read_b128 v[160:163], v168 offset:3072
	ds_read_b128 v[174:177], v169
	ds_read_b128 v[178:181], v169 offset:1024
	ds_read_b128 v[182:185], v169 offset:2048
	ds_read_b128 v[186:189], v169 offset:3072
	s_add_u32 s26, s24, 0xfffc0080
	s_addc_u32 s27, s25, -1
	s_cmp_eq_u32 s50, 12
	s_cselect_b32 s29, s17, s27
	s_cselect_b32 s28, s46, s26
	s_cselect_b32 s27, s15, s49
	s_cselect_b32 s26, s47, s48
	v_lshl_add_u64 v[164:165], s[24:25], 0, v[140:141]
	s_add_i32 m0, s23, 0xc000
	ds_read_b128 v[190:193], v170
	ds_read_b128 v[194:197], v170 offset:1024
	ds_read_b128 v[198:201], v170 offset:2048
	ds_read_b128 v[202:205], v170 offset:3072
	ds_read_b128 v[206:209], v170 offset:4096
	ds_read_b128 v[210:213], v170 offset:5120
	ds_read_b128 v[214:217], v170 offset:6144
	ds_read_b128 v[218:221], v170 offset:7168
	global_load_lds_dwordx4 v[164:165], off
	v_lshl_add_u64 v[164:165], s[24:25], 0, v[142:143]
	s_add_i32 m0, s23, 0xe000
	s_nop 0
	global_load_lds_dwordx4 v[164:165], off
	s_waitcnt vmcnt(8)
	s_waitcnt lgkmcnt(0)
	s_barrier
	s_setprio 1
	s_waitcnt lgkmcnt(0)
	v_mfma_f32_16x16x32_bf16 v[126:129], v[148:151], v[190:193], 0
	v_mfma_f32_16x16x32_bf16 v[118:121], v[156:159], v[190:193], 0
	v_mfma_f32_16x16x32_bf16 v[102:105], v[156:159], v[198:201], 0
	v_mfma_f32_16x16x32_bf16 v[110:113], v[148:151], v[198:201], 0
	v_mfma_f32_16x16x32_bf16 v[94:97], v[148:151], v[206:209], 0
	v_mfma_f32_16x16x32_bf16 v[86:89], v[156:159], v[206:209], 0
	v_mfma_f32_16x16x32_bf16 v[70:73], v[156:159], v[214:217], 0
	v_mfma_f32_16x16x32_bf16 v[78:81], v[148:151], v[214:217], 0
	v_mfma_f32_16x16x32_bf16 v[126:129], v[152:155], v[194:197], v[126:129]
	v_mfma_f32_16x16x32_bf16 v[118:121], v[160:163], v[194:197], v[118:121]
	v_mfma_f32_16x16x32_bf16 v[102:105], v[160:163], v[202:205], v[102:105]
	v_mfma_f32_16x16x32_bf16 v[110:113], v[152:155], v[202:205], v[110:113]
	v_mfma_f32_16x16x32_bf16 v[94:97], v[152:155], v[210:213], v[94:97]
	v_mfma_f32_16x16x32_bf16 v[86:89], v[160:163], v[210:213], v[86:89]
	v_mfma_f32_16x16x32_bf16 v[70:73], v[160:163], v[218:221], v[70:73]
	v_mfma_f32_16x16x32_bf16 v[78:81], v[152:155], v[218:221], v[78:81]
	s_setprio 0
	s_setprio 1
	v_mfma_f32_16x16x32_bf16 v[122:125], v[174:177], v[190:193], 0
	v_mfma_f32_16x16x32_bf16 v[114:117], v[182:185], v[190:193], 0
	v_mfma_f32_16x16x32_bf16 v[98:101], v[182:185], v[198:201], 0
	v_mfma_f32_16x16x32_bf16 v[106:109], v[174:177], v[198:201], 0
	v_mfma_f32_16x16x32_bf16 v[90:93], v[174:177], v[206:209], 0
	v_mfma_f32_16x16x32_bf16 v[82:85], v[182:185], v[206:209], 0
	v_mfma_f32_16x16x32_bf16 v[66:69], v[182:185], v[214:217], 0
	v_mfma_f32_16x16x32_bf16 v[74:77], v[174:177], v[214:217], 0
	v_mfma_f32_16x16x32_bf16 v[122:125], v[178:181], v[194:197], v[122:125]
	v_mfma_f32_16x16x32_bf16 v[114:117], v[186:189], v[194:197], v[114:117]
	v_mfma_f32_16x16x32_bf16 v[98:101], v[186:189], v[202:205], v[98:101]
	v_mfma_f32_16x16x32_bf16 v[106:109], v[178:181], v[202:205], v[106:109]
	v_mfma_f32_16x16x32_bf16 v[90:93], v[178:181], v[210:213], v[90:93]
	v_mfma_f32_16x16x32_bf16 v[82:85], v[186:189], v[210:213], v[82:85]
	v_mfma_f32_16x16x32_bf16 v[66:69], v[186:189], v[218:221], v[66:69]
	v_mfma_f32_16x16x32_bf16 v[74:77], v[178:181], v[218:221], v[74:77]
	s_setprio 0
	s_barrier
	s_add_i32 s51, s42, s30
	v_lshl_add_u64 v[164:165], s[26:27], 0, v[134:135]
	s_mov_b32 m0, s51
	ds_read_b128 v[190:193], v170 offset:16384
	ds_read_b128 v[194:197], v170 offset:17408
	ds_read_b128 v[198:201], v170 offset:18432
	ds_read_b128 v[202:205], v170 offset:19456
	ds_read_b128 v[206:209], v170 offset:20480
	ds_read_b128 v[210:213], v170 offset:21504
	ds_read_b128 v[214:217], v170 offset:22528
	ds_read_b128 v[218:221], v170 offset:23552
	global_load_lds_dwordx4 v[164:165], off
	s_add_i32 m0, s51, 0x2000
	s_add_u32 s52, s26, 0x40000
	v_lshl_add_u64 v[222:223], s[26:27], 0, v[130:131]
	s_addc_u32 s53, s27, 0
	s_add_i32 s51, s43, s30
	global_load_lds_dwordx4 v[222:223], off
	v_lshl_add_u64 v[224:225], s[52:53], 0, v[134:135]
	s_mov_b32 m0, s51
	v_lshl_add_u64 v[226:227], s[28:29], 0, v[132:133]
	global_load_lds_dwordx4 v[224:225], off
	v_lshl_add_u64 v[224:225], s[52:53], 0, v[130:131]
	s_add_i32 m0, s51, 0x2000
	s_nop 0
	global_load_lds_dwordx4 v[224:225], off
	v_lshl_add_u64 v[224:225], s[28:29], 0, v[136:137]
	s_mov_b32 m0, s23
	s_nop 0
	global_load_lds_dwordx4 v[224:225], off
	s_mov_b32 m0, s34
	s_nop 0
	global_load_lds_dwordx4 v[226:227], off
	s_waitcnt vmcnt(8)
	s_waitcnt lgkmcnt(0)
	s_barrier
; #define PG8_STAGE(bufoff, gbase, voff) do { _Pragma("unroll") for (int _i = 0; _i < 2; ++_i) \
;         __builtin_amdgcn_global_load_lds((const unsigned*)((const char*)(gbase) + (voff)[_i]), (PG8_LAS unsigned*)(lds + (bufoff) + ldsw + _i * 8192), 16, 0, 0); } while (0)
; #define PG8_LDA(dst, b, h) do { _Pragma("unroll") for (int m = 0; m < 4; ++m) _Pragma("unroll") for (int k = 0; k < 2; ++k) dst[m][k] = *(const PG8_LAS bf16x8*)(lds + PG8_SA(b, h) + aoff + m * 2048 + k * 1024); } while (0)
; #define PG8_LDB(dst, b, h) do { _Pragma("unroll") for (int n = 0; n < 2; ++n) _Pragma("unroll") for (int k = 0; k < 2; ++k) dst[n][k] = *(const PG8_LAS bf16x8*)(lds + PG8_SB(b, h) + boff + n * 2048 + k * 1024); } while (0)
; #define PG8_MMA(ai, bj, At, Bt) do { __builtin_amdgcn_s_setprio(1); _Pragma("unroll") for (int m = 0; m < 4; ++m) _Pragma("unroll") for (int n = 0; n < 2; ++n) _Pragma("unroll") for (int k = 0; k < 2; ++k) \
;         acc[ai][bj][m][n] = __builtin_amdgcn_mfma_f32_16x16x32_bf16(Bt[n][k], At[m][k], acc[ai][bj][m][n], 0, 0, 0); __builtin_amdgcn_s_setprio(0); } while (0)
; #define PG8_WAIT_V(n) asm volatile("s_waitcnt vmcnt(" #n ")" ::: "memory")
; #define PG8_WAIT_L(n) asm volatile("s_waitcnt lgkmcnt(" #n ")" ::: "memory")
; #define PG8_BAR __builtin_amdgcn_s_barrier()
; #define PG8_SCHED __builtin_amdgcn_sched_barrier(0)
; template <class Epi, class Sched, bool ALIGN_EPI = false, bool SP2 = false>
; __device__ __forceinline__ void gemm_phase(PG8_LAS unsigned char* lds, const Gemm g, const Sched& S, const Epi& E) {
;     ...
;             PG8_WAIT_V(8); PG8_WAIT_L(0); PG8_BAR; PG8_MMA(1, 0, At, B0); PG8_MMA(1, 1, At, B1); PG8_BAR; PG8_SCHED;
;             PG8_LDB(B0, 1, 0); PG8_LDB(B1, 1, 1); PG8_SCHED; PG8_LDA(At, 1, 0); PG8_STAGE(PG8_SA(0, 1), a2 + hstepA, voffA);
;             PG8_WAIT_V(8); PG8_WAIT_L(0); PG8_BAR; PG8_MMA(0, 0, At, B0); PG8_MMA(0, 1, At, B1); PG8_BAR; PG8_SCHED;
	s_setprio 1
	s_waitcnt lgkmcnt(0)
	v_mfma_f32_16x16x32_bf16 v[62:65], v[148:151], v[190:193], 0
	v_mfma_f32_16x16x32_bf16 v[54:57], v[156:159], v[190:193], 0
	v_mfma_f32_16x16x32_bf16 v[38:41], v[156:159], v[198:201], 0
	v_mfma_f32_16x16x32_bf16 v[46:49], v[148:151], v[198:201], 0
	v_mfma_f32_16x16x32_bf16 v[30:33], v[148:151], v[206:209], 0
	v_mfma_f32_16x16x32_bf16 v[22:25], v[156:159], v[206:209], 0
	v_mfma_f32_16x16x32_bf16 v[6:9], v[156:159], v[214:217], 0
	v_mfma_f32_16x16x32_bf16 v[14:17], v[148:151], v[214:217], 0
	v_mfma_f32_16x16x32_bf16 v[62:65], v[152:155], v[194:197], v[62:65]
	v_mfma_f32_16x16x32_bf16 v[54:57], v[160:163], v[194:197], v[54:57]
	v_mfma_f32_16x16x32_bf16 v[38:41], v[160:163], v[202:205], v[38:41]
	v_mfma_f32_16x16x32_bf16 v[46:49], v[152:155], v[202:205], v[46:49]
	v_mfma_f32_16x16x32_bf16 v[30:33], v[152:155], v[210:213], v[30:33]
	v_mfma_f32_16x16x32_bf16 v[22:25], v[160:163], v[210:213], v[22:25]
	v_mfma_f32_16x16x32_bf16 v[6:9], v[160:163], v[218:221], v[6:9]
	v_mfma_f32_16x16x32_bf16 v[14:17], v[152:155], v[218:221], v[14:17]
	s_setprio 0
	s_setprio 1
	v_mfma_f32_16x16x32_bf16 v[58:61], v[174:177], v[190:193], 0
	v_mfma_f32_16x16x32_bf16 v[50:53], v[182:185], v[190:193], 0
	v_mfma_f32_16x16x32_bf16 v[34:37], v[182:185], v[198:201], 0
	v_mfma_f32_16x16x32_bf16 v[42:45], v[174:177], v[198:201], 0
	v_mfma_f32_16x16x32_bf16 v[26:29], v[174:177], v[206:209], 0
	v_mfma_f32_16x16x32_bf16 v[18:21], v[182:185], v[206:209], 0
	v_mfma_f32_16x16x32_bf16 v[2:5], v[182:185], v[214:217], 0
	v_mfma_f32_16x16x32_bf16 v[10:13], v[174:177], v[214:217], 0
	v_mfma_f32_16x16x32_bf16 v[58:61], v[178:181], v[194:197], v[58:61]
	v_mfma_f32_16x16x32_bf16 v[50:53], v[186:189], v[194:197], v[50:53]
	v_mfma_f32_16x16x32_bf16 v[34:37], v[186:189], v[202:205], v[34:37]
	v_mfma_f32_16x16x32_bf16 v[42:45], v[178:181], v[202:205], v[42:45]
	v_mfma_f32_16x16x32_bf16 v[26:29], v[178:181], v[210:213], v[26:29]
	v_mfma_f32_16x16x32_bf16 v[18:21], v[186:189], v[210:213], v[18:21]
	v_mfma_f32_16x16x32_bf16 v[2:5], v[186:189], v[218:221], v[2:5]
	v_mfma_f32_16x16x32_bf16 v[10:13], v[178:181], v[218:221], v[10:13]
	s_setprio 0
	s_barrier
	s_add_i32 s51, 0, 0x18000
	s_add_i32 s52, 0, 0x1c000
	v_add_u32_e32 v160, s51, v166
	v_add_u32_e32 v173, s52, v166
	ds_read_b128 v[148:151], v160
	ds_read_b128 v[152:155], v160 offset:1024
	ds_read_b128 v[156:159], v160 offset:2048
	ds_read_b128 v[160:163], v160 offset:3072
	ds_read_b128 v[174:177], v173
	ds_read_b128 v[178:181], v173 offset:1024
	ds_read_b128 v[182:185], v173 offset:2048
	ds_read_b128 v[186:189], v173 offset:3072
	s_add_u32 s28, s28, 0x40000
	s_addc_u32 s29, s29, 0
	s_mov_b32 m0, s35
	v_lshl_add_u64 v[228:229], s[28:29], 0, v[136:137]
	ds_read_b128 v[190:193], v170 offset:32768
	ds_read_b128 v[194:197], v170 offset:33792
	ds_read_b128 v[198:201], v170 offset:34816
	ds_read_b128 v[202:205], v170 offset:35840
	ds_read_b128 v[206:209], v170 offset:36864
	ds_read_b128 v[210:213], v170 offset:37888
	ds_read_b128 v[214:217], v170 offset:38912
	ds_read_b128 v[218:221], v170 offset:39936
	global_load_lds_dwordx4 v[228:229], off
	v_lshl_add_u64 v[228:229], s[28:29], 0, v[132:133]
	s_mov_b32 m0, s36
	s_nop 0
	global_load_lds_dwordx4 v[228:229], off
	s_waitcnt vmcnt(8)
	s_waitcnt lgkmcnt(0)
	s_barrier
	s_setprio 1
	s_waitcnt lgkmcnt(0)
	v_mfma_f32_16x16x32_bf16 v[126:129], v[148:151], v[190:193], v[126:129]
	v_mfma_f32_16x16x32_bf16 v[118:121], v[156:159], v[190:193], v[118:121]
	v_mfma_f32_16x16x32_bf16 v[102:105], v[156:159], v[198:201], v[102:105]
	v_mfma_f32_16x16x32_bf16 v[110:113], v[148:151], v[198:201], v[110:113]
	v_mfma_f32_16x16x32_bf16 v[94:97], v[148:151], v[206:209], v[94:97]
	v_mfma_f32_16x16x32_bf16 v[86:89], v[156:159], v[206:209], v[86:89]
	v_mfma_f32_16x16x32_bf16 v[70:73], v[156:159], v[214:217], v[70:73]
	v_mfma_f32_16x16x32_bf16 v[78:81], v[148:151], v[214:217], v[78:81]
	v_mfma_f32_16x16x32_bf16 v[126:129], v[152:155], v[194:197], v[126:129]
	v_mfma_f32_16x16x32_bf16 v[118:121], v[160:163], v[194:197], v[118:121]
	v_mfma_f32_16x16x32_bf16 v[102:105], v[160:163], v[202:205], v[102:105]
	v_mfma_f32_16x16x32_bf16 v[110:113], v[152:155], v[202:205], v[110:113]
	v_mfma_f32_16x16x32_bf16 v[94:97], v[152:155], v[210:213], v[94:97]
	v_mfma_f32_16x16x32_bf16 v[86:89], v[160:163], v[210:213], v[86:89]
	v_mfma_f32_16x16x32_bf16 v[70:73], v[160:163], v[218:221], v[70:73]
	v_mfma_f32_16x16x32_bf16 v[78:81], v[152:155], v[218:221], v[78:81]
	s_setprio 0
	s_setprio 1
	v_mfma_f32_16x16x32_bf16 v[122:125], v[174:177], v[190:193], v[122:125]
	v_mfma_f32_16x16x32_bf16 v[114:117], v[182:185], v[190:193], v[114:117]
	v_mfma_f32_16x16x32_bf16 v[98:101], v[182:185], v[198:201], v[98:101]
	v_mfma_f32_16x16x32_bf16 v[106:109], v[174:177], v[198:201], v[106:109]
	v_mfma_f32_16x16x32_bf16 v[90:93], v[174:177], v[206:209], v[90:93]
	v_mfma_f32_16x16x32_bf16 v[82:85], v[182:185], v[206:209], v[82:85]
	v_mfma_f32_16x16x32_bf16 v[66:69], v[182:185], v[214:217], v[66:69]
	v_mfma_f32_16x16x32_bf16 v[74:77], v[174:177], v[214:217], v[74:77]
	v_mfma_f32_16x16x32_bf16 v[122:125], v[178:181], v[194:197], v[122:125]
	v_mfma_f32_16x16x32_bf16 v[114:117], v[186:189], v[194:197], v[114:117]
	v_mfma_f32_16x16x32_bf16 v[98:101], v[186:189], v[202:205], v[98:101]
	v_mfma_f32_16x16x32_bf16 v[106:109], v[178:181], v[202:205], v[106:109]
	v_mfma_f32_16x16x32_bf16 v[90:93], v[178:181], v[210:213], v[90:93]
	v_mfma_f32_16x16x32_bf16 v[82:85], v[186:189], v[210:213], v[82:85]
	v_mfma_f32_16x16x32_bf16 v[66:69], v[186:189], v[218:221], v[66:69]
	v_mfma_f32_16x16x32_bf16 v[74:77], v[178:181], v[218:221], v[74:77]
	s_setprio 0
	s_barrier
; #define PG8_STAGE(bufoff, gbase, voff) do { _Pragma("unroll") for (int _i = 0; _i < 2; ++_i) \
;         __builtin_amdgcn_global_load_lds((const unsigned*)((const char*)(gbase) + (voff)[_i]), (PG8_LAS unsigned*)(lds + (bufoff) + ldsw + _i * 8192), 16, 0, 0); } while (0)
; #define PG8_LDA(dst, b, h) do { _Pragma("unroll") for (int m = 0; m < 4; ++m) _Pragma("unroll") for (int k = 0; k < 2; ++k) dst[m][k] = *(const PG8_LAS bf16x8*)(lds + PG8_SA(b, h) + aoff + m * 2048 + k * 1024); } while (0)
; #define PG8_LDB(dst, b, h) do { _Pragma("unroll") for (int n = 0; n < 2; ++n) _Pragma("unroll") for (int k = 0; k < 2; ++k) dst[n][k] = *(const PG8_LAS bf16x8*)(lds + PG8_SB(b, h) + boff + n * 2048 + k * 1024); } while (0)
; #define PG8_MMA(ai, bj, At, Bt) do { __builtin_amdgcn_s_setprio(1); _Pragma("unroll") for (int m = 0; m < 4; ++m) _Pragma("unroll") for (int n = 0; n < 2; ++n) _Pragma("unroll") for (int k = 0; k < 2; ++k) \
;         acc[ai][bj][m][n] = __builtin_amdgcn_mfma_f32_16x16x32_bf16(Bt[n][k], At[m][k], acc[ai][bj][m][n], 0, 0, 0); __builtin_amdgcn_s_setprio(0); } while (0)
; #define PG8_WAIT_V(n) asm volatile("s_waitcnt vmcnt(" #n ")" ::: "memory")
; template <class Epi, class Sched, bool ALIGN_EPI = false, bool SP2 = false>
; __device__ __forceinline__ void gemm_phase(PG8_LAS unsigned char* lds, const Gemm g, const Sched& S, const Epi& E) {
;     ...
;             PG8_LDB(B0, 0, 0); PG8_LDB(B1, 0, 1); PG8_SCHED; PG8_LDA(At, 0, 0); PG8_STAGE(PG8_SA(1, 1), a1 + hstepA, voffA);
;             PG8_WAIT_V(8); PG8_WAIT_L(0); PG8_BAR; PG8_MMA(0, 0, At, B0); PG8_MMA(0, 1, At, B1); PG8_BAR; PG8_SCHED;
;             PG8_LDA(At, 0, 1); PG8_STAGE(PG8_SB(0, 0), b2, voffB); PG8_STAGE(PG8_SB(0, 1), b2 + hstepB, voffB); PG8_STAGE(PG8_SA(0, 0), a2, voffA);
;             PG8_WAIT_V(8); PG8_WAIT_L(0); PG8_BAR; PG8_MMA(1, 0, At, B0); PG8_MMA(1, 1, At, B1); PG8_BAR; PG8_SCHED;
;             PG8_LDB(B0, 1, 0); PG8_LDB(B1, 1, 1); PG8_SCHED; PG8_LDA(At, 1, 0); PG8_STAGE(PG8_SA(0, 1), a2 + hstepA, voffA);
;             PG8_WAIT_V(8); PG8_WAIT_L(0); PG8_BAR; PG8_MMA(0, 0, At, B0); PG8_MMA(0, 1, At, B1); PG8_BAR; PG8_SCHED;
;             PG8_LDA(At, 1, 1); PG8_STAGE(PG8_SB(1, 0), b3, voffB); PG8_STAGE(PG8_SB(1, 1), b3 + hstepB, voffB); PG8_STAGE(PG8_SA(1, 0), a3, voffA);
;             PG8_WAIT_V(8); PG8_WAIT_L(0); PG8_BAR; PG8_MMA(1, 0, At, B0); PG8_MMA(1, 1, At, B1); PG8_BAR; PG8_SCHED;
	s_add_i32 s28, s51, s30
	v_lshl_add_u64 v[164:165], v[164:165], 0, s[10:11]
	s_mov_b32 m0, s28
	ds_read_b128 v[190:193], v170 offset:49152
	ds_read_b128 v[194:197], v170 offset:50176
	ds_read_b128 v[198:201], v170 offset:51200
	ds_read_b128 v[202:205], v170 offset:52224
	ds_read_b128 v[206:209], v170 offset:53248
	ds_read_b128 v[210:213], v170 offset:54272
	ds_read_b128 v[214:217], v170 offset:55296
	ds_read_b128 v[218:221], v170 offset:56320
	global_load_lds_dwordx4 v[164:165], off
	s_add_i32 m0, s28, 0x2000
	s_add_u32 s26, s26, 0x40080
	v_lshl_add_u64 v[164:165], v[222:223], 0, s[10:11]
	s_addc_u32 s27, s27, 0
	s_add_i32 s28, s52, s30
	global_load_lds_dwordx4 v[164:165], off
	v_lshl_add_u64 v[164:165], s[26:27], 0, v[134:135]
	s_mov_b32 m0, s28
	s_nop 0
	global_load_lds_dwordx4 v[164:165], off
	v_lshl_add_u64 v[164:165], s[26:27], 0, v[130:131]
	s_add_i32 m0, s28, 0x2000
	s_nop 0
	global_load_lds_dwordx4 v[164:165], off
	v_lshl_add_u64 v[164:165], v[224:225], 0, s[10:11]
	s_mov_b32 m0, s38
	s_nop 0
	global_load_lds_dwordx4 v[164:165], off
	v_lshl_add_u64 v[164:165], v[226:227], 0, s[10:11]
	s_mov_b32 m0, s39
	s_nop 0
	global_load_lds_dwordx4 v[164:165], off
	s_waitcnt vmcnt(8)
	s_waitcnt lgkmcnt(0)
	s_barrier
	s_setprio 1
	s_waitcnt lgkmcnt(0)
	v_mfma_f32_16x16x32_bf16 v[62:65], v[148:151], v[190:193], v[62:65]
	v_mfma_f32_16x16x32_bf16 v[54:57], v[156:159], v[190:193], v[54:57]
	v_mfma_f32_16x16x32_bf16 v[38:41], v[156:159], v[198:201], v[38:41]
	v_mfma_f32_16x16x32_bf16 v[46:49], v[148:151], v[198:201], v[46:49]
	v_mfma_f32_16x16x32_bf16 v[30:33], v[148:151], v[206:209], v[30:33]
	v_mfma_f32_16x16x32_bf16 v[22:25], v[156:159], v[206:209], v[22:25]
	v_mfma_f32_16x16x32_bf16 v[6:9], v[156:159], v[214:217], v[6:9]
	v_mfma_f32_16x16x32_bf16 v[14:17], v[148:151], v[214:217], v[14:17]
	v_mfma_f32_16x16x32_bf16 v[62:65], v[152:155], v[194:197], v[62:65]
	v_mfma_f32_16x16x32_bf16 v[54:57], v[160:163], v[194:197], v[54:57]
	v_mfma_f32_16x16x32_bf16 v[38:41], v[160:163], v[202:205], v[38:41]
	v_mfma_f32_16x16x32_bf16 v[46:49], v[152:155], v[202:205], v[46:49]
	v_mfma_f32_16x16x32_bf16 v[30:33], v[152:155], v[210:213], v[30:33]
	v_mfma_f32_16x16x32_bf16 v[22:25], v[160:163], v[210:213], v[22:25]
	v_mfma_f32_16x16x32_bf16 v[6:9], v[160:163], v[218:221], v[6:9]
	v_mfma_f32_16x16x32_bf16 v[14:17], v[152:155], v[218:221], v[14:17]
	s_setprio 0
	s_setprio 1
	v_mfma_f32_16x16x32_bf16 v[58:61], v[174:177], v[190:193], v[58:61]
	v_mfma_f32_16x16x32_bf16 v[50:53], v[182:185], v[190:193], v[50:53]
	v_mfma_f32_16x16x32_bf16 v[34:37], v[182:185], v[198:201], v[34:37]
	v_mfma_f32_16x16x32_bf16 v[42:45], v[174:177], v[198:201], v[42:45]
	v_mfma_f32_16x16x32_bf16 v[26:29], v[174:177], v[206:209], v[26:29]
	v_mfma_f32_16x16x32_bf16 v[18:21], v[182:185], v[206:209], v[18:21]
	v_mfma_f32_16x16x32_bf16 v[2:5], v[182:185], v[214:217], v[2:5]
	v_mfma_f32_16x16x32_bf16 v[10:13], v[174:177], v[214:217], v[10:13]
	v_mfma_f32_16x16x32_bf16 v[58:61], v[178:181], v[194:197], v[58:61]
	v_mfma_f32_16x16x32_bf16 v[50:53], v[186:189], v[194:197], v[50:53]
	v_mfma_f32_16x16x32_bf16 v[34:37], v[186:189], v[202:205], v[34:37]
	v_mfma_f32_16x16x32_bf16 v[42:45], v[178:181], v[202:205], v[42:45]
	v_mfma_f32_16x16x32_bf16 v[26:29], v[178:181], v[210:213], v[26:29]
	v_mfma_f32_16x16x32_bf16 v[18:21], v[186:189], v[210:213], v[18:21]
	v_mfma_f32_16x16x32_bf16 v[2:5], v[186:189], v[218:221], v[2:5]
	v_mfma_f32_16x16x32_bf16 v[10:13], v[178:181], v[218:221], v[10:13]
	s_setprio 0
	s_barrier
	s_add_i32 s50, s50, 2
	s_add_u32 s24, s24, 0x100
	s_addc_u32 s25, s25, 0
	s_add_u32 s48, s48, 0x100
	s_addc_u32 s49, s49, 0
	s_cmp_gt_u32 s50, 13
.LBB0_691:
	ds_read_b128 v[148:151], v168
	ds_read_b128 v[152:155], v168 offset:1024
	ds_read_b128 v[156:159], v168 offset:2048
	ds_read_b128 v[160:163], v168 offset:3072
	ds_read_b128 v[174:177], v169
	ds_read_b128 v[178:181], v169 offset:1024
	ds_read_b128 v[182:185], v169 offset:2048
	ds_read_b128 v[186:189], v169 offset:3072
	s_add_u32 s26, s24, 0xfffc0080
	s_addc_u32 s27, s25, -1
	s_cmp_eq_u32 s50, 12
	s_cselect_b32 s29, s17, s27
	s_cselect_b32 s28, s46, s26
	s_cselect_b32 s27, s15, s49
	s_cselect_b32 s26, s47, s48
	v_lshl_add_u64 v[164:165], s[24:25], 0, v[140:141]
	s_add_i32 m0, s23, 0xc000
	ds_read_b128 v[190:193], v170
	ds_read_b128 v[194:197], v170 offset:1024
	ds_read_b128 v[198:201], v170 offset:2048
	ds_read_b128 v[202:205], v170 offset:3072
	ds_read_b128 v[206:209], v170 offset:4096
	ds_read_b128 v[210:213], v170 offset:5120
	ds_read_b128 v[214:217], v170 offset:6144
	ds_read_b128 v[218:221], v170 offset:7168
	global_load_lds_dwordx4 v[164:165], off
	v_lshl_add_u64 v[164:165], s[24:25], 0, v[142:143]
	s_add_i32 m0, s23, 0xe000
	s_nop 0
	global_load_lds_dwordx4 v[164:165], off
	s_waitcnt vmcnt(8)
	s_waitcnt lgkmcnt(0)
	s_barrier
; #define PG8_STAGE(bufoff, gbase, voff) do { _Pragma("unroll") for (int _i = 0; _i < 2; ++_i) \
;         __builtin_amdgcn_global_load_lds((const unsigned*)((const char*)(gbase) + (voff)[_i]), (PG8_LAS unsigned*)(lds + (bufoff) + ldsw + _i * 8192), 16, 0, 0); } while (0)
; #define PG8_LDA(dst, b, h) do { _Pragma("unroll") for (int m = 0; m < 4; ++m) _Pragma("unroll") for (int k = 0; k < 2; ++k) dst[m][k] = *(const PG8_LAS bf16x8*)(lds + PG8_SA(b, h) + aoff + m * 2048 + k * 1024); } while (0)
; #define PG8_MMA(ai, bj, At, Bt) do { __builtin_amdgcn_s_setprio(1); _Pragma("unroll") for (int m = 0; m < 4; ++m) _Pragma("unroll") for (int n = 0; n < 2; ++n) _Pragma("unroll") for (int k = 0; k < 2; ++k) \
;         acc[ai][bj][m][n] = __builtin_amdgcn_mfma_f32_16x16x32_bf16(Bt[n][k], At[m][k], acc[ai][bj][m][n], 0, 0, 0); __builtin_amdgcn_s_setprio(0); } while (0)
; #define PG8_WAIT_V(n) asm volatile("s_waitcnt vmcnt(" #n ")" ::: "memory")
; #define PG8_WAIT_L(n) asm volatile("s_waitcnt lgkmcnt(" #n ")" ::: "memory")
; #define PG8_BAR __builtin_amdgcn_s_barrier()
; #define PG8_SCHED __builtin_amdgcn_sched_barrier(0)
; template <class Epi, class Sched, bool ALIGN_EPI = false, bool SP2 = false>
; __device__ __forceinline__ void gemm_phase(PG8_LAS unsigned char* lds, const Gemm g, const Sched& S, const Epi& E) {
;     ...
;             PG8_WAIT_V(8); PG8_WAIT_L(0); PG8_BAR; PG8_MMA(0, 0, At, B0); PG8_MMA(0, 1, At, B1); PG8_BAR; PG8_SCHED;
;             PG8_LDA(At, 0, 1); PG8_STAGE(PG8_SB(0, 0), b2, voffB); PG8_STAGE(PG8_SB(0, 1), b2 + hstepB, voffB); PG8_STAGE(PG8_SA(0, 0), a2, voffA);
;             PG8_WAIT_V(8); PG8_WAIT_L(0); PG8_BAR; PG8_MMA(1, 0, At, B0); PG8_MMA(1, 1, At, B1); PG8_BAR; PG8_SCHED;
	s_setprio 1
	s_waitcnt lgkmcnt(0)
	v_mfma_f32_16x16x32_bf16 v[126:129], v[148:151], v[190:193], v[126:129]
	v_mfma_f32_16x16x32_bf16 v[118:121], v[156:159], v[190:193], v[118:121]
	v_mfma_f32_16x16x32_bf16 v[102:105], v[156:159], v[198:201], v[102:105]
	v_mfma_f32_16x16x32_bf16 v[110:113], v[148:151], v[198:201], v[110:113]
	v_mfma_f32_16x16x32_bf16 v[94:97], v[148:151], v[206:209], v[94:97]
	v_mfma_f32_16x16x32_bf16 v[86:89], v[156:159], v[206:209], v[86:89]
	v_mfma_f32_16x16x32_bf16 v[70:73], v[156:159], v[214:217], v[70:73]
	v_mfma_f32_16x16x32_bf16 v[78:81], v[148:151], v[214:217], v[78:81]
	v_mfma_f32_16x16x32_bf16 v[126:129], v[152:155], v[194:197], v[126:129]
	v_mfma_f32_16x16x32_bf16 v[118:121], v[160:163], v[194:197], v[118:121]
	v_mfma_f32_16x16x32_bf16 v[102:105], v[160:163], v[202:205], v[102:105]
	v_mfma_f32_16x16x32_bf16 v[110:113], v[152:155], v[202:205], v[110:113]
	v_mfma_f32_16x16x32_bf16 v[94:97], v[152:155], v[210:213], v[94:97]
	v_mfma_f32_16x16x32_bf16 v[86:89], v[160:163], v[210:213], v[86:89]
	v_mfma_f32_16x16x32_bf16 v[70:73], v[160:163], v[218:221], v[70:73]
	v_mfma_f32_16x16x32_bf16 v[78:81], v[152:155], v[218:221], v[78:81]
	s_setprio 0
	s_setprio 1
	v_mfma_f32_16x16x32_bf16 v[122:125], v[174:177], v[190:193], v[122:125]
	v_mfma_f32_16x16x32_bf16 v[114:117], v[182:185], v[190:193], v[114:117]
	v_mfma_f32_16x16x32_bf16 v[98:101], v[182:185], v[198:201], v[98:101]
	v_mfma_f32_16x16x32_bf16 v[106:109], v[174:177], v[198:201], v[106:109]
	v_mfma_f32_16x16x32_bf16 v[90:93], v[174:177], v[206:209], v[90:93]
	v_mfma_f32_16x16x32_bf16 v[82:85], v[182:185], v[206:209], v[82:85]
	v_mfma_f32_16x16x32_bf16 v[66:69], v[182:185], v[214:217], v[66:69]
	v_mfma_f32_16x16x32_bf16 v[74:77], v[174:177], v[214:217], v[74:77]
	v_mfma_f32_16x16x32_bf16 v[122:125], v[178:181], v[194:197], v[122:125]
	v_mfma_f32_16x16x32_bf16 v[114:117], v[186:189], v[194:197], v[114:117]
	v_mfma_f32_16x16x32_bf16 v[98:101], v[186:189], v[202:205], v[98:101]
	v_mfma_f32_16x16x32_bf16 v[106:109], v[178:181], v[202:205], v[106:109]
	v_mfma_f32_16x16x32_bf16 v[90:93], v[178:181], v[210:213], v[90:93]
	v_mfma_f32_16x16x32_bf16 v[82:85], v[186:189], v[210:213], v[82:85]
	v_mfma_f32_16x16x32_bf16 v[66:69], v[186:189], v[218:221], v[66:69]
	v_mfma_f32_16x16x32_bf16 v[74:77], v[178:181], v[218:221], v[74:77]
	s_setprio 0
	s_barrier
	s_add_i32 s51, s42, s30
	v_lshl_add_u64 v[164:165], s[26:27], 0, v[134:135]
	s_mov_b32 m0, s51
	ds_read_b128 v[190:193], v170 offset:16384
	ds_read_b128 v[194:197], v170 offset:17408
	ds_read_b128 v[198:201], v170 offset:18432
	ds_read_b128 v[202:205], v170 offset:19456
	ds_read_b128 v[206:209], v170 offset:20480
	ds_read_b128 v[210:213], v170 offset:21504
	ds_read_b128 v[214:217], v170 offset:22528
	ds_read_b128 v[218:221], v170 offset:23552
	global_load_lds_dwordx4 v[164:165], off
	s_add_i32 m0, s51, 0x2000
	s_add_u32 s52, s26, 0x40000
	v_lshl_add_u64 v[222:223], s[26:27], 0, v[130:131]
	s_addc_u32 s53, s27, 0
	s_add_i32 s51, s43, s30
	global_load_lds_dwordx4 v[222:223], off
	v_lshl_add_u64 v[224:225], s[52:53], 0, v[134:135]
	s_mov_b32 m0, s51
	v_lshl_add_u64 v[226:227], s[28:29], 0, v[132:133]
	global_load_lds_dwordx4 v[224:225], off
	v_lshl_add_u64 v[224:225], s[52:53], 0, v[130:131]
	s_add_i32 m0, s51, 0x2000
	s_nop 0
	global_load_lds_dwordx4 v[224:225], off
	v_lshl_add_u64 v[224:225], s[28:29], 0, v[136:137]
	s_mov_b32 m0, s23
	s_nop 0
	global_load_lds_dwordx4 v[224:225], off
	s_mov_b32 m0, s34
	s_nop 0
	global_load_lds_dwordx4 v[226:227], off
	s_waitcnt vmcnt(8)
	s_waitcnt lgkmcnt(0)
	s_barrier
	s_setprio 1
	s_waitcnt lgkmcnt(0)
	v_mfma_f32_16x16x32_bf16 v[62:65], v[148:151], v[190:193], v[62:65]
	v_mfma_f32_16x16x32_bf16 v[54:57], v[156:159], v[190:193], v[54:57]
	v_mfma_f32_16x16x32_bf16 v[38:41], v[156:159], v[198:201], v[38:41]
	v_mfma_f32_16x16x32_bf16 v[46:49], v[148:151], v[198:201], v[46:49]
	v_mfma_f32_16x16x32_bf16 v[30:33], v[148:151], v[206:209], v[30:33]
	v_mfma_f32_16x16x32_bf16 v[22:25], v[156:159], v[206:209], v[22:25]
	v_mfma_f32_16x16x32_bf16 v[6:9], v[156:159], v[214:217], v[6:9]
	v_mfma_f32_16x16x32_bf16 v[14:17], v[148:151], v[214:217], v[14:17]
	v_mfma_f32_16x16x32_bf16 v[62:65], v[152:155], v[194:197], v[62:65]
	v_mfma_f32_16x16x32_bf16 v[54:57], v[160:163], v[194:197], v[54:57]
	v_mfma_f32_16x16x32_bf16 v[38:41], v[160:163], v[202:205], v[38:41]
	v_mfma_f32_16x16x32_bf16 v[46:49], v[152:155], v[202:205], v[46:49]
	v_mfma_f32_16x16x32_bf16 v[30:33], v[152:155], v[210:213], v[30:33]
	v_mfma_f32_16x16x32_bf16 v[22:25], v[160:163], v[210:213], v[22:25]
	v_mfma_f32_16x16x32_bf16 v[6:9], v[160:163], v[218:221], v[6:9]
	v_mfma_f32_16x16x32_bf16 v[14:17], v[152:155], v[218:221], v[14:17]
	s_setprio 0
	s_setprio 1
	v_mfma_f32_16x16x32_bf16 v[58:61], v[174:177], v[190:193], v[58:61]
	v_mfma_f32_16x16x32_bf16 v[50:53], v[182:185], v[190:193], v[50:53]
	v_mfma_f32_16x16x32_bf16 v[34:37], v[182:185], v[198:201], v[34:37]
	v_mfma_f32_16x16x32_bf16 v[42:45], v[174:177], v[198:201], v[42:45]
	v_mfma_f32_16x16x32_bf16 v[26:29], v[174:177], v[206:209], v[26:29]
	v_mfma_f32_16x16x32_bf16 v[18:21], v[182:185], v[206:209], v[18:21]
	v_mfma_f32_16x16x32_bf16 v[2:5], v[182:185], v[214:217], v[2:5]
	v_mfma_f32_16x16x32_bf16 v[10:13], v[174:177], v[214:217], v[10:13]
	v_mfma_f32_16x16x32_bf16 v[58:61], v[178:181], v[194:197], v[58:61]
	v_mfma_f32_16x16x32_bf16 v[50:53], v[186:189], v[194:197], v[50:53]
	v_mfma_f32_16x16x32_bf16 v[34:37], v[186:189], v[202:205], v[34:37]
	v_mfma_f32_16x16x32_bf16 v[42:45], v[178:181], v[202:205], v[42:45]
	v_mfma_f32_16x16x32_bf16 v[26:29], v[178:181], v[210:213], v[26:29]
	v_mfma_f32_16x16x32_bf16 v[18:21], v[186:189], v[210:213], v[18:21]
	v_mfma_f32_16x16x32_bf16 v[2:5], v[186:189], v[218:221], v[2:5]
	v_mfma_f32_16x16x32_bf16 v[10:13], v[178:181], v[218:221], v[10:13]
	s_setprio 0
	s_barrier
; #define PG8_STAGE(bufoff, gbase, voff) do { _Pragma("unroll") for (int _i = 0; _i < 2; ++_i) \
;         __builtin_amdgcn_global_load_lds((const unsigned*)((const char*)(gbase) + (voff)[_i]), (PG8_LAS unsigned*)(lds + (bufoff) + ldsw + _i * 8192), 16, 0, 0); } while (0)
; #define PG8_LDA(dst, b, h) do { _Pragma("unroll") for (int m = 0; m < 4; ++m) _Pragma("unroll") for (int k = 0; k < 2; ++k) dst[m][k] = *(const PG8_LAS bf16x8*)(lds + PG8_SA(b, h) + aoff + m * 2048 + k * 1024); } while (0)
; #define PG8_LDB(dst, b, h) do { _Pragma("unroll") for (int n = 0; n < 2; ++n) _Pragma("unroll") for (int k = 0; k < 2; ++k) dst[n][k] = *(const PG8_LAS bf16x8*)(lds + PG8_SB(b, h) + boff + n * 2048 + k * 1024); } while (0)
; #define PG8_MMA(ai, bj, At, Bt) do { __builtin_amdgcn_s_setprio(1); _Pragma("unroll") for (int m = 0; m < 4; ++m) _Pragma("unroll") for (int n = 0; n < 2; ++n) _Pragma("unroll") for (int k = 0; k < 2; ++k) \
;         acc[ai][bj][m][n] = __builtin_amdgcn_mfma_f32_16x16x32_bf16(Bt[n][k], At[m][k], acc[ai][bj][m][n], 0, 0, 0); __builtin_amdgcn_s_setprio(0); } while (0)
; #define PG8_WAIT_V(n) asm volatile("s_waitcnt vmcnt(" #n ")" ::: "memory")
; #define PG8_WAIT_L(n) asm volatile("s_waitcnt lgkmcnt(" #n ")" ::: "memory")
; #define PG8_BAR __builtin_amdgcn_s_barrier()
; #define PG8_SCHED __builtin_amdgcn_sched_barrier(0)
; template <class Epi, class Sched, bool ALIGN_EPI = false, bool SP2 = false>
; __device__ __forceinline__ void gemm_phase(PG8_LAS unsigned char* lds, const Gemm g, const Sched& S, const Epi& E) {
;     ...
;             PG8_LDB(B0, 1, 0); PG8_LDB(B1, 1, 1); PG8_SCHED; PG8_LDA(At, 1, 0); PG8_STAGE(PG8_SA(0, 1), a2 + hstepA, voffA);
;             PG8_WAIT_V(8); PG8_WAIT_L(0); PG8_BAR; PG8_MMA(0, 0, At, B0); PG8_MMA(0, 1, At, B1); PG8_BAR; PG8_SCHED;
	s_add_i32 s51, 0, 0x18000
	s_add_i32 s52, 0, 0x1c000
	v_add_u32_e32 v160, s51, v166
	v_add_u32_e32 v173, s52, v166
	ds_read_b128 v[148:151], v160
	ds_read_b128 v[152:155], v160 offset:1024
	ds_read_b128 v[156:159], v160 offset:2048
	ds_read_b128 v[160:163], v160 offset:3072
	ds_read_b128 v[174:177], v173
	ds_read_b128 v[178:181], v173 offset:1024
	ds_read_b128 v[182:185], v173 offset:2048
	ds_read_b128 v[186:189], v173 offset:3072
	s_add_u32 s28, s28, 0x40000
	s_addc_u32 s29, s29, 0
	s_mov_b32 m0, s35
	v_lshl_add_u64 v[228:229], s[28:29], 0, v[136:137]
	ds_read_b128 v[190:193], v170 offset:32768
	ds_read_b128 v[194:197], v170 offset:33792
	ds_read_b128 v[198:201], v170 offset:34816
	ds_read_b128 v[202:205], v170 offset:35840
	ds_read_b128 v[206:209], v170 offset:36864
	ds_read_b128 v[210:213], v170 offset:37888
	ds_read_b128 v[214:217], v170 offset:38912
	ds_read_b128 v[218:221], v170 offset:39936
	global_load_lds_dwordx4 v[228:229], off
	v_lshl_add_u64 v[228:229], s[28:29], 0, v[132:133]
	s_mov_b32 m0, s36
	s_nop 0
	global_load_lds_dwordx4 v[228:229], off
	s_waitcnt vmcnt(8)
	s_waitcnt lgkmcnt(0)
	s_barrier
	s_setprio 1
	s_waitcnt lgkmcnt(0)
	v_mfma_f32_16x16x32_bf16 v[126:129], v[148:151], v[190:193], v[126:129]
	v_mfma_f32_16x16x32_bf16 v[118:121], v[156:159], v[190:193], v[118:121]
	v_mfma_f32_16x16x32_bf16 v[102:105], v[156:159], v[198:201], v[102:105]
	v_mfma_f32_16x16x32_bf16 v[110:113], v[148:151], v[198:201], v[110:113]
	v_mfma_f32_16x16x32_bf16 v[94:97], v[148:151], v[206:209], v[94:97]
	v_mfma_f32_16x16x32_bf16 v[86:89], v[156:159], v[206:209], v[86:89]
	v_mfma_f32_16x16x32_bf16 v[70:73], v[156:159], v[214:217], v[70:73]
	v_mfma_f32_16x16x32_bf16 v[78:81], v[148:151], v[214:217], v[78:81]
	v_mfma_f32_16x16x32_bf16 v[126:129], v[152:155], v[194:197], v[126:129]
	v_mfma_f32_16x16x32_bf16 v[118:121], v[160:163], v[194:197], v[118:121]
	v_mfma_f32_16x16x32_bf16 v[102:105], v[160:163], v[202:205], v[102:105]
	v_mfma_f32_16x16x32_bf16 v[110:113], v[152:155], v[202:205], v[110:113]
	v_mfma_f32_16x16x32_bf16 v[94:97], v[152:155], v[210:213], v[94:97]
	v_mfma_f32_16x16x32_bf16 v[86:89], v[160:163], v[210:213], v[86:89]
	v_mfma_f32_16x16x32_bf16 v[70:73], v[160:163], v[218:221], v[70:73]
	v_mfma_f32_16x16x32_bf16 v[78:81], v[152:155], v[218:221], v[78:81]
	s_setprio 0
	s_setprio 1
	v_mfma_f32_16x16x32_bf16 v[122:125], v[174:177], v[190:193], v[122:125]
	v_mfma_f32_16x16x32_bf16 v[114:117], v[182:185], v[190:193], v[114:117]
	v_mfma_f32_16x16x32_bf16 v[98:101], v[182:185], v[198:201], v[98:101]
	v_mfma_f32_16x16x32_bf16 v[106:109], v[174:177], v[198:201], v[106:109]
	v_mfma_f32_16x16x32_bf16 v[90:93], v[174:177], v[206:209], v[90:93]
	v_mfma_f32_16x16x32_bf16 v[82:85], v[182:185], v[206:209], v[82:85]
	v_mfma_f32_16x16x32_bf16 v[66:69], v[182:185], v[214:217], v[66:69]
	v_mfma_f32_16x16x32_bf16 v[74:77], v[174:177], v[214:217], v[74:77]
	v_mfma_f32_16x16x32_bf16 v[122:125], v[178:181], v[194:197], v[122:125]
	v_mfma_f32_16x16x32_bf16 v[114:117], v[186:189], v[194:197], v[114:117]
	v_mfma_f32_16x16x32_bf16 v[98:101], v[186:189], v[202:205], v[98:101]
	v_mfma_f32_16x16x32_bf16 v[106:109], v[178:181], v[202:205], v[106:109]
	v_mfma_f32_16x16x32_bf16 v[90:93], v[178:181], v[210:213], v[90:93]
	v_mfma_f32_16x16x32_bf16 v[82:85], v[186:189], v[210:213], v[82:85]
	v_mfma_f32_16x16x32_bf16 v[66:69], v[186:189], v[218:221], v[66:69]
	v_mfma_f32_16x16x32_bf16 v[74:77], v[178:181], v[218:221], v[74:77]
	s_setprio 0
	s_barrier
; #define PG8_STAGE(bufoff, gbase, voff) do { _Pragma("unroll") for (int _i = 0; _i < 2; ++_i) \
;         __builtin_amdgcn_global_load_lds((const unsigned*)((const char*)(gbase) + (voff)[_i]), (PG8_LAS unsigned*)(lds + (bufoff) + ldsw + _i * 8192), 16, 0, 0); } while (0)
; #define PG8_LDA(dst, b, h) do { _Pragma("unroll") for (int m = 0; m < 4; ++m) _Pragma("unroll") for (int k = 0; k < 2; ++k) dst[m][k] = *(const PG8_LAS bf16x8*)(lds + PG8_SA(b, h) + aoff + m * 2048 + k * 1024); } while (0)
; #define PG8_MMA(ai, bj, At, Bt) do { __builtin_amdgcn_s_setprio(1); _Pragma("unroll") for (int m = 0; m < 4; ++m) _Pragma("unroll") for (int n = 0; n < 2; ++n) _Pragma("unroll") for (int k = 0; k < 2; ++k) \
;         acc[ai][bj][m][n] = __builtin_amdgcn_mfma_f32_16x16x32_bf16(Bt[n][k], At[m][k], acc[ai][bj][m][n], 0, 0, 0); __builtin_amdgcn_s_setprio(0); } while (0)
; #define PG8_WAIT_V(n) asm volatile("s_waitcnt vmcnt(" #n ")" ::: "memory")
; #define PG8_WAIT_L(n) asm volatile("s_waitcnt lgkmcnt(" #n ")" ::: "memory")
; #define PG8_BAR __builtin_amdgcn_s_barrier()
; #define PG8_SCHED __builtin_amdgcn_sched_barrier(0)
; template <class Epi, class Sched, bool ALIGN_EPI = false, bool SP2 = false>
; __device__ __forceinline__ void gemm_phase(PG8_LAS unsigned char* lds, const Gemm g, const Sched& S, const Epi& E) {
;     ...
;             PG8_LDA(At, 1, 1); PG8_STAGE(PG8_SB(1, 0), b3, voffB); PG8_STAGE(PG8_SB(1, 1), b3 + hstepB, voffB); PG8_STAGE(PG8_SA(1, 0), a3, voffA);
;             PG8_WAIT_V(8); PG8_WAIT_L(0); PG8_BAR; PG8_MMA(1, 0, At, B0); PG8_MMA(1, 1, At, B1); PG8_BAR; PG8_SCHED;
	s_add_i32 s28, s51, s30
	v_lshl_add_u64 v[164:165], v[164:165], 0, s[10:11]
	s_mov_b32 m0, s28
	ds_read_b128 v[190:193], v170 offset:49152
	ds_read_b128 v[194:197], v170 offset:50176
	ds_read_b128 v[198:201], v170 offset:51200
	ds_read_b128 v[202:205], v170 offset:52224
	ds_read_b128 v[206:209], v170 offset:53248
	ds_read_b128 v[210:213], v170 offset:54272
	ds_read_b128 v[214:217], v170 offset:55296
	ds_read_b128 v[218:221], v170 offset:56320
	global_load_lds_dwordx4 v[164:165], off
	s_add_i32 m0, s28, 0x2000
	s_add_u32 s26, s26, 0x40080
	v_lshl_add_u64 v[164:165], v[222:223], 0, s[10:11]
	s_addc_u32 s27, s27, 0
	s_add_i32 s28, s52, s30
	global_load_lds_dwordx4 v[164:165], off
	v_lshl_add_u64 v[164:165], s[26:27], 0, v[134:135]
	s_mov_b32 m0, s28
	s_nop 0
	global_load_lds_dwordx4 v[164:165], off
	v_lshl_add_u64 v[164:165], s[26:27], 0, v[130:131]
	s_add_i32 m0, s28, 0x2000
	s_nop 0
	global_load_lds_dwordx4 v[164:165], off
	v_lshl_add_u64 v[164:165], v[224:225], 0, s[10:11]
	s_mov_b32 m0, s38
	s_nop 0
	global_load_lds_dwordx4 v[164:165], off
	v_lshl_add_u64 v[164:165], v[226:227], 0, s[10:11]
	s_mov_b32 m0, s39
	s_nop 0
	global_load_lds_dwordx4 v[164:165], off
	s_waitcnt vmcnt(8)
	s_waitcnt lgkmcnt(0)
	s_barrier
	s_setprio 1
	s_waitcnt lgkmcnt(0)
	v_mfma_f32_16x16x32_bf16 v[62:65], v[148:151], v[190:193], v[62:65]
	v_mfma_f32_16x16x32_bf16 v[54:57], v[156:159], v[190:193], v[54:57]
	v_mfma_f32_16x16x32_bf16 v[38:41], v[156:159], v[198:201], v[38:41]
	v_mfma_f32_16x16x32_bf16 v[46:49], v[148:151], v[198:201], v[46:49]
	v_mfma_f32_16x16x32_bf16 v[30:33], v[148:151], v[206:209], v[30:33]
	v_mfma_f32_16x16x32_bf16 v[22:25], v[156:159], v[206:209], v[22:25]
	v_mfma_f32_16x16x32_bf16 v[6:9], v[156:159], v[214:217], v[6:9]
	v_mfma_f32_16x16x32_bf16 v[14:17], v[148:151], v[214:217], v[14:17]
	v_mfma_f32_16x16x32_bf16 v[62:65], v[152:155], v[194:197], v[62:65]
	v_mfma_f32_16x16x32_bf16 v[54:57], v[160:163], v[194:197], v[54:57]
	v_mfma_f32_16x16x32_bf16 v[38:41], v[160:163], v[202:205], v[38:41]
	v_mfma_f32_16x16x32_bf16 v[46:49], v[152:155], v[202:205], v[46:49]
	v_mfma_f32_16x16x32_bf16 v[30:33], v[152:155], v[210:213], v[30:33]
	v_mfma_f32_16x16x32_bf16 v[22:25], v[160:163], v[210:213], v[22:25]
	v_mfma_f32_16x16x32_bf16 v[6:9], v[160:163], v[218:221], v[6:9]
	v_mfma_f32_16x16x32_bf16 v[14:17], v[152:155], v[218:221], v[14:17]
	s_setprio 0
	s_setprio 1
	v_mfma_f32_16x16x32_bf16 v[58:61], v[174:177], v[190:193], v[58:61]
	v_mfma_f32_16x16x32_bf16 v[50:53], v[182:185], v[190:193], v[50:53]
	v_mfma_f32_16x16x32_bf16 v[34:37], v[182:185], v[198:201], v[34:37]
	v_mfma_f32_16x16x32_bf16 v[42:45], v[174:177], v[198:201], v[42:45]
	v_mfma_f32_16x16x32_bf16 v[26:29], v[174:177], v[206:209], v[26:29]
	v_mfma_f32_16x16x32_bf16 v[18:21], v[182:185], v[206:209], v[18:21]
	v_mfma_f32_16x16x32_bf16 v[2:5], v[182:185], v[214:217], v[2:5]
	v_mfma_f32_16x16x32_bf16 v[10:13], v[174:177], v[214:217], v[10:13]
	v_mfma_f32_16x16x32_bf16 v[58:61], v[178:181], v[194:197], v[58:61]
	v_mfma_f32_16x16x32_bf16 v[50:53], v[186:189], v[194:197], v[50:53]
	v_mfma_f32_16x16x32_bf16 v[34:37], v[186:189], v[202:205], v[34:37]
	v_mfma_f32_16x16x32_bf16 v[42:45], v[178:181], v[202:205], v[42:45]
	v_mfma_f32_16x16x32_bf16 v[26:29], v[178:181], v[210:213], v[26:29]
	v_mfma_f32_16x16x32_bf16 v[18:21], v[186:189], v[210:213], v[18:21]
	v_mfma_f32_16x16x32_bf16 v[2:5], v[186:189], v[218:221], v[2:5]
	v_mfma_f32_16x16x32_bf16 v[10:13], v[178:181], v[218:221], v[10:13]
	s_setprio 0
	s_barrier
	s_add_i32 s50, s50, 2
	s_add_u32 s24, s24, 0x100
	s_addc_u32 s25, s25, 0
	s_add_u32 s48, s48, 0x100
	s_addc_u32 s49, s49, 0
	s_cmp_gt_u32 s50, 13
	s_cbranch_scc0 .LBB0_691
	s_and_b64 vcc, exec, s[12:13]
	s_cbranch_vccz .LBB0_694
	s_barrier

; #define PG8_STAGE(bufoff, gbase, voff) do { _Pragma("unroll") for (int _i = 0; _i < 2; ++_i) \
;         __builtin_amdgcn_global_load_lds((const unsigned*)((const char*)(gbase) + (voff)[_i]), (PG8_LAS unsigned*)(lds + (bufoff) + ldsw + _i * 8192), 16, 0, 0); } while (0)
; #define PG8_LDA(dst, b, h) do { _Pragma("unroll") for (int m = 0; m < 4; ++m) _Pragma("unroll") for (int k = 0; k < 2; ++k) dst[m][k] = *(const PG8_LAS bf16x8*)(lds + PG8_SA(b, h) + aoff + m * 2048 + k * 1024); } while (0)
; #define PG8_LDB(dst, b, h) do { _Pragma("unroll") for (int n = 0; n < 2; ++n) _Pragma("unroll") for (int k = 0; k < 2; ++k) dst[n][k] = *(const PG8_LAS bf16x8*)(lds + PG8_SB(b, h) + boff + n * 2048 + k * 1024); } while (0)
; #define PG8_MMA(ai, bj, At, Bt) do { __builtin_amdgcn_s_setprio(1); _Pragma("unroll") for (int m = 0; m < 4; ++m) _Pragma("unroll") for (int n = 0; n < 2; ++n) _Pragma("unroll") for (int k = 0; k < 2; ++k) \
;         acc[ai][bj][m][n] = __builtin_amdgcn_mfma_f32_16x16x32_bf16(Bt[n][k], At[m][k], acc[ai][bj][m][n], 0, 0, 0); __builtin_amdgcn_s_setprio(0); } while (0)
; #define PG8_WAIT_V(n) asm volatile("s_waitcnt vmcnt(" #n ")" ::: "memory")
; #define PG8_WAIT_L(n) asm volatile("s_waitcnt lgkmcnt(" #n ")" ::: "memory")
; #define PG8_BAR __builtin_amdgcn_s_barrier()
; #define PG8_SCHED __builtin_amdgcn_sched_barrier(0)
; template <class Epi, class Sched, bool ALIGN_EPI = false, bool SP2 = false>
; __device__ __forceinline__ void gemm_phase(PG8_LAS unsigned char* lds, const Gemm g, const Sched& S, const Epi& E) {
;     ...
;             PG8_LDB(B0, 0, 0); PG8_LDB(B1, 0, 1); PG8_SCHED; PG8_LDA(At, 0, 0); PG8_STAGE(PG8_SA(1, 1), a1 + hstepA, voffA);
;             PG8_WAIT_V(8); PG8_WAIT_L(0); PG8_BAR; PG8_MMA(0, 0, At, B0); PG8_MMA(0, 1, At, B1); PG8_BAR; PG8_SCHED;
;             PG8_LDA(At, 0, 1); PG8_STAGE(PG8_SB(0, 0), b2, voffB); PG8_STAGE(PG8_SB(0, 1), b2 + hstepB, voffB); PG8_STAGE(PG8_SA(0, 0), a2, voffA);
;             PG8_WAIT_V(8); PG8_WAIT_L(0); PG8_BAR; PG8_MMA(1, 0, At, B0); PG8_MMA(1, 1, At, B1); PG8_BAR; PG8_SCHED;
.LBB0_775:
	s_add_u32 s4, s28, 0x100
	s_addc_u32 s53, s29, 0
	s_mov_b32 s54, -2
	s_waitcnt lgkmcnt(0)
	ds_read_b128 v[130:133], v164
	ds_read_b128 v[134:137], v164 offset:1024
	ds_read_b128 v[154:157], v164 offset:2048
	ds_read_b128 v[158:161], v164 offset:3072
	ds_read_b128 v[168:171], v165
	ds_read_b128 v[172:175], v165 offset:1024
	ds_read_b128 v[176:179], v165 offset:2048
	ds_read_b128 v[180:183], v165 offset:3072
	s_add_u32 s28, s26, 0x100
	s_addc_u32 s29, s27, 0
	s_cmp_eq_u32 s54, 40
	s_cselect_b32 s35, s13, s29
	s_cselect_b32 s34, s12, s28
	s_cselect_b32 s31, s25, s53
	s_cselect_b32 s30, s24, s4
	v_lshl_add_u64 v[216:217], s[26:27], 0, v[146:147]
	s_add_i32 m0, s1, 0xc000
	ds_read_b128 v[184:187], v166
	ds_read_b128 v[188:191], v166 offset:1024
	ds_read_b128 v[192:195], v166 offset:2048
	ds_read_b128 v[196:199], v166 offset:3072
	ds_read_b128 v[200:203], v166 offset:4096
	ds_read_b128 v[204:207], v166 offset:5120
	ds_read_b128 v[208:211], v166 offset:6144
	ds_read_b128 v[212:215], v166 offset:7168
	global_load_lds_dwordx4 v[216:217], off
	v_lshl_add_u64 v[216:217], s[26:27], 0, v[148:149]
	s_add_i32 m0, s1, 0xe000
	s_nop 0
	global_load_lds_dwordx4 v[216:217], off
	s_waitcnt vmcnt(8)
	s_waitcnt lgkmcnt(0)
	s_barrier
	s_setprio 1
	s_waitcnt lgkmcnt(0)
	v_mfma_f32_16x16x32_bf16 v[126:129], v[130:133], v[184:187], 0
	v_mfma_f32_16x16x32_bf16 v[122:125], v[154:157], v[184:187], 0
	v_mfma_f32_16x16x32_bf16 v[106:109], v[154:157], v[192:195], 0
	v_mfma_f32_16x16x32_bf16 v[110:113], v[130:133], v[192:195], 0
	v_mfma_f32_16x16x32_bf16 v[94:97], v[130:133], v[200:203], 0
	v_mfma_f32_16x16x32_bf16 v[90:93], v[154:157], v[200:203], 0
	v_mfma_f32_16x16x32_bf16 v[74:77], v[154:157], v[208:211], 0
	v_mfma_f32_16x16x32_bf16 v[78:81], v[130:133], v[208:211], 0
	v_mfma_f32_16x16x32_bf16 v[126:129], v[134:137], v[188:191], v[126:129]
	v_mfma_f32_16x16x32_bf16 v[122:125], v[158:161], v[188:191], v[122:125]
	v_mfma_f32_16x16x32_bf16 v[106:109], v[158:161], v[196:199], v[106:109]
	v_mfma_f32_16x16x32_bf16 v[110:113], v[134:137], v[196:199], v[110:113]
	v_mfma_f32_16x16x32_bf16 v[94:97], v[134:137], v[204:207], v[94:97]
	v_mfma_f32_16x16x32_bf16 v[90:93], v[158:161], v[204:207], v[90:93]
	v_mfma_f32_16x16x32_bf16 v[74:77], v[158:161], v[212:215], v[74:77]
	v_mfma_f32_16x16x32_bf16 v[78:81], v[134:137], v[212:215], v[78:81]
	s_setprio 0
	s_setprio 1
	v_mfma_f32_16x16x32_bf16 v[118:121], v[168:171], v[184:187], 0
	v_mfma_f32_16x16x32_bf16 v[114:117], v[176:179], v[184:187], 0
	v_mfma_f32_16x16x32_bf16 v[98:101], v[176:179], v[192:195], 0
	v_mfma_f32_16x16x32_bf16 v[102:105], v[168:171], v[192:195], 0
	v_mfma_f32_16x16x32_bf16 v[86:89], v[168:171], v[200:203], 0
	v_mfma_f32_16x16x32_bf16 v[82:85], v[176:179], v[200:203], 0
	v_mfma_f32_16x16x32_bf16 v[66:69], v[176:179], v[208:211], 0
	v_mfma_f32_16x16x32_bf16 v[70:73], v[168:171], v[208:211], 0
	v_mfma_f32_16x16x32_bf16 v[118:121], v[172:175], v[188:191], v[118:121]
	v_mfma_f32_16x16x32_bf16 v[114:117], v[180:183], v[188:191], v[114:117]
	v_mfma_f32_16x16x32_bf16 v[98:101], v[180:183], v[196:199], v[98:101]
	v_mfma_f32_16x16x32_bf16 v[102:105], v[172:175], v[196:199], v[102:105]
	v_mfma_f32_16x16x32_bf16 v[86:89], v[172:175], v[204:207], v[86:89]
	v_mfma_f32_16x16x32_bf16 v[82:85], v[180:183], v[204:207], v[82:85]
	v_mfma_f32_16x16x32_bf16 v[66:69], v[180:183], v[212:215], v[66:69]
	v_mfma_f32_16x16x32_bf16 v[70:73], v[172:175], v[212:215], v[70:73]
	s_setprio 0
	s_barrier
	s_add_i32 s26, s46, s0
	v_lshl_add_u64 v[216:217], s[30:31], 0, v[140:141]
	s_mov_b32 m0, s26
	ds_read_b128 v[184:187], v166 offset:16384
	ds_read_b128 v[188:191], v166 offset:17408
	ds_read_b128 v[192:195], v166 offset:18432
	ds_read_b128 v[196:199], v166 offset:19456
	ds_read_b128 v[200:203], v166 offset:20480
	ds_read_b128 v[204:207], v166 offset:21504
	ds_read_b128 v[208:211], v166 offset:22528
	ds_read_b128 v[212:215], v166 offset:23552
	global_load_lds_dwordx4 v[216:217], off
	s_add_i32 m0, s26, 0x2000
	s_add_u32 s26, s30, 0xb0000
	v_lshl_add_u64 v[218:219], s[30:31], 0, v[144:145]
	s_addc_u32 s27, s31, 0
	s_add_i32 s55, s47, s0
	global_load_lds_dwordx4 v[218:219], off
	v_lshl_add_u64 v[220:221], s[26:27], 0, v[140:141]
	s_mov_b32 m0, s55
	v_lshl_add_u64 v[222:223], s[34:35], 0, v[142:143]
	global_load_lds_dwordx4 v[220:221], off
	v_lshl_add_u64 v[220:221], s[26:27], 0, v[144:145]
	s_add_i32 m0, s55, 0x2000
	s_nop 0
	global_load_lds_dwordx4 v[220:221], off
	v_lshl_add_u64 v[220:221], s[34:35], 0, v[138:139]
	s_mov_b32 m0, s1
	s_nop 0
	global_load_lds_dwordx4 v[220:221], off
	s_mov_b32 m0, s37
	s_nop 0
	global_load_lds_dwordx4 v[222:223], off
	s_waitcnt vmcnt(8)
	s_waitcnt lgkmcnt(0)
	s_barrier
; #define PG8_STAGE(bufoff, gbase, voff) do { _Pragma("unroll") for (int _i = 0; _i < 2; ++_i) \
;         __builtin_amdgcn_global_load_lds((const unsigned*)((const char*)(gbase) + (voff)[_i]), (PG8_LAS unsigned*)(lds + (bufoff) + ldsw + _i * 8192), 16, 0, 0); } while (0)
; #define PG8_LDA(dst, b, h) do { _Pragma("unroll") for (int m = 0; m < 4; ++m) _Pragma("unroll") for (int k = 0; k < 2; ++k) dst[m][k] = *(const PG8_LAS bf16x8*)(lds + PG8_SA(b, h) + aoff + m * 2048 + k * 1024); } while (0)
; #define PG8_LDB(dst, b, h) do { _Pragma("unroll") for (int n = 0; n < 2; ++n) _Pragma("unroll") for (int k = 0; k < 2; ++k) dst[n][k] = *(const PG8_LAS bf16x8*)(lds + PG8_SB(b, h) + boff + n * 2048 + k * 1024); } while (0)
; #define PG8_MMA(ai, bj, At, Bt) do { __builtin_amdgcn_s_setprio(1); _Pragma("unroll") for (int m = 0; m < 4; ++m) _Pragma("unroll") for (int n = 0; n < 2; ++n) _Pragma("unroll") for (int k = 0; k < 2; ++k) \
;         acc[ai][bj][m][n] = __builtin_amdgcn_mfma_f32_16x16x32_bf16(Bt[n][k], At[m][k], acc[ai][bj][m][n], 0, 0, 0); __builtin_amdgcn_s_setprio(0); } while (0)
; #define PG8_WAIT_V(n) asm volatile("s_waitcnt vmcnt(" #n ")" ::: "memory")
; #define PG8_WAIT_L(n) asm volatile("s_waitcnt lgkmcnt(" #n ")" ::: "memory")
; #define PG8_BAR __builtin_amdgcn_s_barrier()
; #define PG8_SCHED __builtin_amdgcn_sched_barrier(0)
; template <class Epi, class Sched, bool ALIGN_EPI = false, bool SP2 = false>
; __device__ __forceinline__ void gemm_phase(PG8_LAS unsigned char* lds, const Gemm g, const Sched& S, const Epi& E) {
;     ...
;             PG8_WAIT_V(8); PG8_WAIT_L(0); PG8_BAR; PG8_MMA(1, 0, At, B0); PG8_MMA(1, 1, At, B1); PG8_BAR; PG8_SCHED;
;             PG8_LDB(B0, 1, 0); PG8_LDB(B1, 1, 1); PG8_SCHED; PG8_LDA(At, 1, 0); PG8_STAGE(PG8_SA(0, 1), a2 + hstepA, voffA);
;             PG8_WAIT_V(8); PG8_WAIT_L(0); PG8_BAR; PG8_MMA(0, 0, At, B0); PG8_MMA(0, 1, At, B1); PG8_BAR; PG8_SCHED;
	s_setprio 1
	s_waitcnt lgkmcnt(0)
	v_mfma_f32_16x16x32_bf16 v[62:65], v[130:133], v[184:187], 0
	v_mfma_f32_16x16x32_bf16 v[58:61], v[154:157], v[184:187], 0
	v_mfma_f32_16x16x32_bf16 v[42:45], v[154:157], v[192:195], 0
	v_mfma_f32_16x16x32_bf16 v[46:49], v[130:133], v[192:195], 0
	v_mfma_f32_16x16x32_bf16 v[30:33], v[130:133], v[200:203], 0
	v_mfma_f32_16x16x32_bf16 v[26:29], v[154:157], v[200:203], 0
	v_mfma_f32_16x16x32_bf16 v[10:13], v[154:157], v[208:211], 0
	v_mfma_f32_16x16x32_bf16 v[14:17], v[130:133], v[208:211], 0
	v_mfma_f32_16x16x32_bf16 v[62:65], v[134:137], v[188:191], v[62:65]
	v_mfma_f32_16x16x32_bf16 v[58:61], v[158:161], v[188:191], v[58:61]
	v_mfma_f32_16x16x32_bf16 v[42:45], v[158:161], v[196:199], v[42:45]
	v_mfma_f32_16x16x32_bf16 v[46:49], v[134:137], v[196:199], v[46:49]
	v_mfma_f32_16x16x32_bf16 v[30:33], v[134:137], v[204:207], v[30:33]
	v_mfma_f32_16x16x32_bf16 v[26:29], v[158:161], v[204:207], v[26:29]
	v_mfma_f32_16x16x32_bf16 v[10:13], v[158:161], v[212:215], v[10:13]
	v_mfma_f32_16x16x32_bf16 v[14:17], v[134:137], v[212:215], v[14:17]
	s_setprio 0
	s_setprio 1
	v_mfma_f32_16x16x32_bf16 v[54:57], v[168:171], v[184:187], 0
	v_mfma_f32_16x16x32_bf16 v[50:53], v[176:179], v[184:187], 0
	v_mfma_f32_16x16x32_bf16 v[34:37], v[176:179], v[192:195], 0
	v_mfma_f32_16x16x32_bf16 v[38:41], v[168:171], v[192:195], 0
	v_mfma_f32_16x16x32_bf16 v[22:25], v[168:171], v[200:203], 0
	v_mfma_f32_16x16x32_bf16 v[18:21], v[176:179], v[200:203], 0
	v_mfma_f32_16x16x32_bf16 v[2:5], v[176:179], v[208:211], 0
	v_mfma_f32_16x16x32_bf16 v[6:9], v[168:171], v[208:211], 0
	v_mfma_f32_16x16x32_bf16 v[54:57], v[172:175], v[188:191], v[54:57]
	v_mfma_f32_16x16x32_bf16 v[50:53], v[180:183], v[188:191], v[50:53]
	v_mfma_f32_16x16x32_bf16 v[34:37], v[180:183], v[196:199], v[34:37]
	v_mfma_f32_16x16x32_bf16 v[38:41], v[172:175], v[196:199], v[38:41]
	v_mfma_f32_16x16x32_bf16 v[22:25], v[172:175], v[204:207], v[22:25]
	v_mfma_f32_16x16x32_bf16 v[18:21], v[180:183], v[204:207], v[18:21]
	v_mfma_f32_16x16x32_bf16 v[2:5], v[180:183], v[212:215], v[2:5]
	v_mfma_f32_16x16x32_bf16 v[6:9], v[172:175], v[212:215], v[6:9]
	s_setprio 0
	s_barrier
	s_add_i32 s55, 0, 0x18000
	s_add_i32 s56, 0, 0x1c000
	v_add_u32_e32 v158, s55, v162
	v_add_u32_e32 v180, s56, v162
	ds_read_b128 v[130:133], v158
	ds_read_b128 v[134:137], v158 offset:1024
	ds_read_b128 v[154:157], v158 offset:2048
	ds_read_b128 v[158:161], v158 offset:3072
	ds_read_b128 v[168:171], v180
	ds_read_b128 v[172:175], v180 offset:1024
	ds_read_b128 v[176:179], v180 offset:2048
	ds_read_b128 v[180:183], v180 offset:3072
	s_add_u32 s26, s34, 0xb0000
	s_addc_u32 s27, s35, 0
	s_mov_b32 m0, s38
	v_lshl_add_u64 v[224:225], s[26:27], 0, v[138:139]
	ds_read_b128 v[184:187], v166 offset:32768
	ds_read_b128 v[188:191], v166 offset:33792
	ds_read_b128 v[192:195], v166 offset:34816
	ds_read_b128 v[196:199], v166 offset:35840
	ds_read_b128 v[200:203], v166 offset:36864
	ds_read_b128 v[204:207], v166 offset:37888
	ds_read_b128 v[208:211], v166 offset:38912
	ds_read_b128 v[212:215], v166 offset:39936
	global_load_lds_dwordx4 v[224:225], off
	v_lshl_add_u64 v[224:225], s[26:27], 0, v[142:143]
	s_mov_b32 m0, s39
	s_nop 0
	global_load_lds_dwordx4 v[224:225], off
	s_waitcnt vmcnt(8)
	s_waitcnt lgkmcnt(0)
	s_barrier
	s_setprio 1
	s_waitcnt lgkmcnt(0)
	v_mfma_f32_16x16x32_bf16 v[126:129], v[130:133], v[184:187], v[126:129]
	v_mfma_f32_16x16x32_bf16 v[122:125], v[154:157], v[184:187], v[122:125]
	v_mfma_f32_16x16x32_bf16 v[106:109], v[154:157], v[192:195], v[106:109]
	v_mfma_f32_16x16x32_bf16 v[110:113], v[130:133], v[192:195], v[110:113]
	v_mfma_f32_16x16x32_bf16 v[94:97], v[130:133], v[200:203], v[94:97]
	v_mfma_f32_16x16x32_bf16 v[90:93], v[154:157], v[200:203], v[90:93]
	v_mfma_f32_16x16x32_bf16 v[74:77], v[154:157], v[208:211], v[74:77]
	v_mfma_f32_16x16x32_bf16 v[78:81], v[130:133], v[208:211], v[78:81]
	v_mfma_f32_16x16x32_bf16 v[126:129], v[134:137], v[188:191], v[126:129]
	v_mfma_f32_16x16x32_bf16 v[122:125], v[158:161], v[188:191], v[122:125]
	v_mfma_f32_16x16x32_bf16 v[106:109], v[158:161], v[196:199], v[106:109]
	v_mfma_f32_16x16x32_bf16 v[110:113], v[134:137], v[196:199], v[110:113]
	v_mfma_f32_16x16x32_bf16 v[94:97], v[134:137], v[204:207], v[94:97]
	v_mfma_f32_16x16x32_bf16 v[90:93], v[158:161], v[204:207], v[90:93]
	v_mfma_f32_16x16x32_bf16 v[74:77], v[158:161], v[212:215], v[74:77]
	v_mfma_f32_16x16x32_bf16 v[78:81], v[134:137], v[212:215], v[78:81]
	s_setprio 0
	s_setprio 1
	v_mfma_f32_16x16x32_bf16 v[118:121], v[168:171], v[184:187], v[118:121]
	v_mfma_f32_16x16x32_bf16 v[114:117], v[176:179], v[184:187], v[114:117]
	v_mfma_f32_16x16x32_bf16 v[98:101], v[176:179], v[192:195], v[98:101]
	v_mfma_f32_16x16x32_bf16 v[102:105], v[168:171], v[192:195], v[102:105]
	v_mfma_f32_16x16x32_bf16 v[86:89], v[168:171], v[200:203], v[86:89]
	v_mfma_f32_16x16x32_bf16 v[82:85], v[176:179], v[200:203], v[82:85]
	v_mfma_f32_16x16x32_bf16 v[66:69], v[176:179], v[208:211], v[66:69]
	v_mfma_f32_16x16x32_bf16 v[70:73], v[168:171], v[208:211], v[70:73]
	v_mfma_f32_16x16x32_bf16 v[118:121], v[172:175], v[188:191], v[118:121]
	v_mfma_f32_16x16x32_bf16 v[114:117], v[180:183], v[188:191], v[114:117]
	v_mfma_f32_16x16x32_bf16 v[98:101], v[180:183], v[196:199], v[98:101]
	v_mfma_f32_16x16x32_bf16 v[102:105], v[172:175], v[196:199], v[102:105]
	v_mfma_f32_16x16x32_bf16 v[86:89], v[172:175], v[204:207], v[86:89]
	v_mfma_f32_16x16x32_bf16 v[82:85], v[180:183], v[204:207], v[82:85]
	v_mfma_f32_16x16x32_bf16 v[66:69], v[180:183], v[212:215], v[66:69]
	v_mfma_f32_16x16x32_bf16 v[70:73], v[172:175], v[212:215], v[70:73]
	s_setprio 0
	s_barrier
; #define PG8_STAGE(bufoff, gbase, voff) do { _Pragma("unroll") for (int _i = 0; _i < 2; ++_i) \
;         __builtin_amdgcn_global_load_lds((const unsigned*)((const char*)(gbase) + (voff)[_i]), (PG8_LAS unsigned*)(lds + (bufoff) + ldsw + _i * 8192), 16, 0, 0); } while (0)
; #define PG8_LDA(dst, b, h) do { _Pragma("unroll") for (int m = 0; m < 4; ++m) _Pragma("unroll") for (int k = 0; k < 2; ++k) dst[m][k] = *(const PG8_LAS bf16x8*)(lds + PG8_SA(b, h) + aoff + m * 2048 + k * 1024); } while (0)
; #define PG8_LDB(dst, b, h) do { _Pragma("unroll") for (int n = 0; n < 2; ++n) _Pragma("unroll") for (int k = 0; k < 2; ++k) dst[n][k] = *(const PG8_LAS bf16x8*)(lds + PG8_SB(b, h) + boff + n * 2048 + k * 1024); } while (0)
; #define PG8_MMA(ai, bj, At, Bt) do { __builtin_amdgcn_s_setprio(1); _Pragma("unroll") for (int m = 0; m < 4; ++m) _Pragma("unroll") for (int n = 0; n < 2; ++n) _Pragma("unroll") for (int k = 0; k < 2; ++k) \
;         acc[ai][bj][m][n] = __builtin_amdgcn_mfma_f32_16x16x32_bf16(Bt[n][k], At[m][k], acc[ai][bj][m][n], 0, 0, 0); __builtin_amdgcn_s_setprio(0); } while (0)
; #define PG8_WAIT_V(n) asm volatile("s_waitcnt vmcnt(" #n ")" ::: "memory")
; template <class Epi, class Sched, bool ALIGN_EPI = false, bool SP2 = false>
; __device__ __forceinline__ void gemm_phase(PG8_LAS unsigned char* lds, const Gemm g, const Sched& S, const Epi& E) {
;     ...
;             PG8_LDB(B0, 0, 0); PG8_LDB(B1, 0, 1); PG8_SCHED; PG8_LDA(At, 0, 0); PG8_STAGE(PG8_SA(1, 1), a1 + hstepA, voffA);
;             PG8_WAIT_V(8); PG8_WAIT_L(0); PG8_BAR; PG8_MMA(0, 0, At, B0); PG8_MMA(0, 1, At, B1); PG8_BAR; PG8_SCHED;
;             PG8_LDA(At, 0, 1); PG8_STAGE(PG8_SB(0, 0), b2, voffB); PG8_STAGE(PG8_SB(0, 1), b2 + hstepB, voffB); PG8_STAGE(PG8_SA(0, 0), a2, voffA);
;             PG8_WAIT_V(8); PG8_WAIT_L(0); PG8_BAR; PG8_MMA(1, 0, At, B0); PG8_MMA(1, 1, At, B1); PG8_BAR; PG8_SCHED;
;             PG8_LDB(B0, 1, 0); PG8_LDB(B1, 1, 1); PG8_SCHED; PG8_LDA(At, 1, 0); PG8_STAGE(PG8_SA(0, 1), a2 + hstepA, voffA);
;             PG8_WAIT_V(8); PG8_WAIT_L(0); PG8_BAR; PG8_MMA(0, 0, At, B0); PG8_MMA(0, 1, At, B1); PG8_BAR; PG8_SCHED;
;             PG8_LDA(At, 1, 1); PG8_STAGE(PG8_SB(1, 0), b3, voffB); PG8_STAGE(PG8_SB(1, 1), b3 + hstepB, voffB); PG8_STAGE(PG8_SA(1, 0), a3, voffA);
;             PG8_WAIT_V(8); PG8_WAIT_L(0); PG8_BAR; PG8_MMA(1, 0, At, B0); PG8_MMA(1, 1, At, B1); PG8_BAR; PG8_SCHED;
	s_add_i32 s26, s55, s0
	v_lshl_add_u64 v[216:217], v[216:217], 0, s[20:21]
	s_mov_b32 m0, s26
	ds_read_b128 v[184:187], v166 offset:49152
	ds_read_b128 v[188:191], v166 offset:50176
	ds_read_b128 v[192:195], v166 offset:51200
	ds_read_b128 v[196:199], v166 offset:52224
	ds_read_b128 v[200:203], v166 offset:53248
	ds_read_b128 v[204:207], v166 offset:54272
	ds_read_b128 v[208:211], v166 offset:55296
	ds_read_b128 v[212:215], v166 offset:56320
	global_load_lds_dwordx4 v[216:217], off
	s_add_i32 m0, s26, 0x2000
	s_add_u32 s26, s30, 0xb0080
	v_lshl_add_u64 v[216:217], v[218:219], 0, s[20:21]
	s_addc_u32 s27, s31, 0
	s_add_i32 s30, s56, s0
	global_load_lds_dwordx4 v[216:217], off
	v_lshl_add_u64 v[216:217], s[26:27], 0, v[140:141]
	s_mov_b32 m0, s30
	s_nop 0
	global_load_lds_dwordx4 v[216:217], off
	v_lshl_add_u64 v[216:217], s[26:27], 0, v[144:145]
	s_add_i32 m0, s30, 0x2000
	s_nop 0
	global_load_lds_dwordx4 v[216:217], off
	v_lshl_add_u64 v[216:217], v[220:221], 0, s[20:21]
	s_mov_b32 m0, s41
	s_nop 0
	global_load_lds_dwordx4 v[216:217], off
	v_lshl_add_u64 v[216:217], v[222:223], 0, s[20:21]
	s_mov_b32 m0, s42
	s_nop 0
	global_load_lds_dwordx4 v[216:217], off
	s_waitcnt vmcnt(8)
	s_waitcnt lgkmcnt(0)
	s_barrier
	s_setprio 1
	s_waitcnt lgkmcnt(0)
	v_mfma_f32_16x16x32_bf16 v[62:65], v[130:133], v[184:187], v[62:65]
	v_mfma_f32_16x16x32_bf16 v[58:61], v[154:157], v[184:187], v[58:61]
	v_mfma_f32_16x16x32_bf16 v[42:45], v[154:157], v[192:195], v[42:45]
	v_mfma_f32_16x16x32_bf16 v[46:49], v[130:133], v[192:195], v[46:49]
	v_mfma_f32_16x16x32_bf16 v[30:33], v[130:133], v[200:203], v[30:33]
	v_mfma_f32_16x16x32_bf16 v[26:29], v[154:157], v[200:203], v[26:29]
	v_mfma_f32_16x16x32_bf16 v[10:13], v[154:157], v[208:211], v[10:13]
	v_mfma_f32_16x16x32_bf16 v[14:17], v[130:133], v[208:211], v[14:17]
	v_mfma_f32_16x16x32_bf16 v[62:65], v[134:137], v[188:191], v[62:65]
	v_mfma_f32_16x16x32_bf16 v[58:61], v[158:161], v[188:191], v[58:61]
	v_mfma_f32_16x16x32_bf16 v[42:45], v[158:161], v[196:199], v[42:45]
	v_mfma_f32_16x16x32_bf16 v[46:49], v[134:137], v[196:199], v[46:49]
	v_mfma_f32_16x16x32_bf16 v[30:33], v[134:137], v[204:207], v[30:33]
	v_mfma_f32_16x16x32_bf16 v[26:29], v[158:161], v[204:207], v[26:29]
	v_mfma_f32_16x16x32_bf16 v[10:13], v[158:161], v[212:215], v[10:13]
	v_mfma_f32_16x16x32_bf16 v[14:17], v[134:137], v[212:215], v[14:17]
	s_setprio 0
	s_setprio 1
	v_mfma_f32_16x16x32_bf16 v[54:57], v[168:171], v[184:187], v[54:57]
	v_mfma_f32_16x16x32_bf16 v[50:53], v[176:179], v[184:187], v[50:53]
	v_mfma_f32_16x16x32_bf16 v[34:37], v[176:179], v[192:195], v[34:37]
	v_mfma_f32_16x16x32_bf16 v[38:41], v[168:171], v[192:195], v[38:41]
	v_mfma_f32_16x16x32_bf16 v[22:25], v[168:171], v[200:203], v[22:25]
	v_mfma_f32_16x16x32_bf16 v[18:21], v[176:179], v[200:203], v[18:21]
	v_mfma_f32_16x16x32_bf16 v[2:5], v[176:179], v[208:211], v[2:5]
	v_mfma_f32_16x16x32_bf16 v[6:9], v[168:171], v[208:211], v[6:9]
	v_mfma_f32_16x16x32_bf16 v[54:57], v[172:175], v[188:191], v[54:57]
	v_mfma_f32_16x16x32_bf16 v[50:53], v[180:183], v[188:191], v[50:53]
	v_mfma_f32_16x16x32_bf16 v[34:37], v[180:183], v[196:199], v[34:37]
	v_mfma_f32_16x16x32_bf16 v[38:41], v[172:175], v[196:199], v[38:41]
	v_mfma_f32_16x16x32_bf16 v[22:25], v[172:175], v[204:207], v[22:25]
	v_mfma_f32_16x16x32_bf16 v[18:21], v[180:183], v[204:207], v[18:21]
	v_mfma_f32_16x16x32_bf16 v[2:5], v[180:183], v[212:215], v[2:5]
	v_mfma_f32_16x16x32_bf16 v[6:9], v[172:175], v[212:215], v[6:9]
	s_setprio 0
	s_barrier
	s_add_i32 s54, s54, 2
	s_add_u32 s4, s4, 0x100
	s_addc_u32 s53, s53, 0
	s_cmp_gt_u32 s54, 41
	s_mov_b64 s[26:27], s[28:29]
.LBB0_776:
	ds_read_b128 v[130:133], v164
	ds_read_b128 v[134:137], v164 offset:1024
	ds_read_b128 v[154:157], v164 offset:2048
	ds_read_b128 v[158:161], v164 offset:3072
	ds_read_b128 v[168:171], v165
	ds_read_b128 v[172:175], v165 offset:1024
	ds_read_b128 v[176:179], v165 offset:2048
	ds_read_b128 v[180:183], v165 offset:3072
	s_add_u32 s28, s26, 0x100
	s_addc_u32 s29, s27, 0
	s_cmp_eq_u32 s54, 40
	s_cselect_b32 s35, s13, s29
	s_cselect_b32 s34, s12, s28
	s_cselect_b32 s31, s25, s53
	s_cselect_b32 s30, s24, s4
	v_lshl_add_u64 v[216:217], s[26:27], 0, v[146:147]
	s_add_i32 m0, s1, 0xc000
	ds_read_b128 v[184:187], v166
	ds_read_b128 v[188:191], v166 offset:1024
	ds_read_b128 v[192:195], v166 offset:2048
	ds_read_b128 v[196:199], v166 offset:3072
	ds_read_b128 v[200:203], v166 offset:4096
	ds_read_b128 v[204:207], v166 offset:5120
	ds_read_b128 v[208:211], v166 offset:6144
	ds_read_b128 v[212:215], v166 offset:7168
	global_load_lds_dwordx4 v[216:217], off
	v_lshl_add_u64 v[216:217], s[26:27], 0, v[148:149]
	s_add_i32 m0, s1, 0xe000
	s_nop 0
	global_load_lds_dwordx4 v[216:217], off
	s_waitcnt vmcnt(8)
	s_waitcnt lgkmcnt(0)
	s_barrier
; #define PG8_STAGE(bufoff, gbase, voff) do { _Pragma("unroll") for (int _i = 0; _i < 2; ++_i) \
;         __builtin_amdgcn_global_load_lds((const unsigned*)((const char*)(gbase) + (voff)[_i]), (PG8_LAS unsigned*)(lds + (bufoff) + ldsw + _i * 8192), 16, 0, 0); } while (0)
; #define PG8_LDA(dst, b, h) do { _Pragma("unroll") for (int m = 0; m < 4; ++m) _Pragma("unroll") for (int k = 0; k < 2; ++k) dst[m][k] = *(const PG8_LAS bf16x8*)(lds + PG8_SA(b, h) + aoff + m * 2048 + k * 1024); } while (0)
; #define PG8_MMA(ai, bj, At, Bt) do { __builtin_amdgcn_s_setprio(1); _Pragma("unroll") for (int m = 0; m < 4; ++m) _Pragma("unroll") for (int n = 0; n < 2; ++n) _Pragma("unroll") for (int k = 0; k < 2; ++k) \
;         acc[ai][bj][m][n] = __builtin_amdgcn_mfma_f32_16x16x32_bf16(Bt[n][k], At[m][k], acc[ai][bj][m][n], 0, 0, 0); __builtin_amdgcn_s_setprio(0); } while (0)
; #define PG8_WAIT_V(n) asm volatile("s_waitcnt vmcnt(" #n ")" ::: "memory")
; #define PG8_WAIT_L(n) asm volatile("s_waitcnt lgkmcnt(" #n ")" ::: "memory")
; #define PG8_BAR __builtin_amdgcn_s_barrier()
; #define PG8_SCHED __builtin_amdgcn_sched_barrier(0)
; template <class Epi, class Sched, bool ALIGN_EPI = false, bool SP2 = false>
; __device__ __forceinline__ void gemm_phase(PG8_LAS unsigned char* lds, const Gemm g, const Sched& S, const Epi& E) {
;     ...
;             PG8_WAIT_V(8); PG8_WAIT_L(0); PG8_BAR; PG8_MMA(0, 0, At, B0); PG8_MMA(0, 1, At, B1); PG8_BAR; PG8_SCHED;
;             PG8_LDA(At, 0, 1); PG8_STAGE(PG8_SB(0, 0), b2, voffB); PG8_STAGE(PG8_SB(0, 1), b2 + hstepB, voffB); PG8_STAGE(PG8_SA(0, 0), a2, voffA);
;             PG8_WAIT_V(8); PG8_WAIT_L(0); PG8_BAR; PG8_MMA(1, 0, At, B0); PG8_MMA(1, 1, At, B1); PG8_BAR; PG8_SCHED;
	s_setprio 1
	s_waitcnt lgkmcnt(0)
	v_mfma_f32_16x16x32_bf16 v[126:129], v[130:133], v[184:187], v[126:129]
	v_mfma_f32_16x16x32_bf16 v[122:125], v[154:157], v[184:187], v[122:125]
	v_mfma_f32_16x16x32_bf16 v[106:109], v[154:157], v[192:195], v[106:109]
	v_mfma_f32_16x16x32_bf16 v[110:113], v[130:133], v[192:195], v[110:113]
	v_mfma_f32_16x16x32_bf16 v[94:97], v[130:133], v[200:203], v[94:97]
	v_mfma_f32_16x16x32_bf16 v[90:93], v[154:157], v[200:203], v[90:93]
	v_mfma_f32_16x16x32_bf16 v[74:77], v[154:157], v[208:211], v[74:77]
	v_mfma_f32_16x16x32_bf16 v[78:81], v[130:133], v[208:211], v[78:81]
	v_mfma_f32_16x16x32_bf16 v[126:129], v[134:137], v[188:191], v[126:129]
	v_mfma_f32_16x16x32_bf16 v[122:125], v[158:161], v[188:191], v[122:125]
	v_mfma_f32_16x16x32_bf16 v[106:109], v[158:161], v[196:199], v[106:109]
	v_mfma_f32_16x16x32_bf16 v[110:113], v[134:137], v[196:199], v[110:113]
	v_mfma_f32_16x16x32_bf16 v[94:97], v[134:137], v[204:207], v[94:97]
	v_mfma_f32_16x16x32_bf16 v[90:93], v[158:161], v[204:207], v[90:93]
	v_mfma_f32_16x16x32_bf16 v[74:77], v[158:161], v[212:215], v[74:77]
	v_mfma_f32_16x16x32_bf16 v[78:81], v[134:137], v[212:215], v[78:81]
	s_setprio 0
	s_setprio 1
	v_mfma_f32_16x16x32_bf16 v[118:121], v[168:171], v[184:187], v[118:121]
	v_mfma_f32_16x16x32_bf16 v[114:117], v[176:179], v[184:187], v[114:117]
	v_mfma_f32_16x16x32_bf16 v[98:101], v[176:179], v[192:195], v[98:101]
	v_mfma_f32_16x16x32_bf16 v[102:105], v[168:171], v[192:195], v[102:105]
	v_mfma_f32_16x16x32_bf16 v[86:89], v[168:171], v[200:203], v[86:89]
	v_mfma_f32_16x16x32_bf16 v[82:85], v[176:179], v[200:203], v[82:85]
	v_mfma_f32_16x16x32_bf16 v[66:69], v[176:179], v[208:211], v[66:69]
	v_mfma_f32_16x16x32_bf16 v[70:73], v[168:171], v[208:211], v[70:73]
	v_mfma_f32_16x16x32_bf16 v[118:121], v[172:175], v[188:191], v[118:121]
	v_mfma_f32_16x16x32_bf16 v[114:117], v[180:183], v[188:191], v[114:117]
	v_mfma_f32_16x16x32_bf16 v[98:101], v[180:183], v[196:199], v[98:101]
	v_mfma_f32_16x16x32_bf16 v[102:105], v[172:175], v[196:199], v[102:105]
	v_mfma_f32_16x16x32_bf16 v[86:89], v[172:175], v[204:207], v[86:89]
	v_mfma_f32_16x16x32_bf16 v[82:85], v[180:183], v[204:207], v[82:85]
	v_mfma_f32_16x16x32_bf16 v[66:69], v[180:183], v[212:215], v[66:69]
	v_mfma_f32_16x16x32_bf16 v[70:73], v[172:175], v[212:215], v[70:73]
	s_setprio 0
	s_barrier
	s_add_i32 s26, s46, s0
	v_lshl_add_u64 v[216:217], s[30:31], 0, v[140:141]
	s_mov_b32 m0, s26
	ds_read_b128 v[184:187], v166 offset:16384
	ds_read_b128 v[188:191], v166 offset:17408
	ds_read_b128 v[192:195], v166 offset:18432
	ds_read_b128 v[196:199], v166 offset:19456
	ds_read_b128 v[200:203], v166 offset:20480
	ds_read_b128 v[204:207], v166 offset:21504
	ds_read_b128 v[208:211], v166 offset:22528
	ds_read_b128 v[212:215], v166 offset:23552
	global_load_lds_dwordx4 v[216:217], off
	s_add_i32 m0, s26, 0x2000
	s_add_u32 s26, s30, 0xb0000
	v_lshl_add_u64 v[218:219], s[30:31], 0, v[144:145]
	s_addc_u32 s27, s31, 0
	s_add_i32 s55, s47, s0
	global_load_lds_dwordx4 v[218:219], off
	v_lshl_add_u64 v[220:221], s[26:27], 0, v[140:141]
	s_mov_b32 m0, s55
	v_lshl_add_u64 v[222:223], s[34:35], 0, v[142:143]
	global_load_lds_dwordx4 v[220:221], off
	v_lshl_add_u64 v[220:221], s[26:27], 0, v[144:145]
	s_add_i32 m0, s55, 0x2000
	s_nop 0
	global_load_lds_dwordx4 v[220:221], off
	v_lshl_add_u64 v[220:221], s[34:35], 0, v[138:139]
	s_mov_b32 m0, s1
	s_nop 0
	global_load_lds_dwordx4 v[220:221], off
	s_mov_b32 m0, s37
	s_nop 0
	global_load_lds_dwordx4 v[222:223], off
	s_waitcnt vmcnt(8)
	s_waitcnt lgkmcnt(0)
	s_barrier
	s_setprio 1
	s_waitcnt lgkmcnt(0)
	v_mfma_f32_16x16x32_bf16 v[62:65], v[130:133], v[184:187], v[62:65]
	v_mfma_f32_16x16x32_bf16 v[58:61], v[154:157], v[184:187], v[58:61]
	v_mfma_f32_16x16x32_bf16 v[42:45], v[154:157], v[192:195], v[42:45]
	v_mfma_f32_16x16x32_bf16 v[46:49], v[130:133], v[192:195], v[46:49]
	v_mfma_f32_16x16x32_bf16 v[30:33], v[130:133], v[200:203], v[30:33]
	v_mfma_f32_16x16x32_bf16 v[26:29], v[154:157], v[200:203], v[26:29]
	v_mfma_f32_16x16x32_bf16 v[10:13], v[154:157], v[208:211], v[10:13]
	v_mfma_f32_16x16x32_bf16 v[14:17], v[130:133], v[208:211], v[14:17]
	v_mfma_f32_16x16x32_bf16 v[62:65], v[134:137], v[188:191], v[62:65]
	v_mfma_f32_16x16x32_bf16 v[58:61], v[158:161], v[188:191], v[58:61]
	v_mfma_f32_16x16x32_bf16 v[42:45], v[158:161], v[196:199], v[42:45]
	v_mfma_f32_16x16x32_bf16 v[46:49], v[134:137], v[196:199], v[46:49]
	v_mfma_f32_16x16x32_bf16 v[30:33], v[134:137], v[204:207], v[30:33]
	v_mfma_f32_16x16x32_bf16 v[26:29], v[158:161], v[204:207], v[26:29]
	v_mfma_f32_16x16x32_bf16 v[10:13], v[158:161], v[212:215], v[10:13]
	v_mfma_f32_16x16x32_bf16 v[14:17], v[134:137], v[212:215], v[14:17]
	s_setprio 0
	s_setprio 1
	v_mfma_f32_16x16x32_bf16 v[54:57], v[168:171], v[184:187], v[54:57]
	v_mfma_f32_16x16x32_bf16 v[50:53], v[176:179], v[184:187], v[50:53]
	v_mfma_f32_16x16x32_bf16 v[34:37], v[176:179], v[192:195], v[34:37]
	v_mfma_f32_16x16x32_bf16 v[38:41], v[168:171], v[192:195], v[38:41]
	v_mfma_f32_16x16x32_bf16 v[22:25], v[168:171], v[200:203], v[22:25]
	v_mfma_f32_16x16x32_bf16 v[18:21], v[176:179], v[200:203], v[18:21]
	v_mfma_f32_16x16x32_bf16 v[2:5], v[176:179], v[208:211], v[2:5]
	v_mfma_f32_16x16x32_bf16 v[6:9], v[168:171], v[208:211], v[6:9]
	v_mfma_f32_16x16x32_bf16 v[54:57], v[172:175], v[188:191], v[54:57]
	v_mfma_f32_16x16x32_bf16 v[50:53], v[180:183], v[188:191], v[50:53]
	v_mfma_f32_16x16x32_bf16 v[34:37], v[180:183], v[196:199], v[34:37]
	v_mfma_f32_16x16x32_bf16 v[38:41], v[172:175], v[196:199], v[38:41]
	v_mfma_f32_16x16x32_bf16 v[22:25], v[172:175], v[204:207], v[22:25]
	v_mfma_f32_16x16x32_bf16 v[18:21], v[180:183], v[204:207], v[18:21]
	v_mfma_f32_16x16x32_bf16 v[2:5], v[180:183], v[212:215], v[2:5]
	v_mfma_f32_16x16x32_bf16 v[6:9], v[172:175], v[212:215], v[6:9]
	s_setprio 0
	s_barrier
; #define PG8_STAGE(bufoff, gbase, voff) do { _Pragma("unroll") for (int _i = 0; _i < 2; ++_i) \
;         __builtin_amdgcn_global_load_lds((const unsigned*)((const char*)(gbase) + (voff)[_i]), (PG8_LAS unsigned*)(lds + (bufoff) + ldsw + _i * 8192), 16, 0, 0); } while (0)
; #define PG8_LDA(dst, b, h) do { _Pragma("unroll") for (int m = 0; m < 4; ++m) _Pragma("unroll") for (int k = 0; k < 2; ++k) dst[m][k] = *(const PG8_LAS bf16x8*)(lds + PG8_SA(b, h) + aoff + m * 2048 + k * 1024); } while (0)
; #define PG8_LDB(dst, b, h) do { _Pragma("unroll") for (int n = 0; n < 2; ++n) _Pragma("unroll") for (int k = 0; k < 2; ++k) dst[n][k] = *(const PG8_LAS bf16x8*)(lds + PG8_SB(b, h) + boff + n * 2048 + k * 1024); } while (0)
; #define PG8_MMA(ai, bj, At, Bt) do { __builtin_amdgcn_s_setprio(1); _Pragma("unroll") for (int m = 0; m < 4; ++m) _Pragma("unroll") for (int n = 0; n < 2; ++n) _Pragma("unroll") for (int k = 0; k < 2; ++k) \
;         acc[ai][bj][m][n] = __builtin_amdgcn_mfma_f32_16x16x32_bf16(Bt[n][k], At[m][k], acc[ai][bj][m][n], 0, 0, 0); __builtin_amdgcn_s_setprio(0); } while (0)
; #define PG8_WAIT_V(n) asm volatile("s_waitcnt vmcnt(" #n ")" ::: "memory")
; #define PG8_WAIT_L(n) asm volatile("s_waitcnt lgkmcnt(" #n ")" ::: "memory")
; #define PG8_BAR __builtin_amdgcn_s_barrier()
; #define PG8_SCHED __builtin_amdgcn_sched_barrier(0)
; template <class Epi, class Sched, bool ALIGN_EPI = false, bool SP2 = false>
; __device__ __forceinline__ void gemm_phase(PG8_LAS unsigned char* lds, const Gemm g, const Sched& S, const Epi& E) {
;     ...
;             PG8_LDB(B0, 1, 0); PG8_LDB(B1, 1, 1); PG8_SCHED; PG8_LDA(At, 1, 0); PG8_STAGE(PG8_SA(0, 1), a2 + hstepA, voffA);
;             PG8_WAIT_V(8); PG8_WAIT_L(0); PG8_BAR; PG8_MMA(0, 0, At, B0); PG8_MMA(0, 1, At, B1); PG8_BAR; PG8_SCHED;
	s_add_i32 s55, 0, 0x18000
	s_add_i32 s56, 0, 0x1c000
	v_add_u32_e32 v158, s55, v162
	v_add_u32_e32 v180, s56, v162
	ds_read_b128 v[130:133], v158
	ds_read_b128 v[134:137], v158 offset:1024
	ds_read_b128 v[154:157], v158 offset:2048
	ds_read_b128 v[158:161], v158 offset:3072
	ds_read_b128 v[168:171], v180
	ds_read_b128 v[172:175], v180 offset:1024
	ds_read_b128 v[176:179], v180 offset:2048
	ds_read_b128 v[180:183], v180 offset:3072
	s_add_u32 s26, s34, 0xb0000
	s_addc_u32 s27, s35, 0
	s_mov_b32 m0, s38
	v_lshl_add_u64 v[224:225], s[26:27], 0, v[138:139]
	ds_read_b128 v[184:187], v166 offset:32768
	ds_read_b128 v[188:191], v166 offset:33792
	ds_read_b128 v[192:195], v166 offset:34816
	ds_read_b128 v[196:199], v166 offset:35840
	ds_read_b128 v[200:203], v166 offset:36864
	ds_read_b128 v[204:207], v166 offset:37888
	ds_read_b128 v[208:211], v166 offset:38912
	ds_read_b128 v[212:215], v166 offset:39936
	global_load_lds_dwordx4 v[224:225], off
	v_lshl_add_u64 v[224:225], s[26:27], 0, v[142:143]
	s_mov_b32 m0, s39
	s_nop 0
	global_load_lds_dwordx4 v[224:225], off
	s_waitcnt vmcnt(8)
	s_waitcnt lgkmcnt(0)
	s_barrier
	s_setprio 1
	s_waitcnt lgkmcnt(0)
	v_mfma_f32_16x16x32_bf16 v[126:129], v[130:133], v[184:187], v[126:129]
	v_mfma_f32_16x16x32_bf16 v[122:125], v[154:157], v[184:187], v[122:125]
	v_mfma_f32_16x16x32_bf16 v[106:109], v[154:157], v[192:195], v[106:109]
	v_mfma_f32_16x16x32_bf16 v[110:113], v[130:133], v[192:195], v[110:113]
	v_mfma_f32_16x16x32_bf16 v[94:97], v[130:133], v[200:203], v[94:97]
	v_mfma_f32_16x16x32_bf16 v[90:93], v[154:157], v[200:203], v[90:93]
	v_mfma_f32_16x16x32_bf16 v[74:77], v[154:157], v[208:211], v[74:77]
	v_mfma_f32_16x16x32_bf16 v[78:81], v[130:133], v[208:211], v[78:81]
	v_mfma_f32_16x16x32_bf16 v[126:129], v[134:137], v[188:191], v[126:129]
	v_mfma_f32_16x16x32_bf16 v[122:125], v[158:161], v[188:191], v[122:125]
	v_mfma_f32_16x16x32_bf16 v[106:109], v[158:161], v[196:199], v[106:109]
	v_mfma_f32_16x16x32_bf16 v[110:113], v[134:137], v[196:199], v[110:113]
	v_mfma_f32_16x16x32_bf16 v[94:97], v[134:137], v[204:207], v[94:97]
	v_mfma_f32_16x16x32_bf16 v[90:93], v[158:161], v[204:207], v[90:93]
	v_mfma_f32_16x16x32_bf16 v[74:77], v[158:161], v[212:215], v[74:77]
	v_mfma_f32_16x16x32_bf16 v[78:81], v[134:137], v[212:215], v[78:81]
	s_setprio 0
	s_setprio 1
	v_mfma_f32_16x16x32_bf16 v[118:121], v[168:171], v[184:187], v[118:121]
	v_mfma_f32_16x16x32_bf16 v[114:117], v[176:179], v[184:187], v[114:117]
	v_mfma_f32_16x16x32_bf16 v[98:101], v[176:179], v[192:195], v[98:101]
	v_mfma_f32_16x16x32_bf16 v[102:105], v[168:171], v[192:195], v[102:105]
	v_mfma_f32_16x16x32_bf16 v[86:89], v[168:171], v[200:203], v[86:89]
	v_mfma_f32_16x16x32_bf16 v[82:85], v[176:179], v[200:203], v[82:85]
	v_mfma_f32_16x16x32_bf16 v[66:69], v[176:179], v[208:211], v[66:69]
	v_mfma_f32_16x16x32_bf16 v[70:73], v[168:171], v[208:211], v[70:73]
	v_mfma_f32_16x16x32_bf16 v[118:121], v[172:175], v[188:191], v[118:121]
	v_mfma_f32_16x16x32_bf16 v[114:117], v[180:183], v[188:191], v[114:117]
	v_mfma_f32_16x16x32_bf16 v[98:101], v[180:183], v[196:199], v[98:101]
	v_mfma_f32_16x16x32_bf16 v[102:105], v[172:175], v[196:199], v[102:105]
	v_mfma_f32_16x16x32_bf16 v[86:89], v[172:175], v[204:207], v[86:89]
	v_mfma_f32_16x16x32_bf16 v[82:85], v[180:183], v[204:207], v[82:85]
	v_mfma_f32_16x16x32_bf16 v[66:69], v[180:183], v[212:215], v[66:69]
	v_mfma_f32_16x16x32_bf16 v[70:73], v[172:175], v[212:215], v[70:73]
	s_setprio 0
	s_barrier
; #define PG8_STAGE(bufoff, gbase, voff) do { _Pragma("unroll") for (int _i = 0; _i < 2; ++_i) \
;         __builtin_amdgcn_global_load_lds((const unsigned*)((const char*)(gbase) + (voff)[_i]), (PG8_LAS unsigned*)(lds + (bufoff) + ldsw + _i * 8192), 16, 0, 0); } while (0)
; #define PG8_LDA(dst, b, h) do { _Pragma("unroll") for (int m = 0; m < 4; ++m) _Pragma("unroll") for (int k = 0; k < 2; ++k) dst[m][k] = *(const PG8_LAS bf16x8*)(lds + PG8_SA(b, h) + aoff + m * 2048 + k * 1024); } while (0)
; #define PG8_MMA(ai, bj, At, Bt) do { __builtin_amdgcn_s_setprio(1); _Pragma("unroll") for (int m = 0; m < 4; ++m) _Pragma("unroll") for (int n = 0; n < 2; ++n) _Pragma("unroll") for (int k = 0; k < 2; ++k) \
;         acc[ai][bj][m][n] = __builtin_amdgcn_mfma_f32_16x16x32_bf16(Bt[n][k], At[m][k], acc[ai][bj][m][n], 0, 0, 0); __builtin_amdgcn_s_setprio(0); } while (0)
; #define PG8_WAIT_V(n) asm volatile("s_waitcnt vmcnt(" #n ")" ::: "memory")
; #define PG8_WAIT_L(n) asm volatile("s_waitcnt lgkmcnt(" #n ")" ::: "memory")
; #define PG8_BAR __builtin_amdgcn_s_barrier()
; #define PG8_SCHED __builtin_amdgcn_sched_barrier(0)
; template <class Epi, class Sched, bool ALIGN_EPI = false, bool SP2 = false>
; __device__ __forceinline__ void gemm_phase(PG8_LAS unsigned char* lds, const Gemm g, const Sched& S, const Epi& E) {
;     ...
;             PG8_LDA(At, 1, 1); PG8_STAGE(PG8_SB(1, 0), b3, voffB); PG8_STAGE(PG8_SB(1, 1), b3 + hstepB, voffB); PG8_STAGE(PG8_SA(1, 0), a3, voffA);
;             PG8_WAIT_V(8); PG8_WAIT_L(0); PG8_BAR; PG8_MMA(1, 0, At, B0); PG8_MMA(1, 1, At, B1); PG8_BAR; PG8_SCHED;
	s_add_i32 s26, s55, s0
	v_lshl_add_u64 v[216:217], v[216:217], 0, s[20:21]
	s_mov_b32 m0, s26
	ds_read_b128 v[184:187], v166 offset:49152
	ds_read_b128 v[188:191], v166 offset:50176
	ds_read_b128 v[192:195], v166 offset:51200
	ds_read_b128 v[196:199], v166 offset:52224
	ds_read_b128 v[200:203], v166 offset:53248
	ds_read_b128 v[204:207], v166 offset:54272
	ds_read_b128 v[208:211], v166 offset:55296
	ds_read_b128 v[212:215], v166 offset:56320
	global_load_lds_dwordx4 v[216:217], off
	s_add_i32 m0, s26, 0x2000
	s_add_u32 s26, s30, 0xb0080
	v_lshl_add_u64 v[216:217], v[218:219], 0, s[20:21]
	s_addc_u32 s27, s31, 0
	s_add_i32 s30, s56, s0
	global_load_lds_dwordx4 v[216:217], off
	v_lshl_add_u64 v[216:217], s[26:27], 0, v[140:141]
	s_mov_b32 m0, s30
	s_nop 0
	global_load_lds_dwordx4 v[216:217], off
	v_lshl_add_u64 v[216:217], s[26:27], 0, v[144:145]
	s_add_i32 m0, s30, 0x2000
	s_nop 0
	global_load_lds_dwordx4 v[216:217], off
	v_lshl_add_u64 v[216:217], v[220:221], 0, s[20:21]
	s_mov_b32 m0, s41
	s_nop 0
	global_load_lds_dwordx4 v[216:217], off
	v_lshl_add_u64 v[216:217], v[222:223], 0, s[20:21]
	s_mov_b32 m0, s42
	s_nop 0
	global_load_lds_dwordx4 v[216:217], off
	s_waitcnt vmcnt(8)
	s_waitcnt lgkmcnt(0)
	s_barrier
	s_setprio 1
	s_waitcnt lgkmcnt(0)
	v_mfma_f32_16x16x32_bf16 v[62:65], v[130:133], v[184:187], v[62:65]
	v_mfma_f32_16x16x32_bf16 v[58:61], v[154:157], v[184:187], v[58:61]
	v_mfma_f32_16x16x32_bf16 v[42:45], v[154:157], v[192:195], v[42:45]
	v_mfma_f32_16x16x32_bf16 v[46:49], v[130:133], v[192:195], v[46:49]
	v_mfma_f32_16x16x32_bf16 v[30:33], v[130:133], v[200:203], v[30:33]
	v_mfma_f32_16x16x32_bf16 v[26:29], v[154:157], v[200:203], v[26:29]
	v_mfma_f32_16x16x32_bf16 v[10:13], v[154:157], v[208:211], v[10:13]
	v_mfma_f32_16x16x32_bf16 v[14:17], v[130:133], v[208:211], v[14:17]
	v_mfma_f32_16x16x32_bf16 v[62:65], v[134:137], v[188:191], v[62:65]
	v_mfma_f32_16x16x32_bf16 v[58:61], v[158:161], v[188:191], v[58:61]
	v_mfma_f32_16x16x32_bf16 v[42:45], v[158:161], v[196:199], v[42:45]
	v_mfma_f32_16x16x32_bf16 v[46:49], v[134:137], v[196:199], v[46:49]
	v_mfma_f32_16x16x32_bf16 v[30:33], v[134:137], v[204:207], v[30:33]
	v_mfma_f32_16x16x32_bf16 v[26:29], v[158:161], v[204:207], v[26:29]
	v_mfma_f32_16x16x32_bf16 v[10:13], v[158:161], v[212:215], v[10:13]
	v_mfma_f32_16x16x32_bf16 v[14:17], v[134:137], v[212:215], v[14:17]
	s_setprio 0
	s_setprio 1
	v_mfma_f32_16x16x32_bf16 v[54:57], v[168:171], v[184:187], v[54:57]
	v_mfma_f32_16x16x32_bf16 v[50:53], v[176:179], v[184:187], v[50:53]
	v_mfma_f32_16x16x32_bf16 v[34:37], v[176:179], v[192:195], v[34:37]
	v_mfma_f32_16x16x32_bf16 v[38:41], v[168:171], v[192:195], v[38:41]
	v_mfma_f32_16x16x32_bf16 v[22:25], v[168:171], v[200:203], v[22:25]
	v_mfma_f32_16x16x32_bf16 v[18:21], v[176:179], v[200:203], v[18:21]
	v_mfma_f32_16x16x32_bf16 v[2:5], v[176:179], v[208:211], v[2:5]
	v_mfma_f32_16x16x32_bf16 v[6:9], v[168:171], v[208:211], v[6:9]
	v_mfma_f32_16x16x32_bf16 v[54:57], v[172:175], v[188:191], v[54:57]
	v_mfma_f32_16x16x32_bf16 v[50:53], v[180:183], v[188:191], v[50:53]
	v_mfma_f32_16x16x32_bf16 v[34:37], v[180:183], v[196:199], v[34:37]
	v_mfma_f32_16x16x32_bf16 v[38:41], v[172:175], v[196:199], v[38:41]
	v_mfma_f32_16x16x32_bf16 v[22:25], v[172:175], v[204:207], v[22:25]
	v_mfma_f32_16x16x32_bf16 v[18:21], v[180:183], v[204:207], v[18:21]
	v_mfma_f32_16x16x32_bf16 v[2:5], v[180:183], v[212:215], v[2:5]
	v_mfma_f32_16x16x32_bf16 v[6:9], v[172:175], v[212:215], v[6:9]
	s_setprio 0
	s_barrier
	s_add_i32 s54, s54, 2
	s_add_u32 s4, s4, 0x100
	s_addc_u32 s53, s53, 0
	s_cmp_gt_u32 s54, 41
	s_mov_b64 s[26:27], s[28:29]
	s_cbranch_scc0 .LBB0_776
	s_and_b64 vcc, exec, s[22:23]
	s_cbranch_vccz .LBB0_779
	s_barrier

; #define PG8_STAGE(bufoff, gbase, voff) do { _Pragma("unroll") for (int _i = 0; _i < 2; ++_i) \
;         __builtin_amdgcn_global_load_lds((const unsigned*)((const char*)(gbase) + (voff)[_i]), (PG8_LAS unsigned*)(lds + (bufoff) + ldsw + _i * 8192), 16, 0, 0); } while (0)
; #define PG8_LDA(dst, b, h) do { _Pragma("unroll") for (int m = 0; m < 4; ++m) _Pragma("unroll") for (int k = 0; k < 2; ++k) dst[m][k] = *(const PG8_LAS bf16x8*)(lds + PG8_SA(b, h) + aoff + m * 2048 + k * 1024); } while (0)
; #define PG8_LDB(dst, b, h) do { _Pragma("unroll") for (int n = 0; n < 2; ++n) _Pragma("unroll") for (int k = 0; k < 2; ++k) dst[n][k] = *(const PG8_LAS bf16x8*)(lds + PG8_SB(b, h) + boff + n * 2048 + k * 1024); } while (0)
; #define PG8_MMA(ai, bj, At, Bt) do { __builtin_amdgcn_s_setprio(1); _Pragma("unroll") for (int m = 0; m < 4; ++m) _Pragma("unroll") for (int n = 0; n < 2; ++n) _Pragma("unroll") for (int k = 0; k < 2; ++k) \
;         acc[ai][bj][m][n] = __builtin_amdgcn_mfma_f32_16x16x32_bf16(Bt[n][k], At[m][k], acc[ai][bj][m][n], 0, 0, 0); __builtin_amdgcn_s_setprio(0); } while (0)
; #define PG8_WAIT_V(n) asm volatile("s_waitcnt vmcnt(" #n ")" ::: "memory")
; #define PG8_WAIT_L(n) asm volatile("s_waitcnt lgkmcnt(" #n ")" ::: "memory")
; #define PG8_BAR __builtin_amdgcn_s_barrier()
; #define PG8_SCHED __builtin_amdgcn_sched_barrier(0)
; template <class Epi, class Sched, bool ALIGN_EPI = false, bool SP2 = false>
; __device__ __forceinline__ void gemm_phase(PG8_LAS unsigned char* lds, const Gemm g, const Sched& S, const Epi& E) {
;     ...
;             PG8_LDB(B0, 0, 0); PG8_LDB(B1, 0, 1); PG8_SCHED; PG8_LDA(At, 0, 0); PG8_STAGE(PG8_SA(1, 1), a1 + hstepA, voffA);
;             PG8_WAIT_V(8); PG8_WAIT_L(0); PG8_BAR; PG8_MMA(0, 0, At, B0); PG8_MMA(0, 1, At, B1); PG8_BAR; PG8_SCHED;
;     ...
; #pragma unroll
;         for (int a = 0; a < 2; ++a)
; #pragma unroll
;             for (int b = 0; b < 2; ++b)
; #pragma unroll
;                 for (int m = 0; m < 4; ++m)
; #pragma unroll
;                     for (int n = 0; n < 2; ++n) acc[a][b][m][n] = (f32x4){0.f, 0.f, 0.f, 0.f};
.LBB0_819:
	v_mov_b32_e32 v125, 0
	s_andn2_b64 vcc, exec, s[22:23]
	v_mov_b32_e32 v124, v125
	v_mov_b32_e32 v123, v125
	v_mov_b32_e32 v122, v125
	v_mov_b32_e32 v129, v125
	v_mov_b32_e32 v128, v125
	v_mov_b32_e32 v127, v125
	v_mov_b32_e32 v126, v125
	v_mov_b32_e32 v113, v125
	v_mov_b32_e32 v112, v125
	v_mov_b32_e32 v111, v125
	v_mov_b32_e32 v110, v125
	v_mov_b32_e32 v109, v125
	v_mov_b32_e32 v108, v125
	v_mov_b32_e32 v107, v125
	v_mov_b32_e32 v106, v125
	v_mov_b32_e32 v97, v125
	v_mov_b32_e32 v96, v125
	v_mov_b32_e32 v95, v125
	v_mov_b32_e32 v94, v125
	v_mov_b32_e32 v93, v125
	v_mov_b32_e32 v92, v125
	v_mov_b32_e32 v91, v125
	v_mov_b32_e32 v90, v125
	v_mov_b32_e32 v81, v125
	v_mov_b32_e32 v80, v125
	v_mov_b32_e32 v79, v125
	v_mov_b32_e32 v78, v125
	v_mov_b32_e32 v77, v125
	v_mov_b32_e32 v76, v125
	v_mov_b32_e32 v75, v125
	v_mov_b32_e32 v74, v125
	v_mov_b32_e32 v121, v125
	v_mov_b32_e32 v120, v125
	v_mov_b32_e32 v119, v125
	v_mov_b32_e32 v118, v125
	v_mov_b32_e32 v117, v125
	v_mov_b32_e32 v116, v125
	v_mov_b32_e32 v115, v125
	v_mov_b32_e32 v114, v125
	v_mov_b32_e32 v105, v125
	v_mov_b32_e32 v104, v125
	v_mov_b32_e32 v103, v125
	v_mov_b32_e32 v102, v125
	v_mov_b32_e32 v101, v125
	v_mov_b32_e32 v100, v125
	v_mov_b32_e32 v99, v125
	v_mov_b32_e32 v98, v125
	v_mov_b32_e32 v89, v125
	v_mov_b32_e32 v88, v125
	v_mov_b32_e32 v87, v125
	v_mov_b32_e32 v86, v125
	v_mov_b32_e32 v85, v125
	v_mov_b32_e32 v84, v125
	v_mov_b32_e32 v83, v125
	v_mov_b32_e32 v82, v125
	v_mov_b32_e32 v73, v125
	v_mov_b32_e32 v72, v125
	v_mov_b32_e32 v71, v125
	v_mov_b32_e32 v70, v125
	v_mov_b32_e32 v69, v125
	v_mov_b32_e32 v68, v125
	v_mov_b32_e32 v67, v125
	v_mov_b32_e32 v66, v125
	v_mov_b32_e32 v65, v125
	v_mov_b32_e32 v64, v125
	v_mov_b32_e32 v63, v125
	v_mov_b32_e32 v62, v125
	v_mov_b32_e32 v61, v125
	v_mov_b32_e32 v60, v125
	v_mov_b32_e32 v59, v125
	v_mov_b32_e32 v58, v125
	v_mov_b32_e32 v49, v125
	v_mov_b32_e32 v48, v125
	v_mov_b32_e32 v47, v125
	v_mov_b32_e32 v46, v125
	v_mov_b32_e32 v45, v125
	v_mov_b32_e32 v44, v125
	v_mov_b32_e32 v43, v125
	v_mov_b32_e32 v42, v125
	v_mov_b32_e32 v33, v125
	v_mov_b32_e32 v32, v125
	v_mov_b32_e32 v31, v125
	v_mov_b32_e32 v30, v125
	v_mov_b32_e32 v29, v125
	v_mov_b32_e32 v28, v125
	v_mov_b32_e32 v27, v125
	v_mov_b32_e32 v26, v125
	v_mov_b32_e32 v17, v125
	v_mov_b32_e32 v16, v125
	v_mov_b32_e32 v15, v125
	v_mov_b32_e32 v14, v125
	v_mov_b32_e32 v13, v125
	v_mov_b32_e32 v12, v125
	v_mov_b32_e32 v11, v125
	v_mov_b32_e32 v10, v125
	v_mov_b32_e32 v57, v125
	v_mov_b32_e32 v56, v125
	v_mov_b32_e32 v55, v125
	v_mov_b32_e32 v54, v125
	v_mov_b32_e32 v53, v125
	v_mov_b32_e32 v52, v125
	v_mov_b32_e32 v51, v125
	v_mov_b32_e32 v50, v125
	v_mov_b32_e32 v41, v125
	v_mov_b32_e32 v40, v125
	v_mov_b32_e32 v39, v125
	v_mov_b32_e32 v38, v125
	v_mov_b32_e32 v37, v125
	v_mov_b32_e32 v36, v125
	v_mov_b32_e32 v35, v125
	v_mov_b32_e32 v34, v125
	v_mov_b32_e32 v25, v125
	v_mov_b32_e32 v24, v125
	v_mov_b32_e32 v23, v125
	v_mov_b32_e32 v22, v125
	v_mov_b32_e32 v21, v125
	v_mov_b32_e32 v20, v125
	v_mov_b32_e32 v19, v125
	v_mov_b32_e32 v18, v125
	v_mov_b32_e32 v9, v125
	v_mov_b32_e32 v8, v125
	v_mov_b32_e32 v7, v125
	v_mov_b32_e32 v6, v125
	v_mov_b32_e32 v5, v125
	v_mov_b32_e32 v4, v125
	v_mov_b32_e32 v3, v125
	v_mov_b32_e32 v2, v125
	s_cbranch_vccnz .LBB0_822
	s_add_u32 s38, s38, 0x80
	s_addc_u32 s39, s39, 0
	s_add_u32 s63, s40, 0x100
	s_addc_u32 s64, s41, 0
	s_mov_b32 s40, 0
	ds_read_b128 v[152:155], v148
	ds_read_b128 v[156:159], v148 offset:1024
	ds_read_b128 v[160:163], v148 offset:2048
	ds_read_b128 v[164:167], v148 offset:3072
	ds_read_b128 v[168:171], v149
	ds_read_b128 v[172:175], v149 offset:1024
	ds_read_b128 v[176:179], v149 offset:2048
	ds_read_b128 v[180:183], v149 offset:3072
	s_add_i32 s65, s40, 2
	s_add_u32 s66, s38, 0x80
	s_addc_u32 s41, s39, 0
	s_cmp_eq_u32 s51, s40
	s_cselect_b32 s40, s8, s66
	s_cselect_b32 s41, s9, s41
	s_cselect_b32 s67, s37, s64
	s_cselect_b32 s66, s36, s63
	v_lshl_add_u64 v[216:217], s[38:39], 0, v[138:139]
	s_add_i32 m0, s43, 0xc000
	ds_read_b128 v[184:187], v150
	ds_read_b128 v[188:191], v150 offset:1024
	ds_read_b128 v[192:195], v150 offset:2048
	ds_read_b128 v[196:199], v150 offset:3072
	ds_read_b128 v[200:203], v150 offset:4096
	ds_read_b128 v[204:207], v150 offset:5120
	ds_read_b128 v[208:211], v150 offset:6144
	ds_read_b128 v[212:215], v150 offset:7168
	global_load_lds_dwordx4 v[216:217], off
	v_lshl_add_u64 v[216:217], s[38:39], 0, v[140:141]
	s_add_i32 m0, s43, 0xe000
	s_nop 0
	global_load_lds_dwordx4 v[216:217], off
	s_waitcnt vmcnt(8)
	s_waitcnt lgkmcnt(0)
	s_barrier
; #define PG8_STAGE(bufoff, gbase, voff) do { _Pragma("unroll") for (int _i = 0; _i < 2; ++_i) \
;         __builtin_amdgcn_global_load_lds((const unsigned*)((const char*)(gbase) + (voff)[_i]), (PG8_LAS unsigned*)(lds + (bufoff) + ldsw + _i * 8192), 16, 0, 0); } while (0)
; #define PG8_LDA(dst, b, h) do { _Pragma("unroll") for (int m = 0; m < 4; ++m) _Pragma("unroll") for (int k = 0; k < 2; ++k) dst[m][k] = *(const PG8_LAS bf16x8*)(lds + PG8_SA(b, h) + aoff + m * 2048 + k * 1024); } while (0)
; #define PG8_MMA(ai, bj, At, Bt) do { __builtin_amdgcn_s_setprio(1); _Pragma("unroll") for (int m = 0; m < 4; ++m) _Pragma("unroll") for (int n = 0; n < 2; ++n) _Pragma("unroll") for (int k = 0; k < 2; ++k) \
;         acc[ai][bj][m][n] = __builtin_amdgcn_mfma_f32_16x16x32_bf16(Bt[n][k], At[m][k], acc[ai][bj][m][n], 0, 0, 0); __builtin_amdgcn_s_setprio(0); } while (0)
; #define PG8_WAIT_V(n) asm volatile("s_waitcnt vmcnt(" #n ")" ::: "memory")
; #define PG8_WAIT_L(n) asm volatile("s_waitcnt lgkmcnt(" #n ")" ::: "memory")
; #define PG8_BAR __builtin_amdgcn_s_barrier()
; #define PG8_SCHED __builtin_amdgcn_sched_barrier(0)
; template <class Epi, class Sched, bool ALIGN_EPI = false, bool SP2 = false>
; __device__ __forceinline__ void gemm_phase(PG8_LAS unsigned char* lds, const Gemm g, const Sched& S, const Epi& E) {
;     ...
;             PG8_WAIT_V(8); PG8_WAIT_L(0); PG8_BAR; PG8_MMA(0, 0, At, B0); PG8_MMA(0, 1, At, B1); PG8_BAR; PG8_SCHED;
;             PG8_LDA(At, 0, 1); PG8_STAGE(PG8_SB(0, 0), b2, voffB); PG8_STAGE(PG8_SB(0, 1), b2 + hstepB, voffB); PG8_STAGE(PG8_SA(0, 0), a2, voffA);
;             PG8_WAIT_V(8); PG8_WAIT_L(0); PG8_BAR; PG8_MMA(1, 0, At, B0); PG8_MMA(1, 1, At, B1); PG8_BAR; PG8_SCHED;
	s_setprio 1
	s_waitcnt lgkmcnt(0)
	v_mfma_f32_16x16x32_bf16 v[122:125], v[152:155], v[184:187], 0
	v_mfma_f32_16x16x32_bf16 v[126:129], v[160:163], v[184:187], 0
	v_mfma_f32_16x16x32_bf16 v[106:109], v[160:163], v[192:195], 0
	v_mfma_f32_16x16x32_bf16 v[110:113], v[152:155], v[192:195], 0
	v_mfma_f32_16x16x32_bf16 v[94:97], v[152:155], v[200:203], 0
	v_mfma_f32_16x16x32_bf16 v[90:93], v[160:163], v[200:203], 0
	v_mfma_f32_16x16x32_bf16 v[74:77], v[160:163], v[208:211], 0
	v_mfma_f32_16x16x32_bf16 v[78:81], v[152:155], v[208:211], 0
	v_mfma_f32_16x16x32_bf16 v[122:125], v[156:159], v[188:191], v[122:125]
	v_mfma_f32_16x16x32_bf16 v[126:129], v[164:167], v[188:191], v[126:129]
	v_mfma_f32_16x16x32_bf16 v[106:109], v[164:167], v[196:199], v[106:109]
	v_mfma_f32_16x16x32_bf16 v[110:113], v[156:159], v[196:199], v[110:113]
	v_mfma_f32_16x16x32_bf16 v[94:97], v[156:159], v[204:207], v[94:97]
	v_mfma_f32_16x16x32_bf16 v[90:93], v[164:167], v[204:207], v[90:93]
	v_mfma_f32_16x16x32_bf16 v[74:77], v[164:167], v[212:215], v[74:77]
	v_mfma_f32_16x16x32_bf16 v[78:81], v[156:159], v[212:215], v[78:81]
	s_setprio 0
	s_setprio 1
	v_mfma_f32_16x16x32_bf16 v[118:121], v[168:171], v[184:187], 0
	v_mfma_f32_16x16x32_bf16 v[114:117], v[176:179], v[184:187], 0
	v_mfma_f32_16x16x32_bf16 v[98:101], v[176:179], v[192:195], 0
	v_mfma_f32_16x16x32_bf16 v[102:105], v[168:171], v[192:195], 0
	v_mfma_f32_16x16x32_bf16 v[86:89], v[168:171], v[200:203], 0
	v_mfma_f32_16x16x32_bf16 v[82:85], v[176:179], v[200:203], 0
	v_mfma_f32_16x16x32_bf16 v[66:69], v[176:179], v[208:211], 0
	v_mfma_f32_16x16x32_bf16 v[70:73], v[168:171], v[208:211], 0
	v_mfma_f32_16x16x32_bf16 v[118:121], v[172:175], v[188:191], v[118:121]
	v_mfma_f32_16x16x32_bf16 v[114:117], v[180:183], v[188:191], v[114:117]
	v_mfma_f32_16x16x32_bf16 v[98:101], v[180:183], v[196:199], v[98:101]
	v_mfma_f32_16x16x32_bf16 v[102:105], v[172:175], v[196:199], v[102:105]
	v_mfma_f32_16x16x32_bf16 v[86:89], v[172:175], v[204:207], v[86:89]
	v_mfma_f32_16x16x32_bf16 v[82:85], v[180:183], v[204:207], v[82:85]
	v_mfma_f32_16x16x32_bf16 v[66:69], v[180:183], v[212:215], v[66:69]
	v_mfma_f32_16x16x32_bf16 v[70:73], v[172:175], v[212:215], v[70:73]
	s_setprio 0
	s_barrier
	s_add_i32 s68, s54, s42
	v_lshl_add_u64 v[216:217], s[66:67], 0, v[132:133]
	s_mov_b32 m0, s68
	ds_read_b128 v[184:187], v150 offset:16384
	ds_read_b128 v[188:191], v150 offset:17408
	ds_read_b128 v[192:195], v150 offset:18432
	ds_read_b128 v[196:199], v150 offset:19456
	ds_read_b128 v[200:203], v150 offset:20480
	ds_read_b128 v[204:207], v150 offset:21504
	ds_read_b128 v[208:211], v150 offset:22528
	ds_read_b128 v[212:215], v150 offset:23552
	global_load_lds_dwordx4 v[216:217], off
	s_add_i32 m0, s68, 0x2000
	v_lshl_add_u64 v[218:219], s[66:67], 0, v[136:137]
	s_add_u32 s66, s66, s10
	s_addc_u32 s67, s67, s11
	s_add_i32 s68, s55, s42
	global_load_lds_dwordx4 v[218:219], off
	v_lshl_add_u64 v[220:221], s[66:67], 0, v[132:133]
	s_mov_b32 m0, s68
	v_lshl_add_u64 v[222:223], s[66:67], 0, v[136:137]
	global_load_lds_dwordx4 v[220:221], off
	s_add_i32 m0, s68, 0x2000
	v_lshl_add_u64 v[224:225], s[40:41], 0, v[130:131]
	global_load_lds_dwordx4 v[222:223], off
	s_mov_b32 m0, s43
	v_lshl_add_u64 v[226:227], s[40:41], 0, v[134:135]
	global_load_lds_dwordx4 v[224:225], off
	s_mov_b32 m0, s44
	s_nop 0
	global_load_lds_dwordx4 v[226:227], off
	s_waitcnt vmcnt(8)
	s_waitcnt lgkmcnt(0)
	s_barrier
	s_setprio 1
	s_waitcnt lgkmcnt(0)
	v_mfma_f32_16x16x32_bf16 v[62:65], v[152:155], v[184:187], 0
	v_mfma_f32_16x16x32_bf16 v[58:61], v[160:163], v[184:187], 0
	v_mfma_f32_16x16x32_bf16 v[42:45], v[160:163], v[192:195], 0
	v_mfma_f32_16x16x32_bf16 v[46:49], v[152:155], v[192:195], 0
	v_mfma_f32_16x16x32_bf16 v[30:33], v[152:155], v[200:203], 0
	v_mfma_f32_16x16x32_bf16 v[26:29], v[160:163], v[200:203], 0
	v_mfma_f32_16x16x32_bf16 v[10:13], v[160:163], v[208:211], 0
	v_mfma_f32_16x16x32_bf16 v[14:17], v[152:155], v[208:211], 0
	v_mfma_f32_16x16x32_bf16 v[62:65], v[156:159], v[188:191], v[62:65]
	v_mfma_f32_16x16x32_bf16 v[58:61], v[164:167], v[188:191], v[58:61]
	v_mfma_f32_16x16x32_bf16 v[42:45], v[164:167], v[196:199], v[42:45]
	v_mfma_f32_16x16x32_bf16 v[46:49], v[156:159], v[196:199], v[46:49]
	v_mfma_f32_16x16x32_bf16 v[30:33], v[156:159], v[204:207], v[30:33]
	v_mfma_f32_16x16x32_bf16 v[26:29], v[164:167], v[204:207], v[26:29]
	v_mfma_f32_16x16x32_bf16 v[10:13], v[164:167], v[212:215], v[10:13]
	v_mfma_f32_16x16x32_bf16 v[14:17], v[156:159], v[212:215], v[14:17]
	s_setprio 0
	s_setprio 1
	v_mfma_f32_16x16x32_bf16 v[54:57], v[168:171], v[184:187], 0
	v_mfma_f32_16x16x32_bf16 v[50:53], v[176:179], v[184:187], 0
	v_mfma_f32_16x16x32_bf16 v[34:37], v[176:179], v[192:195], 0
	v_mfma_f32_16x16x32_bf16 v[38:41], v[168:171], v[192:195], 0
	v_mfma_f32_16x16x32_bf16 v[22:25], v[168:171], v[200:203], 0
	v_mfma_f32_16x16x32_bf16 v[18:21], v[176:179], v[200:203], 0
	v_mfma_f32_16x16x32_bf16 v[2:5], v[176:179], v[208:211], 0
	v_mfma_f32_16x16x32_bf16 v[6:9], v[168:171], v[208:211], 0
	v_mfma_f32_16x16x32_bf16 v[54:57], v[172:175], v[188:191], v[54:57]
	v_mfma_f32_16x16x32_bf16 v[50:53], v[180:183], v[188:191], v[50:53]
	v_mfma_f32_16x16x32_bf16 v[34:37], v[180:183], v[196:199], v[34:37]
	v_mfma_f32_16x16x32_bf16 v[38:41], v[172:175], v[196:199], v[38:41]
	v_mfma_f32_16x16x32_bf16 v[22:25], v[172:175], v[204:207], v[22:25]
	v_mfma_f32_16x16x32_bf16 v[18:21], v[180:183], v[204:207], v[18:21]
	v_mfma_f32_16x16x32_bf16 v[2:5], v[180:183], v[212:215], v[2:5]
	v_mfma_f32_16x16x32_bf16 v[6:9], v[172:175], v[212:215], v[6:9]
	s_setprio 0
	s_barrier
; #define PG8_STAGE(bufoff, gbase, voff) do { _Pragma("unroll") for (int _i = 0; _i < 2; ++_i) \
;         __builtin_amdgcn_global_load_lds((const unsigned*)((const char*)(gbase) + (voff)[_i]), (PG8_LAS unsigned*)(lds + (bufoff) + ldsw + _i * 8192), 16, 0, 0); } while (0)
; #define PG8_LDA(dst, b, h) do { _Pragma("unroll") for (int m = 0; m < 4; ++m) _Pragma("unroll") for (int k = 0; k < 2; ++k) dst[m][k] = *(const PG8_LAS bf16x8*)(lds + PG8_SA(b, h) + aoff + m * 2048 + k * 1024); } while (0)
; #define PG8_LDB(dst, b, h) do { _Pragma("unroll") for (int n = 0; n < 2; ++n) _Pragma("unroll") for (int k = 0; k < 2; ++k) dst[n][k] = *(const PG8_LAS bf16x8*)(lds + PG8_SB(b, h) + boff + n * 2048 + k * 1024); } while (0)
; #define PG8_MMA(ai, bj, At, Bt) do { __builtin_amdgcn_s_setprio(1); _Pragma("unroll") for (int m = 0; m < 4; ++m) _Pragma("unroll") for (int n = 0; n < 2; ++n) _Pragma("unroll") for (int k = 0; k < 2; ++k) \
;         acc[ai][bj][m][n] = __builtin_amdgcn_mfma_f32_16x16x32_bf16(Bt[n][k], At[m][k], acc[ai][bj][m][n], 0, 0, 0); __builtin_amdgcn_s_setprio(0); } while (0)
; #define PG8_WAIT_V(n) asm volatile("s_waitcnt vmcnt(" #n ")" ::: "memory")
; #define PG8_WAIT_L(n) asm volatile("s_waitcnt lgkmcnt(" #n ")" ::: "memory")
; #define PG8_BAR __builtin_amdgcn_s_barrier()
; #define PG8_SCHED __builtin_amdgcn_sched_barrier(0)
; template <class Epi, class Sched, bool ALIGN_EPI = false, bool SP2 = false>
; __device__ __forceinline__ void gemm_phase(PG8_LAS unsigned char* lds, const Gemm g, const Sched& S, const Epi& E) {
;     ...
;             PG8_LDB(B0, 1, 0); PG8_LDB(B1, 1, 1); PG8_SCHED; PG8_LDA(At, 1, 0); PG8_STAGE(PG8_SA(0, 1), a2 + hstepA, voffA);
;             PG8_WAIT_V(8); PG8_WAIT_L(0); PG8_BAR; PG8_MMA(0, 0, At, B0); PG8_MMA(0, 1, At, B1); PG8_BAR; PG8_SCHED;
;             PG8_LDA(At, 1, 1); PG8_STAGE(PG8_SB(1, 0), b3, voffB); PG8_STAGE(PG8_SB(1, 1), b3 + hstepB, voffB); PG8_STAGE(PG8_SA(1, 0), a3, voffA);
	s_add_i32 s66, 0, 0x18000
	v_add_u32_e32 v151, s66, v146
	s_add_i32 s67, 0, 0x1c000
	ds_read_b128 v[152:155], v151
	ds_read_b128 v[156:159], v151 offset:1024
	ds_read_b128 v[160:163], v151 offset:2048
	ds_read_b128 v[164:167], v151 offset:3072
	v_add_u32_e32 v151, s67, v146
	ds_read_b128 v[168:171], v151
	ds_read_b128 v[172:175], v151 offset:1024
	ds_read_b128 v[176:179], v151 offset:2048
	ds_read_b128 v[180:183], v151 offset:3072
	s_add_u32 s40, s40, s4
	s_addc_u32 s41, s41, s5
	s_mov_b32 m0, s45
	v_lshl_add_u64 v[228:229], s[40:41], 0, v[130:131]
	ds_read_b128 v[184:187], v150 offset:32768
	ds_read_b128 v[188:191], v150 offset:33792
	ds_read_b128 v[192:195], v150 offset:34816
	ds_read_b128 v[196:199], v150 offset:35840
	ds_read_b128 v[200:203], v150 offset:36864
	ds_read_b128 v[204:207], v150 offset:37888
	ds_read_b128 v[208:211], v150 offset:38912
	ds_read_b128 v[212:215], v150 offset:39936
	global_load_lds_dwordx4 v[228:229], off
	v_lshl_add_u64 v[228:229], s[40:41], 0, v[134:135]
	s_mov_b32 m0, s46
	s_nop 0
	global_load_lds_dwordx4 v[228:229], off
	s_waitcnt vmcnt(8)
	s_waitcnt lgkmcnt(0)
	s_barrier
	s_setprio 1
	s_waitcnt lgkmcnt(0)
	v_mfma_f32_16x16x32_bf16 v[122:125], v[152:155], v[184:187], v[122:125]
	v_mfma_f32_16x16x32_bf16 v[126:129], v[160:163], v[184:187], v[126:129]
	v_mfma_f32_16x16x32_bf16 v[106:109], v[160:163], v[192:195], v[106:109]
	v_mfma_f32_16x16x32_bf16 v[110:113], v[152:155], v[192:195], v[110:113]
	v_mfma_f32_16x16x32_bf16 v[94:97], v[152:155], v[200:203], v[94:97]
	v_mfma_f32_16x16x32_bf16 v[90:93], v[160:163], v[200:203], v[90:93]
	v_mfma_f32_16x16x32_bf16 v[74:77], v[160:163], v[208:211], v[74:77]
	v_mfma_f32_16x16x32_bf16 v[78:81], v[152:155], v[208:211], v[78:81]
	v_mfma_f32_16x16x32_bf16 v[122:125], v[156:159], v[188:191], v[122:125]
	v_mfma_f32_16x16x32_bf16 v[126:129], v[164:167], v[188:191], v[126:129]
	v_mfma_f32_16x16x32_bf16 v[106:109], v[164:167], v[196:199], v[106:109]
	v_mfma_f32_16x16x32_bf16 v[110:113], v[156:159], v[196:199], v[110:113]
	v_mfma_f32_16x16x32_bf16 v[94:97], v[156:159], v[204:207], v[94:97]
	v_mfma_f32_16x16x32_bf16 v[90:93], v[164:167], v[204:207], v[90:93]
	v_mfma_f32_16x16x32_bf16 v[74:77], v[164:167], v[212:215], v[74:77]
	v_mfma_f32_16x16x32_bf16 v[78:81], v[156:159], v[212:215], v[78:81]
	s_setprio 0
	s_setprio 1
	v_mfma_f32_16x16x32_bf16 v[118:121], v[168:171], v[184:187], v[118:121]
	v_mfma_f32_16x16x32_bf16 v[114:117], v[176:179], v[184:187], v[114:117]
	v_mfma_f32_16x16x32_bf16 v[98:101], v[176:179], v[192:195], v[98:101]
	v_mfma_f32_16x16x32_bf16 v[102:105], v[168:171], v[192:195], v[102:105]
	v_mfma_f32_16x16x32_bf16 v[86:89], v[168:171], v[200:203], v[86:89]
	v_mfma_f32_16x16x32_bf16 v[82:85], v[176:179], v[200:203], v[82:85]
	v_mfma_f32_16x16x32_bf16 v[66:69], v[176:179], v[208:211], v[66:69]
	v_mfma_f32_16x16x32_bf16 v[70:73], v[168:171], v[208:211], v[70:73]
	v_mfma_f32_16x16x32_bf16 v[118:121], v[172:175], v[188:191], v[118:121]
	v_mfma_f32_16x16x32_bf16 v[114:117], v[180:183], v[188:191], v[114:117]
	v_mfma_f32_16x16x32_bf16 v[98:101], v[180:183], v[196:199], v[98:101]
	v_mfma_f32_16x16x32_bf16 v[102:105], v[172:175], v[196:199], v[102:105]
	v_mfma_f32_16x16x32_bf16 v[86:89], v[172:175], v[204:207], v[86:89]
	v_mfma_f32_16x16x32_bf16 v[82:85], v[180:183], v[204:207], v[82:85]
	v_mfma_f32_16x16x32_bf16 v[66:69], v[180:183], v[212:215], v[66:69]
	v_mfma_f32_16x16x32_bf16 v[70:73], v[172:175], v[212:215], v[70:73]
	s_setprio 0
	s_barrier
	s_add_i32 s40, s66, s42
	v_lshl_add_u64 v[216:217], v[216:217], 0, s[20:21]
	s_mov_b32 m0, s40
	ds_read_b128 v[184:187], v150 offset:49152
	ds_read_b128 v[188:191], v150 offset:50176
	ds_read_b128 v[192:195], v150 offset:51200
	ds_read_b128 v[196:199], v150 offset:52224
	ds_read_b128 v[200:203], v150 offset:53248
	ds_read_b128 v[204:207], v150 offset:54272
	ds_read_b128 v[208:211], v150 offset:55296
	ds_read_b128 v[212:215], v150 offset:56320
	global_load_lds_dwordx4 v[216:217], off
	v_lshl_add_u64 v[216:217], v[218:219], 0, s[20:21]
	s_add_i32 m0, s40, 0x2000
	s_add_i32 s40, s67, s42
	global_load_lds_dwordx4 v[216:217], off
	v_lshl_add_u64 v[216:217], v[220:221], 0, s[20:21]
	s_mov_b32 m0, s40
	s_nop 0
	global_load_lds_dwordx4 v[216:217], off
	v_lshl_add_u64 v[216:217], v[222:223], 0, s[20:21]
	s_add_i32 m0, s40, 0x2000
	s_nop 0
	global_load_lds_dwordx4 v[216:217], off
	v_lshl_add_u64 v[216:217], v[224:225], 0, s[20:21]
	s_mov_b32 m0, s48
	s_nop 0
	global_load_lds_dwordx4 v[216:217], off
	v_lshl_add_u64 v[216:217], v[226:227], 0, s[20:21]
	s_mov_b32 m0, s49
	s_nop 0
	global_load_lds_dwordx4 v[216:217], off
	s_waitcnt vmcnt(8)
	s_waitcnt lgkmcnt(0)
	s_barrier
; #define PG8_STAGE(bufoff, gbase, voff) do { _Pragma("unroll") for (int _i = 0; _i < 2; ++_i) \
;         __builtin_amdgcn_global_load_lds((const unsigned*)((const char*)(gbase) + (voff)[_i]), (PG8_LAS unsigned*)(lds + (bufoff) + ldsw + _i * 8192), 16, 0, 0); } while (0)
; #define PG8_LDA(dst, b, h) do { _Pragma("unroll") for (int m = 0; m < 4; ++m) _Pragma("unroll") for (int k = 0; k < 2; ++k) dst[m][k] = *(const PG8_LAS bf16x8*)(lds + PG8_SA(b, h) + aoff + m * 2048 + k * 1024); } while (0)
; #define PG8_LDB(dst, b, h) do { _Pragma("unroll") for (int n = 0; n < 2; ++n) _Pragma("unroll") for (int k = 0; k < 2; ++k) dst[n][k] = *(const PG8_LAS bf16x8*)(lds + PG8_SB(b, h) + boff + n * 2048 + k * 1024); } while (0)
; #define PG8_MMA(ai, bj, At, Bt) do { __builtin_amdgcn_s_setprio(1); _Pragma("unroll") for (int m = 0; m < 4; ++m) _Pragma("unroll") for (int n = 0; n < 2; ++n) _Pragma("unroll") for (int k = 0; k < 2; ++k) \
;         acc[ai][bj][m][n] = __builtin_amdgcn_mfma_f32_16x16x32_bf16(Bt[n][k], At[m][k], acc[ai][bj][m][n], 0, 0, 0); __builtin_amdgcn_s_setprio(0); } while (0)
; #define PG8_WAIT_V(n) asm volatile("s_waitcnt vmcnt(" #n ")" ::: "memory")
; template <class Epi, class Sched, bool ALIGN_EPI = false, bool SP2 = false>
; __device__ __forceinline__ void gemm_phase(PG8_LAS unsigned char* lds, const Gemm g, const Sched& S, const Epi& E) {
;     ...
;             PG8_LDB(B0, 0, 0); PG8_LDB(B1, 0, 1); PG8_SCHED; PG8_LDA(At, 0, 0); PG8_STAGE(PG8_SA(1, 1), a1 + hstepA, voffA);
;             PG8_WAIT_V(8); PG8_WAIT_L(0); PG8_BAR; PG8_MMA(0, 0, At, B0); PG8_MMA(0, 1, At, B1); PG8_BAR; PG8_SCHED;
;             PG8_LDA(At, 0, 1); PG8_STAGE(PG8_SB(0, 0), b2, voffB); PG8_STAGE(PG8_SB(0, 1), b2 + hstepB, voffB); PG8_STAGE(PG8_SA(0, 0), a2, voffA);
;             PG8_WAIT_V(8); PG8_WAIT_L(0); PG8_BAR; PG8_MMA(1, 0, At, B0); PG8_MMA(1, 1, At, B1); PG8_BAR; PG8_SCHED;
;             PG8_LDB(B0, 1, 0); PG8_LDB(B1, 1, 1); PG8_SCHED; PG8_LDA(At, 1, 0); PG8_STAGE(PG8_SA(0, 1), a2 + hstepA, voffA);
;             PG8_WAIT_V(8); PG8_WAIT_L(0); PG8_BAR; PG8_MMA(0, 0, At, B0); PG8_MMA(0, 1, At, B1); PG8_BAR; PG8_SCHED;
;             PG8_LDA(At, 1, 1); PG8_STAGE(PG8_SB(1, 0), b3, voffB); PG8_STAGE(PG8_SB(1, 1), b3 + hstepB, voffB); PG8_STAGE(PG8_SA(1, 0), a3, voffA);
;             PG8_WAIT_V(8); PG8_WAIT_L(0); PG8_BAR; PG8_MMA(1, 0, At, B0); PG8_MMA(1, 1, At, B1); PG8_BAR; PG8_SCHED;
	s_setprio 1
	s_waitcnt lgkmcnt(0)
	v_mfma_f32_16x16x32_bf16 v[62:65], v[152:155], v[184:187], v[62:65]
	v_mfma_f32_16x16x32_bf16 v[58:61], v[160:163], v[184:187], v[58:61]
	v_mfma_f32_16x16x32_bf16 v[42:45], v[160:163], v[192:195], v[42:45]
	v_mfma_f32_16x16x32_bf16 v[46:49], v[152:155], v[192:195], v[46:49]
	v_mfma_f32_16x16x32_bf16 v[30:33], v[152:155], v[200:203], v[30:33]
	v_mfma_f32_16x16x32_bf16 v[26:29], v[160:163], v[200:203], v[26:29]
	v_mfma_f32_16x16x32_bf16 v[10:13], v[160:163], v[208:211], v[10:13]
	v_mfma_f32_16x16x32_bf16 v[14:17], v[152:155], v[208:211], v[14:17]
	v_mfma_f32_16x16x32_bf16 v[62:65], v[156:159], v[188:191], v[62:65]
	v_mfma_f32_16x16x32_bf16 v[58:61], v[164:167], v[188:191], v[58:61]
	v_mfma_f32_16x16x32_bf16 v[42:45], v[164:167], v[196:199], v[42:45]
	v_mfma_f32_16x16x32_bf16 v[46:49], v[156:159], v[196:199], v[46:49]
	v_mfma_f32_16x16x32_bf16 v[30:33], v[156:159], v[204:207], v[30:33]
	v_mfma_f32_16x16x32_bf16 v[26:29], v[164:167], v[204:207], v[26:29]
	v_mfma_f32_16x16x32_bf16 v[10:13], v[164:167], v[212:215], v[10:13]
	v_mfma_f32_16x16x32_bf16 v[14:17], v[156:159], v[212:215], v[14:17]
	s_setprio 0
	s_setprio 1
	v_mfma_f32_16x16x32_bf16 v[54:57], v[168:171], v[184:187], v[54:57]
	v_mfma_f32_16x16x32_bf16 v[50:53], v[176:179], v[184:187], v[50:53]
	v_mfma_f32_16x16x32_bf16 v[34:37], v[176:179], v[192:195], v[34:37]
	v_mfma_f32_16x16x32_bf16 v[38:41], v[168:171], v[192:195], v[38:41]
	v_mfma_f32_16x16x32_bf16 v[22:25], v[168:171], v[200:203], v[22:25]
	v_mfma_f32_16x16x32_bf16 v[18:21], v[176:179], v[200:203], v[18:21]
	v_mfma_f32_16x16x32_bf16 v[2:5], v[176:179], v[208:211], v[2:5]
	v_mfma_f32_16x16x32_bf16 v[6:9], v[168:171], v[208:211], v[6:9]
	v_mfma_f32_16x16x32_bf16 v[54:57], v[172:175], v[188:191], v[54:57]
	v_mfma_f32_16x16x32_bf16 v[50:53], v[180:183], v[188:191], v[50:53]
	v_mfma_f32_16x16x32_bf16 v[34:37], v[180:183], v[196:199], v[34:37]
	v_mfma_f32_16x16x32_bf16 v[38:41], v[172:175], v[196:199], v[38:41]
	v_mfma_f32_16x16x32_bf16 v[22:25], v[172:175], v[204:207], v[22:25]
	v_mfma_f32_16x16x32_bf16 v[18:21], v[180:183], v[204:207], v[18:21]
	v_mfma_f32_16x16x32_bf16 v[2:5], v[180:183], v[212:215], v[2:5]
	v_mfma_f32_16x16x32_bf16 v[6:9], v[172:175], v[212:215], v[6:9]
	s_setprio 0
	s_barrier
	s_add_u32 s38, s38, 0x100
	s_addc_u32 s39, s39, 0
	s_add_u32 s63, s63, 0x100
	s_addc_u32 s64, s64, 0
	s_cmp_ge_i32 s65, s50
	s_mov_b32 s40, s65
.LBB0_821:
	ds_read_b128 v[152:155], v148
	ds_read_b128 v[156:159], v148 offset:1024
	ds_read_b128 v[160:163], v148 offset:2048
	ds_read_b128 v[164:167], v148 offset:3072
	ds_read_b128 v[168:171], v149
	ds_read_b128 v[172:175], v149 offset:1024
	ds_read_b128 v[176:179], v149 offset:2048
	ds_read_b128 v[180:183], v149 offset:3072
	s_add_i32 s65, s40, 2
	s_add_u32 s66, s38, 0x80
	s_addc_u32 s41, s39, 0
	s_cmp_eq_u32 s51, s40
	s_cselect_b32 s40, s8, s66
	s_cselect_b32 s41, s9, s41
	s_cselect_b32 s67, s37, s64
	s_cselect_b32 s66, s36, s63
	v_lshl_add_u64 v[216:217], s[38:39], 0, v[138:139]
	s_add_i32 m0, s43, 0xc000
	ds_read_b128 v[184:187], v150
	ds_read_b128 v[188:191], v150 offset:1024
	ds_read_b128 v[192:195], v150 offset:2048
	ds_read_b128 v[196:199], v150 offset:3072
	ds_read_b128 v[200:203], v150 offset:4096
	ds_read_b128 v[204:207], v150 offset:5120
	ds_read_b128 v[208:211], v150 offset:6144
	ds_read_b128 v[212:215], v150 offset:7168
	global_load_lds_dwordx4 v[216:217], off
	v_lshl_add_u64 v[216:217], s[38:39], 0, v[140:141]
	s_add_i32 m0, s43, 0xe000
	s_nop 0
	global_load_lds_dwordx4 v[216:217], off
	s_waitcnt vmcnt(8)
	s_waitcnt lgkmcnt(0)
	s_barrier
	s_setprio 1
	s_waitcnt lgkmcnt(0)
	v_mfma_f32_16x16x32_bf16 v[122:125], v[152:155], v[184:187], v[122:125]
	v_mfma_f32_16x16x32_bf16 v[126:129], v[160:163], v[184:187], v[126:129]
	v_mfma_f32_16x16x32_bf16 v[106:109], v[160:163], v[192:195], v[106:109]
	v_mfma_f32_16x16x32_bf16 v[110:113], v[152:155], v[192:195], v[110:113]
	v_mfma_f32_16x16x32_bf16 v[94:97], v[152:155], v[200:203], v[94:97]
	v_mfma_f32_16x16x32_bf16 v[90:93], v[160:163], v[200:203], v[90:93]
	v_mfma_f32_16x16x32_bf16 v[74:77], v[160:163], v[208:211], v[74:77]
	v_mfma_f32_16x16x32_bf16 v[78:81], v[152:155], v[208:211], v[78:81]
	v_mfma_f32_16x16x32_bf16 v[122:125], v[156:159], v[188:191], v[122:125]
	v_mfma_f32_16x16x32_bf16 v[126:129], v[164:167], v[188:191], v[126:129]
	v_mfma_f32_16x16x32_bf16 v[106:109], v[164:167], v[196:199], v[106:109]
	v_mfma_f32_16x16x32_bf16 v[110:113], v[156:159], v[196:199], v[110:113]
	v_mfma_f32_16x16x32_bf16 v[94:97], v[156:159], v[204:207], v[94:97]
	v_mfma_f32_16x16x32_bf16 v[90:93], v[164:167], v[204:207], v[90:93]
	v_mfma_f32_16x16x32_bf16 v[74:77], v[164:167], v[212:215], v[74:77]
	v_mfma_f32_16x16x32_bf16 v[78:81], v[156:159], v[212:215], v[78:81]
	s_setprio 0
	s_setprio 1
	v_mfma_f32_16x16x32_bf16 v[118:121], v[168:171], v[184:187], v[118:121]
	v_mfma_f32_16x16x32_bf16 v[114:117], v[176:179], v[184:187], v[114:117]
	v_mfma_f32_16x16x32_bf16 v[98:101], v[176:179], v[192:195], v[98:101]
	v_mfma_f32_16x16x32_bf16 v[102:105], v[168:171], v[192:195], v[102:105]
	v_mfma_f32_16x16x32_bf16 v[86:89], v[168:171], v[200:203], v[86:89]
	v_mfma_f32_16x16x32_bf16 v[82:85], v[176:179], v[200:203], v[82:85]
	v_mfma_f32_16x16x32_bf16 v[66:69], v[176:179], v[208:211], v[66:69]
	v_mfma_f32_16x16x32_bf16 v[70:73], v[168:171], v[208:211], v[70:73]
	v_mfma_f32_16x16x32_bf16 v[118:121], v[172:175], v[188:191], v[118:121]
	v_mfma_f32_16x16x32_bf16 v[114:117], v[180:183], v[188:191], v[114:117]
	v_mfma_f32_16x16x32_bf16 v[98:101], v[180:183], v[196:199], v[98:101]
	v_mfma_f32_16x16x32_bf16 v[102:105], v[172:175], v[196:199], v[102:105]
	v_mfma_f32_16x16x32_bf16 v[86:89], v[172:175], v[204:207], v[86:89]
	v_mfma_f32_16x16x32_bf16 v[82:85], v[180:183], v[204:207], v[82:85]
	v_mfma_f32_16x16x32_bf16 v[66:69], v[180:183], v[212:215], v[66:69]
	v_mfma_f32_16x16x32_bf16 v[70:73], v[172:175], v[212:215], v[70:73]
	s_setprio 0
	s_barrier
; #define PG8_STAGE(bufoff, gbase, voff) do { _Pragma("unroll") for (int _i = 0; _i < 2; ++_i) \
;         __builtin_amdgcn_global_load_lds((const unsigned*)((const char*)(gbase) + (voff)[_i]), (PG8_LAS unsigned*)(lds + (bufoff) + ldsw + _i * 8192), 16, 0, 0); } while (0)
; #define PG8_LDA(dst, b, h) do { _Pragma("unroll") for (int m = 0; m < 4; ++m) _Pragma("unroll") for (int k = 0; k < 2; ++k) dst[m][k] = *(const PG8_LAS bf16x8*)(lds + PG8_SA(b, h) + aoff + m * 2048 + k * 1024); } while (0)
; #define PG8_LDB(dst, b, h) do { _Pragma("unroll") for (int n = 0; n < 2; ++n) _Pragma("unroll") for (int k = 0; k < 2; ++k) dst[n][k] = *(const PG8_LAS bf16x8*)(lds + PG8_SB(b, h) + boff + n * 2048 + k * 1024); } while (0)
; #define PG8_MMA(ai, bj, At, Bt) do { __builtin_amdgcn_s_setprio(1); _Pragma("unroll") for (int m = 0; m < 4; ++m) _Pragma("unroll") for (int n = 0; n < 2; ++n) _Pragma("unroll") for (int k = 0; k < 2; ++k) \
;         acc[ai][bj][m][n] = __builtin_amdgcn_mfma_f32_16x16x32_bf16(Bt[n][k], At[m][k], acc[ai][bj][m][n], 0, 0, 0); __builtin_amdgcn_s_setprio(0); } while (0)
; #define PG8_WAIT_V(n) asm volatile("s_waitcnt vmcnt(" #n ")" ::: "memory")
; #define PG8_WAIT_L(n) asm volatile("s_waitcnt lgkmcnt(" #n ")" ::: "memory")
; #define PG8_BAR __builtin_amdgcn_s_barrier()
; #define PG8_SCHED __builtin_amdgcn_sched_barrier(0)
; template <class Epi, class Sched, bool ALIGN_EPI = false, bool SP2 = false>
; __device__ __forceinline__ void gemm_phase(PG8_LAS unsigned char* lds, const Gemm g, const Sched& S, const Epi& E) {
;     ...
;             PG8_LDA(At, 0, 1); PG8_STAGE(PG8_SB(0, 0), b2, voffB); PG8_STAGE(PG8_SB(0, 1), b2 + hstepB, voffB); PG8_STAGE(PG8_SA(0, 0), a2, voffA);
;             PG8_WAIT_V(8); PG8_WAIT_L(0); PG8_BAR; PG8_MMA(1, 0, At, B0); PG8_MMA(1, 1, At, B1); PG8_BAR; PG8_SCHED;
;             PG8_LDB(B0, 1, 0); PG8_LDB(B1, 1, 1); PG8_SCHED; PG8_LDA(At, 1, 0); PG8_STAGE(PG8_SA(0, 1), a2 + hstepA, voffA);
	s_add_i32 s68, s54, s42
	v_lshl_add_u64 v[216:217], s[66:67], 0, v[132:133]
	s_mov_b32 m0, s68
	ds_read_b128 v[184:187], v150 offset:16384
	ds_read_b128 v[188:191], v150 offset:17408
	ds_read_b128 v[192:195], v150 offset:18432
	ds_read_b128 v[196:199], v150 offset:19456
	ds_read_b128 v[200:203], v150 offset:20480
	ds_read_b128 v[204:207], v150 offset:21504
	ds_read_b128 v[208:211], v150 offset:22528
	ds_read_b128 v[212:215], v150 offset:23552
	global_load_lds_dwordx4 v[216:217], off
	s_add_i32 m0, s68, 0x2000
	v_lshl_add_u64 v[218:219], s[66:67], 0, v[136:137]
	s_add_u32 s66, s66, s10
	s_addc_u32 s67, s67, s11
	s_add_i32 s68, s55, s42
	global_load_lds_dwordx4 v[218:219], off
	v_lshl_add_u64 v[220:221], s[66:67], 0, v[132:133]
	s_mov_b32 m0, s68
	v_lshl_add_u64 v[222:223], s[66:67], 0, v[136:137]
	global_load_lds_dwordx4 v[220:221], off
	s_add_i32 m0, s68, 0x2000
	v_lshl_add_u64 v[224:225], s[40:41], 0, v[130:131]
	global_load_lds_dwordx4 v[222:223], off
	s_mov_b32 m0, s43
	v_lshl_add_u64 v[226:227], s[40:41], 0, v[134:135]
	global_load_lds_dwordx4 v[224:225], off
	s_mov_b32 m0, s44
	s_nop 0
	global_load_lds_dwordx4 v[226:227], off
	s_waitcnt vmcnt(8)
	s_waitcnt lgkmcnt(0)
	s_barrier
	s_setprio 1
	s_waitcnt lgkmcnt(0)
	v_mfma_f32_16x16x32_bf16 v[62:65], v[152:155], v[184:187], v[62:65]
	v_mfma_f32_16x16x32_bf16 v[58:61], v[160:163], v[184:187], v[58:61]
	v_mfma_f32_16x16x32_bf16 v[42:45], v[160:163], v[192:195], v[42:45]
	v_mfma_f32_16x16x32_bf16 v[46:49], v[152:155], v[192:195], v[46:49]
	v_mfma_f32_16x16x32_bf16 v[30:33], v[152:155], v[200:203], v[30:33]
	v_mfma_f32_16x16x32_bf16 v[26:29], v[160:163], v[200:203], v[26:29]
	v_mfma_f32_16x16x32_bf16 v[10:13], v[160:163], v[208:211], v[10:13]
	v_mfma_f32_16x16x32_bf16 v[14:17], v[152:155], v[208:211], v[14:17]
	v_mfma_f32_16x16x32_bf16 v[62:65], v[156:159], v[188:191], v[62:65]
	v_mfma_f32_16x16x32_bf16 v[58:61], v[164:167], v[188:191], v[58:61]
	v_mfma_f32_16x16x32_bf16 v[42:45], v[164:167], v[196:199], v[42:45]
	v_mfma_f32_16x16x32_bf16 v[46:49], v[156:159], v[196:199], v[46:49]
	v_mfma_f32_16x16x32_bf16 v[30:33], v[156:159], v[204:207], v[30:33]
	v_mfma_f32_16x16x32_bf16 v[26:29], v[164:167], v[204:207], v[26:29]
	v_mfma_f32_16x16x32_bf16 v[10:13], v[164:167], v[212:215], v[10:13]
	v_mfma_f32_16x16x32_bf16 v[14:17], v[156:159], v[212:215], v[14:17]
	s_setprio 0
	s_setprio 1
	v_mfma_f32_16x16x32_bf16 v[54:57], v[168:171], v[184:187], v[54:57]
	v_mfma_f32_16x16x32_bf16 v[50:53], v[176:179], v[184:187], v[50:53]
	v_mfma_f32_16x16x32_bf16 v[34:37], v[176:179], v[192:195], v[34:37]
	v_mfma_f32_16x16x32_bf16 v[38:41], v[168:171], v[192:195], v[38:41]
	v_mfma_f32_16x16x32_bf16 v[22:25], v[168:171], v[200:203], v[22:25]
	v_mfma_f32_16x16x32_bf16 v[18:21], v[176:179], v[200:203], v[18:21]
	v_mfma_f32_16x16x32_bf16 v[2:5], v[176:179], v[208:211], v[2:5]
	v_mfma_f32_16x16x32_bf16 v[6:9], v[168:171], v[208:211], v[6:9]
	v_mfma_f32_16x16x32_bf16 v[54:57], v[172:175], v[188:191], v[54:57]
	v_mfma_f32_16x16x32_bf16 v[50:53], v[180:183], v[188:191], v[50:53]
	v_mfma_f32_16x16x32_bf16 v[34:37], v[180:183], v[196:199], v[34:37]
	v_mfma_f32_16x16x32_bf16 v[38:41], v[172:175], v[196:199], v[38:41]
	v_mfma_f32_16x16x32_bf16 v[22:25], v[172:175], v[204:207], v[22:25]
	v_mfma_f32_16x16x32_bf16 v[18:21], v[180:183], v[204:207], v[18:21]
	v_mfma_f32_16x16x32_bf16 v[2:5], v[180:183], v[212:215], v[2:5]
	v_mfma_f32_16x16x32_bf16 v[6:9], v[172:175], v[212:215], v[6:9]
	s_setprio 0
	s_barrier
	s_add_i32 s66, 0, 0x18000
	v_add_u32_e32 v151, s66, v146
	s_add_i32 s67, 0, 0x1c000
	ds_read_b128 v[152:155], v151
	ds_read_b128 v[156:159], v151 offset:1024
	ds_read_b128 v[160:163], v151 offset:2048
	ds_read_b128 v[164:167], v151 offset:3072
	v_add_u32_e32 v151, s67, v146
	ds_read_b128 v[168:171], v151
	ds_read_b128 v[172:175], v151 offset:1024
	ds_read_b128 v[176:179], v151 offset:2048
	ds_read_b128 v[180:183], v151 offset:3072
	s_add_u32 s40, s40, s4
	s_addc_u32 s41, s41, s5
	s_mov_b32 m0, s45
	v_lshl_add_u64 v[228:229], s[40:41], 0, v[130:131]
	ds_read_b128 v[184:187], v150 offset:32768
	ds_read_b128 v[188:191], v150 offset:33792
	ds_read_b128 v[192:195], v150 offset:34816
	ds_read_b128 v[196:199], v150 offset:35840
	ds_read_b128 v[200:203], v150 offset:36864
	ds_read_b128 v[204:207], v150 offset:37888
	ds_read_b128 v[208:211], v150 offset:38912
	ds_read_b128 v[212:215], v150 offset:39936
	global_load_lds_dwordx4 v[228:229], off
	v_lshl_add_u64 v[228:229], s[40:41], 0, v[134:135]
	s_mov_b32 m0, s46
	s_nop 0
	global_load_lds_dwordx4 v[228:229], off
	s_waitcnt vmcnt(8)
	s_waitcnt lgkmcnt(0)
	s_barrier
; #define PG8_STAGE(bufoff, gbase, voff) do { _Pragma("unroll") for (int _i = 0; _i < 2; ++_i) \
;         __builtin_amdgcn_global_load_lds((const unsigned*)((const char*)(gbase) + (voff)[_i]), (PG8_LAS unsigned*)(lds + (bufoff) + ldsw + _i * 8192), 16, 0, 0); } while (0)
; #define PG8_LDA(dst, b, h) do { _Pragma("unroll") for (int m = 0; m < 4; ++m) _Pragma("unroll") for (int k = 0; k < 2; ++k) dst[m][k] = *(const PG8_LAS bf16x8*)(lds + PG8_SA(b, h) + aoff + m * 2048 + k * 1024); } while (0)
; #define PG8_MMA(ai, bj, At, Bt) do { __builtin_amdgcn_s_setprio(1); _Pragma("unroll") for (int m = 0; m < 4; ++m) _Pragma("unroll") for (int n = 0; n < 2; ++n) _Pragma("unroll") for (int k = 0; k < 2; ++k) \
;         acc[ai][bj][m][n] = __builtin_amdgcn_mfma_f32_16x16x32_bf16(Bt[n][k], At[m][k], acc[ai][bj][m][n], 0, 0, 0); __builtin_amdgcn_s_setprio(0); } while (0)
; #define PG8_WAIT_V(n) asm volatile("s_waitcnt vmcnt(" #n ")" ::: "memory")
; #define PG8_WAIT_L(n) asm volatile("s_waitcnt lgkmcnt(" #n ")" ::: "memory")
; #define PG8_BAR __builtin_amdgcn_s_barrier()
; #define PG8_SCHED __builtin_amdgcn_sched_barrier(0)
; template <class Epi, class Sched, bool ALIGN_EPI = false, bool SP2 = false>
; __device__ __forceinline__ void gemm_phase(PG8_LAS unsigned char* lds, const Gemm g, const Sched& S, const Epi& E) {
;     ...
;             PG8_WAIT_V(8); PG8_WAIT_L(0); PG8_BAR; PG8_MMA(0, 0, At, B0); PG8_MMA(0, 1, At, B1); PG8_BAR; PG8_SCHED;
;             PG8_LDA(At, 1, 1); PG8_STAGE(PG8_SB(1, 0), b3, voffB); PG8_STAGE(PG8_SB(1, 1), b3 + hstepB, voffB); PG8_STAGE(PG8_SA(1, 0), a3, voffA);
;             PG8_WAIT_V(8); PG8_WAIT_L(0); PG8_BAR; PG8_MMA(1, 0, At, B0); PG8_MMA(1, 1, At, B1); PG8_BAR; PG8_SCHED;
	s_setprio 1
	s_waitcnt lgkmcnt(0)
	v_mfma_f32_16x16x32_bf16 v[122:125], v[152:155], v[184:187], v[122:125]
	v_mfma_f32_16x16x32_bf16 v[126:129], v[160:163], v[184:187], v[126:129]
	v_mfma_f32_16x16x32_bf16 v[106:109], v[160:163], v[192:195], v[106:109]
	v_mfma_f32_16x16x32_bf16 v[110:113], v[152:155], v[192:195], v[110:113]
	v_mfma_f32_16x16x32_bf16 v[94:97], v[152:155], v[200:203], v[94:97]
	v_mfma_f32_16x16x32_bf16 v[90:93], v[160:163], v[200:203], v[90:93]
	v_mfma_f32_16x16x32_bf16 v[74:77], v[160:163], v[208:211], v[74:77]
	v_mfma_f32_16x16x32_bf16 v[78:81], v[152:155], v[208:211], v[78:81]
	v_mfma_f32_16x16x32_bf16 v[122:125], v[156:159], v[188:191], v[122:125]
	v_mfma_f32_16x16x32_bf16 v[126:129], v[164:167], v[188:191], v[126:129]
	v_mfma_f32_16x16x32_bf16 v[106:109], v[164:167], v[196:199], v[106:109]
	v_mfma_f32_16x16x32_bf16 v[110:113], v[156:159], v[196:199], v[110:113]
	v_mfma_f32_16x16x32_bf16 v[94:97], v[156:159], v[204:207], v[94:97]
	v_mfma_f32_16x16x32_bf16 v[90:93], v[164:167], v[204:207], v[90:93]
	v_mfma_f32_16x16x32_bf16 v[74:77], v[164:167], v[212:215], v[74:77]
	v_mfma_f32_16x16x32_bf16 v[78:81], v[156:159], v[212:215], v[78:81]
	s_setprio 0
	s_setprio 1
	v_mfma_f32_16x16x32_bf16 v[118:121], v[168:171], v[184:187], v[118:121]
	v_mfma_f32_16x16x32_bf16 v[114:117], v[176:179], v[184:187], v[114:117]
	v_mfma_f32_16x16x32_bf16 v[98:101], v[176:179], v[192:195], v[98:101]
	v_mfma_f32_16x16x32_bf16 v[102:105], v[168:171], v[192:195], v[102:105]
	v_mfma_f32_16x16x32_bf16 v[86:89], v[168:171], v[200:203], v[86:89]
	v_mfma_f32_16x16x32_bf16 v[82:85], v[176:179], v[200:203], v[82:85]
	v_mfma_f32_16x16x32_bf16 v[66:69], v[176:179], v[208:211], v[66:69]
	v_mfma_f32_16x16x32_bf16 v[70:73], v[168:171], v[208:211], v[70:73]
	v_mfma_f32_16x16x32_bf16 v[118:121], v[172:175], v[188:191], v[118:121]
	v_mfma_f32_16x16x32_bf16 v[114:117], v[180:183], v[188:191], v[114:117]
	v_mfma_f32_16x16x32_bf16 v[98:101], v[180:183], v[196:199], v[98:101]
	v_mfma_f32_16x16x32_bf16 v[102:105], v[172:175], v[196:199], v[102:105]
	v_mfma_f32_16x16x32_bf16 v[86:89], v[172:175], v[204:207], v[86:89]
	v_mfma_f32_16x16x32_bf16 v[82:85], v[180:183], v[204:207], v[82:85]
	v_mfma_f32_16x16x32_bf16 v[66:69], v[180:183], v[212:215], v[66:69]
	v_mfma_f32_16x16x32_bf16 v[70:73], v[172:175], v[212:215], v[70:73]
	s_setprio 0
	s_barrier
	s_add_i32 s40, s66, s42
	v_lshl_add_u64 v[216:217], v[216:217], 0, s[20:21]
	s_mov_b32 m0, s40
	ds_read_b128 v[184:187], v150 offset:49152
	ds_read_b128 v[188:191], v150 offset:50176
	ds_read_b128 v[192:195], v150 offset:51200
	ds_read_b128 v[196:199], v150 offset:52224
	ds_read_b128 v[200:203], v150 offset:53248
	ds_read_b128 v[204:207], v150 offset:54272
	ds_read_b128 v[208:211], v150 offset:55296
	ds_read_b128 v[212:215], v150 offset:56320
	global_load_lds_dwordx4 v[216:217], off
	v_lshl_add_u64 v[216:217], v[218:219], 0, s[20:21]
	s_add_i32 m0, s40, 0x2000
	s_add_i32 s40, s67, s42
	global_load_lds_dwordx4 v[216:217], off
	v_lshl_add_u64 v[216:217], v[220:221], 0, s[20:21]
	s_mov_b32 m0, s40
	s_nop 0
	global_load_lds_dwordx4 v[216:217], off
	v_lshl_add_u64 v[216:217], v[222:223], 0, s[20:21]
	s_add_i32 m0, s40, 0x2000
	s_nop 0
	global_load_lds_dwordx4 v[216:217], off
	v_lshl_add_u64 v[216:217], v[224:225], 0, s[20:21]
	s_mov_b32 m0, s48
	s_nop 0
	global_load_lds_dwordx4 v[216:217], off
	v_lshl_add_u64 v[216:217], v[226:227], 0, s[20:21]
	s_mov_b32 m0, s49
	s_nop 0
	global_load_lds_dwordx4 v[216:217], off
	s_waitcnt vmcnt(8)
	s_waitcnt lgkmcnt(0)
	s_barrier
	s_setprio 1
	s_waitcnt lgkmcnt(0)
	v_mfma_f32_16x16x32_bf16 v[62:65], v[152:155], v[184:187], v[62:65]
	v_mfma_f32_16x16x32_bf16 v[58:61], v[160:163], v[184:187], v[58:61]
	v_mfma_f32_16x16x32_bf16 v[42:45], v[160:163], v[192:195], v[42:45]
	v_mfma_f32_16x16x32_bf16 v[46:49], v[152:155], v[192:195], v[46:49]
	v_mfma_f32_16x16x32_bf16 v[30:33], v[152:155], v[200:203], v[30:33]
	v_mfma_f32_16x16x32_bf16 v[26:29], v[160:163], v[200:203], v[26:29]
	v_mfma_f32_16x16x32_bf16 v[10:13], v[160:163], v[208:211], v[10:13]
	v_mfma_f32_16x16x32_bf16 v[14:17], v[152:155], v[208:211], v[14:17]
	v_mfma_f32_16x16x32_bf16 v[62:65], v[156:159], v[188:191], v[62:65]
	v_mfma_f32_16x16x32_bf16 v[58:61], v[164:167], v[188:191], v[58:61]
	v_mfma_f32_16x16x32_bf16 v[42:45], v[164:167], v[196:199], v[42:45]
	v_mfma_f32_16x16x32_bf16 v[46:49], v[156:159], v[196:199], v[46:49]
	v_mfma_f32_16x16x32_bf16 v[30:33], v[156:159], v[204:207], v[30:33]
	v_mfma_f32_16x16x32_bf16 v[26:29], v[164:167], v[204:207], v[26:29]
	v_mfma_f32_16x16x32_bf16 v[10:13], v[164:167], v[212:215], v[10:13]
	v_mfma_f32_16x16x32_bf16 v[14:17], v[156:159], v[212:215], v[14:17]
	s_setprio 0
	s_setprio 1
	v_mfma_f32_16x16x32_bf16 v[54:57], v[168:171], v[184:187], v[54:57]
	v_mfma_f32_16x16x32_bf16 v[50:53], v[176:179], v[184:187], v[50:53]
	v_mfma_f32_16x16x32_bf16 v[34:37], v[176:179], v[192:195], v[34:37]
	v_mfma_f32_16x16x32_bf16 v[38:41], v[168:171], v[192:195], v[38:41]
	v_mfma_f32_16x16x32_bf16 v[22:25], v[168:171], v[200:203], v[22:25]
	v_mfma_f32_16x16x32_bf16 v[18:21], v[176:179], v[200:203], v[18:21]
	v_mfma_f32_16x16x32_bf16 v[2:5], v[176:179], v[208:211], v[2:5]
	v_mfma_f32_16x16x32_bf16 v[6:9], v[168:171], v[208:211], v[6:9]
	v_mfma_f32_16x16x32_bf16 v[54:57], v[172:175], v[188:191], v[54:57]
	v_mfma_f32_16x16x32_bf16 v[50:53], v[180:183], v[188:191], v[50:53]
	v_mfma_f32_16x16x32_bf16 v[34:37], v[180:183], v[196:199], v[34:37]
	v_mfma_f32_16x16x32_bf16 v[38:41], v[172:175], v[196:199], v[38:41]
	v_mfma_f32_16x16x32_bf16 v[22:25], v[172:175], v[204:207], v[22:25]
	v_mfma_f32_16x16x32_bf16 v[18:21], v[180:183], v[204:207], v[18:21]
	v_mfma_f32_16x16x32_bf16 v[2:5], v[180:183], v[212:215], v[2:5]
	v_mfma_f32_16x16x32_bf16 v[6:9], v[172:175], v[212:215], v[6:9]
	s_setprio 0
	s_barrier
	s_add_u32 s38, s38, 0x100
	s_addc_u32 s39, s39, 0
	s_add_u32 s63, s63, 0x100
	s_addc_u32 s64, s64, 0
	s_cmp_ge_i32 s65, s50
	s_mov_b32 s40, s65
	s_cbranch_scc0 .LBB0_821

; #define PG8_STAGE(bufoff, gbase, voff) do { _Pragma("unroll") for (int _i = 0; _i < 2; ++_i) \
;         __builtin_amdgcn_global_load_lds((const unsigned*)((const char*)(gbase) + (voff)[_i]), (PG8_LAS unsigned*)(lds + (bufoff) + ldsw + _i * 8192), 16, 0, 0); } while (0)
; #define PG8_LDA(dst, b, h) do { _Pragma("unroll") for (int m = 0; m < 4; ++m) _Pragma("unroll") for (int k = 0; k < 2; ++k) dst[m][k] = *(const PG8_LAS bf16x8*)(lds + PG8_SA(b, h) + aoff + m * 2048 + k * 1024); } while (0)
; #define PG8_LDB(dst, b, h) do { _Pragma("unroll") for (int n = 0; n < 2; ++n) _Pragma("unroll") for (int k = 0; k < 2; ++k) dst[n][k] = *(const PG8_LAS bf16x8*)(lds + PG8_SB(b, h) + boff + n * 2048 + k * 1024); } while (0)
; #define PG8_WAIT_V(n) asm volatile("s_waitcnt vmcnt(" #n ")" ::: "memory")
; #define PG8_WAIT_L(n) asm volatile("s_waitcnt lgkmcnt(" #n ")" ::: "memory")
; #define PG8_BAR __builtin_amdgcn_s_barrier()
; #define PG8_SCHED __builtin_amdgcn_sched_barrier(0)
; template <class Epi, class Sched, bool ALIGN_EPI = false, bool SP2 = false>
; __device__ __forceinline__ void gemm_phase(PG8_LAS unsigned char* lds, const Gemm g, const Sched& S, const Epi& E) {
;     ...
;         const char* nA = has_next ? (const char*)g.A + (size_t)nxt.g * g.gsA * 2 + (size_t)nxt.pm * tstepA : cA; const char* nB = has_next ? (const char*)g.Bt + (size_t)nxt.g * g.gsB * 2 + (size_t)nxt.pn * tstepB : cB;
;         for (int t = 0; t < nt; t += 2) {
;             const bool last = (t == nt - 2);
;             const char* a1 = cA + (size_t)(t + 1) * kstep;
;             const char* a2 = last ? nA : cA + (size_t)(t + 2) * kstep; const char* b2 = last ? nB : cB + (size_t)(t + 2) * kstep;
;             const char* a3 = a2 + kstep; const char* b3 = b2 + kstep;
;             if (last && has_next) S.a_ready(nxt);
;             if constexpr (SP2) {
;             PG8_LDB(B0, 0, 0); PG8_LDB(B1, 0, 1); PG8_SCHED; PG8_LDA(At, 0, 0); PG8_STAGE(PG8_SA(1, 1), a1 + hstepA, voffA);
;             PG8_WAIT_V(8); PG8_WAIT_L(0); PG8_BAR; PG8_MMA(0, 0, At, B0); PG8_MMA(0, 1, At, B1); PG8_BAR; PG8_SCHED;
;             PG8_LDA(At, 0, 1); PG8_STAGE(PG8_SB(0, 0), b2, voffB); PG8_STAGE(PG8_SB(0, 1), b2 + hstepB, voffB); PG8_STAGE(PG8_SA(0, 0), a2, voffA);
;             PG8_WAIT_V(8); PG8_WAIT_L(0); PG8_BAR; PG8_MMA(1, 0, At, B0); PG8_MMA(1, 1, At, B1); PG8_BAR; PG8_SCHED;
.LBB0_902:
	s_ashr_i32 s29, s28, 31
	s_lshl_b64 s[0:1], s[28:29], 19
	s_add_u32 s30, s10, s0
	s_addc_u32 s31, s11, s1
	s_and_b64 s[0:1], s[8:9], exec
	s_cselect_b32 s0, s31, s37
	s_cselect_b32 s1, s30, s36
	s_ashr_i32 s27, s26, 31
	s_lshl_b64 s[34:35], s[26:27], 19
	s_add_u32 s34, s3, s34
	s_addc_u32 s35, s42, s35
	s_and_b64 s[40:41], s[8:9], exec
	s_cselect_b32 s2, s35, s39
	s_cselect_b32 s5, s34, s38
	s_add_u32 s36, s36, 0x40080
	s_addc_u32 s37, s37, 0
	s_add_u32 s27, s38, 0x100
	s_addc_u32 s29, s39, 0
	s_mov_b32 s33, -2
	s_waitcnt lgkmcnt(0)
	ds_read_b128 v[130:133], v186
	ds_read_b128 v[134:137], v186 offset:1024
	ds_read_b128 v[138:141], v186 offset:2048
	ds_read_b128 v[142:145], v186 offset:3072
	ds_read_b128 v[164:167], v187
	ds_read_b128 v[168:171], v187 offset:1024
	ds_read_b128 v[172:175], v187 offset:2048
	ds_read_b128 v[176:179], v187 offset:3072
	s_add_u32 s38, s36, 0xfffc0080
	s_addc_u32 s39, s37, -1
	s_cmp_eq_u32 s33, 12
	s_cselect_b32 s41, s0, s39
	s_cselect_b32 s40, s1, s38
	s_cselect_b32 s39, s2, s29
	s_cselect_b32 s38, s5, s27
	v_lshl_add_u64 v[220:221], s[36:37], 0, v[156:157]
	s_add_i32 m0, s44, 0xc000
	ds_read_b128 v[180:183], v188
	ds_read_b128 v[192:195], v188 offset:1024
	ds_read_b128 v[196:199], v188 offset:2048
	ds_read_b128 v[200:203], v188 offset:3072
	ds_read_b128 v[204:207], v188 offset:4096
	ds_read_b128 v[208:211], v188 offset:5120
	ds_read_b128 v[212:215], v188 offset:6144
	ds_read_b128 v[216:219], v188 offset:7168
	global_load_lds_dwordx4 v[220:221], off
	v_lshl_add_u64 v[220:221], s[36:37], 0, v[158:159]
	s_add_i32 m0, s44, 0xe000
	s_nop 0
	global_load_lds_dwordx4 v[220:221], off
	s_waitcnt vmcnt(8)
	s_waitcnt lgkmcnt(0)
	s_barrier
	s_setprio 1
	s_waitcnt lgkmcnt(0)
	v_mfma_f32_16x16x32_bf16 v[126:129], v[130:133], v[180:183], 0
	v_mfma_f32_16x16x32_bf16 v[122:125], v[138:141], v[180:183], 0
	v_mfma_f32_16x16x32_bf16 v[106:109], v[138:141], v[196:199], 0
	v_mfma_f32_16x16x32_bf16 v[110:113], v[130:133], v[196:199], 0
	v_mfma_f32_16x16x32_bf16 v[94:97], v[130:133], v[204:207], 0
	v_mfma_f32_16x16x32_bf16 v[90:93], v[138:141], v[204:207], 0
	v_mfma_f32_16x16x32_bf16 v[74:77], v[138:141], v[212:215], 0
	v_mfma_f32_16x16x32_bf16 v[78:81], v[130:133], v[212:215], 0
	v_mfma_f32_16x16x32_bf16 v[126:129], v[134:137], v[192:195], v[126:129]
	v_mfma_f32_16x16x32_bf16 v[122:125], v[142:145], v[192:195], v[122:125]
	v_mfma_f32_16x16x32_bf16 v[106:109], v[142:145], v[200:203], v[106:109]
	v_mfma_f32_16x16x32_bf16 v[110:113], v[134:137], v[200:203], v[110:113]
	v_mfma_f32_16x16x32_bf16 v[94:97], v[134:137], v[208:211], v[94:97]
	v_mfma_f32_16x16x32_bf16 v[90:93], v[142:145], v[208:211], v[90:93]
	v_mfma_f32_16x16x32_bf16 v[74:77], v[142:145], v[216:219], v[74:77]
	v_mfma_f32_16x16x32_bf16 v[78:81], v[134:137], v[216:219], v[78:81]
	s_setprio 0
	s_setprio 1
	v_mfma_f32_16x16x32_bf16 v[118:121], v[164:167], v[180:183], 0
	v_mfma_f32_16x16x32_bf16 v[114:117], v[172:175], v[180:183], 0
	v_mfma_f32_16x16x32_bf16 v[98:101], v[172:175], v[196:199], 0
	v_mfma_f32_16x16x32_bf16 v[102:105], v[164:167], v[196:199], 0
	v_mfma_f32_16x16x32_bf16 v[86:89], v[164:167], v[204:207], 0
	v_mfma_f32_16x16x32_bf16 v[82:85], v[172:175], v[204:207], 0
	v_mfma_f32_16x16x32_bf16 v[66:69], v[172:175], v[212:215], 0
	v_mfma_f32_16x16x32_bf16 v[70:73], v[164:167], v[212:215], 0
	v_mfma_f32_16x16x32_bf16 v[118:121], v[168:171], v[192:195], v[118:121]
	v_mfma_f32_16x16x32_bf16 v[114:117], v[176:179], v[192:195], v[114:117]
	v_mfma_f32_16x16x32_bf16 v[98:101], v[176:179], v[200:203], v[98:101]
	v_mfma_f32_16x16x32_bf16 v[102:105], v[168:171], v[200:203], v[102:105]
	v_mfma_f32_16x16x32_bf16 v[86:89], v[168:171], v[208:211], v[86:89]
	v_mfma_f32_16x16x32_bf16 v[82:85], v[176:179], v[208:211], v[82:85]
	v_mfma_f32_16x16x32_bf16 v[66:69], v[176:179], v[216:219], v[66:69]
	v_mfma_f32_16x16x32_bf16 v[70:73], v[168:171], v[216:219], v[70:73]
	s_setprio 0
	s_barrier
	s_add_i32 s58, s55, s43
	v_lshl_add_u64 v[220:221], s[38:39], 0, v[148:149]
	s_mov_b32 m0, s58
	ds_read_b128 v[180:183], v188 offset:16384
	ds_read_b128 v[192:195], v188 offset:17408
	ds_read_b128 v[196:199], v188 offset:18432
	ds_read_b128 v[200:203], v188 offset:19456
	ds_read_b128 v[204:207], v188 offset:20480
	ds_read_b128 v[208:211], v188 offset:21504
	ds_read_b128 v[212:215], v188 offset:22528
	ds_read_b128 v[216:219], v188 offset:23552
	global_load_lds_dwordx4 v[220:221], off
	s_add_i32 m0, s58, 0x2000
	s_add_u32 s58, s38, 0x40000
	v_lshl_add_u64 v[222:223], s[38:39], 0, v[152:153]
	s_addc_u32 s59, s39, 0
	s_add_i32 s60, s56, s43
	global_load_lds_dwordx4 v[222:223], off
	v_lshl_add_u64 v[224:225], s[58:59], 0, v[148:149]
	s_mov_b32 m0, s60
	v_lshl_add_u64 v[226:227], s[40:41], 0, v[150:151]
	global_load_lds_dwordx4 v[224:225], off
	v_lshl_add_u64 v[224:225], s[58:59], 0, v[152:153]
	s_add_i32 m0, s60, 0x2000
	s_nop 0
	global_load_lds_dwordx4 v[224:225], off
	v_lshl_add_u64 v[224:225], s[40:41], 0, v[146:147]
	s_mov_b32 m0, s44
	s_nop 0
	global_load_lds_dwordx4 v[224:225], off
	s_mov_b32 m0, s45
	s_nop 0
	global_load_lds_dwordx4 v[226:227], off
	s_waitcnt vmcnt(8)
	s_waitcnt lgkmcnt(0)
	s_barrier
; #define PG8_STAGE(bufoff, gbase, voff) do { _Pragma("unroll") for (int _i = 0; _i < 2; ++_i) \
;         __builtin_amdgcn_global_load_lds((const unsigned*)((const char*)(gbase) + (voff)[_i]), (PG8_LAS unsigned*)(lds + (bufoff) + ldsw + _i * 8192), 16, 0, 0); } while (0)
; #define PG8_LDA(dst, b, h) do { _Pragma("unroll") for (int m = 0; m < 4; ++m) _Pragma("unroll") for (int k = 0; k < 2; ++k) dst[m][k] = *(const PG8_LAS bf16x8*)(lds + PG8_SA(b, h) + aoff + m * 2048 + k * 1024); } while (0)
; #define PG8_LDB(dst, b, h) do { _Pragma("unroll") for (int n = 0; n < 2; ++n) _Pragma("unroll") for (int k = 0; k < 2; ++k) dst[n][k] = *(const PG8_LAS bf16x8*)(lds + PG8_SB(b, h) + boff + n * 2048 + k * 1024); } while (0)
; #define PG8_MMA(ai, bj, At, Bt) do { __builtin_amdgcn_s_setprio(1); _Pragma("unroll") for (int m = 0; m < 4; ++m) _Pragma("unroll") for (int n = 0; n < 2; ++n) _Pragma("unroll") for (int k = 0; k < 2; ++k) \
;         acc[ai][bj][m][n] = __builtin_amdgcn_mfma_f32_16x16x32_bf16(Bt[n][k], At[m][k], acc[ai][bj][m][n], 0, 0, 0); __builtin_amdgcn_s_setprio(0); } while (0)
; #define PG8_WAIT_V(n) asm volatile("s_waitcnt vmcnt(" #n ")" ::: "memory")
; #define PG8_WAIT_L(n) asm volatile("s_waitcnt lgkmcnt(" #n ")" ::: "memory")
; #define PG8_BAR __builtin_amdgcn_s_barrier()
; #define PG8_SCHED __builtin_amdgcn_sched_barrier(0)
; template <class Epi, class Sched, bool ALIGN_EPI = false, bool SP2 = false>
; __device__ __forceinline__ void gemm_phase(PG8_LAS unsigned char* lds, const Gemm g, const Sched& S, const Epi& E) {
;     ...
;             PG8_WAIT_V(8); PG8_WAIT_L(0); PG8_BAR; PG8_MMA(1, 0, At, B0); PG8_MMA(1, 1, At, B1); PG8_BAR; PG8_SCHED;
;             PG8_LDB(B0, 1, 0); PG8_LDB(B1, 1, 1); PG8_SCHED; PG8_LDA(At, 1, 0); PG8_STAGE(PG8_SA(0, 1), a2 + hstepA, voffA);
;             PG8_WAIT_V(8); PG8_WAIT_L(0); PG8_BAR; PG8_MMA(0, 0, At, B0); PG8_MMA(0, 1, At, B1); PG8_BAR; PG8_SCHED;
	s_setprio 1
	s_waitcnt lgkmcnt(0)
	v_mfma_f32_16x16x32_bf16 v[62:65], v[130:133], v[180:183], 0
	v_mfma_f32_16x16x32_bf16 v[58:61], v[138:141], v[180:183], 0
	v_mfma_f32_16x16x32_bf16 v[42:45], v[138:141], v[196:199], 0
	v_mfma_f32_16x16x32_bf16 v[46:49], v[130:133], v[196:199], 0
	v_mfma_f32_16x16x32_bf16 v[30:33], v[130:133], v[204:207], 0
	v_mfma_f32_16x16x32_bf16 v[26:29], v[138:141], v[204:207], 0
	v_mfma_f32_16x16x32_bf16 v[10:13], v[138:141], v[212:215], 0
	v_mfma_f32_16x16x32_bf16 v[14:17], v[130:133], v[212:215], 0
	v_mfma_f32_16x16x32_bf16 v[62:65], v[134:137], v[192:195], v[62:65]
	v_mfma_f32_16x16x32_bf16 v[58:61], v[142:145], v[192:195], v[58:61]
	v_mfma_f32_16x16x32_bf16 v[42:45], v[142:145], v[200:203], v[42:45]
	v_mfma_f32_16x16x32_bf16 v[46:49], v[134:137], v[200:203], v[46:49]
	v_mfma_f32_16x16x32_bf16 v[30:33], v[134:137], v[208:211], v[30:33]
	v_mfma_f32_16x16x32_bf16 v[26:29], v[142:145], v[208:211], v[26:29]
	v_mfma_f32_16x16x32_bf16 v[10:13], v[142:145], v[216:219], v[10:13]
	v_mfma_f32_16x16x32_bf16 v[14:17], v[134:137], v[216:219], v[14:17]
	s_setprio 0
	s_setprio 1
	v_mfma_f32_16x16x32_bf16 v[54:57], v[164:167], v[180:183], 0
	v_mfma_f32_16x16x32_bf16 v[50:53], v[172:175], v[180:183], 0
	v_mfma_f32_16x16x32_bf16 v[34:37], v[172:175], v[196:199], 0
	v_mfma_f32_16x16x32_bf16 v[38:41], v[164:167], v[196:199], 0
	v_mfma_f32_16x16x32_bf16 v[22:25], v[164:167], v[204:207], 0
	v_mfma_f32_16x16x32_bf16 v[18:21], v[172:175], v[204:207], 0
	v_mfma_f32_16x16x32_bf16 v[2:5], v[172:175], v[212:215], 0
	v_mfma_f32_16x16x32_bf16 v[6:9], v[164:167], v[212:215], 0
	v_mfma_f32_16x16x32_bf16 v[54:57], v[168:171], v[192:195], v[54:57]
	v_mfma_f32_16x16x32_bf16 v[50:53], v[176:179], v[192:195], v[50:53]
	v_mfma_f32_16x16x32_bf16 v[34:37], v[176:179], v[200:203], v[34:37]
	v_mfma_f32_16x16x32_bf16 v[38:41], v[168:171], v[200:203], v[38:41]
	v_mfma_f32_16x16x32_bf16 v[22:25], v[168:171], v[208:211], v[22:25]
	v_mfma_f32_16x16x32_bf16 v[18:21], v[176:179], v[208:211], v[18:21]
	v_mfma_f32_16x16x32_bf16 v[2:5], v[176:179], v[216:219], v[2:5]
	v_mfma_f32_16x16x32_bf16 v[6:9], v[168:171], v[216:219], v[6:9]
	s_setprio 0
	s_barrier
	s_add_i32 s58, 0, 0x18000
	s_add_i32 s59, 0, 0x1c000
	v_add_u32_e32 v142, s58, v184
	v_add_u32_e32 v176, s59, v184
	ds_read_b128 v[130:133], v142
	ds_read_b128 v[134:137], v142 offset:1024
	ds_read_b128 v[138:141], v142 offset:2048
	ds_read_b128 v[142:145], v142 offset:3072
	ds_read_b128 v[164:167], v176
	ds_read_b128 v[168:171], v176 offset:1024
	ds_read_b128 v[172:175], v176 offset:2048
	ds_read_b128 v[176:179], v176 offset:3072
	s_add_u32 s40, s40, 0x40000
	s_addc_u32 s41, s41, 0
	s_mov_b32 m0, s46
	v_lshl_add_u64 v[228:229], s[40:41], 0, v[146:147]
	ds_read_b128 v[180:183], v188 offset:32768
	ds_read_b128 v[192:195], v188 offset:33792
	ds_read_b128 v[196:199], v188 offset:34816
	ds_read_b128 v[200:203], v188 offset:35840
	ds_read_b128 v[204:207], v188 offset:36864
	ds_read_b128 v[208:211], v188 offset:37888
	ds_read_b128 v[212:215], v188 offset:38912
	ds_read_b128 v[216:219], v188 offset:39936
	global_load_lds_dwordx4 v[228:229], off
	v_lshl_add_u64 v[228:229], s[40:41], 0, v[150:151]
	s_mov_b32 m0, s47
	s_nop 0
	global_load_lds_dwordx4 v[228:229], off
	s_waitcnt vmcnt(8)
	s_waitcnt lgkmcnt(0)
	s_barrier
	s_setprio 1
	s_waitcnt lgkmcnt(0)
	v_mfma_f32_16x16x32_bf16 v[126:129], v[130:133], v[180:183], v[126:129]
	v_mfma_f32_16x16x32_bf16 v[122:125], v[138:141], v[180:183], v[122:125]
	v_mfma_f32_16x16x32_bf16 v[106:109], v[138:141], v[196:199], v[106:109]
	v_mfma_f32_16x16x32_bf16 v[110:113], v[130:133], v[196:199], v[110:113]
	v_mfma_f32_16x16x32_bf16 v[94:97], v[130:133], v[204:207], v[94:97]
	v_mfma_f32_16x16x32_bf16 v[90:93], v[138:141], v[204:207], v[90:93]
	v_mfma_f32_16x16x32_bf16 v[74:77], v[138:141], v[212:215], v[74:77]
	v_mfma_f32_16x16x32_bf16 v[78:81], v[130:133], v[212:215], v[78:81]
	v_mfma_f32_16x16x32_bf16 v[126:129], v[134:137], v[192:195], v[126:129]
	v_mfma_f32_16x16x32_bf16 v[122:125], v[142:145], v[192:195], v[122:125]
	v_mfma_f32_16x16x32_bf16 v[106:109], v[142:145], v[200:203], v[106:109]
	v_mfma_f32_16x16x32_bf16 v[110:113], v[134:137], v[200:203], v[110:113]
	v_mfma_f32_16x16x32_bf16 v[94:97], v[134:137], v[208:211], v[94:97]
	v_mfma_f32_16x16x32_bf16 v[90:93], v[142:145], v[208:211], v[90:93]
	v_mfma_f32_16x16x32_bf16 v[74:77], v[142:145], v[216:219], v[74:77]
	v_mfma_f32_16x16x32_bf16 v[78:81], v[134:137], v[216:219], v[78:81]
	s_setprio 0
	s_setprio 1
	v_mfma_f32_16x16x32_bf16 v[118:121], v[164:167], v[180:183], v[118:121]
	v_mfma_f32_16x16x32_bf16 v[114:117], v[172:175], v[180:183], v[114:117]
	v_mfma_f32_16x16x32_bf16 v[98:101], v[172:175], v[196:199], v[98:101]
	v_mfma_f32_16x16x32_bf16 v[102:105], v[164:167], v[196:199], v[102:105]
	v_mfma_f32_16x16x32_bf16 v[86:89], v[164:167], v[204:207], v[86:89]
	v_mfma_f32_16x16x32_bf16 v[82:85], v[172:175], v[204:207], v[82:85]
	v_mfma_f32_16x16x32_bf16 v[66:69], v[172:175], v[212:215], v[66:69]
	v_mfma_f32_16x16x32_bf16 v[70:73], v[164:167], v[212:215], v[70:73]
	v_mfma_f32_16x16x32_bf16 v[118:121], v[168:171], v[192:195], v[118:121]
	v_mfma_f32_16x16x32_bf16 v[114:117], v[176:179], v[192:195], v[114:117]
	v_mfma_f32_16x16x32_bf16 v[98:101], v[176:179], v[200:203], v[98:101]
	v_mfma_f32_16x16x32_bf16 v[102:105], v[168:171], v[200:203], v[102:105]
	v_mfma_f32_16x16x32_bf16 v[86:89], v[168:171], v[208:211], v[86:89]
	v_mfma_f32_16x16x32_bf16 v[82:85], v[176:179], v[208:211], v[82:85]
	v_mfma_f32_16x16x32_bf16 v[66:69], v[176:179], v[216:219], v[66:69]
	v_mfma_f32_16x16x32_bf16 v[70:73], v[168:171], v[216:219], v[70:73]
	s_setprio 0
	s_barrier
; #define PG8_STAGE(bufoff, gbase, voff) do { _Pragma("unroll") for (int _i = 0; _i < 2; ++_i) \
;         __builtin_amdgcn_global_load_lds((const unsigned*)((const char*)(gbase) + (voff)[_i]), (PG8_LAS unsigned*)(lds + (bufoff) + ldsw + _i * 8192), 16, 0, 0); } while (0)
; #define PG8_LDA(dst, b, h) do { _Pragma("unroll") for (int m = 0; m < 4; ++m) _Pragma("unroll") for (int k = 0; k < 2; ++k) dst[m][k] = *(const PG8_LAS bf16x8*)(lds + PG8_SA(b, h) + aoff + m * 2048 + k * 1024); } while (0)
; #define PG8_LDB(dst, b, h) do { _Pragma("unroll") for (int n = 0; n < 2; ++n) _Pragma("unroll") for (int k = 0; k < 2; ++k) dst[n][k] = *(const PG8_LAS bf16x8*)(lds + PG8_SB(b, h) + boff + n * 2048 + k * 1024); } while (0)
; #define PG8_BAR __builtin_amdgcn_s_barrier()
; template <class Epi, class Sched, bool ALIGN_EPI = false, bool SP2 = false>
; __device__ __forceinline__ void gemm_phase(PG8_LAS unsigned char* lds, const Gemm g, const Sched& S, const Epi& E) {
;     ...
;             const bool last = (t == nt - 2);
;             const char* a1 = cA + (size_t)(t + 1) * kstep;
;             const char* a2 = last ? nA : cA + (size_t)(t + 2) * kstep; const char* b2 = last ? nB : cB + (size_t)(t + 2) * kstep;
;             const char* a3 = a2 + kstep; const char* b3 = b2 + kstep;
;             if (last && has_next) S.a_ready(nxt);
;             if constexpr (SP2) {
;             PG8_LDB(B0, 0, 0); PG8_LDB(B1, 0, 1); PG8_SCHED; PG8_LDA(At, 0, 0); PG8_STAGE(PG8_SA(1, 1), a1 + hstepA, voffA);
;             PG8_WAIT_V(8); PG8_WAIT_L(0); PG8_BAR; PG8_MMA(0, 0, At, B0); PG8_MMA(0, 1, At, B1); PG8_BAR; PG8_SCHED;
;             PG8_LDA(At, 0, 1); PG8_STAGE(PG8_SB(0, 0), b2, voffB); PG8_STAGE(PG8_SB(0, 1), b2 + hstepB, voffB); PG8_STAGE(PG8_SA(0, 0), a2, voffA);
;             PG8_WAIT_V(8); PG8_WAIT_L(0); PG8_BAR; PG8_MMA(1, 0, At, B0); PG8_MMA(1, 1, At, B1); PG8_BAR; PG8_SCHED;
;             PG8_LDB(B0, 1, 0); PG8_LDB(B1, 1, 1); PG8_SCHED; PG8_LDA(At, 1, 0); PG8_STAGE(PG8_SA(0, 1), a2 + hstepA, voffA);
;             PG8_WAIT_V(8); PG8_WAIT_L(0); PG8_BAR; PG8_MMA(0, 0, At, B0); PG8_MMA(0, 1, At, B1); PG8_BAR; PG8_SCHED;
;             PG8_LDA(At, 1, 1); PG8_STAGE(PG8_SB(1, 0), b3, voffB); PG8_STAGE(PG8_SB(1, 1), b3 + hstepB, voffB); PG8_STAGE(PG8_SA(1, 0), a3, voffA);
;             PG8_WAIT_V(8); PG8_WAIT_L(0); PG8_BAR; PG8_MMA(1, 0, At, B0); PG8_MMA(1, 1, At, B1); PG8_BAR; PG8_SCHED;
	s_add_i32 s40, s58, s43
	v_lshl_add_u64 v[220:221], v[220:221], 0, s[22:23]
	s_mov_b32 m0, s40
	ds_read_b128 v[180:183], v188 offset:49152
	ds_read_b128 v[192:195], v188 offset:50176
	ds_read_b128 v[196:199], v188 offset:51200
	ds_read_b128 v[200:203], v188 offset:52224
	ds_read_b128 v[204:207], v188 offset:53248
	ds_read_b128 v[208:211], v188 offset:54272
	ds_read_b128 v[212:215], v188 offset:55296
	ds_read_b128 v[216:219], v188 offset:56320
	global_load_lds_dwordx4 v[220:221], off
	s_add_i32 m0, s40, 0x2000
	s_add_u32 s38, s38, 0x40080
	v_lshl_add_u64 v[220:221], v[222:223], 0, s[22:23]
	s_addc_u32 s39, s39, 0
	s_add_i32 s40, s59, s43
	global_load_lds_dwordx4 v[220:221], off
	v_lshl_add_u64 v[220:221], s[38:39], 0, v[148:149]
	s_mov_b32 m0, s40
	s_nop 0
	global_load_lds_dwordx4 v[220:221], off
	v_lshl_add_u64 v[220:221], s[38:39], 0, v[152:153]
	s_add_i32 m0, s40, 0x2000
	s_nop 0
	global_load_lds_dwordx4 v[220:221], off
	v_lshl_add_u64 v[220:221], v[224:225], 0, s[22:23]
	s_mov_b32 m0, s50
	s_nop 0
	global_load_lds_dwordx4 v[220:221], off
	v_lshl_add_u64 v[220:221], v[226:227], 0, s[22:23]
	s_mov_b32 m0, s51
	s_nop 0
	global_load_lds_dwordx4 v[220:221], off
	s_waitcnt vmcnt(8)
	s_waitcnt lgkmcnt(0)
	s_barrier
	s_setprio 1
	s_waitcnt lgkmcnt(0)
	v_mfma_f32_16x16x32_bf16 v[62:65], v[130:133], v[180:183], v[62:65]
	v_mfma_f32_16x16x32_bf16 v[58:61], v[138:141], v[180:183], v[58:61]
	v_mfma_f32_16x16x32_bf16 v[42:45], v[138:141], v[196:199], v[42:45]
	v_mfma_f32_16x16x32_bf16 v[46:49], v[130:133], v[196:199], v[46:49]
	v_mfma_f32_16x16x32_bf16 v[30:33], v[130:133], v[204:207], v[30:33]
	v_mfma_f32_16x16x32_bf16 v[26:29], v[138:141], v[204:207], v[26:29]
	v_mfma_f32_16x16x32_bf16 v[10:13], v[138:141], v[212:215], v[10:13]
	v_mfma_f32_16x16x32_bf16 v[14:17], v[130:133], v[212:215], v[14:17]
	v_mfma_f32_16x16x32_bf16 v[62:65], v[134:137], v[192:195], v[62:65]
	v_mfma_f32_16x16x32_bf16 v[58:61], v[142:145], v[192:195], v[58:61]
	v_mfma_f32_16x16x32_bf16 v[42:45], v[142:145], v[200:203], v[42:45]
	v_mfma_f32_16x16x32_bf16 v[46:49], v[134:137], v[200:203], v[46:49]
	v_mfma_f32_16x16x32_bf16 v[30:33], v[134:137], v[208:211], v[30:33]
	v_mfma_f32_16x16x32_bf16 v[26:29], v[142:145], v[208:211], v[26:29]
	v_mfma_f32_16x16x32_bf16 v[10:13], v[142:145], v[216:219], v[10:13]
	v_mfma_f32_16x16x32_bf16 v[14:17], v[134:137], v[216:219], v[14:17]
	s_setprio 0
	s_setprio 1
	v_mfma_f32_16x16x32_bf16 v[54:57], v[164:167], v[180:183], v[54:57]
	v_mfma_f32_16x16x32_bf16 v[50:53], v[172:175], v[180:183], v[50:53]
	v_mfma_f32_16x16x32_bf16 v[34:37], v[172:175], v[196:199], v[34:37]
	v_mfma_f32_16x16x32_bf16 v[38:41], v[164:167], v[196:199], v[38:41]
	v_mfma_f32_16x16x32_bf16 v[22:25], v[164:167], v[204:207], v[22:25]
	v_mfma_f32_16x16x32_bf16 v[18:21], v[172:175], v[204:207], v[18:21]
	v_mfma_f32_16x16x32_bf16 v[2:5], v[172:175], v[212:215], v[2:5]
	v_mfma_f32_16x16x32_bf16 v[6:9], v[164:167], v[212:215], v[6:9]
	v_mfma_f32_16x16x32_bf16 v[54:57], v[168:171], v[192:195], v[54:57]
	v_mfma_f32_16x16x32_bf16 v[50:53], v[176:179], v[192:195], v[50:53]
	v_mfma_f32_16x16x32_bf16 v[34:37], v[176:179], v[200:203], v[34:37]
	v_mfma_f32_16x16x32_bf16 v[38:41], v[168:171], v[200:203], v[38:41]
	v_mfma_f32_16x16x32_bf16 v[22:25], v[168:171], v[208:211], v[22:25]
	v_mfma_f32_16x16x32_bf16 v[18:21], v[176:179], v[208:211], v[18:21]
	v_mfma_f32_16x16x32_bf16 v[2:5], v[176:179], v[216:219], v[2:5]
	v_mfma_f32_16x16x32_bf16 v[6:9], v[168:171], v[216:219], v[6:9]
	s_setprio 0
	s_barrier
	s_add_i32 s33, s33, 2
	s_add_u32 s36, s36, 0x100
	s_addc_u32 s37, s37, 0
	s_add_u32 s27, s27, 0x100
	s_addc_u32 s29, s29, 0
	s_cmp_gt_u32 s33, 13
.LBB0_903:
	ds_read_b128 v[130:133], v186
	ds_read_b128 v[134:137], v186 offset:1024
	ds_read_b128 v[138:141], v186 offset:2048
	ds_read_b128 v[142:145], v186 offset:3072
	ds_read_b128 v[164:167], v187
	ds_read_b128 v[168:171], v187 offset:1024
	ds_read_b128 v[172:175], v187 offset:2048
	ds_read_b128 v[176:179], v187 offset:3072
	s_add_u32 s38, s36, 0xfffc0080
	s_addc_u32 s39, s37, -1
	s_cmp_eq_u32 s33, 12
	s_cselect_b32 s41, s0, s39
	s_cselect_b32 s40, s1, s38
	s_cselect_b32 s39, s2, s29
	s_cselect_b32 s38, s5, s27
	v_lshl_add_u64 v[220:221], s[36:37], 0, v[156:157]
	s_add_i32 m0, s44, 0xc000
	ds_read_b128 v[180:183], v188
	ds_read_b128 v[192:195], v188 offset:1024
	ds_read_b128 v[196:199], v188 offset:2048
	ds_read_b128 v[200:203], v188 offset:3072
	ds_read_b128 v[204:207], v188 offset:4096
	ds_read_b128 v[208:211], v188 offset:5120
	ds_read_b128 v[212:215], v188 offset:6144
	ds_read_b128 v[216:219], v188 offset:7168
	global_load_lds_dwordx4 v[220:221], off
	v_lshl_add_u64 v[220:221], s[36:37], 0, v[158:159]
	s_add_i32 m0, s44, 0xe000
	s_nop 0
	global_load_lds_dwordx4 v[220:221], off
	s_waitcnt vmcnt(8)
	s_waitcnt lgkmcnt(0)
	s_barrier
; #define PG8_STAGE(bufoff, gbase, voff) do { _Pragma("unroll") for (int _i = 0; _i < 2; ++_i) \
;         __builtin_amdgcn_global_load_lds((const unsigned*)((const char*)(gbase) + (voff)[_i]), (PG8_LAS unsigned*)(lds + (bufoff) + ldsw + _i * 8192), 16, 0, 0); } while (0)
; #define PG8_LDA(dst, b, h) do { _Pragma("unroll") for (int m = 0; m < 4; ++m) _Pragma("unroll") for (int k = 0; k < 2; ++k) dst[m][k] = *(const PG8_LAS bf16x8*)(lds + PG8_SA(b, h) + aoff + m * 2048 + k * 1024); } while (0)
; #define PG8_MMA(ai, bj, At, Bt) do { __builtin_amdgcn_s_setprio(1); _Pragma("unroll") for (int m = 0; m < 4; ++m) _Pragma("unroll") for (int n = 0; n < 2; ++n) _Pragma("unroll") for (int k = 0; k < 2; ++k) \
;         acc[ai][bj][m][n] = __builtin_amdgcn_mfma_f32_16x16x32_bf16(Bt[n][k], At[m][k], acc[ai][bj][m][n], 0, 0, 0); __builtin_amdgcn_s_setprio(0); } while (0)
; #define PG8_WAIT_V(n) asm volatile("s_waitcnt vmcnt(" #n ")" ::: "memory")
; #define PG8_WAIT_L(n) asm volatile("s_waitcnt lgkmcnt(" #n ")" ::: "memory")
; #define PG8_BAR __builtin_amdgcn_s_barrier()
; #define PG8_SCHED __builtin_amdgcn_sched_barrier(0)
; template <class Epi, class Sched, bool ALIGN_EPI = false, bool SP2 = false>
; __device__ __forceinline__ void gemm_phase(PG8_LAS unsigned char* lds, const Gemm g, const Sched& S, const Epi& E) {
;     ...
;             PG8_WAIT_V(8); PG8_WAIT_L(0); PG8_BAR; PG8_MMA(0, 0, At, B0); PG8_MMA(0, 1, At, B1); PG8_BAR; PG8_SCHED;
;             PG8_LDA(At, 0, 1); PG8_STAGE(PG8_SB(0, 0), b2, voffB); PG8_STAGE(PG8_SB(0, 1), b2 + hstepB, voffB); PG8_STAGE(PG8_SA(0, 0), a2, voffA);
;             PG8_WAIT_V(8); PG8_WAIT_L(0); PG8_BAR; PG8_MMA(1, 0, At, B0); PG8_MMA(1, 1, At, B1); PG8_BAR; PG8_SCHED;
	s_setprio 1
	s_waitcnt lgkmcnt(0)
	v_mfma_f32_16x16x32_bf16 v[126:129], v[130:133], v[180:183], v[126:129]
	v_mfma_f32_16x16x32_bf16 v[122:125], v[138:141], v[180:183], v[122:125]
	v_mfma_f32_16x16x32_bf16 v[106:109], v[138:141], v[196:199], v[106:109]
	v_mfma_f32_16x16x32_bf16 v[110:113], v[130:133], v[196:199], v[110:113]
	v_mfma_f32_16x16x32_bf16 v[94:97], v[130:133], v[204:207], v[94:97]
	v_mfma_f32_16x16x32_bf16 v[90:93], v[138:141], v[204:207], v[90:93]
	v_mfma_f32_16x16x32_bf16 v[74:77], v[138:141], v[212:215], v[74:77]
	v_mfma_f32_16x16x32_bf16 v[78:81], v[130:133], v[212:215], v[78:81]
	v_mfma_f32_16x16x32_bf16 v[126:129], v[134:137], v[192:195], v[126:129]
	v_mfma_f32_16x16x32_bf16 v[122:125], v[142:145], v[192:195], v[122:125]
	v_mfma_f32_16x16x32_bf16 v[106:109], v[142:145], v[200:203], v[106:109]
	v_mfma_f32_16x16x32_bf16 v[110:113], v[134:137], v[200:203], v[110:113]
	v_mfma_f32_16x16x32_bf16 v[94:97], v[134:137], v[208:211], v[94:97]
	v_mfma_f32_16x16x32_bf16 v[90:93], v[142:145], v[208:211], v[90:93]
	v_mfma_f32_16x16x32_bf16 v[74:77], v[142:145], v[216:219], v[74:77]
	v_mfma_f32_16x16x32_bf16 v[78:81], v[134:137], v[216:219], v[78:81]
	s_setprio 0
	s_setprio 1
	v_mfma_f32_16x16x32_bf16 v[118:121], v[164:167], v[180:183], v[118:121]
	v_mfma_f32_16x16x32_bf16 v[114:117], v[172:175], v[180:183], v[114:117]
	v_mfma_f32_16x16x32_bf16 v[98:101], v[172:175], v[196:199], v[98:101]
	v_mfma_f32_16x16x32_bf16 v[102:105], v[164:167], v[196:199], v[102:105]
	v_mfma_f32_16x16x32_bf16 v[86:89], v[164:167], v[204:207], v[86:89]
	v_mfma_f32_16x16x32_bf16 v[82:85], v[172:175], v[204:207], v[82:85]
	v_mfma_f32_16x16x32_bf16 v[66:69], v[172:175], v[212:215], v[66:69]
	v_mfma_f32_16x16x32_bf16 v[70:73], v[164:167], v[212:215], v[70:73]
	v_mfma_f32_16x16x32_bf16 v[118:121], v[168:171], v[192:195], v[118:121]
	v_mfma_f32_16x16x32_bf16 v[114:117], v[176:179], v[192:195], v[114:117]
	v_mfma_f32_16x16x32_bf16 v[98:101], v[176:179], v[200:203], v[98:101]
	v_mfma_f32_16x16x32_bf16 v[102:105], v[168:171], v[200:203], v[102:105]
	v_mfma_f32_16x16x32_bf16 v[86:89], v[168:171], v[208:211], v[86:89]
	v_mfma_f32_16x16x32_bf16 v[82:85], v[176:179], v[208:211], v[82:85]
	v_mfma_f32_16x16x32_bf16 v[66:69], v[176:179], v[216:219], v[66:69]
	v_mfma_f32_16x16x32_bf16 v[70:73], v[168:171], v[216:219], v[70:73]
	s_setprio 0
	s_barrier
	s_add_i32 s58, s55, s43
	v_lshl_add_u64 v[220:221], s[38:39], 0, v[148:149]
	s_mov_b32 m0, s58
	ds_read_b128 v[180:183], v188 offset:16384
	ds_read_b128 v[192:195], v188 offset:17408
	ds_read_b128 v[196:199], v188 offset:18432
	ds_read_b128 v[200:203], v188 offset:19456
	ds_read_b128 v[204:207], v188 offset:20480
	ds_read_b128 v[208:211], v188 offset:21504
	ds_read_b128 v[212:215], v188 offset:22528
	ds_read_b128 v[216:219], v188 offset:23552
	global_load_lds_dwordx4 v[220:221], off
	s_add_i32 m0, s58, 0x2000
	s_add_u32 s58, s38, 0x40000
	v_lshl_add_u64 v[222:223], s[38:39], 0, v[152:153]
	s_addc_u32 s59, s39, 0
	s_add_i32 s60, s56, s43
	global_load_lds_dwordx4 v[222:223], off
	v_lshl_add_u64 v[224:225], s[58:59], 0, v[148:149]
	s_mov_b32 m0, s60
	v_lshl_add_u64 v[226:227], s[40:41], 0, v[150:151]
	global_load_lds_dwordx4 v[224:225], off
	v_lshl_add_u64 v[224:225], s[58:59], 0, v[152:153]
	s_add_i32 m0, s60, 0x2000
	s_nop 0
	global_load_lds_dwordx4 v[224:225], off
	v_lshl_add_u64 v[224:225], s[40:41], 0, v[146:147]
	s_mov_b32 m0, s44
	s_nop 0
	global_load_lds_dwordx4 v[224:225], off
	s_mov_b32 m0, s45
	s_nop 0
	global_load_lds_dwordx4 v[226:227], off
	s_waitcnt vmcnt(8)
	s_waitcnt lgkmcnt(0)
	s_barrier
	s_setprio 1
	s_waitcnt lgkmcnt(0)
	v_mfma_f32_16x16x32_bf16 v[62:65], v[130:133], v[180:183], v[62:65]
	v_mfma_f32_16x16x32_bf16 v[58:61], v[138:141], v[180:183], v[58:61]
	v_mfma_f32_16x16x32_bf16 v[42:45], v[138:141], v[196:199], v[42:45]
	v_mfma_f32_16x16x32_bf16 v[46:49], v[130:133], v[196:199], v[46:49]
	v_mfma_f32_16x16x32_bf16 v[30:33], v[130:133], v[204:207], v[30:33]
	v_mfma_f32_16x16x32_bf16 v[26:29], v[138:141], v[204:207], v[26:29]
	v_mfma_f32_16x16x32_bf16 v[10:13], v[138:141], v[212:215], v[10:13]
	v_mfma_f32_16x16x32_bf16 v[14:17], v[130:133], v[212:215], v[14:17]
	v_mfma_f32_16x16x32_bf16 v[62:65], v[134:137], v[192:195], v[62:65]
	v_mfma_f32_16x16x32_bf16 v[58:61], v[142:145], v[192:195], v[58:61]
	v_mfma_f32_16x16x32_bf16 v[42:45], v[142:145], v[200:203], v[42:45]
	v_mfma_f32_16x16x32_bf16 v[46:49], v[134:137], v[200:203], v[46:49]
	v_mfma_f32_16x16x32_bf16 v[30:33], v[134:137], v[208:211], v[30:33]
	v_mfma_f32_16x16x32_bf16 v[26:29], v[142:145], v[208:211], v[26:29]
	v_mfma_f32_16x16x32_bf16 v[10:13], v[142:145], v[216:219], v[10:13]
	v_mfma_f32_16x16x32_bf16 v[14:17], v[134:137], v[216:219], v[14:17]
	s_setprio 0
	s_setprio 1
	v_mfma_f32_16x16x32_bf16 v[54:57], v[164:167], v[180:183], v[54:57]
	v_mfma_f32_16x16x32_bf16 v[50:53], v[172:175], v[180:183], v[50:53]
	v_mfma_f32_16x16x32_bf16 v[34:37], v[172:175], v[196:199], v[34:37]
	v_mfma_f32_16x16x32_bf16 v[38:41], v[164:167], v[196:199], v[38:41]
	v_mfma_f32_16x16x32_bf16 v[22:25], v[164:167], v[204:207], v[22:25]
	v_mfma_f32_16x16x32_bf16 v[18:21], v[172:175], v[204:207], v[18:21]
	v_mfma_f32_16x16x32_bf16 v[2:5], v[172:175], v[212:215], v[2:5]
	v_mfma_f32_16x16x32_bf16 v[6:9], v[164:167], v[212:215], v[6:9]
	v_mfma_f32_16x16x32_bf16 v[54:57], v[168:171], v[192:195], v[54:57]
	v_mfma_f32_16x16x32_bf16 v[50:53], v[176:179], v[192:195], v[50:53]
	v_mfma_f32_16x16x32_bf16 v[34:37], v[176:179], v[200:203], v[34:37]
	v_mfma_f32_16x16x32_bf16 v[38:41], v[168:171], v[200:203], v[38:41]
	v_mfma_f32_16x16x32_bf16 v[22:25], v[168:171], v[208:211], v[22:25]
	v_mfma_f32_16x16x32_bf16 v[18:21], v[176:179], v[208:211], v[18:21]
	v_mfma_f32_16x16x32_bf16 v[2:5], v[176:179], v[216:219], v[2:5]
	v_mfma_f32_16x16x32_bf16 v[6:9], v[168:171], v[216:219], v[6:9]
	s_setprio 0
	s_barrier
; #define PG8_STAGE(bufoff, gbase, voff) do { _Pragma("unroll") for (int _i = 0; _i < 2; ++_i) \
;         __builtin_amdgcn_global_load_lds((const unsigned*)((const char*)(gbase) + (voff)[_i]), (PG8_LAS unsigned*)(lds + (bufoff) + ldsw + _i * 8192), 16, 0, 0); } while (0)
; #define PG8_LDA(dst, b, h) do { _Pragma("unroll") for (int m = 0; m < 4; ++m) _Pragma("unroll") for (int k = 0; k < 2; ++k) dst[m][k] = *(const PG8_LAS bf16x8*)(lds + PG8_SA(b, h) + aoff + m * 2048 + k * 1024); } while (0)
; #define PG8_LDB(dst, b, h) do { _Pragma("unroll") for (int n = 0; n < 2; ++n) _Pragma("unroll") for (int k = 0; k < 2; ++k) dst[n][k] = *(const PG8_LAS bf16x8*)(lds + PG8_SB(b, h) + boff + n * 2048 + k * 1024); } while (0)
; #define PG8_MMA(ai, bj, At, Bt) do { __builtin_amdgcn_s_setprio(1); _Pragma("unroll") for (int m = 0; m < 4; ++m) _Pragma("unroll") for (int n = 0; n < 2; ++n) _Pragma("unroll") for (int k = 0; k < 2; ++k) \
;         acc[ai][bj][m][n] = __builtin_amdgcn_mfma_f32_16x16x32_bf16(Bt[n][k], At[m][k], acc[ai][bj][m][n], 0, 0, 0); __builtin_amdgcn_s_setprio(0); } while (0)
; #define PG8_WAIT_V(n) asm volatile("s_waitcnt vmcnt(" #n ")" ::: "memory")
; #define PG8_WAIT_L(n) asm volatile("s_waitcnt lgkmcnt(" #n ")" ::: "memory")
; #define PG8_BAR __builtin_amdgcn_s_barrier()
; #define PG8_SCHED __builtin_amdgcn_sched_barrier(0)
; template <class Epi, class Sched, bool ALIGN_EPI = false, bool SP2 = false>
; __device__ __forceinline__ void gemm_phase(PG8_LAS unsigned char* lds, const Gemm g, const Sched& S, const Epi& E) {
;     ...
;             PG8_LDB(B0, 1, 0); PG8_LDB(B1, 1, 1); PG8_SCHED; PG8_LDA(At, 1, 0); PG8_STAGE(PG8_SA(0, 1), a2 + hstepA, voffA);
;             PG8_WAIT_V(8); PG8_WAIT_L(0); PG8_BAR; PG8_MMA(0, 0, At, B0); PG8_MMA(0, 1, At, B1); PG8_BAR; PG8_SCHED;
	s_add_i32 s58, 0, 0x18000
	s_add_i32 s59, 0, 0x1c000
	v_add_u32_e32 v142, s58, v184
	v_add_u32_e32 v176, s59, v184
	ds_read_b128 v[130:133], v142
	ds_read_b128 v[134:137], v142 offset:1024
	ds_read_b128 v[138:141], v142 offset:2048
	ds_read_b128 v[142:145], v142 offset:3072
	ds_read_b128 v[164:167], v176
	ds_read_b128 v[168:171], v176 offset:1024
	ds_read_b128 v[172:175], v176 offset:2048
	ds_read_b128 v[176:179], v176 offset:3072
	s_add_u32 s40, s40, 0x40000
	s_addc_u32 s41, s41, 0
	s_mov_b32 m0, s46
	v_lshl_add_u64 v[228:229], s[40:41], 0, v[146:147]
	ds_read_b128 v[180:183], v188 offset:32768
	ds_read_b128 v[192:195], v188 offset:33792
	ds_read_b128 v[196:199], v188 offset:34816
	ds_read_b128 v[200:203], v188 offset:35840
	ds_read_b128 v[204:207], v188 offset:36864
	ds_read_b128 v[208:211], v188 offset:37888
	ds_read_b128 v[212:215], v188 offset:38912
	ds_read_b128 v[216:219], v188 offset:39936
	global_load_lds_dwordx4 v[228:229], off
	v_lshl_add_u64 v[228:229], s[40:41], 0, v[150:151]
	s_mov_b32 m0, s47
	s_nop 0
	global_load_lds_dwordx4 v[228:229], off
	s_waitcnt vmcnt(8)
	s_waitcnt lgkmcnt(0)
	s_barrier
	s_setprio 1
	s_waitcnt lgkmcnt(0)
	v_mfma_f32_16x16x32_bf16 v[126:129], v[130:133], v[180:183], v[126:129]
	v_mfma_f32_16x16x32_bf16 v[122:125], v[138:141], v[180:183], v[122:125]
	v_mfma_f32_16x16x32_bf16 v[106:109], v[138:141], v[196:199], v[106:109]
	v_mfma_f32_16x16x32_bf16 v[110:113], v[130:133], v[196:199], v[110:113]
	v_mfma_f32_16x16x32_bf16 v[94:97], v[130:133], v[204:207], v[94:97]
	v_mfma_f32_16x16x32_bf16 v[90:93], v[138:141], v[204:207], v[90:93]
	v_mfma_f32_16x16x32_bf16 v[74:77], v[138:141], v[212:215], v[74:77]
	v_mfma_f32_16x16x32_bf16 v[78:81], v[130:133], v[212:215], v[78:81]
	v_mfma_f32_16x16x32_bf16 v[126:129], v[134:137], v[192:195], v[126:129]
	v_mfma_f32_16x16x32_bf16 v[122:125], v[142:145], v[192:195], v[122:125]
	v_mfma_f32_16x16x32_bf16 v[106:109], v[142:145], v[200:203], v[106:109]
	v_mfma_f32_16x16x32_bf16 v[110:113], v[134:137], v[200:203], v[110:113]
	v_mfma_f32_16x16x32_bf16 v[94:97], v[134:137], v[208:211], v[94:97]
	v_mfma_f32_16x16x32_bf16 v[90:93], v[142:145], v[208:211], v[90:93]
	v_mfma_f32_16x16x32_bf16 v[74:77], v[142:145], v[216:219], v[74:77]
	v_mfma_f32_16x16x32_bf16 v[78:81], v[134:137], v[216:219], v[78:81]
	s_setprio 0
	s_setprio 1
	v_mfma_f32_16x16x32_bf16 v[118:121], v[164:167], v[180:183], v[118:121]
	v_mfma_f32_16x16x32_bf16 v[114:117], v[172:175], v[180:183], v[114:117]
	v_mfma_f32_16x16x32_bf16 v[98:101], v[172:175], v[196:199], v[98:101]
	v_mfma_f32_16x16x32_bf16 v[102:105], v[164:167], v[196:199], v[102:105]
	v_mfma_f32_16x16x32_bf16 v[86:89], v[164:167], v[204:207], v[86:89]
	v_mfma_f32_16x16x32_bf16 v[82:85], v[172:175], v[204:207], v[82:85]
	v_mfma_f32_16x16x32_bf16 v[66:69], v[172:175], v[212:215], v[66:69]
	v_mfma_f32_16x16x32_bf16 v[70:73], v[164:167], v[212:215], v[70:73]
	v_mfma_f32_16x16x32_bf16 v[118:121], v[168:171], v[192:195], v[118:121]
	v_mfma_f32_16x16x32_bf16 v[114:117], v[176:179], v[192:195], v[114:117]
	v_mfma_f32_16x16x32_bf16 v[98:101], v[176:179], v[200:203], v[98:101]
	v_mfma_f32_16x16x32_bf16 v[102:105], v[168:171], v[200:203], v[102:105]
	v_mfma_f32_16x16x32_bf16 v[86:89], v[168:171], v[208:211], v[86:89]
	v_mfma_f32_16x16x32_bf16 v[82:85], v[176:179], v[208:211], v[82:85]
	v_mfma_f32_16x16x32_bf16 v[66:69], v[176:179], v[216:219], v[66:69]
	v_mfma_f32_16x16x32_bf16 v[70:73], v[168:171], v[216:219], v[70:73]
	s_setprio 0
	s_barrier
; #define PG8_STAGE(bufoff, gbase, voff) do { _Pragma("unroll") for (int _i = 0; _i < 2; ++_i) \
;         __builtin_amdgcn_global_load_lds((const unsigned*)((const char*)(gbase) + (voff)[_i]), (PG8_LAS unsigned*)(lds + (bufoff) + ldsw + _i * 8192), 16, 0, 0); } while (0)
; #define PG8_LDA(dst, b, h) do { _Pragma("unroll") for (int m = 0; m < 4; ++m) _Pragma("unroll") for (int k = 0; k < 2; ++k) dst[m][k] = *(const PG8_LAS bf16x8*)(lds + PG8_SA(b, h) + aoff + m * 2048 + k * 1024); } while (0)
; #define PG8_MMA(ai, bj, At, Bt) do { __builtin_amdgcn_s_setprio(1); _Pragma("unroll") for (int m = 0; m < 4; ++m) _Pragma("unroll") for (int n = 0; n < 2; ++n) _Pragma("unroll") for (int k = 0; k < 2; ++k) \
;         acc[ai][bj][m][n] = __builtin_amdgcn_mfma_f32_16x16x32_bf16(Bt[n][k], At[m][k], acc[ai][bj][m][n], 0, 0, 0); __builtin_amdgcn_s_setprio(0); } while (0)
; #define PG8_WAIT_V(n) asm volatile("s_waitcnt vmcnt(" #n ")" ::: "memory")
; #define PG8_WAIT_L(n) asm volatile("s_waitcnt lgkmcnt(" #n ")" ::: "memory")
; #define PG8_BAR __builtin_amdgcn_s_barrier()
; #define PG8_SCHED __builtin_amdgcn_sched_barrier(0)
; template <class Epi, class Sched, bool ALIGN_EPI = false, bool SP2 = false>
; __device__ __forceinline__ void gemm_phase(PG8_LAS unsigned char* lds, const Gemm g, const Sched& S, const Epi& E) {
;     ...
;             PG8_LDA(At, 1, 1); PG8_STAGE(PG8_SB(1, 0), b3, voffB); PG8_STAGE(PG8_SB(1, 1), b3 + hstepB, voffB); PG8_STAGE(PG8_SA(1, 0), a3, voffA);
;             PG8_WAIT_V(8); PG8_WAIT_L(0); PG8_BAR; PG8_MMA(1, 0, At, B0); PG8_MMA(1, 1, At, B1); PG8_BAR; PG8_SCHED;
;     ...
;         }
;         if constexpr (ALIGN_EPI) { if (wr == 0) PG8_BAR; }
	s_add_i32 s40, s58, s43
	v_lshl_add_u64 v[220:221], v[220:221], 0, s[22:23]
	s_mov_b32 m0, s40
	ds_read_b128 v[180:183], v188 offset:49152
	ds_read_b128 v[192:195], v188 offset:50176
	ds_read_b128 v[196:199], v188 offset:51200
	ds_read_b128 v[200:203], v188 offset:52224
	ds_read_b128 v[204:207], v188 offset:53248
	ds_read_b128 v[208:211], v188 offset:54272
	ds_read_b128 v[212:215], v188 offset:55296
	ds_read_b128 v[216:219], v188 offset:56320
	global_load_lds_dwordx4 v[220:221], off
	s_add_i32 m0, s40, 0x2000
	s_add_u32 s38, s38, 0x40080
	v_lshl_add_u64 v[220:221], v[222:223], 0, s[22:23]
	s_addc_u32 s39, s39, 0
	s_add_i32 s40, s59, s43
	global_load_lds_dwordx4 v[220:221], off
	v_lshl_add_u64 v[220:221], s[38:39], 0, v[148:149]
	s_mov_b32 m0, s40
	s_nop 0
	global_load_lds_dwordx4 v[220:221], off
	v_lshl_add_u64 v[220:221], s[38:39], 0, v[152:153]
	s_add_i32 m0, s40, 0x2000
	s_nop 0
	global_load_lds_dwordx4 v[220:221], off
	v_lshl_add_u64 v[220:221], v[224:225], 0, s[22:23]
	s_mov_b32 m0, s50
	s_nop 0
	global_load_lds_dwordx4 v[220:221], off
	v_lshl_add_u64 v[220:221], v[226:227], 0, s[22:23]
	s_mov_b32 m0, s51
	s_nop 0
	global_load_lds_dwordx4 v[220:221], off
	s_waitcnt vmcnt(8)
	s_waitcnt lgkmcnt(0)
	s_barrier
	s_setprio 1
	s_waitcnt lgkmcnt(0)
	v_mfma_f32_16x16x32_bf16 v[62:65], v[130:133], v[180:183], v[62:65]
	v_mfma_f32_16x16x32_bf16 v[58:61], v[138:141], v[180:183], v[58:61]
	v_mfma_f32_16x16x32_bf16 v[42:45], v[138:141], v[196:199], v[42:45]
	v_mfma_f32_16x16x32_bf16 v[46:49], v[130:133], v[196:199], v[46:49]
	v_mfma_f32_16x16x32_bf16 v[30:33], v[130:133], v[204:207], v[30:33]
	v_mfma_f32_16x16x32_bf16 v[26:29], v[138:141], v[204:207], v[26:29]
	v_mfma_f32_16x16x32_bf16 v[10:13], v[138:141], v[212:215], v[10:13]
	v_mfma_f32_16x16x32_bf16 v[14:17], v[130:133], v[212:215], v[14:17]
	v_mfma_f32_16x16x32_bf16 v[62:65], v[134:137], v[192:195], v[62:65]
	v_mfma_f32_16x16x32_bf16 v[58:61], v[142:145], v[192:195], v[58:61]
	v_mfma_f32_16x16x32_bf16 v[42:45], v[142:145], v[200:203], v[42:45]
	v_mfma_f32_16x16x32_bf16 v[46:49], v[134:137], v[200:203], v[46:49]
	v_mfma_f32_16x16x32_bf16 v[30:33], v[134:137], v[208:211], v[30:33]
	v_mfma_f32_16x16x32_bf16 v[26:29], v[142:145], v[208:211], v[26:29]
	v_mfma_f32_16x16x32_bf16 v[10:13], v[142:145], v[216:219], v[10:13]
	v_mfma_f32_16x16x32_bf16 v[14:17], v[134:137], v[216:219], v[14:17]
	s_setprio 0
	s_setprio 1
	v_mfma_f32_16x16x32_bf16 v[54:57], v[164:167], v[180:183], v[54:57]
	v_mfma_f32_16x16x32_bf16 v[50:53], v[172:175], v[180:183], v[50:53]
	v_mfma_f32_16x16x32_bf16 v[34:37], v[172:175], v[196:199], v[34:37]
	v_mfma_f32_16x16x32_bf16 v[38:41], v[164:167], v[196:199], v[38:41]
	v_mfma_f32_16x16x32_bf16 v[22:25], v[164:167], v[204:207], v[22:25]
	v_mfma_f32_16x16x32_bf16 v[18:21], v[172:175], v[204:207], v[18:21]
	v_mfma_f32_16x16x32_bf16 v[2:5], v[172:175], v[212:215], v[2:5]
	v_mfma_f32_16x16x32_bf16 v[6:9], v[164:167], v[212:215], v[6:9]
	v_mfma_f32_16x16x32_bf16 v[54:57], v[168:171], v[192:195], v[54:57]
	v_mfma_f32_16x16x32_bf16 v[50:53], v[176:179], v[192:195], v[50:53]
	v_mfma_f32_16x16x32_bf16 v[34:37], v[176:179], v[200:203], v[34:37]
	v_mfma_f32_16x16x32_bf16 v[38:41], v[168:171], v[200:203], v[38:41]
	v_mfma_f32_16x16x32_bf16 v[22:25], v[168:171], v[208:211], v[22:25]
	v_mfma_f32_16x16x32_bf16 v[18:21], v[176:179], v[208:211], v[18:21]
	v_mfma_f32_16x16x32_bf16 v[2:5], v[176:179], v[216:219], v[2:5]
	v_mfma_f32_16x16x32_bf16 v[6:9], v[168:171], v[216:219], v[6:9]
	s_setprio 0
	s_barrier
	s_add_i32 s33, s33, 2
	s_add_u32 s36, s36, 0x100
	s_addc_u32 s37, s37, 0
	s_add_u32 s27, s27, 0x100
	s_addc_u32 s29, s29, 0
	s_cmp_gt_u32 s33, 13
	s_cbranch_scc0 .LBB0_903
	s_and_b64 vcc, exec, s[24:25]
	s_cbranch_vccz .LBB0_906
	s_barrier

; #define PG8_STAGE(bufoff, gbase, voff) do { _Pragma("unroll") for (int _i = 0; _i < 2; ++_i) \
;         __builtin_amdgcn_global_load_lds((const unsigned*)((const char*)(gbase) + (voff)[_i]), (PG8_LAS unsigned*)(lds + (bufoff) + ldsw + _i * 8192), 16, 0, 0); } while (0)
; #define PG8_LDA(dst, b, h) do { _Pragma("unroll") for (int m = 0; m < 4; ++m) _Pragma("unroll") for (int k = 0; k < 2; ++k) dst[m][k] = *(const PG8_LAS bf16x8*)(lds + PG8_SA(b, h) + aoff + m * 2048 + k * 1024); } while (0)
; #define PG8_LDB(dst, b, h) do { _Pragma("unroll") for (int n = 0; n < 2; ++n) _Pragma("unroll") for (int k = 0; k < 2; ++k) dst[n][k] = *(const PG8_LAS bf16x8*)(lds + PG8_SB(b, h) + boff + n * 2048 + k * 1024); } while (0)
; #define PG8_MMA(ai, bj, At, Bt) do { __builtin_amdgcn_s_setprio(1); _Pragma("unroll") for (int m = 0; m < 4; ++m) _Pragma("unroll") for (int n = 0; n < 2; ++n) _Pragma("unroll") for (int k = 0; k < 2; ++k) \
;         acc[ai][bj][m][n] = __builtin_amdgcn_mfma_f32_16x16x32_bf16(Bt[n][k], At[m][k], acc[ai][bj][m][n], 0, 0, 0); __builtin_amdgcn_s_setprio(0); } while (0)
; #define PG8_WAIT_V(n) asm volatile("s_waitcnt vmcnt(" #n ")" ::: "memory")
; #define PG8_WAIT_L(n) asm volatile("s_waitcnt lgkmcnt(" #n ")" ::: "memory")
; #define PG8_BAR __builtin_amdgcn_s_barrier()
; #define PG8_SCHED __builtin_amdgcn_sched_barrier(0)
; template <class Epi, class Sched, bool ALIGN_EPI = false, bool SP2 = false>
; __device__ __forceinline__ void gemm_phase(PG8_LAS unsigned char* lds, const Gemm g, const Sched& S, const Epi& E) {
;     ...
;         const bool has_next = S.next(ui + 1, nxt);
;         const char* nA = has_next ? (const char*)g.A + (size_t)nxt.g * g.gsA * 2 + (size_t)nxt.pm * tstepA : cA; const char* nB = has_next ? (const char*)g.Bt + (size_t)nxt.g * g.gsB * 2 + (size_t)nxt.pn * tstepB : cB;
;     ...
;             PG8_LDB(B0, 0, 0); PG8_LDB(B1, 0, 1); PG8_SCHED; PG8_LDA(At, 0, 0); PG8_STAGE(PG8_SA(1, 1), a1 + hstepA, voffA);
;             PG8_WAIT_V(8); PG8_WAIT_L(0); PG8_BAR; PG8_MMA(0, 0, At, B0); PG8_MMA(0, 1, At, B1); PG8_BAR; PG8_SCHED;
;             PG8_LDA(At, 0, 1); PG8_STAGE(PG8_SB(0, 0), b2, voffB); PG8_STAGE(PG8_SB(0, 1), b2 + hstepB, voffB); PG8_STAGE(PG8_SA(0, 0), a2, voffA);
;             PG8_WAIT_V(8); PG8_WAIT_L(0); PG8_BAR; PG8_MMA(1, 0, At, B0); PG8_MMA(1, 1, At, B1); PG8_BAR; PG8_SCHED;
.LBB0_988:
	s_ashr_i32 s19, s18, 31
	s_lshl_b64 s[20:21], s[18:19], 19
	s_add_u32 s20, s3, s20
	s_addc_u32 s21, s30, s21
	s_and_b64 s[22:23], s[6:7], exec
	s_cselect_b32 s1, s21, s25
	s_cselect_b32 s5, s20, s24
	s_ashr_i32 s17, s16, 31
	s_lshl_b64 s[22:23], s[16:17], 19
	s_add_u32 s22, s31, s22
	s_addc_u32 s23, s34, s23
	s_and_b64 s[28:29], s[6:7], exec
	s_cselect_b32 s17, s23, s27
	s_cselect_b32 s19, s22, s26
	s_add_u32 s24, s24, 0x40080
	s_addc_u32 s25, s25, 0
	s_add_u32 s55, s26, 0x100
	s_addc_u32 s56, s27, 0
	s_mov_b32 s57, -2
	ds_read_b128 v[164:167], v157
	ds_read_b128 v[174:177], v157 offset:1024
	ds_read_b128 v[178:181], v157 offset:2048
	ds_read_b128 v[182:185], v157 offset:3072
	ds_read_b128 v[186:189], v159
	ds_read_b128 v[190:193], v159 offset:1024
	ds_read_b128 v[194:197], v159 offset:2048
	ds_read_b128 v[198:201], v159 offset:3072
	s_add_u32 s26, s24, 0xfffc0080
	s_addc_u32 s27, s25, -1
	s_cmp_eq_u32 s57, 12
	s_cselect_b32 s29, s1, s27
	s_cselect_b32 s28, s5, s26
	s_cselect_b32 s27, s17, s56
	s_cselect_b32 s26, s19, s55
	v_lshl_add_u64 v[154:155], s[24:25], 0, v[144:145]
	s_add_i32 m0, s38, 0xc000
	ds_read_b128 v[202:205], v161
	ds_read_b128 v[206:209], v161 offset:1024
	ds_read_b128 v[210:213], v161 offset:2048
	ds_read_b128 v[214:217], v161 offset:3072
	ds_read_b128 v[218:221], v161 offset:4096
	ds_read_b128 v[222:225], v161 offset:5120
	ds_read_b128 v[226:229], v161 offset:6144
	ds_read_b128 v[230:233], v161 offset:7168
	global_load_lds_dwordx4 v[154:155], off
	v_lshl_add_u64 v[154:155], s[24:25], 0, v[146:147]
	s_add_i32 m0, s38, 0xe000
	s_nop 0
	global_load_lds_dwordx4 v[154:155], off
	s_waitcnt vmcnt(8)
	s_waitcnt lgkmcnt(0)
	s_barrier
	s_setprio 1
	s_waitcnt lgkmcnt(0)
	v_mfma_f32_16x16x32_bf16 v[126:129], v[164:167], v[202:205], 0
	v_mfma_f32_16x16x32_bf16 v[122:125], v[178:181], v[202:205], 0
	v_mfma_f32_16x16x32_bf16 v[106:109], v[178:181], v[210:213], 0
	v_mfma_f32_16x16x32_bf16 v[110:113], v[164:167], v[210:213], 0
	v_mfma_f32_16x16x32_bf16 v[94:97], v[164:167], v[218:221], 0
	v_mfma_f32_16x16x32_bf16 v[90:93], v[178:181], v[218:221], 0
	v_mfma_f32_16x16x32_bf16 v[74:77], v[178:181], v[226:229], 0
	v_mfma_f32_16x16x32_bf16 v[78:81], v[164:167], v[226:229], 0
	v_mfma_f32_16x16x32_bf16 v[126:129], v[174:177], v[206:209], v[126:129]
	v_mfma_f32_16x16x32_bf16 v[122:125], v[182:185], v[206:209], v[122:125]
	v_mfma_f32_16x16x32_bf16 v[106:109], v[182:185], v[214:217], v[106:109]
	v_mfma_f32_16x16x32_bf16 v[110:113], v[174:177], v[214:217], v[110:113]
	v_mfma_f32_16x16x32_bf16 v[94:97], v[174:177], v[222:225], v[94:97]
	v_mfma_f32_16x16x32_bf16 v[90:93], v[182:185], v[222:225], v[90:93]
	v_mfma_f32_16x16x32_bf16 v[74:77], v[182:185], v[230:233], v[74:77]
	v_mfma_f32_16x16x32_bf16 v[78:81], v[174:177], v[230:233], v[78:81]
	s_setprio 0
	s_setprio 1
	v_mfma_f32_16x16x32_bf16 v[118:121], v[186:189], v[202:205], 0
	v_mfma_f32_16x16x32_bf16 v[114:117], v[194:197], v[202:205], 0
	v_mfma_f32_16x16x32_bf16 v[98:101], v[194:197], v[210:213], 0
	v_mfma_f32_16x16x32_bf16 v[102:105], v[186:189], v[210:213], 0
	v_mfma_f32_16x16x32_bf16 v[86:89], v[186:189], v[218:221], 0
	v_mfma_f32_16x16x32_bf16 v[82:85], v[194:197], v[218:221], 0
	v_mfma_f32_16x16x32_bf16 v[66:69], v[194:197], v[226:229], 0
	v_mfma_f32_16x16x32_bf16 v[70:73], v[186:189], v[226:229], 0
	v_mfma_f32_16x16x32_bf16 v[118:121], v[190:193], v[206:209], v[118:121]
	v_mfma_f32_16x16x32_bf16 v[114:117], v[198:201], v[206:209], v[114:117]
	v_mfma_f32_16x16x32_bf16 v[98:101], v[198:201], v[214:217], v[98:101]
	v_mfma_f32_16x16x32_bf16 v[102:105], v[190:193], v[214:217], v[102:105]
	v_mfma_f32_16x16x32_bf16 v[86:89], v[190:193], v[222:225], v[86:89]
	v_mfma_f32_16x16x32_bf16 v[82:85], v[198:201], v[222:225], v[82:85]
	v_mfma_f32_16x16x32_bf16 v[66:69], v[198:201], v[230:233], v[66:69]
	v_mfma_f32_16x16x32_bf16 v[70:73], v[190:193], v[230:233], v[70:73]
	s_setprio 0
	s_barrier
	s_add_i32 s58, s49, s35
	v_lshl_add_u64 v[154:155], s[26:27], 0, v[134:135]
	s_mov_b32 m0, s58
	ds_read_b128 v[202:205], v161 offset:16384
	ds_read_b128 v[206:209], v161 offset:17408
	ds_read_b128 v[210:213], v161 offset:18432
	ds_read_b128 v[214:217], v161 offset:19456
	ds_read_b128 v[218:221], v161 offset:20480
	ds_read_b128 v[222:225], v161 offset:21504
	ds_read_b128 v[226:229], v161 offset:22528
	ds_read_b128 v[230:233], v161 offset:23552
	global_load_lds_dwordx4 v[154:155], off
	s_add_i32 m0, s58, 0x2000
	s_add_u32 s58, s26, 0x40000
	v_lshl_add_u64 v[168:169], s[26:27], 0, v[130:131]
	s_addc_u32 s59, s27, 0
	s_add_i32 s60, s50, s35
	global_load_lds_dwordx4 v[168:169], off
	v_lshl_add_u64 v[234:235], s[58:59], 0, v[134:135]
	s_mov_b32 m0, s60
	v_lshl_add_u64 v[236:237], s[28:29], 0, v[132:133]
	global_load_lds_dwordx4 v[234:235], off
	v_lshl_add_u64 v[234:235], s[58:59], 0, v[130:131]
	s_add_i32 m0, s60, 0x2000
	s_nop 0
	global_load_lds_dwordx4 v[234:235], off
	v_lshl_add_u64 v[234:235], s[28:29], 0, v[136:137]
	s_mov_b32 m0, s38
	s_nop 0
	global_load_lds_dwordx4 v[234:235], off
	s_mov_b32 m0, s39
	s_nop 0
	global_load_lds_dwordx4 v[236:237], off
	s_waitcnt vmcnt(8)
	s_waitcnt lgkmcnt(0)
	s_barrier
; #define PG8_STAGE(bufoff, gbase, voff) do { _Pragma("unroll") for (int _i = 0; _i < 2; ++_i) \
;         __builtin_amdgcn_global_load_lds((const unsigned*)((const char*)(gbase) + (voff)[_i]), (PG8_LAS unsigned*)(lds + (bufoff) + ldsw + _i * 8192), 16, 0, 0); } while (0)
; #define PG8_LDA(dst, b, h) do { _Pragma("unroll") for (int m = 0; m < 4; ++m) _Pragma("unroll") for (int k = 0; k < 2; ++k) dst[m][k] = *(const PG8_LAS bf16x8*)(lds + PG8_SA(b, h) + aoff + m * 2048 + k * 1024); } while (0)
; #define PG8_LDB(dst, b, h) do { _Pragma("unroll") for (int n = 0; n < 2; ++n) _Pragma("unroll") for (int k = 0; k < 2; ++k) dst[n][k] = *(const PG8_LAS bf16x8*)(lds + PG8_SB(b, h) + boff + n * 2048 + k * 1024); } while (0)
; #define PG8_MMA(ai, bj, At, Bt) do { __builtin_amdgcn_s_setprio(1); _Pragma("unroll") for (int m = 0; m < 4; ++m) _Pragma("unroll") for (int n = 0; n < 2; ++n) _Pragma("unroll") for (int k = 0; k < 2; ++k) \
;         acc[ai][bj][m][n] = __builtin_amdgcn_mfma_f32_16x16x32_bf16(Bt[n][k], At[m][k], acc[ai][bj][m][n], 0, 0, 0); __builtin_amdgcn_s_setprio(0); } while (0)
; #define PG8_WAIT_V(n) asm volatile("s_waitcnt vmcnt(" #n ")" ::: "memory")
; #define PG8_WAIT_L(n) asm volatile("s_waitcnt lgkmcnt(" #n ")" ::: "memory")
; #define PG8_BAR __builtin_amdgcn_s_barrier()
; #define PG8_SCHED __builtin_amdgcn_sched_barrier(0)
; template <class Epi, class Sched, bool ALIGN_EPI = false, bool SP2 = false>
; __device__ __forceinline__ void gemm_phase(PG8_LAS unsigned char* lds, const Gemm g, const Sched& S, const Epi& E) {
;     ...
;             PG8_WAIT_V(8); PG8_WAIT_L(0); PG8_BAR; PG8_MMA(1, 0, At, B0); PG8_MMA(1, 1, At, B1); PG8_BAR; PG8_SCHED;
;             PG8_LDB(B0, 1, 0); PG8_LDB(B1, 1, 1); PG8_SCHED; PG8_LDA(At, 1, 0); PG8_STAGE(PG8_SA(0, 1), a2 + hstepA, voffA);
;             PG8_WAIT_V(8); PG8_WAIT_L(0); PG8_BAR; PG8_MMA(0, 0, At, B0); PG8_MMA(0, 1, At, B1); PG8_BAR; PG8_SCHED;
	s_setprio 1
	s_waitcnt lgkmcnt(0)
	v_mfma_f32_16x16x32_bf16 v[62:65], v[164:167], v[202:205], 0
	v_mfma_f32_16x16x32_bf16 v[58:61], v[178:181], v[202:205], 0
	v_mfma_f32_16x16x32_bf16 v[42:45], v[178:181], v[210:213], 0
	v_mfma_f32_16x16x32_bf16 v[46:49], v[164:167], v[210:213], 0
	v_mfma_f32_16x16x32_bf16 v[30:33], v[164:167], v[218:221], 0
	v_mfma_f32_16x16x32_bf16 v[26:29], v[178:181], v[218:221], 0
	v_mfma_f32_16x16x32_bf16 v[10:13], v[178:181], v[226:229], 0
	v_mfma_f32_16x16x32_bf16 v[14:17], v[164:167], v[226:229], 0
	v_mfma_f32_16x16x32_bf16 v[62:65], v[174:177], v[206:209], v[62:65]
	v_mfma_f32_16x16x32_bf16 v[58:61], v[182:185], v[206:209], v[58:61]
	v_mfma_f32_16x16x32_bf16 v[42:45], v[182:185], v[214:217], v[42:45]
	v_mfma_f32_16x16x32_bf16 v[46:49], v[174:177], v[214:217], v[46:49]
	v_mfma_f32_16x16x32_bf16 v[30:33], v[174:177], v[222:225], v[30:33]
	v_mfma_f32_16x16x32_bf16 v[26:29], v[182:185], v[222:225], v[26:29]
	v_mfma_f32_16x16x32_bf16 v[10:13], v[182:185], v[230:233], v[10:13]
	v_mfma_f32_16x16x32_bf16 v[14:17], v[174:177], v[230:233], v[14:17]
	s_setprio 0
	s_setprio 1
	v_mfma_f32_16x16x32_bf16 v[54:57], v[186:189], v[202:205], 0
	v_mfma_f32_16x16x32_bf16 v[50:53], v[194:197], v[202:205], 0
	v_mfma_f32_16x16x32_bf16 v[34:37], v[194:197], v[210:213], 0
	v_mfma_f32_16x16x32_bf16 v[38:41], v[186:189], v[210:213], 0
	v_mfma_f32_16x16x32_bf16 v[22:25], v[186:189], v[218:221], 0
	v_mfma_f32_16x16x32_bf16 v[18:21], v[194:197], v[218:221], 0
	v_mfma_f32_16x16x32_bf16 v[2:5], v[194:197], v[226:229], 0
	v_mfma_f32_16x16x32_bf16 v[6:9], v[186:189], v[226:229], 0
	v_mfma_f32_16x16x32_bf16 v[54:57], v[190:193], v[206:209], v[54:57]
	v_mfma_f32_16x16x32_bf16 v[50:53], v[198:201], v[206:209], v[50:53]
	v_mfma_f32_16x16x32_bf16 v[34:37], v[198:201], v[214:217], v[34:37]
	v_mfma_f32_16x16x32_bf16 v[38:41], v[190:193], v[214:217], v[38:41]
	v_mfma_f32_16x16x32_bf16 v[22:25], v[190:193], v[222:225], v[22:25]
	v_mfma_f32_16x16x32_bf16 v[18:21], v[198:201], v[222:225], v[18:21]
	v_mfma_f32_16x16x32_bf16 v[2:5], v[198:201], v[230:233], v[2:5]
	v_mfma_f32_16x16x32_bf16 v[6:9], v[190:193], v[230:233], v[6:9]
	s_setprio 0
	s_barrier
	s_add_i32 s58, 0, 0x18000
	v_add_u32_e32 v138, s58, v141
	s_add_i32 s59, 0, 0x1c000
	ds_read_b128 v[164:167], v138
	ds_read_b128 v[174:177], v138 offset:1024
	ds_read_b128 v[178:181], v138 offset:2048
	ds_read_b128 v[182:185], v138 offset:3072
	v_add_u32_e32 v138, s59, v141
	ds_read_b128 v[186:189], v138
	ds_read_b128 v[190:193], v138 offset:1024
	ds_read_b128 v[194:197], v138 offset:2048
	ds_read_b128 v[198:201], v138 offset:3072
	s_add_u32 s28, s28, 0x40000
	s_addc_u32 s29, s29, 0
	s_mov_b32 m0, s40
	v_lshl_add_u64 v[238:239], s[28:29], 0, v[136:137]
	ds_read_b128 v[202:205], v161 offset:32768
	ds_read_b128 v[206:209], v161 offset:33792
	ds_read_b128 v[210:213], v161 offset:34816
	ds_read_b128 v[214:217], v161 offset:35840
	ds_read_b128 v[218:221], v161 offset:36864
	ds_read_b128 v[222:225], v161 offset:37888
	ds_read_b128 v[226:229], v161 offset:38912
	ds_read_b128 v[230:233], v161 offset:39936
	global_load_lds_dwordx4 v[238:239], off
	v_lshl_add_u64 v[238:239], s[28:29], 0, v[132:133]
	s_mov_b32 m0, s41
	s_nop 0
	global_load_lds_dwordx4 v[238:239], off
	s_waitcnt vmcnt(8)
	s_waitcnt lgkmcnt(0)
	s_barrier
	s_setprio 1
	s_waitcnt lgkmcnt(0)
	v_mfma_f32_16x16x32_bf16 v[126:129], v[164:167], v[202:205], v[126:129]
	v_mfma_f32_16x16x32_bf16 v[122:125], v[178:181], v[202:205], v[122:125]
	v_mfma_f32_16x16x32_bf16 v[106:109], v[178:181], v[210:213], v[106:109]
	v_mfma_f32_16x16x32_bf16 v[110:113], v[164:167], v[210:213], v[110:113]
	v_mfma_f32_16x16x32_bf16 v[94:97], v[164:167], v[218:221], v[94:97]
	v_mfma_f32_16x16x32_bf16 v[90:93], v[178:181], v[218:221], v[90:93]
	v_mfma_f32_16x16x32_bf16 v[74:77], v[178:181], v[226:229], v[74:77]
	v_mfma_f32_16x16x32_bf16 v[78:81], v[164:167], v[226:229], v[78:81]
	v_mfma_f32_16x16x32_bf16 v[126:129], v[174:177], v[206:209], v[126:129]
	v_mfma_f32_16x16x32_bf16 v[122:125], v[182:185], v[206:209], v[122:125]
	v_mfma_f32_16x16x32_bf16 v[106:109], v[182:185], v[214:217], v[106:109]
	v_mfma_f32_16x16x32_bf16 v[110:113], v[174:177], v[214:217], v[110:113]
	v_mfma_f32_16x16x32_bf16 v[94:97], v[174:177], v[222:225], v[94:97]
	v_mfma_f32_16x16x32_bf16 v[90:93], v[182:185], v[222:225], v[90:93]
	v_mfma_f32_16x16x32_bf16 v[74:77], v[182:185], v[230:233], v[74:77]
	v_mfma_f32_16x16x32_bf16 v[78:81], v[174:177], v[230:233], v[78:81]
	s_setprio 0
	s_setprio 1
	v_mfma_f32_16x16x32_bf16 v[118:121], v[186:189], v[202:205], v[118:121]
	v_mfma_f32_16x16x32_bf16 v[114:117], v[194:197], v[202:205], v[114:117]
	v_mfma_f32_16x16x32_bf16 v[98:101], v[194:197], v[210:213], v[98:101]
	v_mfma_f32_16x16x32_bf16 v[102:105], v[186:189], v[210:213], v[102:105]
	v_mfma_f32_16x16x32_bf16 v[86:89], v[186:189], v[218:221], v[86:89]
	v_mfma_f32_16x16x32_bf16 v[82:85], v[194:197], v[218:221], v[82:85]
	v_mfma_f32_16x16x32_bf16 v[66:69], v[194:197], v[226:229], v[66:69]
	v_mfma_f32_16x16x32_bf16 v[70:73], v[186:189], v[226:229], v[70:73]
	v_mfma_f32_16x16x32_bf16 v[118:121], v[190:193], v[206:209], v[118:121]
	v_mfma_f32_16x16x32_bf16 v[114:117], v[198:201], v[206:209], v[114:117]
	v_mfma_f32_16x16x32_bf16 v[98:101], v[198:201], v[214:217], v[98:101]
	v_mfma_f32_16x16x32_bf16 v[102:105], v[190:193], v[214:217], v[102:105]
	v_mfma_f32_16x16x32_bf16 v[86:89], v[190:193], v[222:225], v[86:89]
	v_mfma_f32_16x16x32_bf16 v[82:85], v[198:201], v[222:225], v[82:85]
	v_mfma_f32_16x16x32_bf16 v[66:69], v[198:201], v[230:233], v[66:69]
	v_mfma_f32_16x16x32_bf16 v[70:73], v[190:193], v[230:233], v[70:73]
	s_setprio 0
	s_barrier
; #define PG8_STAGE(bufoff, gbase, voff) do { _Pragma("unroll") for (int _i = 0; _i < 2; ++_i) \
;         __builtin_amdgcn_global_load_lds((const unsigned*)((const char*)(gbase) + (voff)[_i]), (PG8_LAS unsigned*)(lds + (bufoff) + ldsw + _i * 8192), 16, 0, 0); } while (0)
; #define PG8_LDA(dst, b, h) do { _Pragma("unroll") for (int m = 0; m < 4; ++m) _Pragma("unroll") for (int k = 0; k < 2; ++k) dst[m][k] = *(const PG8_LAS bf16x8*)(lds + PG8_SA(b, h) + aoff + m * 2048 + k * 1024); } while (0)
; #define PG8_LDB(dst, b, h) do { _Pragma("unroll") for (int n = 0; n < 2; ++n) _Pragma("unroll") for (int k = 0; k < 2; ++k) dst[n][k] = *(const PG8_LAS bf16x8*)(lds + PG8_SB(b, h) + boff + n * 2048 + k * 1024); } while (0)
; #define PG8_BAR __builtin_amdgcn_s_barrier()
; template <class Epi, class Sched, bool ALIGN_EPI = false, bool SP2 = false>
; __device__ __forceinline__ void gemm_phase(PG8_LAS unsigned char* lds, const Gemm g, const Sched& S, const Epi& E) {
;     ...
;             const bool last = (t == nt - 2);
;             const char* a1 = cA + (size_t)(t + 1) * kstep;
;             const char* a2 = last ? nA : cA + (size_t)(t + 2) * kstep; const char* b2 = last ? nB : cB + (size_t)(t + 2) * kstep;
;             const char* a3 = a2 + kstep; const char* b3 = b2 + kstep;
;             if (last && has_next) S.a_ready(nxt);
;             if constexpr (SP2) {
;             PG8_LDB(B0, 0, 0); PG8_LDB(B1, 0, 1); PG8_SCHED; PG8_LDA(At, 0, 0); PG8_STAGE(PG8_SA(1, 1), a1 + hstepA, voffA);
;             PG8_WAIT_V(8); PG8_WAIT_L(0); PG8_BAR; PG8_MMA(0, 0, At, B0); PG8_MMA(0, 1, At, B1); PG8_BAR; PG8_SCHED;
;             PG8_LDA(At, 0, 1); PG8_STAGE(PG8_SB(0, 0), b2, voffB); PG8_STAGE(PG8_SB(0, 1), b2 + hstepB, voffB); PG8_STAGE(PG8_SA(0, 0), a2, voffA);
;             PG8_WAIT_V(8); PG8_WAIT_L(0); PG8_BAR; PG8_MMA(1, 0, At, B0); PG8_MMA(1, 1, At, B1); PG8_BAR; PG8_SCHED;
;             PG8_LDB(B0, 1, 0); PG8_LDB(B1, 1, 1); PG8_SCHED; PG8_LDA(At, 1, 0); PG8_STAGE(PG8_SA(0, 1), a2 + hstepA, voffA);
;             PG8_WAIT_V(8); PG8_WAIT_L(0); PG8_BAR; PG8_MMA(0, 0, At, B0); PG8_MMA(0, 1, At, B1); PG8_BAR; PG8_SCHED;
;             PG8_LDA(At, 1, 1); PG8_STAGE(PG8_SB(1, 0), b3, voffB); PG8_STAGE(PG8_SB(1, 1), b3 + hstepB, voffB); PG8_STAGE(PG8_SA(1, 0), a3, voffA);
;             PG8_WAIT_V(8); PG8_WAIT_L(0); PG8_BAR; PG8_MMA(1, 0, At, B0); PG8_MMA(1, 1, At, B1); PG8_BAR; PG8_SCHED;
	s_add_i32 s28, s58, s35
	v_lshl_add_u64 v[154:155], v[154:155], 0, s[12:13]
	s_mov_b32 m0, s28
	ds_read_b128 v[202:205], v161 offset:49152
	ds_read_b128 v[206:209], v161 offset:50176
	ds_read_b128 v[210:213], v161 offset:51200
	ds_read_b128 v[214:217], v161 offset:52224
	ds_read_b128 v[218:221], v161 offset:53248
	ds_read_b128 v[222:225], v161 offset:54272
	ds_read_b128 v[226:229], v161 offset:55296
	ds_read_b128 v[230:233], v161 offset:56320
	global_load_lds_dwordx4 v[154:155], off
	s_add_i32 m0, s28, 0x2000
	s_add_u32 s26, s26, 0x40080
	v_lshl_add_u64 v[154:155], v[168:169], 0, s[12:13]
	s_addc_u32 s27, s27, 0
	s_add_i32 s28, s59, s35
	global_load_lds_dwordx4 v[154:155], off
	v_lshl_add_u64 v[154:155], s[26:27], 0, v[134:135]
	s_mov_b32 m0, s28
	s_nop 0
	global_load_lds_dwordx4 v[154:155], off
	v_lshl_add_u64 v[154:155], s[26:27], 0, v[130:131]
	s_add_i32 m0, s28, 0x2000
	s_nop 0
	global_load_lds_dwordx4 v[154:155], off
	v_lshl_add_u64 v[154:155], v[234:235], 0, s[12:13]
	s_mov_b32 m0, s2
	s_nop 0
	global_load_lds_dwordx4 v[154:155], off
	v_lshl_add_u64 v[154:155], v[236:237], 0, s[12:13]
	s_mov_b32 m0, s33
	s_nop 0
	global_load_lds_dwordx4 v[154:155], off
	s_waitcnt vmcnt(8)
	s_waitcnt lgkmcnt(0)
	s_barrier
	s_setprio 1
	s_waitcnt lgkmcnt(0)
	v_mfma_f32_16x16x32_bf16 v[62:65], v[164:167], v[202:205], v[62:65]
	v_mfma_f32_16x16x32_bf16 v[58:61], v[178:181], v[202:205], v[58:61]
	v_mfma_f32_16x16x32_bf16 v[42:45], v[178:181], v[210:213], v[42:45]
	v_mfma_f32_16x16x32_bf16 v[46:49], v[164:167], v[210:213], v[46:49]
	v_mfma_f32_16x16x32_bf16 v[30:33], v[164:167], v[218:221], v[30:33]
	v_mfma_f32_16x16x32_bf16 v[26:29], v[178:181], v[218:221], v[26:29]
	v_mfma_f32_16x16x32_bf16 v[10:13], v[178:181], v[226:229], v[10:13]
	v_mfma_f32_16x16x32_bf16 v[14:17], v[164:167], v[226:229], v[14:17]
	v_mfma_f32_16x16x32_bf16 v[62:65], v[174:177], v[206:209], v[62:65]
	v_mfma_f32_16x16x32_bf16 v[58:61], v[182:185], v[206:209], v[58:61]
	v_mfma_f32_16x16x32_bf16 v[42:45], v[182:185], v[214:217], v[42:45]
	v_mfma_f32_16x16x32_bf16 v[46:49], v[174:177], v[214:217], v[46:49]
	v_mfma_f32_16x16x32_bf16 v[30:33], v[174:177], v[222:225], v[30:33]
	v_mfma_f32_16x16x32_bf16 v[26:29], v[182:185], v[222:225], v[26:29]
	v_mfma_f32_16x16x32_bf16 v[10:13], v[182:185], v[230:233], v[10:13]
	v_mfma_f32_16x16x32_bf16 v[14:17], v[174:177], v[230:233], v[14:17]
	s_setprio 0
	s_setprio 1
	v_mfma_f32_16x16x32_bf16 v[54:57], v[186:189], v[202:205], v[54:57]
	v_mfma_f32_16x16x32_bf16 v[50:53], v[194:197], v[202:205], v[50:53]
	v_mfma_f32_16x16x32_bf16 v[34:37], v[194:197], v[210:213], v[34:37]
	v_mfma_f32_16x16x32_bf16 v[38:41], v[186:189], v[210:213], v[38:41]
	v_mfma_f32_16x16x32_bf16 v[22:25], v[186:189], v[218:221], v[22:25]
	v_mfma_f32_16x16x32_bf16 v[18:21], v[194:197], v[218:221], v[18:21]
	v_mfma_f32_16x16x32_bf16 v[2:5], v[194:197], v[226:229], v[2:5]
	v_mfma_f32_16x16x32_bf16 v[6:9], v[186:189], v[226:229], v[6:9]
	v_mfma_f32_16x16x32_bf16 v[54:57], v[190:193], v[206:209], v[54:57]
	v_mfma_f32_16x16x32_bf16 v[50:53], v[198:201], v[206:209], v[50:53]
	v_mfma_f32_16x16x32_bf16 v[34:37], v[198:201], v[214:217], v[34:37]
	v_mfma_f32_16x16x32_bf16 v[38:41], v[190:193], v[214:217], v[38:41]
	v_mfma_f32_16x16x32_bf16 v[22:25], v[190:193], v[222:225], v[22:25]
	v_mfma_f32_16x16x32_bf16 v[18:21], v[198:201], v[222:225], v[18:21]
	v_mfma_f32_16x16x32_bf16 v[2:5], v[198:201], v[230:233], v[2:5]
	v_mfma_f32_16x16x32_bf16 v[6:9], v[190:193], v[230:233], v[6:9]
	s_setprio 0
	s_barrier
	s_add_i32 s57, s57, 2
	s_add_u32 s24, s24, 0x100
	s_addc_u32 s25, s25, 0
	s_add_u32 s55, s55, 0x100
	s_addc_u32 s56, s56, 0
	s_cmp_gt_u32 s57, 13
.LBB0_989:
	ds_read_b128 v[164:167], v157
	ds_read_b128 v[174:177], v157 offset:1024
	ds_read_b128 v[178:181], v157 offset:2048
	ds_read_b128 v[182:185], v157 offset:3072
	ds_read_b128 v[186:189], v159
	ds_read_b128 v[190:193], v159 offset:1024
	ds_read_b128 v[194:197], v159 offset:2048
	ds_read_b128 v[198:201], v159 offset:3072
	s_add_u32 s26, s24, 0xfffc0080
	s_addc_u32 s27, s25, -1
	s_cmp_eq_u32 s57, 12
	s_cselect_b32 s29, s1, s27
	s_cselect_b32 s28, s5, s26
	s_cselect_b32 s27, s17, s56
	s_cselect_b32 s26, s19, s55
	v_lshl_add_u64 v[154:155], s[24:25], 0, v[144:145]
	s_add_i32 m0, s38, 0xc000
	ds_read_b128 v[202:205], v161
	ds_read_b128 v[206:209], v161 offset:1024
	ds_read_b128 v[210:213], v161 offset:2048
	ds_read_b128 v[214:217], v161 offset:3072
	ds_read_b128 v[218:221], v161 offset:4096
	ds_read_b128 v[222:225], v161 offset:5120
	ds_read_b128 v[226:229], v161 offset:6144
	ds_read_b128 v[230:233], v161 offset:7168
	global_load_lds_dwordx4 v[154:155], off
	v_lshl_add_u64 v[154:155], s[24:25], 0, v[146:147]
	s_add_i32 m0, s38, 0xe000
	s_nop 0
	global_load_lds_dwordx4 v[154:155], off
	s_waitcnt vmcnt(8)
	s_waitcnt lgkmcnt(0)
	s_barrier
; #define PG8_STAGE(bufoff, gbase, voff) do { _Pragma("unroll") for (int _i = 0; _i < 2; ++_i) \
;         __builtin_amdgcn_global_load_lds((const unsigned*)((const char*)(gbase) + (voff)[_i]), (PG8_LAS unsigned*)(lds + (bufoff) + ldsw + _i * 8192), 16, 0, 0); } while (0)
; #define PG8_LDA(dst, b, h) do { _Pragma("unroll") for (int m = 0; m < 4; ++m) _Pragma("unroll") for (int k = 0; k < 2; ++k) dst[m][k] = *(const PG8_LAS bf16x8*)(lds + PG8_SA(b, h) + aoff + m * 2048 + k * 1024); } while (0)
; #define PG8_MMA(ai, bj, At, Bt) do { __builtin_amdgcn_s_setprio(1); _Pragma("unroll") for (int m = 0; m < 4; ++m) _Pragma("unroll") for (int n = 0; n < 2; ++n) _Pragma("unroll") for (int k = 0; k < 2; ++k) \
;         acc[ai][bj][m][n] = __builtin_amdgcn_mfma_f32_16x16x32_bf16(Bt[n][k], At[m][k], acc[ai][bj][m][n], 0, 0, 0); __builtin_amdgcn_s_setprio(0); } while (0)
; #define PG8_WAIT_V(n) asm volatile("s_waitcnt vmcnt(" #n ")" ::: "memory")
; #define PG8_WAIT_L(n) asm volatile("s_waitcnt lgkmcnt(" #n ")" ::: "memory")
; #define PG8_BAR __builtin_amdgcn_s_barrier()
; #define PG8_SCHED __builtin_amdgcn_sched_barrier(0)
; template <class Epi, class Sched, bool ALIGN_EPI = false, bool SP2 = false>
; __device__ __forceinline__ void gemm_phase(PG8_LAS unsigned char* lds, const Gemm g, const Sched& S, const Epi& E) {
;     ...
;             PG8_WAIT_V(8); PG8_WAIT_L(0); PG8_BAR; PG8_MMA(0, 0, At, B0); PG8_MMA(0, 1, At, B1); PG8_BAR; PG8_SCHED;
;             PG8_LDA(At, 0, 1); PG8_STAGE(PG8_SB(0, 0), b2, voffB); PG8_STAGE(PG8_SB(0, 1), b2 + hstepB, voffB); PG8_STAGE(PG8_SA(0, 0), a2, voffA);
;             PG8_WAIT_V(8); PG8_WAIT_L(0); PG8_BAR; PG8_MMA(1, 0, At, B0); PG8_MMA(1, 1, At, B1); PG8_BAR; PG8_SCHED;
	s_setprio 1
	s_waitcnt lgkmcnt(0)
	v_mfma_f32_16x16x32_bf16 v[126:129], v[164:167], v[202:205], v[126:129]
	v_mfma_f32_16x16x32_bf16 v[122:125], v[178:181], v[202:205], v[122:125]
	v_mfma_f32_16x16x32_bf16 v[106:109], v[178:181], v[210:213], v[106:109]
	v_mfma_f32_16x16x32_bf16 v[110:113], v[164:167], v[210:213], v[110:113]
	v_mfma_f32_16x16x32_bf16 v[94:97], v[164:167], v[218:221], v[94:97]
	v_mfma_f32_16x16x32_bf16 v[90:93], v[178:181], v[218:221], v[90:93]
	v_mfma_f32_16x16x32_bf16 v[74:77], v[178:181], v[226:229], v[74:77]
	v_mfma_f32_16x16x32_bf16 v[78:81], v[164:167], v[226:229], v[78:81]
	v_mfma_f32_16x16x32_bf16 v[126:129], v[174:177], v[206:209], v[126:129]
	v_mfma_f32_16x16x32_bf16 v[122:125], v[182:185], v[206:209], v[122:125]
	v_mfma_f32_16x16x32_bf16 v[106:109], v[182:185], v[214:217], v[106:109]
	v_mfma_f32_16x16x32_bf16 v[110:113], v[174:177], v[214:217], v[110:113]
	v_mfma_f32_16x16x32_bf16 v[94:97], v[174:177], v[222:225], v[94:97]
	v_mfma_f32_16x16x32_bf16 v[90:93], v[182:185], v[222:225], v[90:93]
	v_mfma_f32_16x16x32_bf16 v[74:77], v[182:185], v[230:233], v[74:77]
	v_mfma_f32_16x16x32_bf16 v[78:81], v[174:177], v[230:233], v[78:81]
	s_setprio 0
	s_setprio 1
	v_mfma_f32_16x16x32_bf16 v[118:121], v[186:189], v[202:205], v[118:121]
	v_mfma_f32_16x16x32_bf16 v[114:117], v[194:197], v[202:205], v[114:117]
	v_mfma_f32_16x16x32_bf16 v[98:101], v[194:197], v[210:213], v[98:101]
	v_mfma_f32_16x16x32_bf16 v[102:105], v[186:189], v[210:213], v[102:105]
	v_mfma_f32_16x16x32_bf16 v[86:89], v[186:189], v[218:221], v[86:89]
	v_mfma_f32_16x16x32_bf16 v[82:85], v[194:197], v[218:221], v[82:85]
	v_mfma_f32_16x16x32_bf16 v[66:69], v[194:197], v[226:229], v[66:69]
	v_mfma_f32_16x16x32_bf16 v[70:73], v[186:189], v[226:229], v[70:73]
	v_mfma_f32_16x16x32_bf16 v[118:121], v[190:193], v[206:209], v[118:121]
	v_mfma_f32_16x16x32_bf16 v[114:117], v[198:201], v[206:209], v[114:117]
	v_mfma_f32_16x16x32_bf16 v[98:101], v[198:201], v[214:217], v[98:101]
	v_mfma_f32_16x16x32_bf16 v[102:105], v[190:193], v[214:217], v[102:105]
	v_mfma_f32_16x16x32_bf16 v[86:89], v[190:193], v[222:225], v[86:89]
	v_mfma_f32_16x16x32_bf16 v[82:85], v[198:201], v[222:225], v[82:85]
	v_mfma_f32_16x16x32_bf16 v[66:69], v[198:201], v[230:233], v[66:69]
	v_mfma_f32_16x16x32_bf16 v[70:73], v[190:193], v[230:233], v[70:73]
	s_setprio 0
	s_barrier
	s_add_i32 s58, s49, s35
	v_lshl_add_u64 v[154:155], s[26:27], 0, v[134:135]
	s_mov_b32 m0, s58
	ds_read_b128 v[202:205], v161 offset:16384
	ds_read_b128 v[206:209], v161 offset:17408
	ds_read_b128 v[210:213], v161 offset:18432
	ds_read_b128 v[214:217], v161 offset:19456
	ds_read_b128 v[218:221], v161 offset:20480
	ds_read_b128 v[222:225], v161 offset:21504
	ds_read_b128 v[226:229], v161 offset:22528
	ds_read_b128 v[230:233], v161 offset:23552
	global_load_lds_dwordx4 v[154:155], off
	s_add_i32 m0, s58, 0x2000
	s_add_u32 s58, s26, 0x40000
	v_lshl_add_u64 v[168:169], s[26:27], 0, v[130:131]
	s_addc_u32 s59, s27, 0
	s_add_i32 s60, s50, s35
	global_load_lds_dwordx4 v[168:169], off
	v_lshl_add_u64 v[234:235], s[58:59], 0, v[134:135]
	s_mov_b32 m0, s60
	v_lshl_add_u64 v[236:237], s[28:29], 0, v[132:133]
	global_load_lds_dwordx4 v[234:235], off
	v_lshl_add_u64 v[234:235], s[58:59], 0, v[130:131]
	s_add_i32 m0, s60, 0x2000
	s_nop 0
	global_load_lds_dwordx4 v[234:235], off
	v_lshl_add_u64 v[234:235], s[28:29], 0, v[136:137]
	s_mov_b32 m0, s38
	s_nop 0
	global_load_lds_dwordx4 v[234:235], off
	s_mov_b32 m0, s39
	s_nop 0
	global_load_lds_dwordx4 v[236:237], off
	s_waitcnt vmcnt(8)
	s_waitcnt lgkmcnt(0)
	s_barrier
	s_setprio 1
	s_waitcnt lgkmcnt(0)
	v_mfma_f32_16x16x32_bf16 v[62:65], v[164:167], v[202:205], v[62:65]
	v_mfma_f32_16x16x32_bf16 v[58:61], v[178:181], v[202:205], v[58:61]
	v_mfma_f32_16x16x32_bf16 v[42:45], v[178:181], v[210:213], v[42:45]
	v_mfma_f32_16x16x32_bf16 v[46:49], v[164:167], v[210:213], v[46:49]
	v_mfma_f32_16x16x32_bf16 v[30:33], v[164:167], v[218:221], v[30:33]
	v_mfma_f32_16x16x32_bf16 v[26:29], v[178:181], v[218:221], v[26:29]
	v_mfma_f32_16x16x32_bf16 v[10:13], v[178:181], v[226:229], v[10:13]
	v_mfma_f32_16x16x32_bf16 v[14:17], v[164:167], v[226:229], v[14:17]
	v_mfma_f32_16x16x32_bf16 v[62:65], v[174:177], v[206:209], v[62:65]
	v_mfma_f32_16x16x32_bf16 v[58:61], v[182:185], v[206:209], v[58:61]
	v_mfma_f32_16x16x32_bf16 v[42:45], v[182:185], v[214:217], v[42:45]
	v_mfma_f32_16x16x32_bf16 v[46:49], v[174:177], v[214:217], v[46:49]
	v_mfma_f32_16x16x32_bf16 v[30:33], v[174:177], v[222:225], v[30:33]
	v_mfma_f32_16x16x32_bf16 v[26:29], v[182:185], v[222:225], v[26:29]
	v_mfma_f32_16x16x32_bf16 v[10:13], v[182:185], v[230:233], v[10:13]
	v_mfma_f32_16x16x32_bf16 v[14:17], v[174:177], v[230:233], v[14:17]
	s_setprio 0
	s_setprio 1
	v_mfma_f32_16x16x32_bf16 v[54:57], v[186:189], v[202:205], v[54:57]
	v_mfma_f32_16x16x32_bf16 v[50:53], v[194:197], v[202:205], v[50:53]
	v_mfma_f32_16x16x32_bf16 v[34:37], v[194:197], v[210:213], v[34:37]
	v_mfma_f32_16x16x32_bf16 v[38:41], v[186:189], v[210:213], v[38:41]
	v_mfma_f32_16x16x32_bf16 v[22:25], v[186:189], v[218:221], v[22:25]
	v_mfma_f32_16x16x32_bf16 v[18:21], v[194:197], v[218:221], v[18:21]
	v_mfma_f32_16x16x32_bf16 v[2:5], v[194:197], v[226:229], v[2:5]
	v_mfma_f32_16x16x32_bf16 v[6:9], v[186:189], v[226:229], v[6:9]
	v_mfma_f32_16x16x32_bf16 v[54:57], v[190:193], v[206:209], v[54:57]
	v_mfma_f32_16x16x32_bf16 v[50:53], v[198:201], v[206:209], v[50:53]
	v_mfma_f32_16x16x32_bf16 v[34:37], v[198:201], v[214:217], v[34:37]
	v_mfma_f32_16x16x32_bf16 v[38:41], v[190:193], v[214:217], v[38:41]
	v_mfma_f32_16x16x32_bf16 v[22:25], v[190:193], v[222:225], v[22:25]
	v_mfma_f32_16x16x32_bf16 v[18:21], v[198:201], v[222:225], v[18:21]
	v_mfma_f32_16x16x32_bf16 v[2:5], v[198:201], v[230:233], v[2:5]
	v_mfma_f32_16x16x32_bf16 v[6:9], v[190:193], v[230:233], v[6:9]
	s_setprio 0
	s_barrier
; #define PG8_STAGE(bufoff, gbase, voff) do { _Pragma("unroll") for (int _i = 0; _i < 2; ++_i) \
;         __builtin_amdgcn_global_load_lds((const unsigned*)((const char*)(gbase) + (voff)[_i]), (PG8_LAS unsigned*)(lds + (bufoff) + ldsw + _i * 8192), 16, 0, 0); } while (0)
; #define PG8_LDA(dst, b, h) do { _Pragma("unroll") for (int m = 0; m < 4; ++m) _Pragma("unroll") for (int k = 0; k < 2; ++k) dst[m][k] = *(const PG8_LAS bf16x8*)(lds + PG8_SA(b, h) + aoff + m * 2048 + k * 1024); } while (0)
; #define PG8_LDB(dst, b, h) do { _Pragma("unroll") for (int n = 0; n < 2; ++n) _Pragma("unroll") for (int k = 0; k < 2; ++k) dst[n][k] = *(const PG8_LAS bf16x8*)(lds + PG8_SB(b, h) + boff + n * 2048 + k * 1024); } while (0)
; #define PG8_MMA(ai, bj, At, Bt) do { __builtin_amdgcn_s_setprio(1); _Pragma("unroll") for (int m = 0; m < 4; ++m) _Pragma("unroll") for (int n = 0; n < 2; ++n) _Pragma("unroll") for (int k = 0; k < 2; ++k) \
;         acc[ai][bj][m][n] = __builtin_amdgcn_mfma_f32_16x16x32_bf16(Bt[n][k], At[m][k], acc[ai][bj][m][n], 0, 0, 0); __builtin_amdgcn_s_setprio(0); } while (0)
; #define PG8_WAIT_V(n) asm volatile("s_waitcnt vmcnt(" #n ")" ::: "memory")
; #define PG8_WAIT_L(n) asm volatile("s_waitcnt lgkmcnt(" #n ")" ::: "memory")
; #define PG8_BAR __builtin_amdgcn_s_barrier()
; #define PG8_SCHED __builtin_amdgcn_sched_barrier(0)
; template <class Epi, class Sched, bool ALIGN_EPI = false, bool SP2 = false>
; __device__ __forceinline__ void gemm_phase(PG8_LAS unsigned char* lds, const Gemm g, const Sched& S, const Epi& E) {
;     ...
;             PG8_LDB(B0, 1, 0); PG8_LDB(B1, 1, 1); PG8_SCHED; PG8_LDA(At, 1, 0); PG8_STAGE(PG8_SA(0, 1), a2 + hstepA, voffA);
;             PG8_WAIT_V(8); PG8_WAIT_L(0); PG8_BAR; PG8_MMA(0, 0, At, B0); PG8_MMA(0, 1, At, B1); PG8_BAR; PG8_SCHED;
	s_add_i32 s58, 0, 0x18000
	v_add_u32_e32 v138, s58, v141
	s_add_i32 s59, 0, 0x1c000
	ds_read_b128 v[164:167], v138
	ds_read_b128 v[174:177], v138 offset:1024
	ds_read_b128 v[178:181], v138 offset:2048
	ds_read_b128 v[182:185], v138 offset:3072
	v_add_u32_e32 v138, s59, v141
	ds_read_b128 v[186:189], v138
	ds_read_b128 v[190:193], v138 offset:1024
	ds_read_b128 v[194:197], v138 offset:2048
	ds_read_b128 v[198:201], v138 offset:3072
	s_add_u32 s28, s28, 0x40000
	s_addc_u32 s29, s29, 0
	s_mov_b32 m0, s40
	v_lshl_add_u64 v[238:239], s[28:29], 0, v[136:137]
	ds_read_b128 v[202:205], v161 offset:32768
	ds_read_b128 v[206:209], v161 offset:33792
	ds_read_b128 v[210:213], v161 offset:34816
	ds_read_b128 v[214:217], v161 offset:35840
	ds_read_b128 v[218:221], v161 offset:36864
	ds_read_b128 v[222:225], v161 offset:37888
	ds_read_b128 v[226:229], v161 offset:38912
	ds_read_b128 v[230:233], v161 offset:39936
	global_load_lds_dwordx4 v[238:239], off
	v_lshl_add_u64 v[238:239], s[28:29], 0, v[132:133]
	s_mov_b32 m0, s41
	s_nop 0
	global_load_lds_dwordx4 v[238:239], off
	s_waitcnt vmcnt(8)
	s_waitcnt lgkmcnt(0)
	s_barrier
	s_setprio 1
	s_waitcnt lgkmcnt(0)
	v_mfma_f32_16x16x32_bf16 v[126:129], v[164:167], v[202:205], v[126:129]
	v_mfma_f32_16x16x32_bf16 v[122:125], v[178:181], v[202:205], v[122:125]
	v_mfma_f32_16x16x32_bf16 v[106:109], v[178:181], v[210:213], v[106:109]
	v_mfma_f32_16x16x32_bf16 v[110:113], v[164:167], v[210:213], v[110:113]
	v_mfma_f32_16x16x32_bf16 v[94:97], v[164:167], v[218:221], v[94:97]
	v_mfma_f32_16x16x32_bf16 v[90:93], v[178:181], v[218:221], v[90:93]
	v_mfma_f32_16x16x32_bf16 v[74:77], v[178:181], v[226:229], v[74:77]
	v_mfma_f32_16x16x32_bf16 v[78:81], v[164:167], v[226:229], v[78:81]
	v_mfma_f32_16x16x32_bf16 v[126:129], v[174:177], v[206:209], v[126:129]
	v_mfma_f32_16x16x32_bf16 v[122:125], v[182:185], v[206:209], v[122:125]
	v_mfma_f32_16x16x32_bf16 v[106:109], v[182:185], v[214:217], v[106:109]
	v_mfma_f32_16x16x32_bf16 v[110:113], v[174:177], v[214:217], v[110:113]
	v_mfma_f32_16x16x32_bf16 v[94:97], v[174:177], v[222:225], v[94:97]
	v_mfma_f32_16x16x32_bf16 v[90:93], v[182:185], v[222:225], v[90:93]
	v_mfma_f32_16x16x32_bf16 v[74:77], v[182:185], v[230:233], v[74:77]
	v_mfma_f32_16x16x32_bf16 v[78:81], v[174:177], v[230:233], v[78:81]
	s_setprio 0
	s_setprio 1
	v_mfma_f32_16x16x32_bf16 v[118:121], v[186:189], v[202:205], v[118:121]
	v_mfma_f32_16x16x32_bf16 v[114:117], v[194:197], v[202:205], v[114:117]
	v_mfma_f32_16x16x32_bf16 v[98:101], v[194:197], v[210:213], v[98:101]
	v_mfma_f32_16x16x32_bf16 v[102:105], v[186:189], v[210:213], v[102:105]
	v_mfma_f32_16x16x32_bf16 v[86:89], v[186:189], v[218:221], v[86:89]
	v_mfma_f32_16x16x32_bf16 v[82:85], v[194:197], v[218:221], v[82:85]
	v_mfma_f32_16x16x32_bf16 v[66:69], v[194:197], v[226:229], v[66:69]
	v_mfma_f32_16x16x32_bf16 v[70:73], v[186:189], v[226:229], v[70:73]
	v_mfma_f32_16x16x32_bf16 v[118:121], v[190:193], v[206:209], v[118:121]
	v_mfma_f32_16x16x32_bf16 v[114:117], v[198:201], v[206:209], v[114:117]
	v_mfma_f32_16x16x32_bf16 v[98:101], v[198:201], v[214:217], v[98:101]
	v_mfma_f32_16x16x32_bf16 v[102:105], v[190:193], v[214:217], v[102:105]
	v_mfma_f32_16x16x32_bf16 v[86:89], v[190:193], v[222:225], v[86:89]
	v_mfma_f32_16x16x32_bf16 v[82:85], v[198:201], v[222:225], v[82:85]
	v_mfma_f32_16x16x32_bf16 v[66:69], v[198:201], v[230:233], v[66:69]
	v_mfma_f32_16x16x32_bf16 v[70:73], v[190:193], v[230:233], v[70:73]
	s_setprio 0
	s_barrier
; #define PG8_STAGE(bufoff, gbase, voff) do { _Pragma("unroll") for (int _i = 0; _i < 2; ++_i) \
;         __builtin_amdgcn_global_load_lds((const unsigned*)((const char*)(gbase) + (voff)[_i]), (PG8_LAS unsigned*)(lds + (bufoff) + ldsw + _i * 8192), 16, 0, 0); } while (0)
; #define PG8_LDA(dst, b, h) do { _Pragma("unroll") for (int m = 0; m < 4; ++m) _Pragma("unroll") for (int k = 0; k < 2; ++k) dst[m][k] = *(const PG8_LAS bf16x8*)(lds + PG8_SA(b, h) + aoff + m * 2048 + k * 1024); } while (0)
; #define PG8_MMA(ai, bj, At, Bt) do { __builtin_amdgcn_s_setprio(1); _Pragma("unroll") for (int m = 0; m < 4; ++m) _Pragma("unroll") for (int n = 0; n < 2; ++n) _Pragma("unroll") for (int k = 0; k < 2; ++k) \
;         acc[ai][bj][m][n] = __builtin_amdgcn_mfma_f32_16x16x32_bf16(Bt[n][k], At[m][k], acc[ai][bj][m][n], 0, 0, 0); __builtin_amdgcn_s_setprio(0); } while (0)
; #define PG8_WAIT_V(n) asm volatile("s_waitcnt vmcnt(" #n ")" ::: "memory")
; #define PG8_WAIT_L(n) asm volatile("s_waitcnt lgkmcnt(" #n ")" ::: "memory")
; #define PG8_BAR __builtin_amdgcn_s_barrier()
; #define PG8_SCHED __builtin_amdgcn_sched_barrier(0)
; template <class Epi, class Sched, bool ALIGN_EPI = false, bool SP2 = false>
; __device__ __forceinline__ void gemm_phase(PG8_LAS unsigned char* lds, const Gemm g, const Sched& S, const Epi& E) {
;     ...
;             PG8_LDA(At, 1, 1); PG8_STAGE(PG8_SB(1, 0), b3, voffB); PG8_STAGE(PG8_SB(1, 1), b3 + hstepB, voffB); PG8_STAGE(PG8_SA(1, 0), a3, voffA);
;             PG8_WAIT_V(8); PG8_WAIT_L(0); PG8_BAR; PG8_MMA(1, 0, At, B0); PG8_MMA(1, 1, At, B1); PG8_BAR; PG8_SCHED;
;     ...
;         }
;         if constexpr (ALIGN_EPI) { if (wr == 0) PG8_BAR; }
	s_add_i32 s28, s58, s35
	v_lshl_add_u64 v[154:155], v[154:155], 0, s[12:13]
	s_mov_b32 m0, s28
	ds_read_b128 v[202:205], v161 offset:49152
	ds_read_b128 v[206:209], v161 offset:50176
	ds_read_b128 v[210:213], v161 offset:51200
	ds_read_b128 v[214:217], v161 offset:52224
	ds_read_b128 v[218:221], v161 offset:53248
	ds_read_b128 v[222:225], v161 offset:54272
	ds_read_b128 v[226:229], v161 offset:55296
	ds_read_b128 v[230:233], v161 offset:56320
	global_load_lds_dwordx4 v[154:155], off
	s_add_i32 m0, s28, 0x2000
	s_add_u32 s26, s26, 0x40080
	v_lshl_add_u64 v[154:155], v[168:169], 0, s[12:13]
	s_addc_u32 s27, s27, 0
	s_add_i32 s28, s59, s35
	global_load_lds_dwordx4 v[154:155], off
	v_lshl_add_u64 v[154:155], s[26:27], 0, v[134:135]
	s_mov_b32 m0, s28
	s_nop 0
	global_load_lds_dwordx4 v[154:155], off
	v_lshl_add_u64 v[154:155], s[26:27], 0, v[130:131]
	s_add_i32 m0, s28, 0x2000
	s_nop 0
	global_load_lds_dwordx4 v[154:155], off
	v_lshl_add_u64 v[154:155], v[234:235], 0, s[12:13]
	s_mov_b32 m0, s2
	s_nop 0
	global_load_lds_dwordx4 v[154:155], off
	v_lshl_add_u64 v[154:155], v[236:237], 0, s[12:13]
	s_mov_b32 m0, s33
	s_nop 0
	global_load_lds_dwordx4 v[154:155], off
	s_waitcnt vmcnt(8)
	s_waitcnt lgkmcnt(0)
	s_barrier
	s_setprio 1
	s_waitcnt lgkmcnt(0)
	v_mfma_f32_16x16x32_bf16 v[62:65], v[164:167], v[202:205], v[62:65]
	v_mfma_f32_16x16x32_bf16 v[58:61], v[178:181], v[202:205], v[58:61]
	v_mfma_f32_16x16x32_bf16 v[42:45], v[178:181], v[210:213], v[42:45]
	v_mfma_f32_16x16x32_bf16 v[46:49], v[164:167], v[210:213], v[46:49]
	v_mfma_f32_16x16x32_bf16 v[30:33], v[164:167], v[218:221], v[30:33]
	v_mfma_f32_16x16x32_bf16 v[26:29], v[178:181], v[218:221], v[26:29]
	v_mfma_f32_16x16x32_bf16 v[10:13], v[178:181], v[226:229], v[10:13]
	v_mfma_f32_16x16x32_bf16 v[14:17], v[164:167], v[226:229], v[14:17]
	v_mfma_f32_16x16x32_bf16 v[62:65], v[174:177], v[206:209], v[62:65]
	v_mfma_f32_16x16x32_bf16 v[58:61], v[182:185], v[206:209], v[58:61]
	v_mfma_f32_16x16x32_bf16 v[42:45], v[182:185], v[214:217], v[42:45]
	v_mfma_f32_16x16x32_bf16 v[46:49], v[174:177], v[214:217], v[46:49]
	v_mfma_f32_16x16x32_bf16 v[30:33], v[174:177], v[222:225], v[30:33]
	v_mfma_f32_16x16x32_bf16 v[26:29], v[182:185], v[222:225], v[26:29]
	v_mfma_f32_16x16x32_bf16 v[10:13], v[182:185], v[230:233], v[10:13]
	v_mfma_f32_16x16x32_bf16 v[14:17], v[174:177], v[230:233], v[14:17]
	s_setprio 0
	s_setprio 1
	v_mfma_f32_16x16x32_bf16 v[54:57], v[186:189], v[202:205], v[54:57]
	v_mfma_f32_16x16x32_bf16 v[50:53], v[194:197], v[202:205], v[50:53]
	v_mfma_f32_16x16x32_bf16 v[34:37], v[194:197], v[210:213], v[34:37]
	v_mfma_f32_16x16x32_bf16 v[38:41], v[186:189], v[210:213], v[38:41]
	v_mfma_f32_16x16x32_bf16 v[22:25], v[186:189], v[218:221], v[22:25]
	v_mfma_f32_16x16x32_bf16 v[18:21], v[194:197], v[218:221], v[18:21]
	v_mfma_f32_16x16x32_bf16 v[2:5], v[194:197], v[226:229], v[2:5]
	v_mfma_f32_16x16x32_bf16 v[6:9], v[186:189], v[226:229], v[6:9]
	v_mfma_f32_16x16x32_bf16 v[54:57], v[190:193], v[206:209], v[54:57]
	v_mfma_f32_16x16x32_bf16 v[50:53], v[198:201], v[206:209], v[50:53]
	v_mfma_f32_16x16x32_bf16 v[34:37], v[198:201], v[214:217], v[34:37]
	v_mfma_f32_16x16x32_bf16 v[38:41], v[190:193], v[214:217], v[38:41]
	v_mfma_f32_16x16x32_bf16 v[22:25], v[190:193], v[222:225], v[22:25]
	v_mfma_f32_16x16x32_bf16 v[18:21], v[198:201], v[222:225], v[18:21]
	v_mfma_f32_16x16x32_bf16 v[2:5], v[198:201], v[230:233], v[2:5]
	v_mfma_f32_16x16x32_bf16 v[6:9], v[190:193], v[230:233], v[6:9]
	s_setprio 0
	s_barrier
	s_add_i32 s57, s57, 2
	s_add_u32 s24, s24, 0x100
	s_addc_u32 s25, s25, 0
	s_add_u32 s55, s55, 0x100
	s_addc_u32 s56, s56, 0
	s_cmp_gt_u32 s57, 13
	s_cbranch_scc0 .LBB0_989
	s_and_b64 vcc, exec, s[14:15]
	s_cbranch_vccz .LBB0_992
	s_barrier

; #define PG8_STAGE(bufoff, gbase, voff) do { _Pragma("unroll") for (int _i = 0; _i < 2; ++_i) \
;         __builtin_amdgcn_global_load_lds((const unsigned*)((const char*)(gbase) + (voff)[_i]), (PG8_LAS unsigned*)(lds + (bufoff) + ldsw + _i * 8192), 16, 0, 0); } while (0)
; #define PG8_LDA(dst, b, h) do { _Pragma("unroll") for (int m = 0; m < 4; ++m) _Pragma("unroll") for (int k = 0; k < 2; ++k) dst[m][k] = *(const PG8_LAS bf16x8*)(lds + PG8_SA(b, h) + aoff + m * 2048 + k * 1024); } while (0)
; #define PG8_LDB(dst, b, h) do { _Pragma("unroll") for (int n = 0; n < 2; ++n) _Pragma("unroll") for (int k = 0; k < 2; ++k) dst[n][k] = *(const PG8_LAS bf16x8*)(lds + PG8_SB(b, h) + boff + n * 2048 + k * 1024); } while (0)
; #define PG8_MMA(ai, bj, At, Bt) do { __builtin_amdgcn_s_setprio(1); _Pragma("unroll") for (int m = 0; m < 4; ++m) _Pragma("unroll") for (int n = 0; n < 2; ++n) _Pragma("unroll") for (int k = 0; k < 2; ++k) \
;         acc[ai][bj][m][n] = __builtin_amdgcn_mfma_f32_16x16x32_bf16(Bt[n][k], At[m][k], acc[ai][bj][m][n], 0, 0, 0); __builtin_amdgcn_s_setprio(0); } while (0)
; #define PG8_WAIT_V(n) asm volatile("s_waitcnt vmcnt(" #n ")" ::: "memory")
; #define PG8_WAIT_L(n) asm volatile("s_waitcnt lgkmcnt(" #n ")" ::: "memory")
; #define PG8_BAR __builtin_amdgcn_s_barrier()
; #define PG8_SCHED __builtin_amdgcn_sched_barrier(0)
; template <class Epi, class Sched, bool ALIGN_EPI = false, bool SP2 = false>
; __device__ __forceinline__ void gemm_phase(PG8_LAS unsigned char* lds, const Gemm g, const Sched& S, const Epi& E) {
;     ...
;         const bool has_next = S.next(ui + 1, nxt);
;         const char* nA = has_next ? (const char*)g.A + (size_t)nxt.g * g.gsA * 2 + (size_t)nxt.pm * tstepA : cA; const char* nB = has_next ? (const char*)g.Bt + (size_t)nxt.g * g.gsB * 2 + (size_t)nxt.pn * tstepB : cB;
;     ...
;             PG8_LDB(B0, 0, 0); PG8_LDB(B1, 0, 1); PG8_SCHED; PG8_LDA(At, 0, 0); PG8_STAGE(PG8_SA(1, 1), a1 + hstepA, voffA);
;             PG8_WAIT_V(8); PG8_WAIT_L(0); PG8_BAR; PG8_MMA(0, 0, At, B0); PG8_MMA(0, 1, At, B1); PG8_BAR; PG8_SCHED;
;             PG8_LDA(At, 0, 1); PG8_STAGE(PG8_SB(0, 0), b2, voffB); PG8_STAGE(PG8_SB(0, 1), b2 + hstepB, voffB); PG8_STAGE(PG8_SA(0, 0), a2, voffA);
;             PG8_WAIT_V(8); PG8_WAIT_L(0); PG8_BAR; PG8_MMA(1, 0, At, B0); PG8_MMA(1, 1, At, B1); PG8_BAR; PG8_SCHED;
.LBB0_1466:
	s_ashr_i32 s23, s22, 31
	s_lshl_b64 s[24:25], s[22:23], 19
	s_add_u32 s24, s2, s24
	s_addc_u32 s25, s3, s25
	s_and_b64 s[26:27], s[8:9], exec
	s_cselect_b32 s23, s25, s31
	s_cselect_b32 s29, s24, s30
	s_ashr_i32 s21, s20, 31
	s_lshl_b64 s[26:27], s[20:21], 19
	s_add_u32 s26, s33, s26
	s_addc_u32 s27, s38, s27
	s_and_b64 s[36:37], s[8:9], exec
	s_cselect_b32 s21, s27, s35
	s_cselect_b32 s51, s26, s34
	s_add_u32 s30, s30, 0x40080
	s_addc_u32 s31, s31, 0
	s_add_u32 s52, s34, 0x100
	s_addc_u32 s53, s35, 0
	s_mov_b32 s54, -2
	s_waitcnt lgkmcnt(0)
	ds_read_b128 v[130:133], v164
	ds_read_b128 v[134:137], v164 offset:1024
	ds_read_b128 v[154:157], v164 offset:2048
	ds_read_b128 v[158:161], v164 offset:3072
	ds_read_b128 v[168:171], v165
	ds_read_b128 v[172:175], v165 offset:1024
	ds_read_b128 v[176:179], v165 offset:2048
	ds_read_b128 v[180:183], v165 offset:3072
	s_add_u32 s34, s30, 0xfffc0080
	s_addc_u32 s35, s31, -1
	s_cmp_eq_u32 s54, 12
	s_cselect_b32 s37, s23, s35
	s_cselect_b32 s36, s29, s34
	s_cselect_b32 s35, s21, s53
	s_cselect_b32 s34, s51, s52
	v_lshl_add_u64 v[216:217], s[30:31], 0, v[146:147]
	s_add_i32 m0, s1, 0xc000
	ds_read_b128 v[184:187], v166
	ds_read_b128 v[188:191], v166 offset:1024
	ds_read_b128 v[192:195], v166 offset:2048
	ds_read_b128 v[196:199], v166 offset:3072
	ds_read_b128 v[200:203], v166 offset:4096
	ds_read_b128 v[204:207], v166 offset:5120
	ds_read_b128 v[208:211], v166 offset:6144
	ds_read_b128 v[212:215], v166 offset:7168
	global_load_lds_dwordx4 v[216:217], off
	v_lshl_add_u64 v[216:217], s[30:31], 0, v[148:149]
	s_add_i32 m0, s1, 0xe000
	s_nop 0
	global_load_lds_dwordx4 v[216:217], off
	s_waitcnt vmcnt(8)
	s_waitcnt lgkmcnt(0)
	s_barrier
	s_setprio 1
	s_waitcnt lgkmcnt(0)
	v_mfma_f32_16x16x32_bf16 v[126:129], v[130:133], v[184:187], 0
	v_mfma_f32_16x16x32_bf16 v[122:125], v[154:157], v[184:187], 0
	v_mfma_f32_16x16x32_bf16 v[106:109], v[154:157], v[192:195], 0
	v_mfma_f32_16x16x32_bf16 v[110:113], v[130:133], v[192:195], 0
	v_mfma_f32_16x16x32_bf16 v[94:97], v[130:133], v[200:203], 0
	v_mfma_f32_16x16x32_bf16 v[90:93], v[154:157], v[200:203], 0
	v_mfma_f32_16x16x32_bf16 v[74:77], v[154:157], v[208:211], 0
	v_mfma_f32_16x16x32_bf16 v[78:81], v[130:133], v[208:211], 0
	v_mfma_f32_16x16x32_bf16 v[126:129], v[134:137], v[188:191], v[126:129]
	v_mfma_f32_16x16x32_bf16 v[122:125], v[158:161], v[188:191], v[122:125]
	v_mfma_f32_16x16x32_bf16 v[106:109], v[158:161], v[196:199], v[106:109]
	v_mfma_f32_16x16x32_bf16 v[110:113], v[134:137], v[196:199], v[110:113]
	v_mfma_f32_16x16x32_bf16 v[94:97], v[134:137], v[204:207], v[94:97]
	v_mfma_f32_16x16x32_bf16 v[90:93], v[158:161], v[204:207], v[90:93]
	v_mfma_f32_16x16x32_bf16 v[74:77], v[158:161], v[212:215], v[74:77]
	v_mfma_f32_16x16x32_bf16 v[78:81], v[134:137], v[212:215], v[78:81]
	s_setprio 0
	s_setprio 1
	v_mfma_f32_16x16x32_bf16 v[118:121], v[168:171], v[184:187], 0
	v_mfma_f32_16x16x32_bf16 v[114:117], v[176:179], v[184:187], 0
	v_mfma_f32_16x16x32_bf16 v[98:101], v[176:179], v[192:195], 0
	v_mfma_f32_16x16x32_bf16 v[102:105], v[168:171], v[192:195], 0
	v_mfma_f32_16x16x32_bf16 v[86:89], v[168:171], v[200:203], 0
	v_mfma_f32_16x16x32_bf16 v[82:85], v[176:179], v[200:203], 0
	v_mfma_f32_16x16x32_bf16 v[66:69], v[176:179], v[208:211], 0
	v_mfma_f32_16x16x32_bf16 v[70:73], v[168:171], v[208:211], 0
	v_mfma_f32_16x16x32_bf16 v[118:121], v[172:175], v[188:191], v[118:121]
	v_mfma_f32_16x16x32_bf16 v[114:117], v[180:183], v[188:191], v[114:117]
	v_mfma_f32_16x16x32_bf16 v[98:101], v[180:183], v[196:199], v[98:101]
	v_mfma_f32_16x16x32_bf16 v[102:105], v[172:175], v[196:199], v[102:105]
	v_mfma_f32_16x16x32_bf16 v[86:89], v[172:175], v[204:207], v[86:89]
	v_mfma_f32_16x16x32_bf16 v[82:85], v[180:183], v[204:207], v[82:85]
	v_mfma_f32_16x16x32_bf16 v[66:69], v[180:183], v[212:215], v[66:69]
	v_mfma_f32_16x16x32_bf16 v[70:73], v[172:175], v[212:215], v[70:73]
	s_setprio 0
	s_barrier
	s_add_i32 s55, s48, s0
	v_lshl_add_u64 v[216:217], s[34:35], 0, v[140:141]
	s_mov_b32 m0, s55
	ds_read_b128 v[184:187], v166 offset:16384
	ds_read_b128 v[188:191], v166 offset:17408
	ds_read_b128 v[192:195], v166 offset:18432
	ds_read_b128 v[196:199], v166 offset:19456
	ds_read_b128 v[200:203], v166 offset:20480
	ds_read_b128 v[204:207], v166 offset:21504
	ds_read_b128 v[208:211], v166 offset:22528
	ds_read_b128 v[212:215], v166 offset:23552
	global_load_lds_dwordx4 v[216:217], off
	s_add_i32 m0, s55, 0x2000
	s_add_u32 s56, s34, 0x40000
	v_lshl_add_u64 v[218:219], s[34:35], 0, v[144:145]
	s_addc_u32 s57, s35, 0
	s_add_i32 s55, s49, s0
	global_load_lds_dwordx4 v[218:219], off
	v_lshl_add_u64 v[220:221], s[56:57], 0, v[140:141]
	s_mov_b32 m0, s55
	v_lshl_add_u64 v[222:223], s[36:37], 0, v[142:143]
	global_load_lds_dwordx4 v[220:221], off
	v_lshl_add_u64 v[220:221], s[56:57], 0, v[144:145]
	s_add_i32 m0, s55, 0x2000
	s_nop 0
	global_load_lds_dwordx4 v[220:221], off
	v_lshl_add_u64 v[220:221], s[36:37], 0, v[138:139]
	s_mov_b32 m0, s1
	s_nop 0
	global_load_lds_dwordx4 v[220:221], off
	s_mov_b32 m0, s39
	s_nop 0
	global_load_lds_dwordx4 v[222:223], off
	s_waitcnt vmcnt(8)
	s_waitcnt lgkmcnt(0)
	s_barrier
; #define PG8_STAGE(bufoff, gbase, voff) do { _Pragma("unroll") for (int _i = 0; _i < 2; ++_i) \
;         __builtin_amdgcn_global_load_lds((const unsigned*)((const char*)(gbase) + (voff)[_i]), (PG8_LAS unsigned*)(lds + (bufoff) + ldsw + _i * 8192), 16, 0, 0); } while (0)
; #define PG8_LDA(dst, b, h) do { _Pragma("unroll") for (int m = 0; m < 4; ++m) _Pragma("unroll") for (int k = 0; k < 2; ++k) dst[m][k] = *(const PG8_LAS bf16x8*)(lds + PG8_SA(b, h) + aoff + m * 2048 + k * 1024); } while (0)
; #define PG8_LDB(dst, b, h) do { _Pragma("unroll") for (int n = 0; n < 2; ++n) _Pragma("unroll") for (int k = 0; k < 2; ++k) dst[n][k] = *(const PG8_LAS bf16x8*)(lds + PG8_SB(b, h) + boff + n * 2048 + k * 1024); } while (0)
; #define PG8_MMA(ai, bj, At, Bt) do { __builtin_amdgcn_s_setprio(1); _Pragma("unroll") for (int m = 0; m < 4; ++m) _Pragma("unroll") for (int n = 0; n < 2; ++n) _Pragma("unroll") for (int k = 0; k < 2; ++k) \
;         acc[ai][bj][m][n] = __builtin_amdgcn_mfma_f32_16x16x32_bf16(Bt[n][k], At[m][k], acc[ai][bj][m][n], 0, 0, 0); __builtin_amdgcn_s_setprio(0); } while (0)
; #define PG8_WAIT_V(n) asm volatile("s_waitcnt vmcnt(" #n ")" ::: "memory")
; #define PG8_WAIT_L(n) asm volatile("s_waitcnt lgkmcnt(" #n ")" ::: "memory")
; #define PG8_BAR __builtin_amdgcn_s_barrier()
; #define PG8_SCHED __builtin_amdgcn_sched_barrier(0)
; template <class Epi, class Sched, bool ALIGN_EPI = false, bool SP2 = false>
; __device__ __forceinline__ void gemm_phase(PG8_LAS unsigned char* lds, const Gemm g, const Sched& S, const Epi& E) {
;     ...
;             PG8_WAIT_V(8); PG8_WAIT_L(0); PG8_BAR; PG8_MMA(1, 0, At, B0); PG8_MMA(1, 1, At, B1); PG8_BAR; PG8_SCHED;
;             PG8_LDB(B0, 1, 0); PG8_LDB(B1, 1, 1); PG8_SCHED; PG8_LDA(At, 1, 0); PG8_STAGE(PG8_SA(0, 1), a2 + hstepA, voffA);
;             PG8_WAIT_V(8); PG8_WAIT_L(0); PG8_BAR; PG8_MMA(0, 0, At, B0); PG8_MMA(0, 1, At, B1); PG8_BAR; PG8_SCHED;
	s_setprio 1
	s_waitcnt lgkmcnt(0)
	v_mfma_f32_16x16x32_bf16 v[62:65], v[130:133], v[184:187], 0
	v_mfma_f32_16x16x32_bf16 v[58:61], v[154:157], v[184:187], 0
	v_mfma_f32_16x16x32_bf16 v[42:45], v[154:157], v[192:195], 0
	v_mfma_f32_16x16x32_bf16 v[46:49], v[130:133], v[192:195], 0
	v_mfma_f32_16x16x32_bf16 v[30:33], v[130:133], v[200:203], 0
	v_mfma_f32_16x16x32_bf16 v[26:29], v[154:157], v[200:203], 0
	v_mfma_f32_16x16x32_bf16 v[10:13], v[154:157], v[208:211], 0
	v_mfma_f32_16x16x32_bf16 v[14:17], v[130:133], v[208:211], 0
	v_mfma_f32_16x16x32_bf16 v[62:65], v[134:137], v[188:191], v[62:65]
	v_mfma_f32_16x16x32_bf16 v[58:61], v[158:161], v[188:191], v[58:61]
	v_mfma_f32_16x16x32_bf16 v[42:45], v[158:161], v[196:199], v[42:45]
	v_mfma_f32_16x16x32_bf16 v[46:49], v[134:137], v[196:199], v[46:49]
	v_mfma_f32_16x16x32_bf16 v[30:33], v[134:137], v[204:207], v[30:33]
	v_mfma_f32_16x16x32_bf16 v[26:29], v[158:161], v[204:207], v[26:29]
	v_mfma_f32_16x16x32_bf16 v[10:13], v[158:161], v[212:215], v[10:13]
	v_mfma_f32_16x16x32_bf16 v[14:17], v[134:137], v[212:215], v[14:17]
	s_setprio 0
	s_setprio 1
	v_mfma_f32_16x16x32_bf16 v[54:57], v[168:171], v[184:187], 0
	v_mfma_f32_16x16x32_bf16 v[50:53], v[176:179], v[184:187], 0
	v_mfma_f32_16x16x32_bf16 v[34:37], v[176:179], v[192:195], 0
	v_mfma_f32_16x16x32_bf16 v[38:41], v[168:171], v[192:195], 0
	v_mfma_f32_16x16x32_bf16 v[22:25], v[168:171], v[200:203], 0
	v_mfma_f32_16x16x32_bf16 v[18:21], v[176:179], v[200:203], 0
	v_mfma_f32_16x16x32_bf16 v[2:5], v[176:179], v[208:211], 0
	v_mfma_f32_16x16x32_bf16 v[6:9], v[168:171], v[208:211], 0
	v_mfma_f32_16x16x32_bf16 v[54:57], v[172:175], v[188:191], v[54:57]
	v_mfma_f32_16x16x32_bf16 v[50:53], v[180:183], v[188:191], v[50:53]
	v_mfma_f32_16x16x32_bf16 v[34:37], v[180:183], v[196:199], v[34:37]
	v_mfma_f32_16x16x32_bf16 v[38:41], v[172:175], v[196:199], v[38:41]
	v_mfma_f32_16x16x32_bf16 v[22:25], v[172:175], v[204:207], v[22:25]
	v_mfma_f32_16x16x32_bf16 v[18:21], v[180:183], v[204:207], v[18:21]
	v_mfma_f32_16x16x32_bf16 v[2:5], v[180:183], v[212:215], v[2:5]
	v_mfma_f32_16x16x32_bf16 v[6:9], v[172:175], v[212:215], v[6:9]
	s_setprio 0
	s_barrier
	s_add_i32 s55, 0, 0x18000
	s_add_i32 s56, 0, 0x1c000
	v_add_u32_e32 v158, s55, v162
	v_add_u32_e32 v180, s56, v162
	ds_read_b128 v[130:133], v158
	ds_read_b128 v[134:137], v158 offset:1024
	ds_read_b128 v[154:157], v158 offset:2048
	ds_read_b128 v[158:161], v158 offset:3072
	ds_read_b128 v[168:171], v180
	ds_read_b128 v[172:175], v180 offset:1024
	ds_read_b128 v[176:179], v180 offset:2048
	ds_read_b128 v[180:183], v180 offset:3072
	s_add_u32 s36, s36, 0x40000
	s_addc_u32 s37, s37, 0
	s_mov_b32 m0, s40
	v_lshl_add_u64 v[224:225], s[36:37], 0, v[138:139]
	ds_read_b128 v[184:187], v166 offset:32768
	ds_read_b128 v[188:191], v166 offset:33792
	ds_read_b128 v[192:195], v166 offset:34816
	ds_read_b128 v[196:199], v166 offset:35840
	ds_read_b128 v[200:203], v166 offset:36864
	ds_read_b128 v[204:207], v166 offset:37888
	ds_read_b128 v[208:211], v166 offset:38912
	ds_read_b128 v[212:215], v166 offset:39936
	global_load_lds_dwordx4 v[224:225], off
	v_lshl_add_u64 v[224:225], s[36:37], 0, v[142:143]
	s_mov_b32 m0, s41
	s_nop 0
	global_load_lds_dwordx4 v[224:225], off
	s_waitcnt vmcnt(8)
	s_waitcnt lgkmcnt(0)
	s_barrier
	s_setprio 1
	s_waitcnt lgkmcnt(0)
	v_mfma_f32_16x16x32_bf16 v[126:129], v[130:133], v[184:187], v[126:129]
	v_mfma_f32_16x16x32_bf16 v[122:125], v[154:157], v[184:187], v[122:125]
	v_mfma_f32_16x16x32_bf16 v[106:109], v[154:157], v[192:195], v[106:109]
	v_mfma_f32_16x16x32_bf16 v[110:113], v[130:133], v[192:195], v[110:113]
	v_mfma_f32_16x16x32_bf16 v[94:97], v[130:133], v[200:203], v[94:97]
	v_mfma_f32_16x16x32_bf16 v[90:93], v[154:157], v[200:203], v[90:93]
	v_mfma_f32_16x16x32_bf16 v[74:77], v[154:157], v[208:211], v[74:77]
	v_mfma_f32_16x16x32_bf16 v[78:81], v[130:133], v[208:211], v[78:81]
	v_mfma_f32_16x16x32_bf16 v[126:129], v[134:137], v[188:191], v[126:129]
	v_mfma_f32_16x16x32_bf16 v[122:125], v[158:161], v[188:191], v[122:125]
	v_mfma_f32_16x16x32_bf16 v[106:109], v[158:161], v[196:199], v[106:109]
	v_mfma_f32_16x16x32_bf16 v[110:113], v[134:137], v[196:199], v[110:113]
	v_mfma_f32_16x16x32_bf16 v[94:97], v[134:137], v[204:207], v[94:97]
	v_mfma_f32_16x16x32_bf16 v[90:93], v[158:161], v[204:207], v[90:93]
	v_mfma_f32_16x16x32_bf16 v[74:77], v[158:161], v[212:215], v[74:77]
	v_mfma_f32_16x16x32_bf16 v[78:81], v[134:137], v[212:215], v[78:81]
	s_setprio 0
	s_setprio 1
	v_mfma_f32_16x16x32_bf16 v[118:121], v[168:171], v[184:187], v[118:121]
	v_mfma_f32_16x16x32_bf16 v[114:117], v[176:179], v[184:187], v[114:117]
	v_mfma_f32_16x16x32_bf16 v[98:101], v[176:179], v[192:195], v[98:101]
	v_mfma_f32_16x16x32_bf16 v[102:105], v[168:171], v[192:195], v[102:105]
	v_mfma_f32_16x16x32_bf16 v[86:89], v[168:171], v[200:203], v[86:89]
	v_mfma_f32_16x16x32_bf16 v[82:85], v[176:179], v[200:203], v[82:85]
	v_mfma_f32_16x16x32_bf16 v[66:69], v[176:179], v[208:211], v[66:69]
	v_mfma_f32_16x16x32_bf16 v[70:73], v[168:171], v[208:211], v[70:73]
	v_mfma_f32_16x16x32_bf16 v[118:121], v[172:175], v[188:191], v[118:121]
	v_mfma_f32_16x16x32_bf16 v[114:117], v[180:183], v[188:191], v[114:117]
	v_mfma_f32_16x16x32_bf16 v[98:101], v[180:183], v[196:199], v[98:101]
	v_mfma_f32_16x16x32_bf16 v[102:105], v[172:175], v[196:199], v[102:105]
	v_mfma_f32_16x16x32_bf16 v[86:89], v[172:175], v[204:207], v[86:89]
	v_mfma_f32_16x16x32_bf16 v[82:85], v[180:183], v[204:207], v[82:85]
	v_mfma_f32_16x16x32_bf16 v[66:69], v[180:183], v[212:215], v[66:69]
	v_mfma_f32_16x16x32_bf16 v[70:73], v[172:175], v[212:215], v[70:73]
	s_setprio 0
	s_barrier
; #define PG8_STAGE(bufoff, gbase, voff) do { _Pragma("unroll") for (int _i = 0; _i < 2; ++_i) \
;         __builtin_amdgcn_global_load_lds((const unsigned*)((const char*)(gbase) + (voff)[_i]), (PG8_LAS unsigned*)(lds + (bufoff) + ldsw + _i * 8192), 16, 0, 0); } while (0)
; #define PG8_LDA(dst, b, h) do { _Pragma("unroll") for (int m = 0; m < 4; ++m) _Pragma("unroll") for (int k = 0; k < 2; ++k) dst[m][k] = *(const PG8_LAS bf16x8*)(lds + PG8_SA(b, h) + aoff + m * 2048 + k * 1024); } while (0)
; #define PG8_LDB(dst, b, h) do { _Pragma("unroll") for (int n = 0; n < 2; ++n) _Pragma("unroll") for (int k = 0; k < 2; ++k) dst[n][k] = *(const PG8_LAS bf16x8*)(lds + PG8_SB(b, h) + boff + n * 2048 + k * 1024); } while (0)
; #define PG8_BAR __builtin_amdgcn_s_barrier()
; template <class Epi, class Sched, bool ALIGN_EPI = false, bool SP2 = false>
; __device__ __forceinline__ void gemm_phase(PG8_LAS unsigned char* lds, const Gemm g, const Sched& S, const Epi& E) {
;     ...
;             const bool last = (t == nt - 2);
;             const char* a1 = cA + (size_t)(t + 1) * kstep;
;             const char* a2 = last ? nA : cA + (size_t)(t + 2) * kstep; const char* b2 = last ? nB : cB + (size_t)(t + 2) * kstep;
;             const char* a3 = a2 + kstep; const char* b3 = b2 + kstep;
;             if (last && has_next) S.a_ready(nxt);
;             if constexpr (SP2) {
;             PG8_LDB(B0, 0, 0); PG8_LDB(B1, 0, 1); PG8_SCHED; PG8_LDA(At, 0, 0); PG8_STAGE(PG8_SA(1, 1), a1 + hstepA, voffA);
;             PG8_WAIT_V(8); PG8_WAIT_L(0); PG8_BAR; PG8_MMA(0, 0, At, B0); PG8_MMA(0, 1, At, B1); PG8_BAR; PG8_SCHED;
;             PG8_LDA(At, 0, 1); PG8_STAGE(PG8_SB(0, 0), b2, voffB); PG8_STAGE(PG8_SB(0, 1), b2 + hstepB, voffB); PG8_STAGE(PG8_SA(0, 0), a2, voffA);
;             PG8_WAIT_V(8); PG8_WAIT_L(0); PG8_BAR; PG8_MMA(1, 0, At, B0); PG8_MMA(1, 1, At, B1); PG8_BAR; PG8_SCHED;
;             PG8_LDB(B0, 1, 0); PG8_LDB(B1, 1, 1); PG8_SCHED; PG8_LDA(At, 1, 0); PG8_STAGE(PG8_SA(0, 1), a2 + hstepA, voffA);
;             PG8_WAIT_V(8); PG8_WAIT_L(0); PG8_BAR; PG8_MMA(0, 0, At, B0); PG8_MMA(0, 1, At, B1); PG8_BAR; PG8_SCHED;
;             PG8_LDA(At, 1, 1); PG8_STAGE(PG8_SB(1, 0), b3, voffB); PG8_STAGE(PG8_SB(1, 1), b3 + hstepB, voffB); PG8_STAGE(PG8_SA(1, 0), a3, voffA);
;             PG8_WAIT_V(8); PG8_WAIT_L(0); PG8_BAR; PG8_MMA(1, 0, At, B0); PG8_MMA(1, 1, At, B1); PG8_BAR; PG8_SCHED;
	s_add_i32 s36, s55, s0
	v_lshl_add_u64 v[216:217], v[216:217], 0, s[16:17]
	s_mov_b32 m0, s36
	ds_read_b128 v[184:187], v166 offset:49152
	ds_read_b128 v[188:191], v166 offset:50176
	ds_read_b128 v[192:195], v166 offset:51200
	ds_read_b128 v[196:199], v166 offset:52224
	ds_read_b128 v[200:203], v166 offset:53248
	ds_read_b128 v[204:207], v166 offset:54272
	ds_read_b128 v[208:211], v166 offset:55296
	ds_read_b128 v[212:215], v166 offset:56320
	global_load_lds_dwordx4 v[216:217], off
	s_add_i32 m0, s36, 0x2000
	s_add_u32 s34, s34, 0x40080
	v_lshl_add_u64 v[216:217], v[218:219], 0, s[16:17]
	s_addc_u32 s35, s35, 0
	s_add_i32 s36, s56, s0
	global_load_lds_dwordx4 v[216:217], off
	v_lshl_add_u64 v[216:217], s[34:35], 0, v[140:141]
	s_mov_b32 m0, s36
	s_nop 0
	global_load_lds_dwordx4 v[216:217], off
	v_lshl_add_u64 v[216:217], s[34:35], 0, v[144:145]
	s_add_i32 m0, s36, 0x2000
	s_nop 0
	global_load_lds_dwordx4 v[216:217], off
	v_lshl_add_u64 v[216:217], v[220:221], 0, s[16:17]
	s_mov_b32 m0, s43
	s_nop 0
	global_load_lds_dwordx4 v[216:217], off
	v_lshl_add_u64 v[216:217], v[222:223], 0, s[16:17]
	s_mov_b32 m0, s44
	s_nop 0
	global_load_lds_dwordx4 v[216:217], off
	s_waitcnt vmcnt(8)
	s_waitcnt lgkmcnt(0)
	s_barrier
	s_setprio 1
	s_waitcnt lgkmcnt(0)
	v_mfma_f32_16x16x32_bf16 v[62:65], v[130:133], v[184:187], v[62:65]
	v_mfma_f32_16x16x32_bf16 v[58:61], v[154:157], v[184:187], v[58:61]
	v_mfma_f32_16x16x32_bf16 v[42:45], v[154:157], v[192:195], v[42:45]
	v_mfma_f32_16x16x32_bf16 v[46:49], v[130:133], v[192:195], v[46:49]
	v_mfma_f32_16x16x32_bf16 v[30:33], v[130:133], v[200:203], v[30:33]
	v_mfma_f32_16x16x32_bf16 v[26:29], v[154:157], v[200:203], v[26:29]
	v_mfma_f32_16x16x32_bf16 v[10:13], v[154:157], v[208:211], v[10:13]
	v_mfma_f32_16x16x32_bf16 v[14:17], v[130:133], v[208:211], v[14:17]
	v_mfma_f32_16x16x32_bf16 v[62:65], v[134:137], v[188:191], v[62:65]
	v_mfma_f32_16x16x32_bf16 v[58:61], v[158:161], v[188:191], v[58:61]
	v_mfma_f32_16x16x32_bf16 v[42:45], v[158:161], v[196:199], v[42:45]
	v_mfma_f32_16x16x32_bf16 v[46:49], v[134:137], v[196:199], v[46:49]
	v_mfma_f32_16x16x32_bf16 v[30:33], v[134:137], v[204:207], v[30:33]
	v_mfma_f32_16x16x32_bf16 v[26:29], v[158:161], v[204:207], v[26:29]
	v_mfma_f32_16x16x32_bf16 v[10:13], v[158:161], v[212:215], v[10:13]
	v_mfma_f32_16x16x32_bf16 v[14:17], v[134:137], v[212:215], v[14:17]
	s_setprio 0
	s_setprio 1
	v_mfma_f32_16x16x32_bf16 v[54:57], v[168:171], v[184:187], v[54:57]
	v_mfma_f32_16x16x32_bf16 v[50:53], v[176:179], v[184:187], v[50:53]
	v_mfma_f32_16x16x32_bf16 v[34:37], v[176:179], v[192:195], v[34:37]
	v_mfma_f32_16x16x32_bf16 v[38:41], v[168:171], v[192:195], v[38:41]
	v_mfma_f32_16x16x32_bf16 v[22:25], v[168:171], v[200:203], v[22:25]
	v_mfma_f32_16x16x32_bf16 v[18:21], v[176:179], v[200:203], v[18:21]
	v_mfma_f32_16x16x32_bf16 v[2:5], v[176:179], v[208:211], v[2:5]
	v_mfma_f32_16x16x32_bf16 v[6:9], v[168:171], v[208:211], v[6:9]
	v_mfma_f32_16x16x32_bf16 v[54:57], v[172:175], v[188:191], v[54:57]
	v_mfma_f32_16x16x32_bf16 v[50:53], v[180:183], v[188:191], v[50:53]
	v_mfma_f32_16x16x32_bf16 v[34:37], v[180:183], v[196:199], v[34:37]
	v_mfma_f32_16x16x32_bf16 v[38:41], v[172:175], v[196:199], v[38:41]
	v_mfma_f32_16x16x32_bf16 v[22:25], v[172:175], v[204:207], v[22:25]
	v_mfma_f32_16x16x32_bf16 v[18:21], v[180:183], v[204:207], v[18:21]
	v_mfma_f32_16x16x32_bf16 v[2:5], v[180:183], v[212:215], v[2:5]
	v_mfma_f32_16x16x32_bf16 v[6:9], v[172:175], v[212:215], v[6:9]
	s_setprio 0
	s_barrier
	s_add_i32 s54, s54, 2
	s_add_u32 s30, s30, 0x100
	s_addc_u32 s31, s31, 0
	s_add_u32 s52, s52, 0x100
	s_addc_u32 s53, s53, 0
	s_cmp_gt_u32 s54, 13
.LBB0_1467:
	ds_read_b128 v[130:133], v164
	ds_read_b128 v[134:137], v164 offset:1024
	ds_read_b128 v[154:157], v164 offset:2048
	ds_read_b128 v[158:161], v164 offset:3072
	ds_read_b128 v[168:171], v165
	ds_read_b128 v[172:175], v165 offset:1024
	ds_read_b128 v[176:179], v165 offset:2048
	ds_read_b128 v[180:183], v165 offset:3072
	s_add_u32 s34, s30, 0xfffc0080
	s_addc_u32 s35, s31, -1
	s_cmp_eq_u32 s54, 12
	s_cselect_b32 s37, s23, s35
	s_cselect_b32 s36, s29, s34
	s_cselect_b32 s35, s21, s53
	s_cselect_b32 s34, s51, s52
	v_lshl_add_u64 v[216:217], s[30:31], 0, v[146:147]
	s_add_i32 m0, s1, 0xc000
	ds_read_b128 v[184:187], v166
	ds_read_b128 v[188:191], v166 offset:1024
	ds_read_b128 v[192:195], v166 offset:2048
	ds_read_b128 v[196:199], v166 offset:3072
	ds_read_b128 v[200:203], v166 offset:4096
	ds_read_b128 v[204:207], v166 offset:5120
	ds_read_b128 v[208:211], v166 offset:6144
	ds_read_b128 v[212:215], v166 offset:7168
	global_load_lds_dwordx4 v[216:217], off
	v_lshl_add_u64 v[216:217], s[30:31], 0, v[148:149]
	s_add_i32 m0, s1, 0xe000
	s_nop 0
	global_load_lds_dwordx4 v[216:217], off
	s_waitcnt vmcnt(8)
	s_waitcnt lgkmcnt(0)
	s_barrier
; #define PG8_STAGE(bufoff, gbase, voff) do { _Pragma("unroll") for (int _i = 0; _i < 2; ++_i) \
;         __builtin_amdgcn_global_load_lds((const unsigned*)((const char*)(gbase) + (voff)[_i]), (PG8_LAS unsigned*)(lds + (bufoff) + ldsw + _i * 8192), 16, 0, 0); } while (0)
; #define PG8_LDA(dst, b, h) do { _Pragma("unroll") for (int m = 0; m < 4; ++m) _Pragma("unroll") for (int k = 0; k < 2; ++k) dst[m][k] = *(const PG8_LAS bf16x8*)(lds + PG8_SA(b, h) + aoff + m * 2048 + k * 1024); } while (0)
; #define PG8_MMA(ai, bj, At, Bt) do { __builtin_amdgcn_s_setprio(1); _Pragma("unroll") for (int m = 0; m < 4; ++m) _Pragma("unroll") for (int n = 0; n < 2; ++n) _Pragma("unroll") for (int k = 0; k < 2; ++k) \
;         acc[ai][bj][m][n] = __builtin_amdgcn_mfma_f32_16x16x32_bf16(Bt[n][k], At[m][k], acc[ai][bj][m][n], 0, 0, 0); __builtin_amdgcn_s_setprio(0); } while (0)
; #define PG8_WAIT_V(n) asm volatile("s_waitcnt vmcnt(" #n ")" ::: "memory")
; #define PG8_WAIT_L(n) asm volatile("s_waitcnt lgkmcnt(" #n ")" ::: "memory")
; #define PG8_BAR __builtin_amdgcn_s_barrier()
; #define PG8_SCHED __builtin_amdgcn_sched_barrier(0)
; template <class Epi, class Sched, bool ALIGN_EPI = false, bool SP2 = false>
; __device__ __forceinline__ void gemm_phase(PG8_LAS unsigned char* lds, const Gemm g, const Sched& S, const Epi& E) {
;     ...
;             PG8_WAIT_V(8); PG8_WAIT_L(0); PG8_BAR; PG8_MMA(0, 0, At, B0); PG8_MMA(0, 1, At, B1); PG8_BAR; PG8_SCHED;
;             PG8_LDA(At, 0, 1); PG8_STAGE(PG8_SB(0, 0), b2, voffB); PG8_STAGE(PG8_SB(0, 1), b2 + hstepB, voffB); PG8_STAGE(PG8_SA(0, 0), a2, voffA);
;             PG8_WAIT_V(8); PG8_WAIT_L(0); PG8_BAR; PG8_MMA(1, 0, At, B0); PG8_MMA(1, 1, At, B1); PG8_BAR; PG8_SCHED;
	s_setprio 1
	s_waitcnt lgkmcnt(0)
	v_mfma_f32_16x16x32_bf16 v[126:129], v[130:133], v[184:187], v[126:129]
	v_mfma_f32_16x16x32_bf16 v[122:125], v[154:157], v[184:187], v[122:125]
	v_mfma_f32_16x16x32_bf16 v[106:109], v[154:157], v[192:195], v[106:109]
	v_mfma_f32_16x16x32_bf16 v[110:113], v[130:133], v[192:195], v[110:113]
	v_mfma_f32_16x16x32_bf16 v[94:97], v[130:133], v[200:203], v[94:97]
	v_mfma_f32_16x16x32_bf16 v[90:93], v[154:157], v[200:203], v[90:93]
	v_mfma_f32_16x16x32_bf16 v[74:77], v[154:157], v[208:211], v[74:77]
	v_mfma_f32_16x16x32_bf16 v[78:81], v[130:133], v[208:211], v[78:81]
	v_mfma_f32_16x16x32_bf16 v[126:129], v[134:137], v[188:191], v[126:129]
	v_mfma_f32_16x16x32_bf16 v[122:125], v[158:161], v[188:191], v[122:125]
	v_mfma_f32_16x16x32_bf16 v[106:109], v[158:161], v[196:199], v[106:109]
	v_mfma_f32_16x16x32_bf16 v[110:113], v[134:137], v[196:199], v[110:113]
	v_mfma_f32_16x16x32_bf16 v[94:97], v[134:137], v[204:207], v[94:97]
	v_mfma_f32_16x16x32_bf16 v[90:93], v[158:161], v[204:207], v[90:93]
	v_mfma_f32_16x16x32_bf16 v[74:77], v[158:161], v[212:215], v[74:77]
	v_mfma_f32_16x16x32_bf16 v[78:81], v[134:137], v[212:215], v[78:81]
	s_setprio 0
	s_setprio 1
	v_mfma_f32_16x16x32_bf16 v[118:121], v[168:171], v[184:187], v[118:121]
	v_mfma_f32_16x16x32_bf16 v[114:117], v[176:179], v[184:187], v[114:117]
	v_mfma_f32_16x16x32_bf16 v[98:101], v[176:179], v[192:195], v[98:101]
	v_mfma_f32_16x16x32_bf16 v[102:105], v[168:171], v[192:195], v[102:105]
	v_mfma_f32_16x16x32_bf16 v[86:89], v[168:171], v[200:203], v[86:89]
	v_mfma_f32_16x16x32_bf16 v[82:85], v[176:179], v[200:203], v[82:85]
	v_mfma_f32_16x16x32_bf16 v[66:69], v[176:179], v[208:211], v[66:69]
	v_mfma_f32_16x16x32_bf16 v[70:73], v[168:171], v[208:211], v[70:73]
	v_mfma_f32_16x16x32_bf16 v[118:121], v[172:175], v[188:191], v[118:121]
	v_mfma_f32_16x16x32_bf16 v[114:117], v[180:183], v[188:191], v[114:117]
	v_mfma_f32_16x16x32_bf16 v[98:101], v[180:183], v[196:199], v[98:101]
	v_mfma_f32_16x16x32_bf16 v[102:105], v[172:175], v[196:199], v[102:105]
	v_mfma_f32_16x16x32_bf16 v[86:89], v[172:175], v[204:207], v[86:89]
	v_mfma_f32_16x16x32_bf16 v[82:85], v[180:183], v[204:207], v[82:85]
	v_mfma_f32_16x16x32_bf16 v[66:69], v[180:183], v[212:215], v[66:69]
	v_mfma_f32_16x16x32_bf16 v[70:73], v[172:175], v[212:215], v[70:73]
	s_setprio 0
	s_barrier
	s_add_i32 s55, s48, s0
	v_lshl_add_u64 v[216:217], s[34:35], 0, v[140:141]
	s_mov_b32 m0, s55
	ds_read_b128 v[184:187], v166 offset:16384
	ds_read_b128 v[188:191], v166 offset:17408
	ds_read_b128 v[192:195], v166 offset:18432
	ds_read_b128 v[196:199], v166 offset:19456
	ds_read_b128 v[200:203], v166 offset:20480
	ds_read_b128 v[204:207], v166 offset:21504
	ds_read_b128 v[208:211], v166 offset:22528
	ds_read_b128 v[212:215], v166 offset:23552
	global_load_lds_dwordx4 v[216:217], off
	s_add_i32 m0, s55, 0x2000
	s_add_u32 s56, s34, 0x40000
	v_lshl_add_u64 v[218:219], s[34:35], 0, v[144:145]
	s_addc_u32 s57, s35, 0
	s_add_i32 s55, s49, s0
	global_load_lds_dwordx4 v[218:219], off
	v_lshl_add_u64 v[220:221], s[56:57], 0, v[140:141]
	s_mov_b32 m0, s55
	v_lshl_add_u64 v[222:223], s[36:37], 0, v[142:143]
	global_load_lds_dwordx4 v[220:221], off
	v_lshl_add_u64 v[220:221], s[56:57], 0, v[144:145]
	s_add_i32 m0, s55, 0x2000
	s_nop 0
	global_load_lds_dwordx4 v[220:221], off
	v_lshl_add_u64 v[220:221], s[36:37], 0, v[138:139]
	s_mov_b32 m0, s1
	s_nop 0
	global_load_lds_dwordx4 v[220:221], off
	s_mov_b32 m0, s39
	s_nop 0
	global_load_lds_dwordx4 v[222:223], off
	s_waitcnt vmcnt(8)
	s_waitcnt lgkmcnt(0)
	s_barrier
	s_setprio 1
	s_waitcnt lgkmcnt(0)
	v_mfma_f32_16x16x32_bf16 v[62:65], v[130:133], v[184:187], v[62:65]
	v_mfma_f32_16x16x32_bf16 v[58:61], v[154:157], v[184:187], v[58:61]
	v_mfma_f32_16x16x32_bf16 v[42:45], v[154:157], v[192:195], v[42:45]
	v_mfma_f32_16x16x32_bf16 v[46:49], v[130:133], v[192:195], v[46:49]
	v_mfma_f32_16x16x32_bf16 v[30:33], v[130:133], v[200:203], v[30:33]
	v_mfma_f32_16x16x32_bf16 v[26:29], v[154:157], v[200:203], v[26:29]
	v_mfma_f32_16x16x32_bf16 v[10:13], v[154:157], v[208:211], v[10:13]
	v_mfma_f32_16x16x32_bf16 v[14:17], v[130:133], v[208:211], v[14:17]
	v_mfma_f32_16x16x32_bf16 v[62:65], v[134:137], v[188:191], v[62:65]
	v_mfma_f32_16x16x32_bf16 v[58:61], v[158:161], v[188:191], v[58:61]
	v_mfma_f32_16x16x32_bf16 v[42:45], v[158:161], v[196:199], v[42:45]
	v_mfma_f32_16x16x32_bf16 v[46:49], v[134:137], v[196:199], v[46:49]
	v_mfma_f32_16x16x32_bf16 v[30:33], v[134:137], v[204:207], v[30:33]
	v_mfma_f32_16x16x32_bf16 v[26:29], v[158:161], v[204:207], v[26:29]
	v_mfma_f32_16x16x32_bf16 v[10:13], v[158:161], v[212:215], v[10:13]
	v_mfma_f32_16x16x32_bf16 v[14:17], v[134:137], v[212:215], v[14:17]
	s_setprio 0
	s_setprio 1
	v_mfma_f32_16x16x32_bf16 v[54:57], v[168:171], v[184:187], v[54:57]
	v_mfma_f32_16x16x32_bf16 v[50:53], v[176:179], v[184:187], v[50:53]
	v_mfma_f32_16x16x32_bf16 v[34:37], v[176:179], v[192:195], v[34:37]
	v_mfma_f32_16x16x32_bf16 v[38:41], v[168:171], v[192:195], v[38:41]
	v_mfma_f32_16x16x32_bf16 v[22:25], v[168:171], v[200:203], v[22:25]
	v_mfma_f32_16x16x32_bf16 v[18:21], v[176:179], v[200:203], v[18:21]
	v_mfma_f32_16x16x32_bf16 v[2:5], v[176:179], v[208:211], v[2:5]
	v_mfma_f32_16x16x32_bf16 v[6:9], v[168:171], v[208:211], v[6:9]
	v_mfma_f32_16x16x32_bf16 v[54:57], v[172:175], v[188:191], v[54:57]
	v_mfma_f32_16x16x32_bf16 v[50:53], v[180:183], v[188:191], v[50:53]
	v_mfma_f32_16x16x32_bf16 v[34:37], v[180:183], v[196:199], v[34:37]
	v_mfma_f32_16x16x32_bf16 v[38:41], v[172:175], v[196:199], v[38:41]
	v_mfma_f32_16x16x32_bf16 v[22:25], v[172:175], v[204:207], v[22:25]
	v_mfma_f32_16x16x32_bf16 v[18:21], v[180:183], v[204:207], v[18:21]
	v_mfma_f32_16x16x32_bf16 v[2:5], v[180:183], v[212:215], v[2:5]
	v_mfma_f32_16x16x32_bf16 v[6:9], v[172:175], v[212:215], v[6:9]
	s_setprio 0
	s_barrier
; #define PG8_STAGE(bufoff, gbase, voff) do { _Pragma("unroll") for (int _i = 0; _i < 2; ++_i) \
;         __builtin_amdgcn_global_load_lds((const unsigned*)((const char*)(gbase) + (voff)[_i]), (PG8_LAS unsigned*)(lds + (bufoff) + ldsw + _i * 8192), 16, 0, 0); } while (0)
; #define PG8_LDA(dst, b, h) do { _Pragma("unroll") for (int m = 0; m < 4; ++m) _Pragma("unroll") for (int k = 0; k < 2; ++k) dst[m][k] = *(const PG8_LAS bf16x8*)(lds + PG8_SA(b, h) + aoff + m * 2048 + k * 1024); } while (0)
; #define PG8_LDB(dst, b, h) do { _Pragma("unroll") for (int n = 0; n < 2; ++n) _Pragma("unroll") for (int k = 0; k < 2; ++k) dst[n][k] = *(const PG8_LAS bf16x8*)(lds + PG8_SB(b, h) + boff + n * 2048 + k * 1024); } while (0)
; #define PG8_MMA(ai, bj, At, Bt) do { __builtin_amdgcn_s_setprio(1); _Pragma("unroll") for (int m = 0; m < 4; ++m) _Pragma("unroll") for (int n = 0; n < 2; ++n) _Pragma("unroll") for (int k = 0; k < 2; ++k) \
;         acc[ai][bj][m][n] = __builtin_amdgcn_mfma_f32_16x16x32_bf16(Bt[n][k], At[m][k], acc[ai][bj][m][n], 0, 0, 0); __builtin_amdgcn_s_setprio(0); } while (0)
; #define PG8_WAIT_V(n) asm volatile("s_waitcnt vmcnt(" #n ")" ::: "memory")
; #define PG8_WAIT_L(n) asm volatile("s_waitcnt lgkmcnt(" #n ")" ::: "memory")
; #define PG8_BAR __builtin_amdgcn_s_barrier()
; #define PG8_SCHED __builtin_amdgcn_sched_barrier(0)
; template <class Epi, class Sched, bool ALIGN_EPI = false, bool SP2 = false>
; __device__ __forceinline__ void gemm_phase(PG8_LAS unsigned char* lds, const Gemm g, const Sched& S, const Epi& E) {
;     ...
;             PG8_LDB(B0, 1, 0); PG8_LDB(B1, 1, 1); PG8_SCHED; PG8_LDA(At, 1, 0); PG8_STAGE(PG8_SA(0, 1), a2 + hstepA, voffA);
;             PG8_WAIT_V(8); PG8_WAIT_L(0); PG8_BAR; PG8_MMA(0, 0, At, B0); PG8_MMA(0, 1, At, B1); PG8_BAR; PG8_SCHED;
	s_add_i32 s55, 0, 0x18000
	s_add_i32 s56, 0, 0x1c000
	v_add_u32_e32 v158, s55, v162
	v_add_u32_e32 v180, s56, v162
	ds_read_b128 v[130:133], v158
	ds_read_b128 v[134:137], v158 offset:1024
	ds_read_b128 v[154:157], v158 offset:2048
	ds_read_b128 v[158:161], v158 offset:3072
	ds_read_b128 v[168:171], v180
	ds_read_b128 v[172:175], v180 offset:1024
	ds_read_b128 v[176:179], v180 offset:2048
	ds_read_b128 v[180:183], v180 offset:3072
	s_add_u32 s36, s36, 0x40000
	s_addc_u32 s37, s37, 0
	s_mov_b32 m0, s40
	v_lshl_add_u64 v[224:225], s[36:37], 0, v[138:139]
	ds_read_b128 v[184:187], v166 offset:32768
	ds_read_b128 v[188:191], v166 offset:33792
	ds_read_b128 v[192:195], v166 offset:34816
	ds_read_b128 v[196:199], v166 offset:35840
	ds_read_b128 v[200:203], v166 offset:36864
	ds_read_b128 v[204:207], v166 offset:37888
	ds_read_b128 v[208:211], v166 offset:38912
	ds_read_b128 v[212:215], v166 offset:39936
	global_load_lds_dwordx4 v[224:225], off
	v_lshl_add_u64 v[224:225], s[36:37], 0, v[142:143]
	s_mov_b32 m0, s41
	s_nop 0
	global_load_lds_dwordx4 v[224:225], off
	s_waitcnt vmcnt(8)
	s_waitcnt lgkmcnt(0)
	s_barrier
	s_setprio 1
	s_waitcnt lgkmcnt(0)
	v_mfma_f32_16x16x32_bf16 v[126:129], v[130:133], v[184:187], v[126:129]
	v_mfma_f32_16x16x32_bf16 v[122:125], v[154:157], v[184:187], v[122:125]
	v_mfma_f32_16x16x32_bf16 v[106:109], v[154:157], v[192:195], v[106:109]
	v_mfma_f32_16x16x32_bf16 v[110:113], v[130:133], v[192:195], v[110:113]
	v_mfma_f32_16x16x32_bf16 v[94:97], v[130:133], v[200:203], v[94:97]
	v_mfma_f32_16x16x32_bf16 v[90:93], v[154:157], v[200:203], v[90:93]
	v_mfma_f32_16x16x32_bf16 v[74:77], v[154:157], v[208:211], v[74:77]
	v_mfma_f32_16x16x32_bf16 v[78:81], v[130:133], v[208:211], v[78:81]
	v_mfma_f32_16x16x32_bf16 v[126:129], v[134:137], v[188:191], v[126:129]
	v_mfma_f32_16x16x32_bf16 v[122:125], v[158:161], v[188:191], v[122:125]
	v_mfma_f32_16x16x32_bf16 v[106:109], v[158:161], v[196:199], v[106:109]
	v_mfma_f32_16x16x32_bf16 v[110:113], v[134:137], v[196:199], v[110:113]
	v_mfma_f32_16x16x32_bf16 v[94:97], v[134:137], v[204:207], v[94:97]
	v_mfma_f32_16x16x32_bf16 v[90:93], v[158:161], v[204:207], v[90:93]
	v_mfma_f32_16x16x32_bf16 v[74:77], v[158:161], v[212:215], v[74:77]
	v_mfma_f32_16x16x32_bf16 v[78:81], v[134:137], v[212:215], v[78:81]
	s_setprio 0
	s_setprio 1
	v_mfma_f32_16x16x32_bf16 v[118:121], v[168:171], v[184:187], v[118:121]
	v_mfma_f32_16x16x32_bf16 v[114:117], v[176:179], v[184:187], v[114:117]
	v_mfma_f32_16x16x32_bf16 v[98:101], v[176:179], v[192:195], v[98:101]
	v_mfma_f32_16x16x32_bf16 v[102:105], v[168:171], v[192:195], v[102:105]
	v_mfma_f32_16x16x32_bf16 v[86:89], v[168:171], v[200:203], v[86:89]
	v_mfma_f32_16x16x32_bf16 v[82:85], v[176:179], v[200:203], v[82:85]
	v_mfma_f32_16x16x32_bf16 v[66:69], v[176:179], v[208:211], v[66:69]
	v_mfma_f32_16x16x32_bf16 v[70:73], v[168:171], v[208:211], v[70:73]
	v_mfma_f32_16x16x32_bf16 v[118:121], v[172:175], v[188:191], v[118:121]
	v_mfma_f32_16x16x32_bf16 v[114:117], v[180:183], v[188:191], v[114:117]
	v_mfma_f32_16x16x32_bf16 v[98:101], v[180:183], v[196:199], v[98:101]
	v_mfma_f32_16x16x32_bf16 v[102:105], v[172:175], v[196:199], v[102:105]
	v_mfma_f32_16x16x32_bf16 v[86:89], v[172:175], v[204:207], v[86:89]
	v_mfma_f32_16x16x32_bf16 v[82:85], v[180:183], v[204:207], v[82:85]
	v_mfma_f32_16x16x32_bf16 v[66:69], v[180:183], v[212:215], v[66:69]
	v_mfma_f32_16x16x32_bf16 v[70:73], v[172:175], v[212:215], v[70:73]
	s_setprio 0
	s_barrier
; #define PG8_STAGE(bufoff, gbase, voff) do { _Pragma("unroll") for (int _i = 0; _i < 2; ++_i) \
;         __builtin_amdgcn_global_load_lds((const unsigned*)((const char*)(gbase) + (voff)[_i]), (PG8_LAS unsigned*)(lds + (bufoff) + ldsw + _i * 8192), 16, 0, 0); } while (0)
; #define PG8_LDA(dst, b, h) do { _Pragma("unroll") for (int m = 0; m < 4; ++m) _Pragma("unroll") for (int k = 0; k < 2; ++k) dst[m][k] = *(const PG8_LAS bf16x8*)(lds + PG8_SA(b, h) + aoff + m * 2048 + k * 1024); } while (0)
; #define PG8_MMA(ai, bj, At, Bt) do { __builtin_amdgcn_s_setprio(1); _Pragma("unroll") for (int m = 0; m < 4; ++m) _Pragma("unroll") for (int n = 0; n < 2; ++n) _Pragma("unroll") for (int k = 0; k < 2; ++k) \
;         acc[ai][bj][m][n] = __builtin_amdgcn_mfma_f32_16x16x32_bf16(Bt[n][k], At[m][k], acc[ai][bj][m][n], 0, 0, 0); __builtin_amdgcn_s_setprio(0); } while (0)
; #define PG8_WAIT_V(n) asm volatile("s_waitcnt vmcnt(" #n ")" ::: "memory")
; #define PG8_WAIT_L(n) asm volatile("s_waitcnt lgkmcnt(" #n ")" ::: "memory")
; #define PG8_BAR __builtin_amdgcn_s_barrier()
; #define PG8_SCHED __builtin_amdgcn_sched_barrier(0)
; template <class Epi, class Sched, bool ALIGN_EPI = false, bool SP2 = false>
; __device__ __forceinline__ void gemm_phase(PG8_LAS unsigned char* lds, const Gemm g, const Sched& S, const Epi& E) {
;     ...
;             PG8_LDA(At, 1, 1); PG8_STAGE(PG8_SB(1, 0), b3, voffB); PG8_STAGE(PG8_SB(1, 1), b3 + hstepB, voffB); PG8_STAGE(PG8_SA(1, 0), a3, voffA);
;             PG8_WAIT_V(8); PG8_WAIT_L(0); PG8_BAR; PG8_MMA(1, 0, At, B0); PG8_MMA(1, 1, At, B1); PG8_BAR; PG8_SCHED;
;     ...
;         }
;         if constexpr (ALIGN_EPI) { if (wr == 0) PG8_BAR; }
	s_add_i32 s36, s55, s0
	v_lshl_add_u64 v[216:217], v[216:217], 0, s[16:17]
	s_mov_b32 m0, s36
	ds_read_b128 v[184:187], v166 offset:49152
	ds_read_b128 v[188:191], v166 offset:50176
	ds_read_b128 v[192:195], v166 offset:51200
	ds_read_b128 v[196:199], v166 offset:52224
	ds_read_b128 v[200:203], v166 offset:53248
	ds_read_b128 v[204:207], v166 offset:54272
	ds_read_b128 v[208:211], v166 offset:55296
	ds_read_b128 v[212:215], v166 offset:56320
	global_load_lds_dwordx4 v[216:217], off
	s_add_i32 m0, s36, 0x2000
	s_add_u32 s34, s34, 0x40080
	v_lshl_add_u64 v[216:217], v[218:219], 0, s[16:17]
	s_addc_u32 s35, s35, 0
	s_add_i32 s36, s56, s0
	global_load_lds_dwordx4 v[216:217], off
	v_lshl_add_u64 v[216:217], s[34:35], 0, v[140:141]
	s_mov_b32 m0, s36
	s_nop 0
	global_load_lds_dwordx4 v[216:217], off
	v_lshl_add_u64 v[216:217], s[34:35], 0, v[144:145]
	s_add_i32 m0, s36, 0x2000
	s_nop 0
	global_load_lds_dwordx4 v[216:217], off
	v_lshl_add_u64 v[216:217], v[220:221], 0, s[16:17]
	s_mov_b32 m0, s43
	s_nop 0
	global_load_lds_dwordx4 v[216:217], off
	v_lshl_add_u64 v[216:217], v[222:223], 0, s[16:17]
	s_mov_b32 m0, s44
	s_nop 0
	global_load_lds_dwordx4 v[216:217], off
	s_waitcnt vmcnt(8)
	s_waitcnt lgkmcnt(0)
	s_barrier
	s_setprio 1
	s_waitcnt lgkmcnt(0)
	v_mfma_f32_16x16x32_bf16 v[62:65], v[130:133], v[184:187], v[62:65]
	v_mfma_f32_16x16x32_bf16 v[58:61], v[154:157], v[184:187], v[58:61]
	v_mfma_f32_16x16x32_bf16 v[42:45], v[154:157], v[192:195], v[42:45]
	v_mfma_f32_16x16x32_bf16 v[46:49], v[130:133], v[192:195], v[46:49]
	v_mfma_f32_16x16x32_bf16 v[30:33], v[130:133], v[200:203], v[30:33]
	v_mfma_f32_16x16x32_bf16 v[26:29], v[154:157], v[200:203], v[26:29]
	v_mfma_f32_16x16x32_bf16 v[10:13], v[154:157], v[208:211], v[10:13]
	v_mfma_f32_16x16x32_bf16 v[14:17], v[130:133], v[208:211], v[14:17]
	v_mfma_f32_16x16x32_bf16 v[62:65], v[134:137], v[188:191], v[62:65]
	v_mfma_f32_16x16x32_bf16 v[58:61], v[158:161], v[188:191], v[58:61]
	v_mfma_f32_16x16x32_bf16 v[42:45], v[158:161], v[196:199], v[42:45]
	v_mfma_f32_16x16x32_bf16 v[46:49], v[134:137], v[196:199], v[46:49]
	v_mfma_f32_16x16x32_bf16 v[30:33], v[134:137], v[204:207], v[30:33]
	v_mfma_f32_16x16x32_bf16 v[26:29], v[158:161], v[204:207], v[26:29]
	v_mfma_f32_16x16x32_bf16 v[10:13], v[158:161], v[212:215], v[10:13]
	v_mfma_f32_16x16x32_bf16 v[14:17], v[134:137], v[212:215], v[14:17]
	s_setprio 0
	s_setprio 1
	v_mfma_f32_16x16x32_bf16 v[54:57], v[168:171], v[184:187], v[54:57]
	v_mfma_f32_16x16x32_bf16 v[50:53], v[176:179], v[184:187], v[50:53]
	v_mfma_f32_16x16x32_bf16 v[34:37], v[176:179], v[192:195], v[34:37]
	v_mfma_f32_16x16x32_bf16 v[38:41], v[168:171], v[192:195], v[38:41]
	v_mfma_f32_16x16x32_bf16 v[22:25], v[168:171], v[200:203], v[22:25]
	v_mfma_f32_16x16x32_bf16 v[18:21], v[176:179], v[200:203], v[18:21]
	v_mfma_f32_16x16x32_bf16 v[2:5], v[176:179], v[208:211], v[2:5]
	v_mfma_f32_16x16x32_bf16 v[6:9], v[168:171], v[208:211], v[6:9]
	v_mfma_f32_16x16x32_bf16 v[54:57], v[172:175], v[188:191], v[54:57]
	v_mfma_f32_16x16x32_bf16 v[50:53], v[180:183], v[188:191], v[50:53]
	v_mfma_f32_16x16x32_bf16 v[34:37], v[180:183], v[196:199], v[34:37]
	v_mfma_f32_16x16x32_bf16 v[38:41], v[172:175], v[196:199], v[38:41]
	v_mfma_f32_16x16x32_bf16 v[22:25], v[172:175], v[204:207], v[22:25]
	v_mfma_f32_16x16x32_bf16 v[18:21], v[180:183], v[204:207], v[18:21]
	v_mfma_f32_16x16x32_bf16 v[2:5], v[180:183], v[212:215], v[2:5]
	v_mfma_f32_16x16x32_bf16 v[6:9], v[172:175], v[212:215], v[6:9]
	s_setprio 0
	s_barrier
	s_add_i32 s54, s54, 2
	s_add_u32 s30, s30, 0x100
	s_addc_u32 s31, s31, 0
	s_add_u32 s52, s52, 0x100
	s_addc_u32 s53, s53, 0
	s_cmp_gt_u32 s54, 13
	s_cbranch_scc0 .LBB0_1467
	s_and_b64 vcc, exec, s[18:19]
	s_cbranch_vccz .LBB0_1470
	s_barrier
